# t38 with GEMM wave priorities inverted: load/staging segments run at s_setprio 1, MFMA segments at 0 (same bytes otherwise)
# baseline (speedup 1.0000x reference)
;     __host__ __device__ bool next(int i, Unit& u) const { if (i != 0 || r < 0 || r >= 148) return false; if (r < 116) { u.pm = r % 29; u.pn = 47 + r / 29; } else { u.pm = 32; u.pn = 19 + (r - 116); } u.ko = 0; return true; }
;     __host__ __device__ bool next(int i, Unit& u) const { const int L = i * G + (G - 1 - c); if (L >= nN * S) return false; u.pm = pm; u.pn = L % nN; u.ko = (L / nN) * ksub; return true; }
; #define PG8_STAGE(bufoff, gbase, voff) do { _Pragma("unroll") for (int _i = 0; _i < 2; ++_i) \
;         __builtin_amdgcn_global_load_lds((const unsigned*)((const char*)(gbase) + (voff)[_i]), (PG8_LAS unsigned*)(lds + (bufoff) + ldsw + _i * 8192), 16, 0, 0); } while (0)
; #define PG8_LDA(dst, b, h) do { _Pragma("unroll") for (int m = 0; m < 4; ++m) _Pragma("unroll") for (int k = 0; k < 2; ++k) dst[m][k] = *(const PG8_LAS bf16x8*)(lds + PG8_SA(b, h) + aoff + m * 2048 + k * 1024); } while (0)
; #define PG8_WAIT_V(n) asm volatile("s_waitcnt vmcnt(" #n ")" ::: "memory")
; #define PG8_WAIT_L(n) asm volatile("s_waitcnt lgkmcnt(" #n ")" ::: "memory")
; template <class Epi, class Sched, bool ALIGN_EPI = false, bool SP2 = false>
; __device__ __forceinline__ void gemm_phase(PG8_LAS unsigned char* lds, const Gemm g, const Sched& S, const Epi& E) {
;     ...
;     for (;;) {
;         const bool has_next = S.next(ui + 1, nxt);
;         const char* nA = has_next ? (const char*)g.A + (size_t)nxt.pm * tstep + (size_t)nxt.ko * 2 : cA; const char* nB = has_next ? (const char*)g.Bt + (size_t)nxt.pn * tstep + (size_t)nxt.ko * 2 : cB;
;         for (int t = 0; t < nt; t += 2) {
;             const bool last = (t == nt - 2);
;             const char* a1 = cA + (size_t)(t + 1) * kstep;
;             const char* a2 = last ? nA : cA + (size_t)(t + 2) * kstep; const char* b2 = last ? nB : cB + (size_t)(t + 2) * kstep;
;             const char* a3 = a2 + kstep; const char* b3 = b2 + kstep;
;             if (last && has_next) S.a_ready(nxt);
;             if constexpr (SP2) {
;             PG8_LDB(B0, 0, 0); PG8_LDB(B1, 0, 1); PG8_SCHED; PG8_LDA(At, 0, 0); PG8_STAGE(PG8_SA(1, 1), a1 + hstep, voffA);
;             PG8_WAIT_V(8); PG8_WAIT_L(0); PG8_BAR; PG8_MMA(0, 0, At, B0); PG8_MMA(0, 1, At, B1); PG8_BAR; PG8_SCHED;
;             PG8_LDA(At, 0, 1); PG8_STAGE(PG8_SB(0, 0), b2, voffB); PG8_STAGE(PG8_SB(0, 1), b2 + hstep, voffB); PG8_STAGE(PG8_SA(0, 0), a2, voffA);
.LBB0_239:
	s_add_u32 s48, s12, 0xfff80080
	s_addc_u32 s49, s13, -1
	s_cmp_eq_u32 s47, 28
	s_cselect_b32 s51, s1, s49
	s_cselect_b32 s50, s2, s48
	s_cselect_b32 s49, s3, s37
	s_cselect_b32 s48, s15, s35
	s_add_i32 s65, 0, 0x10000
	v_add_u32_e32 v0, s65, v185
	s_add_i32 s68, 0, 0x14000
	ds_read_b128 v[132:135], v0
	ds_read_b128 v[136:139], v0 offset:1024
	ds_read_b128 v[140:143], v0 offset:2048
	ds_read_b128 v[144:147], v0 offset:3072
	v_add_u32_e32 v0, s68, v185
	ds_read_b128 v[148:151], v0
	ds_read_b128 v[152:155], v0 offset:1024
	ds_read_b128 v[172:175], v0 offset:2048
	ds_read_b128 v[176:179], v0 offset:3072
	v_lshl_add_u64 v[228:229], s[12:13], 0, v[168:169]
	s_add_i32 m0, s53, 0xc000
	ds_read_b128 v[180:183], v190
	ds_read_b128 v[192:195], v190 offset:1024
	ds_read_b128 v[196:199], v190 offset:2048
	ds_read_b128 v[200:203], v190 offset:3072
	ds_read_b128 v[204:207], v190 offset:4096
	ds_read_b128 v[208:211], v190 offset:5120
	ds_read_b128 v[220:223], v190 offset:6144
	ds_read_b128 v[224:227], v190 offset:7168
	global_load_lds_dwordx4 v[228:229], off
	v_lshl_add_u64 v[228:229], s[12:13], 0, v[170:171]
	s_add_i32 m0, s53, 0xe000
	s_nop 0
	global_load_lds_dwordx4 v[228:229], off
	s_waitcnt vmcnt(8)
	s_waitcnt lgkmcnt(0)
	s_barrier
	s_setprio 0
	s_waitcnt lgkmcnt(0)
	v_mfma_f32_16x16x32_bf16 v[128:131], v[132:135], v[180:183], v[128:131]
	v_mfma_f32_16x16x32_bf16 v[124:127], v[140:143], v[180:183], v[124:127]
	v_mfma_f32_16x16x32_bf16 v[112:115], v[132:135], v[196:199], v[112:115]
	v_mfma_f32_16x16x32_bf16 v[108:111], v[140:143], v[196:199], v[108:111]
	v_mfma_f32_16x16x32_bf16 v[96:99], v[132:135], v[204:207], v[96:99]
	v_mfma_f32_16x16x32_bf16 v[92:95], v[140:143], v[204:207], v[92:95]
	v_mfma_f32_16x16x32_bf16 v[80:83], v[132:135], v[220:223], v[80:83]
	v_mfma_f32_16x16x32_bf16 v[76:79], v[140:143], v[220:223], v[76:79]
	v_mfma_f32_16x16x32_bf16 v[128:131], v[136:139], v[192:195], v[128:131]
	v_mfma_f32_16x16x32_bf16 v[124:127], v[144:147], v[192:195], v[124:127]
	v_mfma_f32_16x16x32_bf16 v[112:115], v[136:139], v[200:203], v[112:115]
	v_mfma_f32_16x16x32_bf16 v[108:111], v[144:147], v[200:203], v[108:111]
	v_mfma_f32_16x16x32_bf16 v[96:99], v[136:139], v[208:211], v[96:99]
	v_mfma_f32_16x16x32_bf16 v[92:95], v[144:147], v[208:211], v[92:95]
	v_mfma_f32_16x16x32_bf16 v[80:83], v[136:139], v[224:227], v[80:83]
	v_mfma_f32_16x16x32_bf16 v[76:79], v[144:147], v[224:227], v[76:79]
	s_setprio 0
	s_setprio 0
	v_mfma_f32_16x16x32_bf16 v[120:123], v[148:151], v[180:183], v[120:123]
	v_mfma_f32_16x16x32_bf16 v[116:119], v[172:175], v[180:183], v[116:119]
	v_mfma_f32_16x16x32_bf16 v[104:107], v[148:151], v[196:199], v[104:107]
	v_mfma_f32_16x16x32_bf16 v[100:103], v[172:175], v[196:199], v[100:103]
	v_mfma_f32_16x16x32_bf16 v[88:91], v[148:151], v[204:207], v[88:91]
	v_mfma_f32_16x16x32_bf16 v[84:87], v[172:175], v[204:207], v[84:87]
	v_mfma_f32_16x16x32_bf16 v[72:75], v[148:151], v[220:223], v[72:75]
	v_mfma_f32_16x16x32_bf16 v[68:71], v[172:175], v[220:223], v[68:71]
	v_mfma_f32_16x16x32_bf16 v[120:123], v[152:155], v[192:195], v[120:123]
	v_mfma_f32_16x16x32_bf16 v[116:119], v[176:179], v[192:195], v[116:119]
	v_mfma_f32_16x16x32_bf16 v[104:107], v[152:155], v[200:203], v[104:107]
	v_mfma_f32_16x16x32_bf16 v[100:103], v[176:179], v[200:203], v[100:103]
	v_mfma_f32_16x16x32_bf16 v[88:91], v[152:155], v[208:211], v[88:91]
	v_mfma_f32_16x16x32_bf16 v[84:87], v[176:179], v[208:211], v[84:87]
	v_mfma_f32_16x16x32_bf16 v[72:75], v[152:155], v[224:227], v[72:75]
	v_mfma_f32_16x16x32_bf16 v[68:71], v[176:179], v[224:227], v[68:71]
	s_setprio 1
	s_barrier
	s_add_i32 s65, s65, s52
	v_lshl_add_u64 v[228:229], s[48:49], 0, v[158:159]
	s_mov_b32 m0, s65
	ds_read_b128 v[180:183], v190 offset:16384
	ds_read_b128 v[192:195], v190 offset:17408
	ds_read_b128 v[196:199], v190 offset:18432
	ds_read_b128 v[200:203], v190 offset:19456
	ds_read_b128 v[204:207], v190 offset:20480
	ds_read_b128 v[208:211], v190 offset:21504
	ds_read_b128 v[220:223], v190 offset:22528
	ds_read_b128 v[224:227], v190 offset:23552
	global_load_lds_dwordx4 v[228:229], off
	s_add_i32 m0, s65, 0x2000
	s_add_u32 s66, s48, 0x80000
	v_lshl_add_u64 v[230:231], s[48:49], 0, v[162:163]
	s_addc_u32 s67, s49, 0
	s_add_i32 s65, s68, s52
	global_load_lds_dwordx4 v[230:231], off
	v_lshl_add_u64 v[232:233], s[66:67], 0, v[158:159]
	s_mov_b32 m0, s65
	v_lshl_add_u64 v[234:235], s[50:51], 0, v[160:161]
	global_load_lds_dwordx4 v[232:233], off
	v_lshl_add_u64 v[232:233], s[66:67], 0, v[162:163]
	s_add_i32 m0, s65, 0x2000
	s_nop 0
	global_load_lds_dwordx4 v[232:233], off
	v_lshl_add_u64 v[232:233], s[50:51], 0, v[156:157]
	s_mov_b32 m0, s53
	s_nop 0
	global_load_lds_dwordx4 v[232:233], off
	s_mov_b32 m0, s54
	s_nop 0
	global_load_lds_dwordx4 v[234:235], off
	s_waitcnt vmcnt(8)
	s_waitcnt lgkmcnt(0)
	s_barrier
; #define PG8_STAGE(bufoff, gbase, voff) do { _Pragma("unroll") for (int _i = 0; _i < 2; ++_i) \
;         __builtin_amdgcn_global_load_lds((const unsigned*)((const char*)(gbase) + (voff)[_i]), (PG8_LAS unsigned*)(lds + (bufoff) + ldsw + _i * 8192), 16, 0, 0); } while (0)
; #define PG8_LDA(dst, b, h) do { _Pragma("unroll") for (int m = 0; m < 4; ++m) _Pragma("unroll") for (int k = 0; k < 2; ++k) dst[m][k] = *(const PG8_LAS bf16x8*)(lds + PG8_SA(b, h) + aoff + m * 2048 + k * 1024); } while (0)
; #define PG8_LDB(dst, b, h) do { _Pragma("unroll") for (int n = 0; n < 2; ++n) _Pragma("unroll") for (int k = 0; k < 2; ++k) dst[n][k] = *(const PG8_LAS bf16x8*)(lds + PG8_SB(b, h) + boff + n * 2048 + k * 1024); } while (0)
; #define PG8_MMA(ai, bj, At, Bt) do { __builtin_amdgcn_s_setprio(1); _Pragma("unroll") for (int m = 0; m < 4; ++m) _Pragma("unroll") for (int n = 0; n < 2; ++n) _Pragma("unroll") for (int k = 0; k < 2; ++k) \
;         acc[ai][bj][m][n] = __builtin_amdgcn_mfma_f32_16x16x32_bf16(Bt[n][k], At[m][k], acc[ai][bj][m][n], 0, 0, 0); __builtin_amdgcn_s_setprio(0); } while (0)
; #define PG8_WAIT_V(n) asm volatile("s_waitcnt vmcnt(" #n ")" ::: "memory")
; #define PG8_WAIT_L(n) asm volatile("s_waitcnt lgkmcnt(" #n ")" ::: "memory")
; #define PG8_BAR __builtin_amdgcn_s_barrier()
; #define PG8_SCHED __builtin_amdgcn_sched_barrier(0)
; template <class Epi, class Sched, bool ALIGN_EPI = false, bool SP2 = false>
; __device__ __forceinline__ void gemm_phase(PG8_LAS unsigned char* lds, const Gemm g, const Sched& S, const Epi& E) {
;     ...
;             PG8_WAIT_V(8); PG8_WAIT_L(0); PG8_BAR; PG8_MMA(1, 0, At, B0); PG8_MMA(1, 1, At, B1); PG8_BAR; PG8_SCHED;
;             PG8_LDB(B0, 1, 0); PG8_LDB(B1, 1, 1); PG8_SCHED; PG8_LDA(At, 1, 0); PG8_STAGE(PG8_SA(0, 1), a2 + hstep, voffA);
;             PG8_WAIT_V(8); PG8_WAIT_L(0); PG8_BAR; PG8_MMA(0, 0, At, B0); PG8_MMA(0, 1, At, B1); PG8_BAR; PG8_SCHED;
	s_setprio 0
	s_waitcnt lgkmcnt(0)
	v_mfma_f32_16x16x32_bf16 v[62:65], v[132:135], v[180:183], v[62:65]
	v_mfma_f32_16x16x32_bf16 v[58:61], v[140:143], v[180:183], v[58:61]
	v_mfma_f32_16x16x32_bf16 v[46:49], v[132:135], v[196:199], v[46:49]
	v_mfma_f32_16x16x32_bf16 v[42:45], v[140:143], v[196:199], v[42:45]
	v_mfma_f32_16x16x32_bf16 v[30:33], v[132:135], v[204:207], v[30:33]
	v_mfma_f32_16x16x32_bf16 v[26:29], v[140:143], v[204:207], v[26:29]
	v_mfma_f32_16x16x32_bf16 v[14:17], v[132:135], v[220:223], v[14:17]
	v_mfma_f32_16x16x32_bf16 v[10:13], v[140:143], v[220:223], v[10:13]
	v_mfma_f32_16x16x32_bf16 v[62:65], v[136:139], v[192:195], v[62:65]
	v_mfma_f32_16x16x32_bf16 v[58:61], v[144:147], v[192:195], v[58:61]
	v_mfma_f32_16x16x32_bf16 v[46:49], v[136:139], v[200:203], v[46:49]
	v_mfma_f32_16x16x32_bf16 v[42:45], v[144:147], v[200:203], v[42:45]
	v_mfma_f32_16x16x32_bf16 v[30:33], v[136:139], v[208:211], v[30:33]
	v_mfma_f32_16x16x32_bf16 v[26:29], v[144:147], v[208:211], v[26:29]
	v_mfma_f32_16x16x32_bf16 v[14:17], v[136:139], v[224:227], v[14:17]
	v_mfma_f32_16x16x32_bf16 v[10:13], v[144:147], v[224:227], v[10:13]
	s_setprio 0
	s_setprio 0
	v_mfma_f32_16x16x32_bf16 v[54:57], v[148:151], v[180:183], v[54:57]
	v_mfma_f32_16x16x32_bf16 v[50:53], v[172:175], v[180:183], v[50:53]
	v_mfma_f32_16x16x32_bf16 v[38:41], v[148:151], v[196:199], v[38:41]
	v_mfma_f32_16x16x32_bf16 v[34:37], v[172:175], v[196:199], v[34:37]
	v_mfma_f32_16x16x32_bf16 v[22:25], v[148:151], v[204:207], v[22:25]
	v_mfma_f32_16x16x32_bf16 v[18:21], v[172:175], v[204:207], v[18:21]
	v_mfma_f32_16x16x32_bf16 v[6:9], v[148:151], v[220:223], v[6:9]
	v_mfma_f32_16x16x32_bf16 v[2:5], v[172:175], v[220:223], v[2:5]
	v_mfma_f32_16x16x32_bf16 v[54:57], v[152:155], v[192:195], v[54:57]
	v_mfma_f32_16x16x32_bf16 v[50:53], v[176:179], v[192:195], v[50:53]
	v_mfma_f32_16x16x32_bf16 v[38:41], v[152:155], v[200:203], v[38:41]
	v_mfma_f32_16x16x32_bf16 v[34:37], v[176:179], v[200:203], v[34:37]
	v_mfma_f32_16x16x32_bf16 v[22:25], v[152:155], v[208:211], v[22:25]
	v_mfma_f32_16x16x32_bf16 v[18:21], v[176:179], v[208:211], v[18:21]
	v_mfma_f32_16x16x32_bf16 v[6:9], v[152:155], v[224:227], v[6:9]
	v_mfma_f32_16x16x32_bf16 v[2:5], v[176:179], v[224:227], v[2:5]
	s_setprio 1
	s_barrier
	s_add_i32 s65, 0, 0x18000
	v_add_u32_e32 v0, s65, v185
	s_add_i32 s66, 0, 0x1c000
	ds_read_b128 v[132:135], v0
	ds_read_b128 v[136:139], v0 offset:1024
	ds_read_b128 v[140:143], v0 offset:2048
	ds_read_b128 v[144:147], v0 offset:3072
	v_add_u32_e32 v0, s66, v185
	ds_read_b128 v[148:151], v0
	ds_read_b128 v[152:155], v0 offset:1024
	ds_read_b128 v[172:175], v0 offset:2048
	ds_read_b128 v[176:179], v0 offset:3072
	s_add_u32 s50, s50, 0x80000
	s_addc_u32 s51, s51, 0
	s_mov_b32 m0, s55
	v_lshl_add_u64 v[246:247], s[50:51], 0, v[156:157]
	ds_read_b128 v[180:183], v190 offset:32768
	ds_read_b128 v[192:195], v190 offset:33792
	ds_read_b128 v[196:199], v190 offset:34816
	ds_read_b128 v[200:203], v190 offset:35840
	ds_read_b128 v[204:207], v190 offset:36864
	ds_read_b128 v[208:211], v190 offset:37888
	ds_read_b128 v[220:223], v190 offset:38912
	ds_read_b128 v[224:227], v190 offset:39936
	global_load_lds_dwordx4 v[246:247], off
	v_lshl_add_u64 v[246:247], s[50:51], 0, v[160:161]
	s_mov_b32 m0, s56
	s_nop 0
	global_load_lds_dwordx4 v[246:247], off
	s_waitcnt vmcnt(8)
	s_waitcnt lgkmcnt(0)
	s_barrier
	s_setprio 0
	s_waitcnt lgkmcnt(0)
	v_mfma_f32_16x16x32_bf16 v[128:131], v[132:135], v[180:183], v[128:131]
	v_mfma_f32_16x16x32_bf16 v[124:127], v[140:143], v[180:183], v[124:127]
	v_mfma_f32_16x16x32_bf16 v[112:115], v[132:135], v[196:199], v[112:115]
	v_mfma_f32_16x16x32_bf16 v[108:111], v[140:143], v[196:199], v[108:111]
	v_mfma_f32_16x16x32_bf16 v[96:99], v[132:135], v[204:207], v[96:99]
	v_mfma_f32_16x16x32_bf16 v[92:95], v[140:143], v[204:207], v[92:95]
	v_mfma_f32_16x16x32_bf16 v[80:83], v[132:135], v[220:223], v[80:83]
	v_mfma_f32_16x16x32_bf16 v[76:79], v[140:143], v[220:223], v[76:79]
	v_mfma_f32_16x16x32_bf16 v[128:131], v[136:139], v[192:195], v[128:131]
	v_mfma_f32_16x16x32_bf16 v[124:127], v[144:147], v[192:195], v[124:127]
	v_mfma_f32_16x16x32_bf16 v[112:115], v[136:139], v[200:203], v[112:115]
	v_mfma_f32_16x16x32_bf16 v[108:111], v[144:147], v[200:203], v[108:111]
	v_mfma_f32_16x16x32_bf16 v[96:99], v[136:139], v[208:211], v[96:99]
	v_mfma_f32_16x16x32_bf16 v[92:95], v[144:147], v[208:211], v[92:95]
	v_mfma_f32_16x16x32_bf16 v[80:83], v[136:139], v[224:227], v[80:83]
	v_mfma_f32_16x16x32_bf16 v[76:79], v[144:147], v[224:227], v[76:79]
	s_setprio 0
	s_setprio 0
	v_mfma_f32_16x16x32_bf16 v[120:123], v[148:151], v[180:183], v[120:123]
	v_mfma_f32_16x16x32_bf16 v[116:119], v[172:175], v[180:183], v[116:119]
	v_mfma_f32_16x16x32_bf16 v[104:107], v[148:151], v[196:199], v[104:107]
	v_mfma_f32_16x16x32_bf16 v[100:103], v[172:175], v[196:199], v[100:103]
	v_mfma_f32_16x16x32_bf16 v[88:91], v[148:151], v[204:207], v[88:91]
	v_mfma_f32_16x16x32_bf16 v[84:87], v[172:175], v[204:207], v[84:87]
	v_mfma_f32_16x16x32_bf16 v[72:75], v[148:151], v[220:223], v[72:75]
	v_mfma_f32_16x16x32_bf16 v[68:71], v[172:175], v[220:223], v[68:71]
	v_mfma_f32_16x16x32_bf16 v[120:123], v[152:155], v[192:195], v[120:123]
	v_mfma_f32_16x16x32_bf16 v[116:119], v[176:179], v[192:195], v[116:119]
	v_mfma_f32_16x16x32_bf16 v[104:107], v[152:155], v[200:203], v[104:107]
	v_mfma_f32_16x16x32_bf16 v[100:103], v[176:179], v[200:203], v[100:103]
	v_mfma_f32_16x16x32_bf16 v[88:91], v[152:155], v[208:211], v[88:91]
	v_mfma_f32_16x16x32_bf16 v[84:87], v[176:179], v[208:211], v[84:87]
	v_mfma_f32_16x16x32_bf16 v[72:75], v[152:155], v[224:227], v[72:75]
	v_mfma_f32_16x16x32_bf16 v[68:71], v[176:179], v[224:227], v[68:71]
	s_setprio 1
	s_barrier
; #define PG8_STAGE(bufoff, gbase, voff) do { _Pragma("unroll") for (int _i = 0; _i < 2; ++_i) \
;         __builtin_amdgcn_global_load_lds((const unsigned*)((const char*)(gbase) + (voff)[_i]), (PG8_LAS unsigned*)(lds + (bufoff) + ldsw + _i * 8192), 16, 0, 0); } while (0)
; #define PG8_WAIT_V(n) asm volatile("s_waitcnt vmcnt(" #n ")" ::: "memory")
; #define PG8_WAIT_L(n) asm volatile("s_waitcnt lgkmcnt(" #n ")" ::: "memory")
; template <class Epi, class Sched, bool ALIGN_EPI = false, bool SP2 = false>
; __device__ __forceinline__ void gemm_phase(PG8_LAS unsigned char* lds, const Gemm g, const Sched& S, const Epi& E) {
;     ...
;             PG8_LDA(At, 1, 1); PG8_STAGE(PG8_SB(1, 0), b3, voffB); PG8_STAGE(PG8_SB(1, 1), b3 + hstep, voffB); PG8_STAGE(PG8_SA(1, 0), a3, voffA);
;             PG8_WAIT_V(8); PG8_WAIT_L(0); PG8_BAR; PG8_MMA(1, 0, At, B0); PG8_MMA(1, 1, At, B1); PG8_BAR; PG8_SCHED;
;             } else {
;             PG8_LDB(B0, 0, 0); PG8_SCHED; PG8_LDA(At, 0, 0); PG8_STAGE(PG8_SA(1, 1), a1 + hstep, voffA);
;             PG8_WAIT_L(8); PG8_BAR; PG8_WAIT_L(0); PG8_MMA(0, 0, At, B0); PG8_BAR; PG8_SCHED;
;             PG8_LDB(B1, 0, 1); PG8_STAGE(PG8_SB(0, 0), b2, voffB);
;             PG8_BAR; PG8_WAIT_L(0); PG8_MMA(0, 1, At, B1); PG8_BAR;
;             PG8_LDA(At, 0, 1); PG8_STAGE(PG8_SA(0, 0), a2, voffA);
;             PG8_BAR; PG8_WAIT_L(0); PG8_MMA(1, 0, At, B0); PG8_BAR; PG8_SCHED;
;             PG8_STAGE(PG8_SB(0, 1), b2 + hstep, voffB);
;             PG8_WAIT_V(6); PG8_BAR; PG8_MMA(1, 1, At, B1); PG8_BAR;
;             PG8_LDB(B0, 1, 0); PG8_SCHED; PG8_LDA(At, 1, 0); PG8_STAGE(PG8_SA(0, 1), a2 + hstep, voffA);
;             PG8_WAIT_L(8); PG8_BAR; PG8_WAIT_L(0); PG8_MMA(0, 0, At, B0); PG8_BAR; PG8_SCHED;
;             PG8_LDB(B1, 1, 1); PG8_STAGE(PG8_SB(1, 0), b3, voffB);
;             PG8_BAR; PG8_WAIT_L(0); PG8_MMA(0, 1, At, B1); PG8_BAR;
;             PG8_LDA(At, 1, 1); PG8_STAGE(PG8_SA(1, 0), a3, voffA);
;             PG8_BAR; PG8_WAIT_L(0); PG8_MMA(1, 0, At, B0); PG8_BAR; PG8_SCHED;
;             PG8_STAGE(PG8_SB(1, 1), b3 + hstep, voffB);
;             PG8_WAIT_V(6); PG8_BAR; PG8_MMA(1, 1, At, B1); PG8_BAR;
;             }
;             if constexpr (Epi::HAS_MID) { if ((((t + 2) & 7) == 0) && ((t + 2) < nt)) E.mid(acc, cur, ((t + 2) >> 3) - 1, wr, wc, fr, fq); }
;         }
;         if constexpr (ALIGN_EPI) { if (wr == 0) PG8_BAR; }
	s_add_i32 s50, s65, s52
	v_lshl_add_u64 v[228:229], v[228:229], 0, s[88:89]
	s_mov_b32 m0, s50
	ds_read_b128 v[180:183], v190 offset:49152
	ds_read_b128 v[192:195], v190 offset:50176
	ds_read_b128 v[196:199], v190 offset:51200
	ds_read_b128 v[200:203], v190 offset:52224
	ds_read_b128 v[204:207], v190 offset:53248
	ds_read_b128 v[208:211], v190 offset:54272
	ds_read_b128 v[220:223], v190 offset:55296
	ds_read_b128 v[224:227], v190 offset:56320
	global_load_lds_dwordx4 v[228:229], off
	s_add_i32 m0, s50, 0x2000
	s_add_u32 s48, s48, 0x80080
	v_lshl_add_u64 v[228:229], v[230:231], 0, s[88:89]
	s_addc_u32 s49, s49, 0
	s_add_i32 s50, s66, s52
	global_load_lds_dwordx4 v[228:229], off
	v_lshl_add_u64 v[228:229], s[48:49], 0, v[158:159]
	s_mov_b32 m0, s50
	s_nop 0
	global_load_lds_dwordx4 v[228:229], off
	v_lshl_add_u64 v[228:229], s[48:49], 0, v[162:163]
	s_add_i32 m0, s50, 0x2000
	s_nop 0
	global_load_lds_dwordx4 v[228:229], off
	v_lshl_add_u64 v[228:229], v[232:233], 0, s[88:89]
	s_mov_b32 m0, s58
	s_nop 0
	global_load_lds_dwordx4 v[228:229], off
	v_lshl_add_u64 v[228:229], v[234:235], 0, s[88:89]
	s_mov_b32 m0, s59
	s_nop 0
	global_load_lds_dwordx4 v[228:229], off
	s_waitcnt vmcnt(8)
	s_waitcnt lgkmcnt(0)
	s_barrier
	s_setprio 0
	s_waitcnt lgkmcnt(0)
	v_mfma_f32_16x16x32_bf16 v[62:65], v[132:135], v[180:183], v[62:65]
	v_mfma_f32_16x16x32_bf16 v[58:61], v[140:143], v[180:183], v[58:61]
	v_mfma_f32_16x16x32_bf16 v[46:49], v[132:135], v[196:199], v[46:49]
	v_mfma_f32_16x16x32_bf16 v[42:45], v[140:143], v[196:199], v[42:45]
	v_mfma_f32_16x16x32_bf16 v[30:33], v[132:135], v[204:207], v[30:33]
	v_mfma_f32_16x16x32_bf16 v[26:29], v[140:143], v[204:207], v[26:29]
	v_mfma_f32_16x16x32_bf16 v[14:17], v[132:135], v[220:223], v[14:17]
	v_mfma_f32_16x16x32_bf16 v[10:13], v[140:143], v[220:223], v[10:13]
	v_mfma_f32_16x16x32_bf16 v[62:65], v[136:139], v[192:195], v[62:65]
	v_mfma_f32_16x16x32_bf16 v[58:61], v[144:147], v[192:195], v[58:61]
	v_mfma_f32_16x16x32_bf16 v[46:49], v[136:139], v[200:203], v[46:49]
	v_mfma_f32_16x16x32_bf16 v[42:45], v[144:147], v[200:203], v[42:45]
	v_mfma_f32_16x16x32_bf16 v[30:33], v[136:139], v[208:211], v[30:33]
	v_mfma_f32_16x16x32_bf16 v[26:29], v[144:147], v[208:211], v[26:29]
	v_mfma_f32_16x16x32_bf16 v[14:17], v[136:139], v[224:227], v[14:17]
	v_mfma_f32_16x16x32_bf16 v[10:13], v[144:147], v[224:227], v[10:13]
	s_setprio 0
	s_setprio 0
	v_mfma_f32_16x16x32_bf16 v[54:57], v[148:151], v[180:183], v[54:57]
	v_mfma_f32_16x16x32_bf16 v[50:53], v[172:175], v[180:183], v[50:53]
	v_mfma_f32_16x16x32_bf16 v[38:41], v[148:151], v[196:199], v[38:41]
	v_mfma_f32_16x16x32_bf16 v[34:37], v[172:175], v[196:199], v[34:37]
	v_mfma_f32_16x16x32_bf16 v[22:25], v[148:151], v[204:207], v[22:25]
	v_mfma_f32_16x16x32_bf16 v[18:21], v[172:175], v[204:207], v[18:21]
	v_mfma_f32_16x16x32_bf16 v[6:9], v[148:151], v[220:223], v[6:9]
	v_mfma_f32_16x16x32_bf16 v[2:5], v[172:175], v[220:223], v[2:5]
	v_mfma_f32_16x16x32_bf16 v[54:57], v[152:155], v[192:195], v[54:57]
	v_mfma_f32_16x16x32_bf16 v[50:53], v[176:179], v[192:195], v[50:53]
	v_mfma_f32_16x16x32_bf16 v[38:41], v[152:155], v[200:203], v[38:41]
	v_mfma_f32_16x16x32_bf16 v[34:37], v[176:179], v[200:203], v[34:37]
	v_mfma_f32_16x16x32_bf16 v[22:25], v[152:155], v[208:211], v[22:25]
	v_mfma_f32_16x16x32_bf16 v[18:21], v[176:179], v[208:211], v[18:21]
	v_mfma_f32_16x16x32_bf16 v[6:9], v[152:155], v[224:227], v[6:9]
	v_mfma_f32_16x16x32_bf16 v[2:5], v[176:179], v[224:227], v[2:5]
	s_setprio 1
	s_barrier
	s_add_i32 s47, s47, 2
	s_add_u32 s12, s12, 0x100
	s_addc_u32 s13, s13, 0
	s_add_u32 s35, s35, 0x100
	s_addc_u32 s37, s37, 0
	s_cmp_gt_u32 s47, 29
	s_cbranch_scc0 .LBB0_239
	s_and_b64 vcc, exec, s[30:31]
	s_cbranch_vccz .LBB0_242
	s_barrier

;     __host__ __device__ bool next(int i, Unit& u) const { if (i != 0 || r < 0 || r >= 148) return false; if (r < 116) { u.pm = r % 29; u.pn = 47 + r / 29; } else { u.pm = 32; u.pn = 19 + (r - 116); } u.ko = 0; return true; }
;     __host__ __device__ bool next(int i, Unit& u) const { const int L = i * G + (G - 1 - c); if (L >= nN * S) return false; u.pm = pm; u.pn = L % nN; u.ko = (L / nN) * ksub; return true; }
; #define PG8_STAGE(bufoff, gbase, voff) do { _Pragma("unroll") for (int _i = 0; _i < 2; ++_i) \
;         __builtin_amdgcn_global_load_lds((const unsigned*)((const char*)(gbase) + (voff)[_i]), (PG8_LAS unsigned*)(lds + (bufoff) + ldsw + _i * 8192), 16, 0, 0); } while (0)
; #define PG8_LDA(dst, b, h) do { _Pragma("unroll") for (int m = 0; m < 4; ++m) _Pragma("unroll") for (int k = 0; k < 2; ++k) dst[m][k] = *(const PG8_LAS bf16x8*)(lds + PG8_SA(b, h) + aoff + m * 2048 + k * 1024); } while (0)
; #define PG8_WAIT_V(n) asm volatile("s_waitcnt vmcnt(" #n ")" ::: "memory")
; #define PG8_WAIT_L(n) asm volatile("s_waitcnt lgkmcnt(" #n ")" ::: "memory")
; template <class Epi, class Sched, bool ALIGN_EPI = false, bool SP2 = false>
; __device__ __forceinline__ void gemm_phase(PG8_LAS unsigned char* lds, const Gemm g, const Sched& S, const Epi& E) {
;     ...
;     for (;;) {
;         const bool has_next = S.next(ui + 1, nxt);
;         const char* nA = has_next ? (const char*)g.A + (size_t)nxt.pm * tstep + (size_t)nxt.ko * 2 : cA; const char* nB = has_next ? (const char*)g.Bt + (size_t)nxt.pn * tstep + (size_t)nxt.ko * 2 : cB;
;         for (int t = 0; t < nt; t += 2) {
;             const bool last = (t == nt - 2);
;             const char* a1 = cA + (size_t)(t + 1) * kstep;
;             const char* a2 = last ? nA : cA + (size_t)(t + 2) * kstep; const char* b2 = last ? nB : cB + (size_t)(t + 2) * kstep;
;             const char* a3 = a2 + kstep; const char* b3 = b2 + kstep;
;             if (last && has_next) S.a_ready(nxt);
;             if constexpr (SP2) {
;             PG8_LDB(B0, 0, 0); PG8_LDB(B1, 0, 1); PG8_SCHED; PG8_LDA(At, 0, 0); PG8_STAGE(PG8_SA(1, 1), a1 + hstep, voffA);
;             PG8_WAIT_V(8); PG8_WAIT_L(0); PG8_BAR; PG8_MMA(0, 0, At, B0); PG8_MMA(0, 1, At, B1); PG8_BAR; PG8_SCHED;
;             PG8_LDA(At, 0, 1); PG8_STAGE(PG8_SB(0, 0), b2, voffB); PG8_STAGE(PG8_SB(0, 1), b2 + hstep, voffB); PG8_STAGE(PG8_SA(0, 0), a2, voffA);
.LBB0_398:
	s_lshl_b32 s54, s43, 7
	s_add_u32 s55, s30, s54
	s_addc_u32 s56, s31, 0
	s_add_u32 s57, s55, 0x100
	s_addc_u32 s58, s56, 0
	s_and_b64 s[52:53], s[12:13], exec
	s_cselect_b32 s53, s58, s1
	s_cselect_b32 s52, s57, s2
	s_add_u32 s54, s34, s54
	s_addc_u32 s57, s35, 0
	s_add_u32 s54, s54, 0x100
	s_addc_u32 s57, s57, 0
	s_and_b64 s[12:13], s[12:13], exec
	s_cselect_b32 s13, s57, s3
	s_cselect_b32 s12, s54, s41
	s_add_i32 s57, 0, 0x10000
	v_add_u32_e32 v0, s57, v181
	s_add_i32 s58, 0, 0x14000
	ds_read_b128 v[132:135], v0
	ds_read_b128 v[136:139], v0 offset:1024
	ds_read_b128 v[140:143], v0 offset:2048
	ds_read_b128 v[144:147], v0 offset:3072
	v_add_u32_e32 v0, s58, v181
	ds_read_b128 v[148:151], v0
	ds_read_b128 v[152:155], v0 offset:1024
	ds_read_b128 v[168:171], v0 offset:2048
	ds_read_b128 v[172:175], v0 offset:3072
	s_add_u32 s54, s55, 0x80080
	s_addc_u32 s55, s56, 0
	v_lshl_add_u64 v[224:225], s[54:55], 0, v[156:157]
	s_add_i32 m0, s29, 0xc000
	ds_read_b128 v[176:179], v187
	ds_read_b128 v[188:191], v187 offset:1024
	ds_read_b128 v[192:195], v187 offset:2048
	ds_read_b128 v[196:199], v187 offset:3072
	ds_read_b128 v[200:203], v187 offset:4096
	ds_read_b128 v[204:207], v187 offset:5120
	ds_read_b128 v[208:211], v187 offset:6144
	ds_read_b128 v[220:223], v187 offset:7168
	global_load_lds_dwordx4 v[224:225], off
	v_lshl_add_u64 v[224:225], s[54:55], 0, v[160:161]
	s_add_i32 m0, s29, 0xe000
	s_nop 0
	global_load_lds_dwordx4 v[224:225], off
	s_waitcnt vmcnt(8)
	s_waitcnt lgkmcnt(0)
	s_barrier
	s_setprio 0
	s_waitcnt lgkmcnt(0)
	v_mfma_f32_16x16x32_bf16 v[128:131], v[132:135], v[176:179], v[128:131]
	v_mfma_f32_16x16x32_bf16 v[124:127], v[140:143], v[176:179], v[124:127]
	v_mfma_f32_16x16x32_bf16 v[120:123], v[132:135], v[192:195], v[120:123]
	v_mfma_f32_16x16x32_bf16 v[116:119], v[140:143], v[192:195], v[116:119]
	v_mfma_f32_16x16x32_bf16 v[112:115], v[132:135], v[200:203], v[112:115]
	v_mfma_f32_16x16x32_bf16 v[108:111], v[140:143], v[200:203], v[108:111]
	v_mfma_f32_16x16x32_bf16 v[104:107], v[132:135], v[208:211], v[104:107]
	v_mfma_f32_16x16x32_bf16 v[100:103], v[140:143], v[208:211], v[100:103]
	v_mfma_f32_16x16x32_bf16 v[128:131], v[136:139], v[188:191], v[128:131]
	v_mfma_f32_16x16x32_bf16 v[124:127], v[144:147], v[188:191], v[124:127]
	v_mfma_f32_16x16x32_bf16 v[120:123], v[136:139], v[196:199], v[120:123]
	v_mfma_f32_16x16x32_bf16 v[116:119], v[144:147], v[196:199], v[116:119]
	v_mfma_f32_16x16x32_bf16 v[112:115], v[136:139], v[204:207], v[112:115]
	v_mfma_f32_16x16x32_bf16 v[108:111], v[144:147], v[204:207], v[108:111]
	v_mfma_f32_16x16x32_bf16 v[104:107], v[136:139], v[220:223], v[104:107]
	v_mfma_f32_16x16x32_bf16 v[100:103], v[144:147], v[220:223], v[100:103]
	s_setprio 0
	s_setprio 0
	v_mfma_f32_16x16x32_bf16 v[96:99], v[148:151], v[176:179], v[96:99]
	v_mfma_f32_16x16x32_bf16 v[92:95], v[168:171], v[176:179], v[92:95]
	v_mfma_f32_16x16x32_bf16 v[88:91], v[148:151], v[192:195], v[88:91]
	v_mfma_f32_16x16x32_bf16 v[84:87], v[168:171], v[192:195], v[84:87]
	v_mfma_f32_16x16x32_bf16 v[80:83], v[148:151], v[200:203], v[80:83]
	v_mfma_f32_16x16x32_bf16 v[76:79], v[168:171], v[200:203], v[76:79]
	v_mfma_f32_16x16x32_bf16 v[72:75], v[148:151], v[208:211], v[72:75]
	v_mfma_f32_16x16x32_bf16 v[68:71], v[168:171], v[208:211], v[68:71]
	v_mfma_f32_16x16x32_bf16 v[96:99], v[152:155], v[188:191], v[96:99]
	v_mfma_f32_16x16x32_bf16 v[92:95], v[172:175], v[188:191], v[92:95]
	v_mfma_f32_16x16x32_bf16 v[88:91], v[152:155], v[196:199], v[88:91]
	v_mfma_f32_16x16x32_bf16 v[84:87], v[172:175], v[196:199], v[84:87]
	v_mfma_f32_16x16x32_bf16 v[80:83], v[152:155], v[204:207], v[80:83]
	v_mfma_f32_16x16x32_bf16 v[76:79], v[172:175], v[204:207], v[76:79]
	v_mfma_f32_16x16x32_bf16 v[72:75], v[152:155], v[220:223], v[72:75]
	v_mfma_f32_16x16x32_bf16 v[68:71], v[172:175], v[220:223], v[68:71]
	s_setprio 1
	s_barrier
	s_add_i32 s54, s57, s15
	v_lshl_add_u64 v[224:225], s[12:13], 0, v[158:159]
	s_mov_b32 m0, s54
	ds_read_b128 v[176:179], v187 offset:16384
	ds_read_b128 v[188:191], v187 offset:17408
	ds_read_b128 v[192:195], v187 offset:18432
	ds_read_b128 v[196:199], v187 offset:19456
	ds_read_b128 v[200:203], v187 offset:20480
	ds_read_b128 v[204:207], v187 offset:21504
	ds_read_b128 v[208:211], v187 offset:22528
	ds_read_b128 v[220:223], v187 offset:23552
	global_load_lds_dwordx4 v[224:225], off
	s_add_i32 m0, s54, 0x2000
	s_add_u32 s54, s12, 0x80000
	v_lshl_add_u64 v[226:227], s[12:13], 0, v[162:163]
	s_addc_u32 s55, s13, 0
	s_add_i32 s56, s58, s15
	global_load_lds_dwordx4 v[226:227], off
	v_lshl_add_u64 v[228:229], s[54:55], 0, v[158:159]
	s_mov_b32 m0, s56
	v_lshl_add_u64 v[230:231], s[52:53], 0, v[160:161]
	global_load_lds_dwordx4 v[228:229], off
	v_lshl_add_u64 v[228:229], s[54:55], 0, v[162:163]
	s_add_i32 m0, s56, 0x2000
	s_nop 0
	global_load_lds_dwordx4 v[228:229], off
	v_lshl_add_u64 v[228:229], s[52:53], 0, v[156:157]
	s_mov_b32 m0, s29
	s_nop 0
	global_load_lds_dwordx4 v[228:229], off
	s_mov_b32 m0, s65
	s_nop 0
	global_load_lds_dwordx4 v[230:231], off
	s_waitcnt vmcnt(8)
	s_waitcnt lgkmcnt(0)
	s_barrier
; #define PG8_STAGE(bufoff, gbase, voff) do { _Pragma("unroll") for (int _i = 0; _i < 2; ++_i) \
;         __builtin_amdgcn_global_load_lds((const unsigned*)((const char*)(gbase) + (voff)[_i]), (PG8_LAS unsigned*)(lds + (bufoff) + ldsw + _i * 8192), 16, 0, 0); } while (0)
; #define PG8_LDA(dst, b, h) do { _Pragma("unroll") for (int m = 0; m < 4; ++m) _Pragma("unroll") for (int k = 0; k < 2; ++k) dst[m][k] = *(const PG8_LAS bf16x8*)(lds + PG8_SA(b, h) + aoff + m * 2048 + k * 1024); } while (0)
; #define PG8_LDB(dst, b, h) do { _Pragma("unroll") for (int n = 0; n < 2; ++n) _Pragma("unroll") for (int k = 0; k < 2; ++k) dst[n][k] = *(const PG8_LAS bf16x8*)(lds + PG8_SB(b, h) + boff + n * 2048 + k * 1024); } while (0)
; #define PG8_MMA(ai, bj, At, Bt) do { __builtin_amdgcn_s_setprio(1); _Pragma("unroll") for (int m = 0; m < 4; ++m) _Pragma("unroll") for (int n = 0; n < 2; ++n) _Pragma("unroll") for (int k = 0; k < 2; ++k) \
;         acc[ai][bj][m][n] = __builtin_amdgcn_mfma_f32_16x16x32_bf16(Bt[n][k], At[m][k], acc[ai][bj][m][n], 0, 0, 0); __builtin_amdgcn_s_setprio(0); } while (0)
; #define PG8_WAIT_V(n) asm volatile("s_waitcnt vmcnt(" #n ")" ::: "memory")
; #define PG8_WAIT_L(n) asm volatile("s_waitcnt lgkmcnt(" #n ")" ::: "memory")
; #define PG8_BAR __builtin_amdgcn_s_barrier()
; #define PG8_SCHED __builtin_amdgcn_sched_barrier(0)
; template <class Epi, class Sched, bool ALIGN_EPI = false, bool SP2 = false>
; __device__ __forceinline__ void gemm_phase(PG8_LAS unsigned char* lds, const Gemm g, const Sched& S, const Epi& E) {
;     ...
;             PG8_WAIT_V(8); PG8_WAIT_L(0); PG8_BAR; PG8_MMA(1, 0, At, B0); PG8_MMA(1, 1, At, B1); PG8_BAR; PG8_SCHED;
;             PG8_LDB(B0, 1, 0); PG8_LDB(B1, 1, 1); PG8_SCHED; PG8_LDA(At, 1, 0); PG8_STAGE(PG8_SA(0, 1), a2 + hstep, voffA);
;             PG8_WAIT_V(8); PG8_WAIT_L(0); PG8_BAR; PG8_MMA(0, 0, At, B0); PG8_MMA(0, 1, At, B1); PG8_BAR; PG8_SCHED;
	s_setprio 0
	s_waitcnt lgkmcnt(0)
	v_mfma_f32_16x16x32_bf16 v[62:65], v[132:135], v[176:179], v[62:65]
	v_mfma_f32_16x16x32_bf16 v[58:61], v[140:143], v[176:179], v[58:61]
	v_mfma_f32_16x16x32_bf16 v[54:57], v[132:135], v[192:195], v[54:57]
	v_mfma_f32_16x16x32_bf16 v[50:53], v[140:143], v[192:195], v[50:53]
	v_mfma_f32_16x16x32_bf16 v[46:49], v[132:135], v[200:203], v[46:49]
	v_mfma_f32_16x16x32_bf16 v[42:45], v[140:143], v[200:203], v[42:45]
	v_mfma_f32_16x16x32_bf16 v[38:41], v[132:135], v[208:211], v[38:41]
	v_mfma_f32_16x16x32_bf16 v[34:37], v[140:143], v[208:211], v[34:37]
	v_mfma_f32_16x16x32_bf16 v[62:65], v[136:139], v[188:191], v[62:65]
	v_mfma_f32_16x16x32_bf16 v[58:61], v[144:147], v[188:191], v[58:61]
	v_mfma_f32_16x16x32_bf16 v[54:57], v[136:139], v[196:199], v[54:57]
	v_mfma_f32_16x16x32_bf16 v[50:53], v[144:147], v[196:199], v[50:53]
	v_mfma_f32_16x16x32_bf16 v[46:49], v[136:139], v[204:207], v[46:49]
	v_mfma_f32_16x16x32_bf16 v[42:45], v[144:147], v[204:207], v[42:45]
	v_mfma_f32_16x16x32_bf16 v[38:41], v[136:139], v[220:223], v[38:41]
	v_mfma_f32_16x16x32_bf16 v[34:37], v[144:147], v[220:223], v[34:37]
	s_setprio 0
	s_setprio 0
	v_mfma_f32_16x16x32_bf16 v[30:33], v[148:151], v[176:179], v[30:33]
	v_mfma_f32_16x16x32_bf16 v[26:29], v[168:171], v[176:179], v[26:29]
	v_mfma_f32_16x16x32_bf16 v[22:25], v[148:151], v[192:195], v[22:25]
	v_mfma_f32_16x16x32_bf16 v[18:21], v[168:171], v[192:195], v[18:21]
	v_mfma_f32_16x16x32_bf16 v[14:17], v[148:151], v[200:203], v[14:17]
	v_mfma_f32_16x16x32_bf16 v[10:13], v[168:171], v[200:203], v[10:13]
	v_mfma_f32_16x16x32_bf16 v[6:9], v[148:151], v[208:211], v[6:9]
	v_mfma_f32_16x16x32_bf16 v[2:5], v[168:171], v[208:211], v[2:5]
	v_mfma_f32_16x16x32_bf16 v[30:33], v[152:155], v[188:191], v[30:33]
	v_mfma_f32_16x16x32_bf16 v[26:29], v[172:175], v[188:191], v[26:29]
	v_mfma_f32_16x16x32_bf16 v[22:25], v[152:155], v[196:199], v[22:25]
	v_mfma_f32_16x16x32_bf16 v[18:21], v[172:175], v[196:199], v[18:21]
	v_mfma_f32_16x16x32_bf16 v[14:17], v[152:155], v[204:207], v[14:17]
	v_mfma_f32_16x16x32_bf16 v[10:13], v[172:175], v[204:207], v[10:13]
	v_mfma_f32_16x16x32_bf16 v[6:9], v[152:155], v[220:223], v[6:9]
	v_mfma_f32_16x16x32_bf16 v[2:5], v[172:175], v[220:223], v[2:5]
	s_setprio 1
	s_barrier
	s_add_i32 s54, 0, 0x18000
	v_add_u32_e32 v0, s54, v181
	s_add_i32 s55, 0, 0x1c000
	ds_read_b128 v[132:135], v0
	ds_read_b128 v[136:139], v0 offset:1024
	ds_read_b128 v[140:143], v0 offset:2048
	ds_read_b128 v[144:147], v0 offset:3072
	v_add_u32_e32 v0, s55, v181
	ds_read_b128 v[148:151], v0
	ds_read_b128 v[152:155], v0 offset:1024
	ds_read_b128 v[168:171], v0 offset:2048
	ds_read_b128 v[172:175], v0 offset:3072
	s_add_u32 s52, s52, 0x80000
	s_addc_u32 s53, s53, 0
	s_mov_b32 m0, s66
	v_lshl_add_u64 v[232:233], s[52:53], 0, v[156:157]
	ds_read_b128 v[176:179], v187 offset:32768
	ds_read_b128 v[188:191], v187 offset:33792
	ds_read_b128 v[192:195], v187 offset:34816
	ds_read_b128 v[196:199], v187 offset:35840
	ds_read_b128 v[200:203], v187 offset:36864
	ds_read_b128 v[204:207], v187 offset:37888
	ds_read_b128 v[208:211], v187 offset:38912
	ds_read_b128 v[220:223], v187 offset:39936
	global_load_lds_dwordx4 v[232:233], off
	v_lshl_add_u64 v[232:233], s[52:53], 0, v[160:161]
	s_mov_b32 m0, s67
	s_nop 0
	global_load_lds_dwordx4 v[232:233], off
	s_waitcnt vmcnt(8)
	s_waitcnt lgkmcnt(0)
	s_barrier
	s_setprio 0
	s_waitcnt lgkmcnt(0)
	v_mfma_f32_16x16x32_bf16 v[128:131], v[132:135], v[176:179], v[128:131]
	v_mfma_f32_16x16x32_bf16 v[124:127], v[140:143], v[176:179], v[124:127]
	v_mfma_f32_16x16x32_bf16 v[120:123], v[132:135], v[192:195], v[120:123]
	v_mfma_f32_16x16x32_bf16 v[116:119], v[140:143], v[192:195], v[116:119]
	v_mfma_f32_16x16x32_bf16 v[112:115], v[132:135], v[200:203], v[112:115]
	v_mfma_f32_16x16x32_bf16 v[108:111], v[140:143], v[200:203], v[108:111]
	v_mfma_f32_16x16x32_bf16 v[104:107], v[132:135], v[208:211], v[104:107]
	v_mfma_f32_16x16x32_bf16 v[100:103], v[140:143], v[208:211], v[100:103]
	v_mfma_f32_16x16x32_bf16 v[128:131], v[136:139], v[188:191], v[128:131]
	v_mfma_f32_16x16x32_bf16 v[124:127], v[144:147], v[188:191], v[124:127]
	v_mfma_f32_16x16x32_bf16 v[120:123], v[136:139], v[196:199], v[120:123]
	v_mfma_f32_16x16x32_bf16 v[116:119], v[144:147], v[196:199], v[116:119]
	v_mfma_f32_16x16x32_bf16 v[112:115], v[136:139], v[204:207], v[112:115]
	v_mfma_f32_16x16x32_bf16 v[108:111], v[144:147], v[204:207], v[108:111]
	v_mfma_f32_16x16x32_bf16 v[104:107], v[136:139], v[220:223], v[104:107]
	v_mfma_f32_16x16x32_bf16 v[100:103], v[144:147], v[220:223], v[100:103]
	s_setprio 0
	s_setprio 0
	v_mfma_f32_16x16x32_bf16 v[96:99], v[148:151], v[176:179], v[96:99]
	v_mfma_f32_16x16x32_bf16 v[92:95], v[168:171], v[176:179], v[92:95]
	v_mfma_f32_16x16x32_bf16 v[88:91], v[148:151], v[192:195], v[88:91]
	v_mfma_f32_16x16x32_bf16 v[84:87], v[168:171], v[192:195], v[84:87]
	v_mfma_f32_16x16x32_bf16 v[80:83], v[148:151], v[200:203], v[80:83]
	v_mfma_f32_16x16x32_bf16 v[76:79], v[168:171], v[200:203], v[76:79]
	v_mfma_f32_16x16x32_bf16 v[72:75], v[148:151], v[208:211], v[72:75]
	v_mfma_f32_16x16x32_bf16 v[68:71], v[168:171], v[208:211], v[68:71]
	v_mfma_f32_16x16x32_bf16 v[96:99], v[152:155], v[188:191], v[96:99]
	v_mfma_f32_16x16x32_bf16 v[92:95], v[172:175], v[188:191], v[92:95]
	v_mfma_f32_16x16x32_bf16 v[88:91], v[152:155], v[196:199], v[88:91]
	v_mfma_f32_16x16x32_bf16 v[84:87], v[172:175], v[196:199], v[84:87]
	v_mfma_f32_16x16x32_bf16 v[80:83], v[152:155], v[204:207], v[80:83]
	v_mfma_f32_16x16x32_bf16 v[76:79], v[172:175], v[204:207], v[76:79]
	v_mfma_f32_16x16x32_bf16 v[72:75], v[152:155], v[220:223], v[72:75]
	v_mfma_f32_16x16x32_bf16 v[68:71], v[172:175], v[220:223], v[68:71]
	s_setprio 1
	s_barrier
; #define PG8_STAGE(bufoff, gbase, voff) do { _Pragma("unroll") for (int _i = 0; _i < 2; ++_i) \
;         __builtin_amdgcn_global_load_lds((const unsigned*)((const char*)(gbase) + (voff)[_i]), (PG8_LAS unsigned*)(lds + (bufoff) + ldsw + _i * 8192), 16, 0, 0); } while (0)
; #define PG8_LDA(dst, b, h) do { _Pragma("unroll") for (int m = 0; m < 4; ++m) _Pragma("unroll") for (int k = 0; k < 2; ++k) dst[m][k] = *(const PG8_LAS bf16x8*)(lds + PG8_SA(b, h) + aoff + m * 2048 + k * 1024); } while (0)
; #define PG8_MMA(ai, bj, At, Bt) do { __builtin_amdgcn_s_setprio(1); _Pragma("unroll") for (int m = 0; m < 4; ++m) _Pragma("unroll") for (int n = 0; n < 2; ++n) _Pragma("unroll") for (int k = 0; k < 2; ++k) \
;         acc[ai][bj][m][n] = __builtin_amdgcn_mfma_f32_16x16x32_bf16(Bt[n][k], At[m][k], acc[ai][bj][m][n], 0, 0, 0); __builtin_amdgcn_s_setprio(0); } while (0)
; #define PG8_WAIT_V(n) asm volatile("s_waitcnt vmcnt(" #n ")" ::: "memory")
; #define PG8_WAIT_L(n) asm volatile("s_waitcnt lgkmcnt(" #n ")" ::: "memory")
; #define PG8_BAR __builtin_amdgcn_s_barrier()
; #define PG8_SCHED __builtin_amdgcn_sched_barrier(0)
; template <class Epi, class Sched, bool ALIGN_EPI = false, bool SP2 = false>
; __device__ __forceinline__ void gemm_phase(PG8_LAS unsigned char* lds, const Gemm g, const Sched& S, const Epi& E) {
;     ...
;             PG8_LDA(At, 1, 1); PG8_STAGE(PG8_SB(1, 0), b3, voffB); PG8_STAGE(PG8_SB(1, 1), b3 + hstep, voffB); PG8_STAGE(PG8_SA(1, 0), a3, voffA);
;             PG8_WAIT_V(8); PG8_WAIT_L(0); PG8_BAR; PG8_MMA(1, 0, At, B0); PG8_MMA(1, 1, At, B1); PG8_BAR; PG8_SCHED;
	s_add_i32 s52, s54, s15
	v_lshl_add_u64 v[224:225], v[224:225], 0, s[88:89]
	s_mov_b32 m0, s52
	ds_read_b128 v[176:179], v187 offset:49152
	ds_read_b128 v[188:191], v187 offset:50176
	ds_read_b128 v[192:195], v187 offset:51200
	ds_read_b128 v[196:199], v187 offset:52224
	ds_read_b128 v[200:203], v187 offset:53248
	ds_read_b128 v[204:207], v187 offset:54272
	ds_read_b128 v[208:211], v187 offset:55296
	ds_read_b128 v[220:223], v187 offset:56320
	global_load_lds_dwordx4 v[224:225], off
	s_add_i32 m0, s52, 0x2000
	s_add_u32 s12, s12, 0x80080
	v_lshl_add_u64 v[224:225], v[226:227], 0, s[88:89]
	s_addc_u32 s13, s13, 0
	s_add_i32 s52, s55, s15
	global_load_lds_dwordx4 v[224:225], off
	v_lshl_add_u64 v[224:225], s[12:13], 0, v[158:159]
	s_mov_b32 m0, s52
	s_nop 0
	global_load_lds_dwordx4 v[224:225], off
	v_lshl_add_u64 v[224:225], s[12:13], 0, v[162:163]
	s_add_i32 m0, s52, 0x2000
	s_nop 0
	global_load_lds_dwordx4 v[224:225], off
	v_lshl_add_u64 v[224:225], v[228:229], 0, s[88:89]
	s_mov_b32 m0, s69
	s_nop 0
	global_load_lds_dwordx4 v[224:225], off
	v_lshl_add_u64 v[224:225], v[230:231], 0, s[88:89]
	s_mov_b32 m0, s70
	s_nop 0
	global_load_lds_dwordx4 v[224:225], off
	s_waitcnt vmcnt(8)
	s_waitcnt lgkmcnt(0)
	s_barrier
	s_setprio 0
	s_waitcnt lgkmcnt(0)
	v_mfma_f32_16x16x32_bf16 v[62:65], v[132:135], v[176:179], v[62:65]
	v_mfma_f32_16x16x32_bf16 v[58:61], v[140:143], v[176:179], v[58:61]
	v_mfma_f32_16x16x32_bf16 v[54:57], v[132:135], v[192:195], v[54:57]
	v_mfma_f32_16x16x32_bf16 v[50:53], v[140:143], v[192:195], v[50:53]
	v_mfma_f32_16x16x32_bf16 v[46:49], v[132:135], v[200:203], v[46:49]
	v_mfma_f32_16x16x32_bf16 v[42:45], v[140:143], v[200:203], v[42:45]
	v_mfma_f32_16x16x32_bf16 v[38:41], v[132:135], v[208:211], v[38:41]
	v_mfma_f32_16x16x32_bf16 v[34:37], v[140:143], v[208:211], v[34:37]
	v_mfma_f32_16x16x32_bf16 v[62:65], v[136:139], v[188:191], v[62:65]
	v_mfma_f32_16x16x32_bf16 v[58:61], v[144:147], v[188:191], v[58:61]
	v_mfma_f32_16x16x32_bf16 v[54:57], v[136:139], v[196:199], v[54:57]
	v_mfma_f32_16x16x32_bf16 v[50:53], v[144:147], v[196:199], v[50:53]
	v_mfma_f32_16x16x32_bf16 v[46:49], v[136:139], v[204:207], v[46:49]
	v_mfma_f32_16x16x32_bf16 v[42:45], v[144:147], v[204:207], v[42:45]
	v_mfma_f32_16x16x32_bf16 v[38:41], v[136:139], v[220:223], v[38:41]
	v_mfma_f32_16x16x32_bf16 v[34:37], v[144:147], v[220:223], v[34:37]
	s_setprio 0
	s_setprio 0
	v_mfma_f32_16x16x32_bf16 v[30:33], v[148:151], v[176:179], v[30:33]
	v_mfma_f32_16x16x32_bf16 v[26:29], v[168:171], v[176:179], v[26:29]
	v_mfma_f32_16x16x32_bf16 v[22:25], v[148:151], v[192:195], v[22:25]
	v_mfma_f32_16x16x32_bf16 v[18:21], v[168:171], v[192:195], v[18:21]
	v_mfma_f32_16x16x32_bf16 v[14:17], v[148:151], v[200:203], v[14:17]
	v_mfma_f32_16x16x32_bf16 v[10:13], v[168:171], v[200:203], v[10:13]
	v_mfma_f32_16x16x32_bf16 v[6:9], v[148:151], v[208:211], v[6:9]
	v_mfma_f32_16x16x32_bf16 v[2:5], v[168:171], v[208:211], v[2:5]
	v_mfma_f32_16x16x32_bf16 v[30:33], v[152:155], v[188:191], v[30:33]
	v_mfma_f32_16x16x32_bf16 v[26:29], v[172:175], v[188:191], v[26:29]
	v_mfma_f32_16x16x32_bf16 v[22:25], v[152:155], v[196:199], v[22:25]
	v_mfma_f32_16x16x32_bf16 v[18:21], v[172:175], v[196:199], v[18:21]
	v_mfma_f32_16x16x32_bf16 v[14:17], v[152:155], v[204:207], v[14:17]
	v_mfma_f32_16x16x32_bf16 v[10:13], v[172:175], v[204:207], v[10:13]
	v_mfma_f32_16x16x32_bf16 v[6:9], v[152:155], v[220:223], v[6:9]
	v_mfma_f32_16x16x32_bf16 v[2:5], v[172:175], v[220:223], v[2:5]
	s_setprio 1
	s_barrier
	s_add_i32 s12, s43, 2
	s_cmp_gt_u32 s43, 29
	s_cbranch_scc1 .LBB0_400
	s_mov_b32 s43, s12
	s_branch .LBB0_384

;     __host__ __device__ bool next(int i, Unit& u) const { if (i != 0 || r < 0 || r >= 148) return false; if (r < 116) { u.pm = r % 29; u.pn = 47 + r / 29; } else { u.pm = 32; u.pn = 19 + (r - 116); } u.ko = 0; return true; }
;     __host__ __device__ bool next(int i, Unit& u) const { const int L = i * G + (G - 1 - c); if (L >= nN * S) return false; u.pm = pm; u.pn = L % nN; u.ko = (L / nN) * ksub; return true; }
; #define PG8_STAGE(bufoff, gbase, voff) do { _Pragma("unroll") for (int _i = 0; _i < 2; ++_i) \
;         __builtin_amdgcn_global_load_lds((const unsigned*)((const char*)(gbase) + (voff)[_i]), (PG8_LAS unsigned*)(lds + (bufoff) + ldsw + _i * 8192), 16, 0, 0); } while (0)
; #define PG8_LDA(dst, b, h) do { _Pragma("unroll") for (int m = 0; m < 4; ++m) _Pragma("unroll") for (int k = 0; k < 2; ++k) dst[m][k] = *(const PG8_LAS bf16x8*)(lds + PG8_SA(b, h) + aoff + m * 2048 + k * 1024); } while (0)
; #define PG8_WAIT_V(n) asm volatile("s_waitcnt vmcnt(" #n ")" ::: "memory")
; #define PG8_WAIT_L(n) asm volatile("s_waitcnt lgkmcnt(" #n ")" ::: "memory")
; template <class Epi, class Sched, bool ALIGN_EPI = false, bool SP2 = false>
; __device__ __forceinline__ void gemm_phase(PG8_LAS unsigned char* lds, const Gemm g, const Sched& S, const Epi& E) {
;     ...
;     for (;;) {
;         const bool has_next = S.next(ui + 1, nxt);
;         const char* nA = has_next ? (const char*)g.A + (size_t)nxt.pm * tstep + (size_t)nxt.ko * 2 : cA; const char* nB = has_next ? (const char*)g.Bt + (size_t)nxt.pn * tstep + (size_t)nxt.ko * 2 : cB;
;         for (int t = 0; t < nt; t += 2) {
;             const bool last = (t == nt - 2);
;             const char* a1 = cA + (size_t)(t + 1) * kstep;
;             const char* a2 = last ? nA : cA + (size_t)(t + 2) * kstep; const char* b2 = last ? nB : cB + (size_t)(t + 2) * kstep;
;             const char* a3 = a2 + kstep; const char* b3 = b2 + kstep;
;             if (last && has_next) S.a_ready(nxt);
;             if constexpr (SP2) {
;             PG8_LDB(B0, 0, 0); PG8_LDB(B1, 0, 1); PG8_SCHED; PG8_LDA(At, 0, 0); PG8_STAGE(PG8_SA(1, 1), a1 + hstep, voffA);
;             PG8_WAIT_V(8); PG8_WAIT_L(0); PG8_BAR; PG8_MMA(0, 0, At, B0); PG8_MMA(0, 1, At, B1); PG8_BAR; PG8_SCHED;
;             PG8_LDA(At, 0, 1); PG8_STAGE(PG8_SB(0, 0), b2, voffB); PG8_STAGE(PG8_SB(0, 1), b2 + hstep, voffB); PG8_STAGE(PG8_SA(0, 0), a2, voffA);
.LBB0_702:
	s_add_u32 s14, s26, s12
	s_addc_u32 s15, s27, s13
	s_add_u32 s14, s14, 0x5800100
	s_addc_u32 s15, s15, 0
	s_add_u32 s31, s28, s12
	s_addc_u32 s34, s29, s13
	s_add_i32 s35, 0, 0x10000
	s_cmpk_eq_i32 s12, 0xf00
	s_cselect_b32 s17, s9, s15
	s_cselect_b32 s16, s8, s14
	v_add_u32_e32 v89, s35, v87
	s_cselect_b32 s15, s7, s34
	s_cselect_b32 s14, s6, s31
	s_add_i32 s31, 0, 0x14000
	ds_read_b128 v[148:151], v89
	ds_read_b128 v[152:155], v89 offset:1024
	ds_read_b128 v[156:159], v89 offset:2048
	ds_read_b128 v[160:163], v89 offset:3072
	v_add_u32_e32 v89, s31, v87
	ds_read_b128 v[166:169], v89
	ds_read_b128 v[170:173], v89 offset:1024
	ds_read_b128 v[174:177], v89 offset:2048
	ds_read_b128 v[178:181], v89 offset:3072
	v_lshl_add_u64 v[90:91], v[74:75], 0, s[12:13]
	s_add_i32 m0, s20, 0xc000
	ds_read_b128 v[182:185], v88
	ds_read_b128 v[186:189], v88 offset:1024
	ds_read_b128 v[190:193], v88 offset:2048
	ds_read_b128 v[194:197], v88 offset:3072
	ds_read_b128 v[200:203], v88 offset:4096
	ds_read_b128 v[204:207], v88 offset:5120
	ds_read_b128 v[208:211], v88 offset:6144
	ds_read_b128 v[220:223], v88 offset:7168
	global_load_lds_dwordx4 v[90:91], off
	v_lshl_add_u64 v[90:91], v[84:85], 0, s[12:13]
	s_add_i32 m0, s20, 0xe000
	s_nop 0
	global_load_lds_dwordx4 v[90:91], off
	s_waitcnt vmcnt(8)
	s_waitcnt lgkmcnt(0)
	s_barrier
	s_setprio 0
	s_waitcnt lgkmcnt(0)
	v_mfma_f32_16x16x32_bf16 v[144:147], v[148:151], v[182:185], v[144:147]
	v_mfma_f32_16x16x32_bf16 v[140:143], v[156:159], v[182:185], v[140:143]
	v_mfma_f32_16x16x32_bf16 v[128:131], v[148:151], v[190:193], v[128:131]
	v_mfma_f32_16x16x32_bf16 v[124:127], v[156:159], v[190:193], v[124:127]
	v_mfma_f32_16x16x32_bf16 v[112:115], v[148:151], v[200:203], v[112:115]
	v_mfma_f32_16x16x32_bf16 v[108:111], v[156:159], v[200:203], v[108:111]
	v_mfma_f32_16x16x32_bf16 v[96:99], v[148:151], v[208:211], v[96:99]
	v_mfma_f32_16x16x32_bf16 v[90:93], v[156:159], v[208:211], v[92:95]
	v_mfma_f32_16x16x32_bf16 v[144:147], v[152:155], v[186:189], v[144:147]
	v_mfma_f32_16x16x32_bf16 v[140:143], v[160:163], v[186:189], v[140:143]
	v_mfma_f32_16x16x32_bf16 v[128:131], v[152:155], v[194:197], v[128:131]
	v_mfma_f32_16x16x32_bf16 v[124:127], v[160:163], v[194:197], v[124:127]
	v_mfma_f32_16x16x32_bf16 v[112:115], v[152:155], v[204:207], v[112:115]
	v_mfma_f32_16x16x32_bf16 v[108:111], v[160:163], v[204:207], v[108:111]
	v_mfma_f32_16x16x32_bf16 v[96:99], v[152:155], v[220:223], v[96:99]
	v_mfma_f32_16x16x32_bf16 v[90:93], v[160:163], v[220:223], v[90:93]
	s_setprio 0
	s_setprio 0
	v_mfma_f32_16x16x32_bf16 v[136:139], v[166:169], v[182:185], v[136:139]
	v_mfma_f32_16x16x32_bf16 v[132:135], v[174:177], v[182:185], v[132:135]
	v_mfma_f32_16x16x32_bf16 v[120:123], v[166:169], v[190:193], v[120:123]
	v_mfma_f32_16x16x32_bf16 v[116:119], v[174:177], v[190:193], v[116:119]
	v_mfma_f32_16x16x32_bf16 v[104:107], v[166:169], v[200:203], v[104:107]
	v_mfma_f32_16x16x32_bf16 v[100:103], v[174:177], v[200:203], v[100:103]
	v_mfma_f32_16x16x32_bf16 v[80:83], v[166:169], v[208:211], v[80:83]
	v_mfma_f32_16x16x32_bf16 v[76:79], v[174:177], v[208:211], v[76:79]
	v_mfma_f32_16x16x32_bf16 v[136:139], v[170:173], v[186:189], v[136:139]
	v_mfma_f32_16x16x32_bf16 v[132:135], v[178:181], v[186:189], v[132:135]
	v_mfma_f32_16x16x32_bf16 v[120:123], v[170:173], v[194:197], v[120:123]
	v_mfma_f32_16x16x32_bf16 v[116:119], v[178:181], v[194:197], v[116:119]
	v_mfma_f32_16x16x32_bf16 v[104:107], v[170:173], v[204:207], v[104:107]
	v_mfma_f32_16x16x32_bf16 v[100:103], v[178:181], v[204:207], v[100:103]
	v_mfma_f32_16x16x32_bf16 v[80:83], v[170:173], v[220:223], v[80:83]
	v_mfma_f32_16x16x32_bf16 v[76:79], v[178:181], v[220:223], v[76:79]
	s_setprio 1
	s_barrier
	s_add_i32 s34, s35, s18
	v_lshl_add_u64 v[224:225], s[14:15], 0, v[66:67]
	s_mov_b32 m0, s34
	ds_read_b128 v[182:185], v88 offset:16384
	ds_read_b128 v[186:189], v88 offset:17408
	ds_read_b128 v[190:193], v88 offset:18432
	ds_read_b128 v[194:197], v88 offset:19456
	ds_read_b128 v[200:203], v88 offset:20480
	ds_read_b128 v[204:207], v88 offset:21504
	ds_read_b128 v[208:211], v88 offset:22528
	ds_read_b128 v[220:223], v88 offset:23552
	global_load_lds_dwordx4 v[224:225], off
	s_add_i32 m0, s34, 0x2000
	s_add_u32 s34, s14, 0x80000
	v_lshl_add_u64 v[226:227], s[14:15], 0, v[72:73]
	s_addc_u32 s35, s15, 0
	s_add_i32 s31, s31, s18
	global_load_lds_dwordx4 v[226:227], off
	v_lshl_add_u64 v[94:95], s[34:35], 0, v[66:67]
	s_mov_b32 m0, s31
	v_lshl_add_u64 v[228:229], s[16:17], 0, v[68:69]
	global_load_lds_dwordx4 v[94:95], off
	v_lshl_add_u64 v[94:95], s[34:35], 0, v[72:73]
	s_add_i32 m0, s31, 0x2000
	v_lshl_add_u64 v[230:231], s[16:17], 0, v[70:71]
	global_load_lds_dwordx4 v[94:95], off
	s_mov_b32 m0, s20
	s_nop 0
	global_load_lds_dwordx4 v[228:229], off
	s_mov_b32 m0, s3
	s_nop 0
	global_load_lds_dwordx4 v[230:231], off
	s_waitcnt vmcnt(8)
	s_waitcnt lgkmcnt(0)
	s_barrier
; #define PG8_STAGE(bufoff, gbase, voff) do { _Pragma("unroll") for (int _i = 0; _i < 2; ++_i) \
;         __builtin_amdgcn_global_load_lds((const unsigned*)((const char*)(gbase) + (voff)[_i]), (PG8_LAS unsigned*)(lds + (bufoff) + ldsw + _i * 8192), 16, 0, 0); } while (0)
; #define PG8_LDA(dst, b, h) do { _Pragma("unroll") for (int m = 0; m < 4; ++m) _Pragma("unroll") for (int k = 0; k < 2; ++k) dst[m][k] = *(const PG8_LAS bf16x8*)(lds + PG8_SA(b, h) + aoff + m * 2048 + k * 1024); } while (0)
; #define PG8_LDB(dst, b, h) do { _Pragma("unroll") for (int n = 0; n < 2; ++n) _Pragma("unroll") for (int k = 0; k < 2; ++k) dst[n][k] = *(const PG8_LAS bf16x8*)(lds + PG8_SB(b, h) + boff + n * 2048 + k * 1024); } while (0)
; #define PG8_MMA(ai, bj, At, Bt) do { __builtin_amdgcn_s_setprio(1); _Pragma("unroll") for (int m = 0; m < 4; ++m) _Pragma("unroll") for (int n = 0; n < 2; ++n) _Pragma("unroll") for (int k = 0; k < 2; ++k) \
;         acc[ai][bj][m][n] = __builtin_amdgcn_mfma_f32_16x16x32_bf16(Bt[n][k], At[m][k], acc[ai][bj][m][n], 0, 0, 0); __builtin_amdgcn_s_setprio(0); } while (0)
; #define PG8_WAIT_V(n) asm volatile("s_waitcnt vmcnt(" #n ")" ::: "memory")
; #define PG8_WAIT_L(n) asm volatile("s_waitcnt lgkmcnt(" #n ")" ::: "memory")
; #define PG8_BAR __builtin_amdgcn_s_barrier()
; #define PG8_SCHED __builtin_amdgcn_sched_barrier(0)
; template <class Epi, class Sched, bool ALIGN_EPI = false, bool SP2 = false>
; __device__ __forceinline__ void gemm_phase(PG8_LAS unsigned char* lds, const Gemm g, const Sched& S, const Epi& E) {
;     ...
;             PG8_WAIT_V(8); PG8_WAIT_L(0); PG8_BAR; PG8_MMA(1, 0, At, B0); PG8_MMA(1, 1, At, B1); PG8_BAR; PG8_SCHED;
;             PG8_LDB(B0, 1, 0); PG8_LDB(B1, 1, 1); PG8_SCHED; PG8_LDA(At, 1, 0); PG8_STAGE(PG8_SA(0, 1), a2 + hstep, voffA);
;             PG8_WAIT_V(8); PG8_WAIT_L(0); PG8_BAR; PG8_MMA(0, 0, At, B0); PG8_MMA(0, 1, At, B1); PG8_BAR; PG8_SCHED;
	s_setprio 0
	s_waitcnt lgkmcnt(0)
	v_mfma_f32_16x16x32_bf16 v[62:65], v[148:151], v[182:185], v[62:65]
	v_mfma_f32_16x16x32_bf16 v[58:61], v[156:159], v[182:185], v[58:61]
	v_mfma_f32_16x16x32_bf16 v[46:49], v[148:151], v[190:193], v[46:49]
	v_mfma_f32_16x16x32_bf16 v[42:45], v[156:159], v[190:193], v[42:45]
	v_mfma_f32_16x16x32_bf16 v[30:33], v[148:151], v[200:203], v[30:33]
	v_mfma_f32_16x16x32_bf16 v[26:29], v[156:159], v[200:203], v[26:29]
	v_mfma_f32_16x16x32_bf16 v[14:17], v[148:151], v[208:211], v[14:17]
	v_mfma_f32_16x16x32_bf16 v[10:13], v[156:159], v[208:211], v[10:13]
	v_mfma_f32_16x16x32_bf16 v[62:65], v[152:155], v[186:189], v[62:65]
	v_mfma_f32_16x16x32_bf16 v[58:61], v[160:163], v[186:189], v[58:61]
	v_mfma_f32_16x16x32_bf16 v[46:49], v[152:155], v[194:197], v[46:49]
	v_mfma_f32_16x16x32_bf16 v[42:45], v[160:163], v[194:197], v[42:45]
	v_mfma_f32_16x16x32_bf16 v[30:33], v[152:155], v[204:207], v[30:33]
	v_mfma_f32_16x16x32_bf16 v[26:29], v[160:163], v[204:207], v[26:29]
	v_mfma_f32_16x16x32_bf16 v[14:17], v[152:155], v[220:223], v[14:17]
	v_mfma_f32_16x16x32_bf16 v[10:13], v[160:163], v[220:223], v[10:13]
	s_setprio 0
	s_setprio 0
	v_mfma_f32_16x16x32_bf16 v[54:57], v[166:169], v[182:185], v[54:57]
	v_mfma_f32_16x16x32_bf16 v[50:53], v[174:177], v[182:185], v[50:53]
	v_mfma_f32_16x16x32_bf16 v[38:41], v[166:169], v[190:193], v[38:41]
	v_mfma_f32_16x16x32_bf16 v[34:37], v[174:177], v[190:193], v[34:37]
	v_mfma_f32_16x16x32_bf16 v[22:25], v[166:169], v[200:203], v[22:25]
	v_mfma_f32_16x16x32_bf16 v[18:21], v[174:177], v[200:203], v[18:21]
	v_mfma_f32_16x16x32_bf16 v[6:9], v[166:169], v[208:211], v[6:9]
	v_mfma_f32_16x16x32_bf16 v[2:5], v[174:177], v[208:211], v[2:5]
	v_mfma_f32_16x16x32_bf16 v[54:57], v[170:173], v[186:189], v[54:57]
	v_mfma_f32_16x16x32_bf16 v[50:53], v[178:181], v[186:189], v[50:53]
	v_mfma_f32_16x16x32_bf16 v[38:41], v[170:173], v[194:197], v[38:41]
	v_mfma_f32_16x16x32_bf16 v[34:37], v[178:181], v[194:197], v[34:37]
	v_mfma_f32_16x16x32_bf16 v[22:25], v[170:173], v[204:207], v[22:25]
	v_mfma_f32_16x16x32_bf16 v[18:21], v[178:181], v[204:207], v[18:21]
	v_mfma_f32_16x16x32_bf16 v[6:9], v[170:173], v[220:223], v[6:9]
	v_mfma_f32_16x16x32_bf16 v[2:5], v[178:181], v[220:223], v[2:5]
	s_setprio 1
	s_barrier
	s_add_i32 s31, 0, 0x18000
	v_add_u32_e32 v89, s31, v87
	s_add_i32 s34, 0, 0x1c000
	ds_read_b128 v[148:151], v89
	ds_read_b128 v[152:155], v89 offset:1024
	ds_read_b128 v[156:159], v89 offset:2048
	ds_read_b128 v[160:163], v89 offset:3072
	v_add_u32_e32 v89, s34, v87
	ds_read_b128 v[166:169], v89
	ds_read_b128 v[170:173], v89 offset:1024
	ds_read_b128 v[174:177], v89 offset:2048
	ds_read_b128 v[178:181], v89 offset:3072
	s_add_u32 s16, s16, 0x80000
	s_addc_u32 s17, s17, 0
	s_mov_b32 m0, s21
	v_lshl_add_u64 v[94:95], s[16:17], 0, v[68:69]
	ds_read_b128 v[182:185], v88 offset:32768
	ds_read_b128 v[186:189], v88 offset:33792
	ds_read_b128 v[190:193], v88 offset:34816
	ds_read_b128 v[194:197], v88 offset:35840
	ds_read_b128 v[200:203], v88 offset:36864
	ds_read_b128 v[204:207], v88 offset:37888
	ds_read_b128 v[208:211], v88 offset:38912
	ds_read_b128 v[220:223], v88 offset:39936
	global_load_lds_dwordx4 v[94:95], off
	v_lshl_add_u64 v[94:95], s[16:17], 0, v[70:71]
	s_mov_b32 m0, s22
	s_nop 0
	global_load_lds_dwordx4 v[94:95], off
	s_waitcnt vmcnt(8)
	s_waitcnt lgkmcnt(0)
	s_barrier
	s_setprio 0
	s_waitcnt lgkmcnt(0)
	v_mfma_f32_16x16x32_bf16 v[144:147], v[148:151], v[182:185], v[144:147]
	v_mfma_f32_16x16x32_bf16 v[140:143], v[156:159], v[182:185], v[140:143]
	v_mfma_f32_16x16x32_bf16 v[128:131], v[148:151], v[190:193], v[128:131]
	v_mfma_f32_16x16x32_bf16 v[124:127], v[156:159], v[190:193], v[124:127]
	v_mfma_f32_16x16x32_bf16 v[112:115], v[148:151], v[200:203], v[112:115]
	v_mfma_f32_16x16x32_bf16 v[108:111], v[156:159], v[200:203], v[108:111]
	v_mfma_f32_16x16x32_bf16 v[94:97], v[148:151], v[208:211], v[96:99]
	v_mfma_f32_16x16x32_bf16 v[90:93], v[156:159], v[208:211], v[90:93]
	v_mfma_f32_16x16x32_bf16 v[144:147], v[152:155], v[186:189], v[144:147]
	v_mfma_f32_16x16x32_bf16 v[140:143], v[160:163], v[186:189], v[140:143]
	v_mfma_f32_16x16x32_bf16 v[128:131], v[152:155], v[194:197], v[128:131]
	v_mfma_f32_16x16x32_bf16 v[124:127], v[160:163], v[194:197], v[124:127]
	v_mfma_f32_16x16x32_bf16 v[112:115], v[152:155], v[204:207], v[112:115]
	v_mfma_f32_16x16x32_bf16 v[108:111], v[160:163], v[204:207], v[108:111]
	v_mfma_f32_16x16x32_bf16 v[96:99], v[152:155], v[220:223], v[94:97]
	v_mfma_f32_16x16x32_bf16 v[92:95], v[160:163], v[220:223], v[90:93]
	s_setprio 0
	s_setprio 0
	v_mfma_f32_16x16x32_bf16 v[136:139], v[166:169], v[182:185], v[136:139]
	v_mfma_f32_16x16x32_bf16 v[132:135], v[174:177], v[182:185], v[132:135]
	v_mfma_f32_16x16x32_bf16 v[120:123], v[166:169], v[190:193], v[120:123]
	v_mfma_f32_16x16x32_bf16 v[116:119], v[174:177], v[190:193], v[116:119]
	v_mfma_f32_16x16x32_bf16 v[104:107], v[166:169], v[200:203], v[104:107]
	v_mfma_f32_16x16x32_bf16 v[100:103], v[174:177], v[200:203], v[100:103]
	v_mfma_f32_16x16x32_bf16 v[80:83], v[166:169], v[208:211], v[80:83]
	v_mfma_f32_16x16x32_bf16 v[76:79], v[174:177], v[208:211], v[76:79]
	v_mfma_f32_16x16x32_bf16 v[136:139], v[170:173], v[186:189], v[136:139]
	v_mfma_f32_16x16x32_bf16 v[132:135], v[178:181], v[186:189], v[132:135]
	v_mfma_f32_16x16x32_bf16 v[120:123], v[170:173], v[194:197], v[120:123]
	v_mfma_f32_16x16x32_bf16 v[116:119], v[178:181], v[194:197], v[116:119]
	v_mfma_f32_16x16x32_bf16 v[104:107], v[170:173], v[204:207], v[104:107]
	v_mfma_f32_16x16x32_bf16 v[100:103], v[178:181], v[204:207], v[100:103]
	v_mfma_f32_16x16x32_bf16 v[80:83], v[170:173], v[220:223], v[80:83]
	v_mfma_f32_16x16x32_bf16 v[76:79], v[178:181], v[220:223], v[76:79]
	s_setprio 1
	s_barrier
; #define PG8_STAGE(bufoff, gbase, voff) do { _Pragma("unroll") for (int _i = 0; _i < 2; ++_i) \
;         __builtin_amdgcn_global_load_lds((const unsigned*)((const char*)(gbase) + (voff)[_i]), (PG8_LAS unsigned*)(lds + (bufoff) + ldsw + _i * 8192), 16, 0, 0); } while (0)
; #define PG8_WAIT_V(n) asm volatile("s_waitcnt vmcnt(" #n ")" ::: "memory")
; #define PG8_WAIT_L(n) asm volatile("s_waitcnt lgkmcnt(" #n ")" ::: "memory")
; template <class Epi, class Sched, bool ALIGN_EPI = false, bool SP2 = false>
; __device__ __forceinline__ void gemm_phase(PG8_LAS unsigned char* lds, const Gemm g, const Sched& S, const Epi& E) {
;     ...
;             PG8_LDA(At, 1, 1); PG8_STAGE(PG8_SB(1, 0), b3, voffB); PG8_STAGE(PG8_SB(1, 1), b3 + hstep, voffB); PG8_STAGE(PG8_SA(1, 0), a3, voffA);
;             PG8_WAIT_V(8); PG8_WAIT_L(0); PG8_BAR; PG8_MMA(1, 0, At, B0); PG8_MMA(1, 1, At, B1); PG8_BAR; PG8_SCHED;
;             } else {
;             PG8_LDB(B0, 0, 0); PG8_SCHED; PG8_LDA(At, 0, 0); PG8_STAGE(PG8_SA(1, 1), a1 + hstep, voffA);
;             PG8_WAIT_L(8); PG8_BAR; PG8_WAIT_L(0); PG8_MMA(0, 0, At, B0); PG8_BAR; PG8_SCHED;
;             PG8_LDB(B1, 0, 1); PG8_STAGE(PG8_SB(0, 0), b2, voffB);
;             PG8_BAR; PG8_WAIT_L(0); PG8_MMA(0, 1, At, B1); PG8_BAR;
;             PG8_LDA(At, 0, 1); PG8_STAGE(PG8_SA(0, 0), a2, voffA);
;             PG8_BAR; PG8_WAIT_L(0); PG8_MMA(1, 0, At, B0); PG8_BAR; PG8_SCHED;
;             PG8_STAGE(PG8_SB(0, 1), b2 + hstep, voffB);
;             PG8_WAIT_V(6); PG8_BAR; PG8_MMA(1, 1, At, B1); PG8_BAR;
;             PG8_LDB(B0, 1, 0); PG8_SCHED; PG8_LDA(At, 1, 0); PG8_STAGE(PG8_SA(0, 1), a2 + hstep, voffA);
;             PG8_WAIT_L(8); PG8_BAR; PG8_WAIT_L(0); PG8_MMA(0, 0, At, B0); PG8_BAR; PG8_SCHED;
;             PG8_LDB(B1, 1, 1); PG8_STAGE(PG8_SB(1, 0), b3, voffB);
;             PG8_BAR; PG8_WAIT_L(0); PG8_MMA(0, 1, At, B1); PG8_BAR;
;             PG8_LDA(At, 1, 1); PG8_STAGE(PG8_SA(1, 0), a3, voffA);
;             PG8_BAR; PG8_WAIT_L(0); PG8_MMA(1, 0, At, B0); PG8_BAR; PG8_SCHED;
;             PG8_STAGE(PG8_SB(1, 1), b3 + hstep, voffB);
;             PG8_WAIT_V(6); PG8_BAR; PG8_MMA(1, 1, At, B1); PG8_BAR;
;             }
;             if constexpr (Epi::HAS_MID) { if ((((t + 2) & 7) == 0) && ((t + 2) < nt)) E.mid(acc, cur, ((t + 2) >> 3) - 1, wr, wc, fr, fq); }
;         }
;         if constexpr (ALIGN_EPI) { if (wr == 0) PG8_BAR; }
	s_add_i32 s16, s31, s18
	v_lshl_add_u64 v[90:91], v[224:225], 0, s[88:89]
	s_mov_b32 m0, s16
	ds_read_b128 v[182:185], v88 offset:49152
	ds_read_b128 v[186:189], v88 offset:50176
	ds_read_b128 v[190:193], v88 offset:51200
	ds_read_b128 v[194:197], v88 offset:52224
	ds_read_b128 v[200:203], v88 offset:53248
	ds_read_b128 v[204:207], v88 offset:54272
	ds_read_b128 v[208:211], v88 offset:55296
	ds_read_b128 v[220:223], v88 offset:56320
	global_load_lds_dwordx4 v[90:91], off
	s_add_i32 m0, s16, 0x2000
	s_add_u32 s14, s14, 0x80080
	v_lshl_add_u64 v[90:91], v[226:227], 0, s[88:89]
	s_addc_u32 s15, s15, 0
	s_add_i32 s16, s34, s18
	global_load_lds_dwordx4 v[90:91], off
	v_lshl_add_u64 v[90:91], s[14:15], 0, v[66:67]
	s_mov_b32 m0, s16
	s_nop 0
	global_load_lds_dwordx4 v[90:91], off
	v_lshl_add_u64 v[90:91], s[14:15], 0, v[72:73]
	s_add_i32 m0, s16, 0x2000
	s_nop 0
	global_load_lds_dwordx4 v[90:91], off
	v_lshl_add_u64 v[90:91], v[228:229], 0, s[88:89]
	s_mov_b32 m0, s24
	s_nop 0
	global_load_lds_dwordx4 v[90:91], off
	v_lshl_add_u64 v[90:91], v[230:231], 0, s[88:89]
	s_mov_b32 m0, s25
	s_nop 0
	global_load_lds_dwordx4 v[90:91], off
	s_waitcnt vmcnt(8)
	s_waitcnt lgkmcnt(0)
	s_barrier
	s_setprio 0
	s_waitcnt lgkmcnt(0)
	v_mfma_f32_16x16x32_bf16 v[62:65], v[148:151], v[182:185], v[62:65]
	v_mfma_f32_16x16x32_bf16 v[58:61], v[156:159], v[182:185], v[58:61]
	v_mfma_f32_16x16x32_bf16 v[46:49], v[148:151], v[190:193], v[46:49]
	v_mfma_f32_16x16x32_bf16 v[42:45], v[156:159], v[190:193], v[42:45]
	v_mfma_f32_16x16x32_bf16 v[30:33], v[148:151], v[200:203], v[30:33]
	v_mfma_f32_16x16x32_bf16 v[26:29], v[156:159], v[200:203], v[26:29]
	v_mfma_f32_16x16x32_bf16 v[14:17], v[148:151], v[208:211], v[14:17]
	v_mfma_f32_16x16x32_bf16 v[10:13], v[156:159], v[208:211], v[10:13]
	v_mfma_f32_16x16x32_bf16 v[62:65], v[152:155], v[186:189], v[62:65]
	v_mfma_f32_16x16x32_bf16 v[58:61], v[160:163], v[186:189], v[58:61]
	v_mfma_f32_16x16x32_bf16 v[46:49], v[152:155], v[194:197], v[46:49]
	v_mfma_f32_16x16x32_bf16 v[42:45], v[160:163], v[194:197], v[42:45]
	v_mfma_f32_16x16x32_bf16 v[30:33], v[152:155], v[204:207], v[30:33]
	v_mfma_f32_16x16x32_bf16 v[26:29], v[160:163], v[204:207], v[26:29]
	v_mfma_f32_16x16x32_bf16 v[14:17], v[152:155], v[220:223], v[14:17]
	v_mfma_f32_16x16x32_bf16 v[10:13], v[160:163], v[220:223], v[10:13]
	s_setprio 0
	s_setprio 0
	v_mfma_f32_16x16x32_bf16 v[54:57], v[166:169], v[182:185], v[54:57]
	v_mfma_f32_16x16x32_bf16 v[50:53], v[174:177], v[182:185], v[50:53]
	v_mfma_f32_16x16x32_bf16 v[38:41], v[166:169], v[190:193], v[38:41]
	v_mfma_f32_16x16x32_bf16 v[34:37], v[174:177], v[190:193], v[34:37]
	v_mfma_f32_16x16x32_bf16 v[22:25], v[166:169], v[200:203], v[22:25]
	v_mfma_f32_16x16x32_bf16 v[18:21], v[174:177], v[200:203], v[18:21]
	v_mfma_f32_16x16x32_bf16 v[6:9], v[166:169], v[208:211], v[6:9]
	v_mfma_f32_16x16x32_bf16 v[2:5], v[174:177], v[208:211], v[2:5]
	v_mfma_f32_16x16x32_bf16 v[54:57], v[170:173], v[186:189], v[54:57]
	v_mfma_f32_16x16x32_bf16 v[50:53], v[178:181], v[186:189], v[50:53]
	v_mfma_f32_16x16x32_bf16 v[38:41], v[170:173], v[194:197], v[38:41]
	v_mfma_f32_16x16x32_bf16 v[34:37], v[178:181], v[194:197], v[34:37]
	v_mfma_f32_16x16x32_bf16 v[22:25], v[170:173], v[204:207], v[22:25]
	v_mfma_f32_16x16x32_bf16 v[18:21], v[178:181], v[204:207], v[18:21]
	v_mfma_f32_16x16x32_bf16 v[6:9], v[170:173], v[220:223], v[6:9]
	v_mfma_f32_16x16x32_bf16 v[2:5], v[178:181], v[220:223], v[2:5]
	s_setprio 1
	s_barrier
	s_add_i32 s30, s30, 2
	s_add_u32 s12, s12, 0x100
	s_addc_u32 s13, s13, 0
	s_cmp_gt_u32 s30, 29
	s_cbranch_scc0 .LBB0_702
	s_cmpk_lt_u32 s1, 0x100
	s_cbranch_scc0 .LBB0_705
	s_barrier

;     __host__ __device__ bool next(int i, Unit& u) const { if (i != 0 || r < 0 || r >= 148) return false; if (r < 116) { u.pm = r % 29; u.pn = 47 + r / 29; } else { u.pm = 32; u.pn = 19 + (r - 116); } u.ko = 0; return true; }
;     __host__ __device__ bool next(int i, Unit& u) const { const int L = i * G + (G - 1 - c); if (L >= nN * S) return false; u.pm = pm; u.pn = L % nN; u.ko = (L / nN) * ksub; return true; }
; #define PG8_STAGE(bufoff, gbase, voff) do { _Pragma("unroll") for (int _i = 0; _i < 2; ++_i) \
;         __builtin_amdgcn_global_load_lds((const unsigned*)((const char*)(gbase) + (voff)[_i]), (PG8_LAS unsigned*)(lds + (bufoff) + ldsw + _i * 8192), 16, 0, 0); } while (0)
; #define PG8_LDA(dst, b, h) do { _Pragma("unroll") for (int m = 0; m < 4; ++m) _Pragma("unroll") for (int k = 0; k < 2; ++k) dst[m][k] = *(const PG8_LAS bf16x8*)(lds + PG8_SA(b, h) + aoff + m * 2048 + k * 1024); } while (0)
; #define PG8_WAIT_V(n) asm volatile("s_waitcnt vmcnt(" #n ")" ::: "memory")
; #define PG8_WAIT_L(n) asm volatile("s_waitcnt lgkmcnt(" #n ")" ::: "memory")
; template <class Epi, class Sched, bool ALIGN_EPI = false, bool SP2 = false>
; __device__ __forceinline__ void gemm_phase(PG8_LAS unsigned char* lds, const Gemm g, const Sched& S, const Epi& E) {
;     ...
;     for (;;) {
;         const bool has_next = S.next(ui + 1, nxt);
;         const char* nA = has_next ? (const char*)g.A + (size_t)nxt.pm * tstep + (size_t)nxt.ko * 2 : cA; const char* nB = has_next ? (const char*)g.Bt + (size_t)nxt.pn * tstep + (size_t)nxt.ko * 2 : cB;
;         for (int t = 0; t < nt; t += 2) {
;             const bool last = (t == nt - 2);
;             const char* a1 = cA + (size_t)(t + 1) * kstep;
;             const char* a2 = last ? nA : cA + (size_t)(t + 2) * kstep; const char* b2 = last ? nB : cB + (size_t)(t + 2) * kstep;
;             const char* a3 = a2 + kstep; const char* b3 = b2 + kstep;
;             if (last && has_next) S.a_ready(nxt);
;             if constexpr (SP2) {
;             PG8_LDB(B0, 0, 0); PG8_LDB(B1, 0, 1); PG8_SCHED; PG8_LDA(At, 0, 0); PG8_STAGE(PG8_SA(1, 1), a1 + hstep, voffA);
;             PG8_WAIT_V(8); PG8_WAIT_L(0); PG8_BAR; PG8_MMA(0, 0, At, B0); PG8_MMA(0, 1, At, B1); PG8_BAR; PG8_SCHED;
;             PG8_LDA(At, 0, 1); PG8_STAGE(PG8_SB(0, 0), b2, voffB); PG8_STAGE(PG8_SB(0, 1), b2 + hstep, voffB); PG8_STAGE(PG8_SA(0, 0), a2, voffA);
.LBB0_782:
	s_add_u32 s1, s26, 0xfff80080
	s_addc_u32 s2, s27, -1
	s_add_i32 s3, 0, 0x10000
	s_cmpk_eq_i32 s28, 0x1e00
	s_cselect_b32 s35, s21, s2
	s_cselect_b32 s34, s50, s1
	v_add_u32_e32 v66, s3, v206
	s_cselect_b32 s31, s19, s53
	s_cselect_b32 s30, s51, s52
	s_add_i32 s1, 0, 0x14000
	ds_read_b128 v[152:155], v66
	ds_read_b128 v[156:159], v66 offset:1024
	ds_read_b128 v[160:163], v66 offset:2048
	ds_read_b128 v[164:167], v66 offset:3072
	v_add_u32_e32 v66, s1, v206
	ds_read_b128 v[168:171], v66
	ds_read_b128 v[172:175], v66 offset:1024
	ds_read_b128 v[176:179], v66 offset:2048
	ds_read_b128 v[180:183], v66 offset:3072
	v_lshl_add_u64 v[68:69], s[26:27], 0, v[142:143]
	s_add_i32 m0, s43, 0xc000
	ds_read_b128 v[184:187], v208
	ds_read_b128 v[188:191], v208 offset:1024
	ds_read_b128 v[192:195], v208 offset:2048
	ds_read_b128 v[196:199], v208 offset:3072
	ds_read_b128 v[200:203], v208 offset:4096
	ds_read_b128 v[220:223], v208 offset:5120
	ds_read_b128 v[224:227], v208 offset:6144
	ds_read_b128 v[228:231], v208 offset:7168
	global_load_lds_dwordx4 v[68:69], off
	v_lshl_add_u64 v[68:69], s[26:27], 0, v[144:145]
	s_add_i32 m0, s43, 0xe000
	s_nop 0
	global_load_lds_dwordx4 v[68:69], off
	s_waitcnt vmcnt(8)
	s_waitcnt lgkmcnt(0)
	s_barrier
	s_setprio 0
	s_waitcnt lgkmcnt(0)
	v_mfma_f32_16x16x32_bf16 v[130:133], v[152:155], v[184:187], v[130:133]
	v_mfma_f32_16x16x32_bf16 v[126:129], v[160:163], v[184:187], v[126:129]
	v_mfma_f32_16x16x32_bf16 v[114:117], v[152:155], v[192:195], v[114:117]
	v_mfma_f32_16x16x32_bf16 v[110:113], v[160:163], v[192:195], v[110:113]
	v_mfma_f32_16x16x32_bf16 v[98:101], v[152:155], v[200:203], v[98:101]
	v_mfma_f32_16x16x32_bf16 v[94:97], v[160:163], v[200:203], v[94:97]
	v_mfma_f32_16x16x32_bf16 v[82:85], v[152:155], v[224:227], v[82:85]
	v_mfma_f32_16x16x32_bf16 v[78:81], v[160:163], v[224:227], v[78:81]
	v_mfma_f32_16x16x32_bf16 v[130:133], v[156:159], v[188:191], v[130:133]
	v_mfma_f32_16x16x32_bf16 v[126:129], v[164:167], v[188:191], v[126:129]
	v_mfma_f32_16x16x32_bf16 v[114:117], v[156:159], v[196:199], v[114:117]
	v_mfma_f32_16x16x32_bf16 v[110:113], v[164:167], v[196:199], v[110:113]
	v_mfma_f32_16x16x32_bf16 v[98:101], v[156:159], v[220:223], v[98:101]
	v_mfma_f32_16x16x32_bf16 v[94:97], v[164:167], v[220:223], v[94:97]
	v_mfma_f32_16x16x32_bf16 v[82:85], v[156:159], v[228:231], v[82:85]
	v_mfma_f32_16x16x32_bf16 v[78:81], v[164:167], v[228:231], v[78:81]
	s_setprio 0
	s_setprio 0
	v_mfma_f32_16x16x32_bf16 v[122:125], v[168:171], v[184:187], v[122:125]
	v_mfma_f32_16x16x32_bf16 v[118:121], v[176:179], v[184:187], v[118:121]
	v_mfma_f32_16x16x32_bf16 v[106:109], v[168:171], v[192:195], v[106:109]
	v_mfma_f32_16x16x32_bf16 v[102:105], v[176:179], v[192:195], v[102:105]
	v_mfma_f32_16x16x32_bf16 v[90:93], v[168:171], v[200:203], v[90:93]
	v_mfma_f32_16x16x32_bf16 v[86:89], v[176:179], v[200:203], v[86:89]
	v_mfma_f32_16x16x32_bf16 v[74:77], v[168:171], v[224:227], v[74:77]
	v_mfma_f32_16x16x32_bf16 v[68:71], v[176:179], v[224:227], v[70:73]
	v_mfma_f32_16x16x32_bf16 v[122:125], v[172:175], v[188:191], v[122:125]
	v_mfma_f32_16x16x32_bf16 v[118:121], v[180:183], v[188:191], v[118:121]
	v_mfma_f32_16x16x32_bf16 v[106:109], v[172:175], v[196:199], v[106:109]
	v_mfma_f32_16x16x32_bf16 v[102:105], v[180:183], v[196:199], v[102:105]
	v_mfma_f32_16x16x32_bf16 v[90:93], v[172:175], v[220:223], v[90:93]
	v_mfma_f32_16x16x32_bf16 v[86:89], v[180:183], v[220:223], v[86:89]
	v_mfma_f32_16x16x32_bf16 v[74:77], v[172:175], v[228:231], v[74:77]
	v_mfma_f32_16x16x32_bf16 v[68:71], v[180:183], v[228:231], v[68:71]
	s_setprio 1
	s_barrier
	s_add_i32 s2, s3, s42
	v_lshl_add_u64 v[204:205], s[30:31], 0, v[138:139]
	s_mov_b32 m0, s2
	ds_read_b128 v[184:187], v208 offset:16384
	ds_read_b128 v[188:191], v208 offset:17408
	ds_read_b128 v[192:195], v208 offset:18432
	ds_read_b128 v[196:199], v208 offset:19456
	ds_read_b128 v[200:203], v208 offset:20480
	ds_read_b128 v[220:223], v208 offset:21504
	ds_read_b128 v[224:227], v208 offset:22528
	ds_read_b128 v[228:231], v208 offset:23552
	global_load_lds_dwordx4 v[204:205], off
	s_add_i32 m0, s2, 0x2000
	s_add_u32 s2, s30, 0x80000
	v_lshl_add_u64 v[210:211], s[30:31], 0, v[134:135]
	s_addc_u32 s3, s31, 0
	s_add_i32 s1, s1, s42
	global_load_lds_dwordx4 v[210:211], off
	v_lshl_add_u64 v[72:73], s[2:3], 0, v[138:139]
	s_mov_b32 m0, s1
	v_lshl_add_u64 v[232:233], s[34:35], 0, v[140:141]
	global_load_lds_dwordx4 v[72:73], off
	v_lshl_add_u64 v[72:73], s[2:3], 0, v[134:135]
	s_add_i32 m0, s1, 0x2000
	v_lshl_add_u64 v[234:235], s[34:35], 0, v[136:137]
	global_load_lds_dwordx4 v[72:73], off
	s_mov_b32 m0, s43
	s_nop 0
	global_load_lds_dwordx4 v[232:233], off
	s_mov_b32 m0, s44
	s_nop 0
	global_load_lds_dwordx4 v[234:235], off
	s_waitcnt vmcnt(8)
	s_waitcnt lgkmcnt(0)
	s_barrier
; #define PG8_STAGE(bufoff, gbase, voff) do { _Pragma("unroll") for (int _i = 0; _i < 2; ++_i) \
;         __builtin_amdgcn_global_load_lds((const unsigned*)((const char*)(gbase) + (voff)[_i]), (PG8_LAS unsigned*)(lds + (bufoff) + ldsw + _i * 8192), 16, 0, 0); } while (0)
; #define PG8_LDA(dst, b, h) do { _Pragma("unroll") for (int m = 0; m < 4; ++m) _Pragma("unroll") for (int k = 0; k < 2; ++k) dst[m][k] = *(const PG8_LAS bf16x8*)(lds + PG8_SA(b, h) + aoff + m * 2048 + k * 1024); } while (0)
; #define PG8_LDB(dst, b, h) do { _Pragma("unroll") for (int n = 0; n < 2; ++n) _Pragma("unroll") for (int k = 0; k < 2; ++k) dst[n][k] = *(const PG8_LAS bf16x8*)(lds + PG8_SB(b, h) + boff + n * 2048 + k * 1024); } while (0)
; #define PG8_MMA(ai, bj, At, Bt) do { __builtin_amdgcn_s_setprio(1); _Pragma("unroll") for (int m = 0; m < 4; ++m) _Pragma("unroll") for (int n = 0; n < 2; ++n) _Pragma("unroll") for (int k = 0; k < 2; ++k) \
;         acc[ai][bj][m][n] = __builtin_amdgcn_mfma_f32_16x16x32_bf16(Bt[n][k], At[m][k], acc[ai][bj][m][n], 0, 0, 0); __builtin_amdgcn_s_setprio(0); } while (0)
; #define PG8_WAIT_V(n) asm volatile("s_waitcnt vmcnt(" #n ")" ::: "memory")
; #define PG8_WAIT_L(n) asm volatile("s_waitcnt lgkmcnt(" #n ")" ::: "memory")
; #define PG8_BAR __builtin_amdgcn_s_barrier()
; #define PG8_SCHED __builtin_amdgcn_sched_barrier(0)
; template <class Epi, class Sched, bool ALIGN_EPI = false, bool SP2 = false>
; __device__ __forceinline__ void gemm_phase(PG8_LAS unsigned char* lds, const Gemm g, const Sched& S, const Epi& E) {
;     ...
;             PG8_WAIT_V(8); PG8_WAIT_L(0); PG8_BAR; PG8_MMA(1, 0, At, B0); PG8_MMA(1, 1, At, B1); PG8_BAR; PG8_SCHED;
;             PG8_LDB(B0, 1, 0); PG8_LDB(B1, 1, 1); PG8_SCHED; PG8_LDA(At, 1, 0); PG8_STAGE(PG8_SA(0, 1), a2 + hstep, voffA);
;             PG8_WAIT_V(8); PG8_WAIT_L(0); PG8_BAR; PG8_MMA(0, 0, At, B0); PG8_MMA(0, 1, At, B1); PG8_BAR; PG8_SCHED;
	s_setprio 0
	s_waitcnt lgkmcnt(0)
	v_mfma_f32_16x16x32_bf16 v[62:65], v[152:155], v[184:187], v[62:65]
	v_mfma_f32_16x16x32_bf16 v[58:61], v[160:163], v[184:187], v[58:61]
	v_mfma_f32_16x16x32_bf16 v[46:49], v[152:155], v[192:195], v[46:49]
	v_mfma_f32_16x16x32_bf16 v[42:45], v[160:163], v[192:195], v[42:45]
	v_mfma_f32_16x16x32_bf16 v[30:33], v[152:155], v[200:203], v[30:33]
	v_mfma_f32_16x16x32_bf16 v[26:29], v[160:163], v[200:203], v[26:29]
	v_mfma_f32_16x16x32_bf16 v[14:17], v[152:155], v[224:227], v[14:17]
	v_mfma_f32_16x16x32_bf16 v[10:13], v[160:163], v[224:227], v[10:13]
	v_mfma_f32_16x16x32_bf16 v[62:65], v[156:159], v[188:191], v[62:65]
	v_mfma_f32_16x16x32_bf16 v[58:61], v[164:167], v[188:191], v[58:61]
	v_mfma_f32_16x16x32_bf16 v[46:49], v[156:159], v[196:199], v[46:49]
	v_mfma_f32_16x16x32_bf16 v[42:45], v[164:167], v[196:199], v[42:45]
	v_mfma_f32_16x16x32_bf16 v[30:33], v[156:159], v[220:223], v[30:33]
	v_mfma_f32_16x16x32_bf16 v[26:29], v[164:167], v[220:223], v[26:29]
	v_mfma_f32_16x16x32_bf16 v[14:17], v[156:159], v[228:231], v[14:17]
	v_mfma_f32_16x16x32_bf16 v[10:13], v[164:167], v[228:231], v[10:13]
	s_setprio 0
	s_setprio 0
	v_mfma_f32_16x16x32_bf16 v[54:57], v[168:171], v[184:187], v[54:57]
	v_mfma_f32_16x16x32_bf16 v[50:53], v[176:179], v[184:187], v[50:53]
	v_mfma_f32_16x16x32_bf16 v[38:41], v[168:171], v[192:195], v[38:41]
	v_mfma_f32_16x16x32_bf16 v[34:37], v[176:179], v[192:195], v[34:37]
	v_mfma_f32_16x16x32_bf16 v[22:25], v[168:171], v[200:203], v[22:25]
	v_mfma_f32_16x16x32_bf16 v[18:21], v[176:179], v[200:203], v[18:21]
	v_mfma_f32_16x16x32_bf16 v[6:9], v[168:171], v[224:227], v[6:9]
	v_mfma_f32_16x16x32_bf16 v[2:5], v[176:179], v[224:227], v[2:5]
	v_mfma_f32_16x16x32_bf16 v[54:57], v[172:175], v[188:191], v[54:57]
	v_mfma_f32_16x16x32_bf16 v[50:53], v[180:183], v[188:191], v[50:53]
	v_mfma_f32_16x16x32_bf16 v[38:41], v[172:175], v[196:199], v[38:41]
	v_mfma_f32_16x16x32_bf16 v[34:37], v[180:183], v[196:199], v[34:37]
	v_mfma_f32_16x16x32_bf16 v[22:25], v[172:175], v[220:223], v[22:25]
	v_mfma_f32_16x16x32_bf16 v[18:21], v[180:183], v[220:223], v[18:21]
	v_mfma_f32_16x16x32_bf16 v[6:9], v[172:175], v[228:231], v[6:9]
	v_mfma_f32_16x16x32_bf16 v[2:5], v[180:183], v[228:231], v[2:5]
	s_setprio 1
	s_barrier
	s_add_i32 s1, 0, 0x18000
	v_add_u32_e32 v66, s1, v206
	s_add_i32 s55, 0, 0x1c000
	ds_read_b128 v[152:155], v66
	ds_read_b128 v[156:159], v66 offset:1024
	ds_read_b128 v[160:163], v66 offset:2048
	ds_read_b128 v[164:167], v66 offset:3072
	v_add_u32_e32 v66, s55, v206
	ds_read_b128 v[168:171], v66
	ds_read_b128 v[172:175], v66 offset:1024
	ds_read_b128 v[176:179], v66 offset:2048
	ds_read_b128 v[180:183], v66 offset:3072
	s_add_u32 s2, s34, 0x80000
	s_addc_u32 s3, s35, 0
	s_mov_b32 m0, s45
	v_lshl_add_u64 v[72:73], s[2:3], 0, v[140:141]
	ds_read_b128 v[184:187], v208 offset:32768
	ds_read_b128 v[188:191], v208 offset:33792
	ds_read_b128 v[192:195], v208 offset:34816
	ds_read_b128 v[196:199], v208 offset:35840
	ds_read_b128 v[200:203], v208 offset:36864
	ds_read_b128 v[220:223], v208 offset:37888
	ds_read_b128 v[224:227], v208 offset:38912
	ds_read_b128 v[228:231], v208 offset:39936
	global_load_lds_dwordx4 v[72:73], off
	v_lshl_add_u64 v[72:73], s[2:3], 0, v[136:137]
	s_mov_b32 m0, s46
	s_nop 0
	global_load_lds_dwordx4 v[72:73], off
	s_waitcnt vmcnt(8)
	s_waitcnt lgkmcnt(0)
	s_barrier
	s_setprio 0
	s_waitcnt lgkmcnt(0)
	v_mfma_f32_16x16x32_bf16 v[130:133], v[152:155], v[184:187], v[130:133]
	v_mfma_f32_16x16x32_bf16 v[126:129], v[160:163], v[184:187], v[126:129]
	v_mfma_f32_16x16x32_bf16 v[114:117], v[152:155], v[192:195], v[114:117]
	v_mfma_f32_16x16x32_bf16 v[110:113], v[160:163], v[192:195], v[110:113]
	v_mfma_f32_16x16x32_bf16 v[98:101], v[152:155], v[200:203], v[98:101]
	v_mfma_f32_16x16x32_bf16 v[94:97], v[160:163], v[200:203], v[94:97]
	v_mfma_f32_16x16x32_bf16 v[82:85], v[152:155], v[224:227], v[82:85]
	v_mfma_f32_16x16x32_bf16 v[78:81], v[160:163], v[224:227], v[78:81]
	v_mfma_f32_16x16x32_bf16 v[130:133], v[156:159], v[188:191], v[130:133]
	v_mfma_f32_16x16x32_bf16 v[126:129], v[164:167], v[188:191], v[126:129]
	v_mfma_f32_16x16x32_bf16 v[114:117], v[156:159], v[196:199], v[114:117]
	v_mfma_f32_16x16x32_bf16 v[110:113], v[164:167], v[196:199], v[110:113]
	v_mfma_f32_16x16x32_bf16 v[98:101], v[156:159], v[220:223], v[98:101]
	v_mfma_f32_16x16x32_bf16 v[94:97], v[164:167], v[220:223], v[94:97]
	v_mfma_f32_16x16x32_bf16 v[82:85], v[156:159], v[228:231], v[82:85]
	v_mfma_f32_16x16x32_bf16 v[78:81], v[164:167], v[228:231], v[78:81]
	s_setprio 0
	s_setprio 0
	v_mfma_f32_16x16x32_bf16 v[122:125], v[168:171], v[184:187], v[122:125]
	v_mfma_f32_16x16x32_bf16 v[118:121], v[176:179], v[184:187], v[118:121]
	v_mfma_f32_16x16x32_bf16 v[106:109], v[168:171], v[192:195], v[106:109]
	v_mfma_f32_16x16x32_bf16 v[102:105], v[176:179], v[192:195], v[102:105]
	v_mfma_f32_16x16x32_bf16 v[90:93], v[168:171], v[200:203], v[90:93]
	v_mfma_f32_16x16x32_bf16 v[86:89], v[176:179], v[200:203], v[86:89]
	v_mfma_f32_16x16x32_bf16 v[72:75], v[168:171], v[224:227], v[74:77]
	v_mfma_f32_16x16x32_bf16 v[68:71], v[176:179], v[224:227], v[68:71]
	v_mfma_f32_16x16x32_bf16 v[122:125], v[172:175], v[188:191], v[122:125]
	v_mfma_f32_16x16x32_bf16 v[118:121], v[180:183], v[188:191], v[118:121]
	v_mfma_f32_16x16x32_bf16 v[106:109], v[172:175], v[196:199], v[106:109]
	v_mfma_f32_16x16x32_bf16 v[102:105], v[180:183], v[196:199], v[102:105]
	v_mfma_f32_16x16x32_bf16 v[90:93], v[172:175], v[220:223], v[90:93]
	v_mfma_f32_16x16x32_bf16 v[86:89], v[180:183], v[220:223], v[86:89]
	v_mfma_f32_16x16x32_bf16 v[74:77], v[172:175], v[228:231], v[72:75]
	v_mfma_f32_16x16x32_bf16 v[70:73], v[180:183], v[228:231], v[68:71]
	s_setprio 1
	s_barrier
; template <class Epi, class Sched, bool ALIGN_EPI = false, bool SP2 = false>
; __device__ __forceinline__ void gemm_phase(PG8_LAS unsigned char* lds, const Gemm g, const Sched& S, const Epi& E) {
;     ...
;             PG8_LDB(B0, 0, 0); PG8_LDB(B1, 0, 1); PG8_SCHED; PG8_LDA(At, 0, 0); PG8_STAGE(PG8_SA(1, 1), a1 + hstep, voffA);
;             PG8_WAIT_V(8); PG8_WAIT_L(0); PG8_BAR; PG8_MMA(0, 0, At, B0); PG8_MMA(0, 1, At, B1); PG8_BAR; PG8_SCHED;
;             PG8_LDA(At, 0, 1); PG8_STAGE(PG8_SB(0, 0), b2, voffB); PG8_STAGE(PG8_SB(0, 1), b2 + hstep, voffB); PG8_STAGE(PG8_SA(0, 0), a2, voffA);
;             PG8_WAIT_V(8); PG8_WAIT_L(0); PG8_BAR; PG8_MMA(1, 0, At, B0); PG8_MMA(1, 1, At, B1); PG8_BAR; PG8_SCHED;
;             PG8_LDB(B0, 1, 0); PG8_LDB(B1, 1, 1); PG8_SCHED; PG8_LDA(At, 1, 0); PG8_STAGE(PG8_SA(0, 1), a2 + hstep, voffA);
;             PG8_WAIT_V(8); PG8_WAIT_L(0); PG8_BAR; PG8_MMA(0, 0, At, B0); PG8_MMA(0, 1, At, B1); PG8_BAR; PG8_SCHED;
;             PG8_LDA(At, 1, 1); PG8_STAGE(PG8_SB(1, 0), b3, voffB); PG8_STAGE(PG8_SB(1, 1), b3 + hstep, voffB); PG8_STAGE(PG8_SA(1, 0), a3, voffA);
;             PG8_WAIT_V(8); PG8_WAIT_L(0); PG8_BAR; PG8_MMA(1, 0, At, B0); PG8_MMA(1, 1, At, B1); PG8_BAR; PG8_SCHED;
;             } else {
;             PG8_LDB(B0, 0, 0); PG8_SCHED; PG8_LDA(At, 0, 0); PG8_STAGE(PG8_SA(1, 1), a1 + hstep, voffA);
;             PG8_WAIT_L(8); PG8_BAR; PG8_WAIT_L(0); PG8_MMA(0, 0, At, B0); PG8_BAR; PG8_SCHED;
;             PG8_LDB(B1, 0, 1); PG8_STAGE(PG8_SB(0, 0), b2, voffB);
;             PG8_BAR; PG8_WAIT_L(0); PG8_MMA(0, 1, At, B1); PG8_BAR;
;             PG8_LDA(At, 0, 1); PG8_STAGE(PG8_SA(0, 0), a2, voffA);
;             PG8_BAR; PG8_WAIT_L(0); PG8_MMA(1, 0, At, B0); PG8_BAR; PG8_SCHED;
;             PG8_STAGE(PG8_SB(0, 1), b2 + hstep, voffB);
;             PG8_WAIT_V(6); PG8_BAR; PG8_MMA(1, 1, At, B1); PG8_BAR;
;             PG8_LDB(B0, 1, 0); PG8_SCHED; PG8_LDA(At, 1, 0); PG8_STAGE(PG8_SA(0, 1), a2 + hstep, voffA);
;             PG8_WAIT_L(8); PG8_BAR; PG8_WAIT_L(0); PG8_MMA(0, 0, At, B0); PG8_BAR; PG8_SCHED;
;             PG8_LDB(B1, 1, 1); PG8_STAGE(PG8_SB(1, 0), b3, voffB);
;             PG8_BAR; PG8_WAIT_L(0); PG8_MMA(0, 1, At, B1); PG8_BAR;
;             PG8_LDA(At, 1, 1); PG8_STAGE(PG8_SA(1, 0), a3, voffA);
;             PG8_BAR; PG8_WAIT_L(0); PG8_MMA(1, 0, At, B0); PG8_BAR; PG8_SCHED;
	s_add_i32 s1, s1, s42
	v_lshl_add_u64 v[68:69], v[204:205], 0, s[88:89]
	s_mov_b32 m0, s1
	ds_read_b128 v[184:187], v208 offset:49152
	ds_read_b128 v[188:191], v208 offset:50176
	ds_read_b128 v[192:195], v208 offset:51200
	ds_read_b128 v[196:199], v208 offset:52224
	ds_read_b128 v[200:203], v208 offset:53248
	ds_read_b128 v[220:223], v208 offset:54272
	ds_read_b128 v[224:227], v208 offset:55296
	ds_read_b128 v[228:231], v208 offset:56320
	global_load_lds_dwordx4 v[68:69], off
	s_add_i32 m0, s1, 0x2000
	s_add_u32 s2, s30, 0x80080
	v_lshl_add_u64 v[68:69], v[210:211], 0, s[88:89]
	s_addc_u32 s3, s31, 0
	s_add_i32 s1, s55, s42
	global_load_lds_dwordx4 v[68:69], off
	v_lshl_add_u64 v[68:69], s[2:3], 0, v[138:139]
	s_mov_b32 m0, s1
	s_nop 0
	global_load_lds_dwordx4 v[68:69], off
	v_lshl_add_u64 v[68:69], s[2:3], 0, v[134:135]
	s_add_i32 m0, s1, 0x2000
	s_nop 0
	global_load_lds_dwordx4 v[68:69], off
	v_lshl_add_u64 v[68:69], v[232:233], 0, s[88:89]
	s_mov_b32 m0, s47
	s_nop 0
	global_load_lds_dwordx4 v[68:69], off
	v_lshl_add_u64 v[68:69], v[234:235], 0, s[88:89]
	s_mov_b32 m0, s48
	s_nop 0
	global_load_lds_dwordx4 v[68:69], off
	s_waitcnt vmcnt(8)
	s_waitcnt lgkmcnt(0)
	s_barrier
	s_setprio 0
	s_waitcnt lgkmcnt(0)
	v_mfma_f32_16x16x32_bf16 v[62:65], v[152:155], v[184:187], v[62:65]
	v_mfma_f32_16x16x32_bf16 v[58:61], v[160:163], v[184:187], v[58:61]
	v_mfma_f32_16x16x32_bf16 v[46:49], v[152:155], v[192:195], v[46:49]
	v_mfma_f32_16x16x32_bf16 v[42:45], v[160:163], v[192:195], v[42:45]
	v_mfma_f32_16x16x32_bf16 v[30:33], v[152:155], v[200:203], v[30:33]
	v_mfma_f32_16x16x32_bf16 v[26:29], v[160:163], v[200:203], v[26:29]
	v_mfma_f32_16x16x32_bf16 v[14:17], v[152:155], v[224:227], v[14:17]
	v_mfma_f32_16x16x32_bf16 v[10:13], v[160:163], v[224:227], v[10:13]
	v_mfma_f32_16x16x32_bf16 v[62:65], v[156:159], v[188:191], v[62:65]
	v_mfma_f32_16x16x32_bf16 v[58:61], v[164:167], v[188:191], v[58:61]
	v_mfma_f32_16x16x32_bf16 v[46:49], v[156:159], v[196:199], v[46:49]
	v_mfma_f32_16x16x32_bf16 v[42:45], v[164:167], v[196:199], v[42:45]
	v_mfma_f32_16x16x32_bf16 v[30:33], v[156:159], v[220:223], v[30:33]
	v_mfma_f32_16x16x32_bf16 v[26:29], v[164:167], v[220:223], v[26:29]
	v_mfma_f32_16x16x32_bf16 v[14:17], v[156:159], v[228:231], v[14:17]
	v_mfma_f32_16x16x32_bf16 v[10:13], v[164:167], v[228:231], v[10:13]
	s_setprio 0
	s_setprio 0
	v_mfma_f32_16x16x32_bf16 v[54:57], v[168:171], v[184:187], v[54:57]
	v_mfma_f32_16x16x32_bf16 v[50:53], v[176:179], v[184:187], v[50:53]
	v_mfma_f32_16x16x32_bf16 v[38:41], v[168:171], v[192:195], v[38:41]
	v_mfma_f32_16x16x32_bf16 v[34:37], v[176:179], v[192:195], v[34:37]
	v_mfma_f32_16x16x32_bf16 v[22:25], v[168:171], v[200:203], v[22:25]
	v_mfma_f32_16x16x32_bf16 v[18:21], v[176:179], v[200:203], v[18:21]
	v_mfma_f32_16x16x32_bf16 v[6:9], v[168:171], v[224:227], v[6:9]
	v_mfma_f32_16x16x32_bf16 v[2:5], v[176:179], v[224:227], v[2:5]
	v_mfma_f32_16x16x32_bf16 v[54:57], v[172:175], v[188:191], v[54:57]
	v_mfma_f32_16x16x32_bf16 v[50:53], v[180:183], v[188:191], v[50:53]
	v_mfma_f32_16x16x32_bf16 v[38:41], v[172:175], v[196:199], v[38:41]
	v_mfma_f32_16x16x32_bf16 v[34:37], v[180:183], v[196:199], v[34:37]
	v_mfma_f32_16x16x32_bf16 v[22:25], v[172:175], v[220:223], v[22:25]
	v_mfma_f32_16x16x32_bf16 v[18:21], v[180:183], v[220:223], v[18:21]
	v_mfma_f32_16x16x32_bf16 v[6:9], v[172:175], v[228:231], v[6:9]
	v_mfma_f32_16x16x32_bf16 v[2:5], v[180:183], v[228:231], v[2:5]
	s_setprio 1
	s_barrier
	s_mov_b32 s1, s54
	s_add_i32 s54, s54, 2
	s_and_b32 s2, s54, 6
	s_cmp_eq_u32 s2, 0
	s_cselect_b64 s[2:3], -1, 0
	s_cmp_gt_u32 s1, 29
	s_cselect_b64 s[30:31], -1, 0
	s_cmp_lt_u32 s1, 30
	s_cselect_b64 s[34:35], -1, 0
	s_and_b64 s[2:3], s[2:3], s[34:35]
	s_andn2_b64 vcc, exec, s[2:3]
	s_cbranch_vccnz .LBB0_781
	v_mov_b32_e32 v68, v148
	s_nop 0
	v_ashrrev_i32_e32 v69, 31, v68
	v_lshlrev_b64 v[68:69], 13, v[68:69]
	v_lshl_add_u64 v[68:69], s[28:29], 0, v[68:69]
	v_lshl_add_u64 v[68:69], v[150:151], 0, v[68:69]
	v_add_co_u32_e32 v152, vcc, 0xcbff000, v68
	s_nop 1
	v_addc_co_u32_e32 v153, vcc, 0, v69, vcc
	v_add_co_u32_e32 v154, vcc, 0xcc00000, v68
	s_nop 1
	v_addc_co_u32_e32 v155, vcc, 0, v69, vcc
	global_load_dwordx2 v[210:211], v[152:153], off offset:2560
	global_load_dwordx2 v[220:221], v[154:155], off offset:512
	global_load_dwordx2 v[222:223], v[154:155], off offset:640
	global_load_dwordx2 v[224:225], v[152:153], off offset:2688
	v_add_co_u32_e32 v152, vcc, 0xcc1f000, v68
	s_nop 1
	v_addc_co_u32_e32 v153, vcc, 0, v69, vcc
	v_add_co_u32_e32 v154, vcc, 0xcc20000, v68
	s_nop 0
	s_nop 0
	v_addc_co_u32_e32 v155, vcc, 0, v69, vcc
	global_load_dwordx2 v[202:203], v[152:153], off offset:2560
	global_load_dwordx2 v[204:205], v[154:155], off offset:512
	global_load_dwordx2 v[200:201], v[154:155], off offset:640
	global_load_dwordx2 v[198:199], v[152:153], off offset:2688
	v_add_co_u32_e32 v152, vcc, 0xcc3f000, v68
	s_nop 0
	s_nop 0
	v_addc_co_u32_e32 v153, vcc, 0, v69, vcc
	v_add_co_u32_e32 v154, vcc, 0xcc40000, v68
	s_nop 0
	s_nop 0
	v_addc_co_u32_e32 v155, vcc, 0, v69, vcc
	global_load_dwordx2 v[194:195], v[152:153], off offset:2560
	global_load_dwordx2 v[196:197], v[154:155], off offset:512
	global_load_dwordx2 v[192:193], v[154:155], off offset:640
	global_load_dwordx2 v[190:191], v[152:153], off offset:2688
	v_add_co_u32_e32 v152, vcc, 0xcc5f000, v68
	s_nop 0
	s_nop 0
	v_addc_co_u32_e32 v153, vcc, 0, v69, vcc
	v_add_co_u32_e32 v154, vcc, 0xcc60000, v68
	s_nop 1
	v_addc_co_u32_e32 v155, vcc, 0, v69, vcc
	global_load_dwordx2 v[186:187], v[152:153], off offset:2560
	global_load_dwordx2 v[188:189], v[154:155], off offset:512
; __device__ __forceinline__ float gate_v(unsigned q) { return (float)q; }
;     __device__ __forceinline__ void mid(f32x4 (&acc)[2][2][4][2], const Unit& u, int seg, int wr, int wc, int fr, int fq) const {
;     ...
;             for (int m = 0; m < 4; ++m) { const unsigned char* rowp = G + (size_t)(row0 + ai * HALF + m * 16) * 8192 + col0 + seg * 2048;
; #pragma unroll
;                 for (int bj = 0; bj < 2; ++bj) { ga[ai][m][bj] = *(const u32x2v*)(rowp + bj * HALF); gb[ai][m][bj] = *(const u32x2v*)(rowp + 2048 + bj * HALF); } }
; #pragma unroll
;         for (int ai = 0; ai < 2; ++ai)
; #pragma unroll
;             for (int m = 0; m < 4; ++m)
; #pragma unroll
;                 for (int bj = 0; bj < 2; ++bj)
; #pragma unroll
;                     for (int e = 0; e < 8; ++e) { const unsigned a = (ga[ai][m][bj][e >> 2] >> (8 * (e & 3))) & 255u, b = (gb[ai][m][bj][e >> 2] >> (8 * (e & 3))) & 255u;
;                         acc[ai][bj][m][e >> 2][e & 3] *= gate_v(a) * __builtin_amdgcn_rcpf(gate_v(b)); }
	global_load_dwordx2 v[184:185], v[154:155], off offset:640
	global_load_dwordx2 v[182:183], v[152:153], off offset:2688
	v_add_co_u32_e32 v152, vcc, 0xccff000, v68
	s_nop 1
	v_addc_co_u32_e32 v153, vcc, 0, v69, vcc
	v_add_co_u32_e32 v154, vcc, 0xcd00000, v68
	s_nop 1
	v_addc_co_u32_e32 v155, vcc, 0, v69, vcc
	global_load_dwordx2 v[178:179], v[152:153], off offset:2560
	global_load_dwordx2 v[180:181], v[154:155], off offset:512
	global_load_dwordx2 v[176:177], v[154:155], off offset:640
	global_load_dwordx2 v[174:175], v[152:153], off offset:2688
	v_add_co_u32_e32 v152, vcc, 0xcd1f000, v68
	s_nop 1
	v_addc_co_u32_e32 v153, vcc, 0, v69, vcc
	v_add_co_u32_e32 v154, vcc, 0xcd20000, v68
	s_nop 1
	v_addc_co_u32_e32 v155, vcc, 0, v69, vcc
	global_load_dwordx2 v[170:171], v[152:153], off offset:2560
	global_load_dwordx2 v[172:173], v[154:155], off offset:512
	global_load_dwordx2 v[168:169], v[154:155], off offset:640
	global_load_dwordx2 v[166:167], v[152:153], off offset:2688
	v_add_co_u32_e32 v152, vcc, 0xcd3f000, v68
	s_nop 1
	v_addc_co_u32_e32 v153, vcc, 0, v69, vcc
	v_add_co_u32_e32 v154, vcc, 0xcd40000, v68
	s_nop 1
	v_addc_co_u32_e32 v155, vcc, 0, v69, vcc
	v_add_co_u32_e32 v226, vcc, 0xcd5f000, v68
	global_load_dwordx2 v[162:163], v[152:153], off offset:2560
	global_load_dwordx2 v[164:165], v[154:155], off offset:512
	global_load_dwordx2 v[160:161], v[154:155], off offset:640
	global_load_dwordx2 v[158:159], v[152:153], off offset:2688
	v_addc_co_u32_e32 v227, vcc, 0, v69, vcc
	v_add_co_u32_e32 v68, vcc, 0xcd60000, v68
	s_nop 1
	v_addc_co_u32_e32 v69, vcc, 0, v69, vcc
	global_load_dwordx2 v[154:155], v[226:227], off offset:2560
	global_load_dwordx2 v[156:157], v[68:69], off offset:512
	global_load_dwordx2 v[152:153], v[68:69], off offset:640
	s_nop 0
	global_load_dwordx2 v[68:69], v[226:227], off offset:2688
	s_waitcnt vmcnt(28)
	v_cvt_f32_ubyte1_e32 v233, v210
	v_cvt_f32_ubyte0_e32 v66, v220
	v_cvt_f32_ubyte0_e32 v232, v210
	v_cvt_f32_ubyte3_e32 v231, v210
	v_cvt_f32_ubyte2_e32 v230, v210
	v_rcp_iflag_f32_e32 v226, v66
	v_cvt_f32_ubyte1_e32 v66, v220
	v_rcp_iflag_f32_e32 v227, v66
	v_cvt_f32_ubyte2_e32 v66, v220
	v_rcp_iflag_f32_e32 v228, v66
	v_cvt_f32_ubyte3_e32 v66, v220
	v_rcp_iflag_f32_e32 v229, v66
	v_pk_mul_f32 v[226:227], v[226:227], v[232:233]
	v_cvt_f32_ubyte0_e32 v66, v221
	v_pk_mul_f32 v[130:131], v[130:131], v[226:227]
	v_rcp_iflag_f32_e32 v226, v66
	v_cvt_f32_ubyte1_e32 v66, v221
	v_rcp_iflag_f32_e32 v227, v66
	v_cvt_f32_ubyte2_e32 v66, v221
	v_pk_mul_f32 v[228:229], v[228:229], v[230:231]
	v_rcp_iflag_f32_e32 v220, v66
	v_cvt_f32_ubyte3_e32 v66, v221
	v_cvt_f32_ubyte1_e32 v231, v211
	v_cvt_f32_ubyte0_e32 v230, v211
	v_pk_mul_f32 v[132:133], v[132:133], v[228:229]
	v_rcp_iflag_f32_e32 v221, v66
	v_cvt_f32_ubyte3_e32 v229, v211
	v_cvt_f32_ubyte2_e32 v228, v211
	v_pk_mul_f32 v[210:211], v[226:227], v[230:231]
	v_cvt_f32_ubyte0_e32 v66, v222
	v_pk_mul_f32 v[126:127], v[126:127], v[210:211]
	v_rcp_iflag_f32_e32 v210, v66
	v_cvt_f32_ubyte1_e32 v66, v222
	v_rcp_iflag_f32_e32 v211, v66
	v_pk_mul_f32 v[220:221], v[220:221], v[228:229]
	v_cvt_f32_ubyte2_e32 v66, v222
	v_pk_mul_f32 v[128:129], v[128:129], v[220:221]
	v_rcp_iflag_f32_e32 v220, v66
	v_cvt_f32_ubyte3_e32 v66, v222
	v_cvt_f32_ubyte1_e32 v229, v224
	v_cvt_f32_ubyte0_e32 v228, v224
	v_rcp_iflag_f32_e32 v221, v66
	v_pk_mul_f32 v[210:211], v[210:211], v[228:229]
	v_cvt_f32_ubyte0_e32 v66, v223
	v_pk_mul_f32 v[122:123], v[122:123], v[210:211]
	v_rcp_iflag_f32_e32 v210, v66
	v_cvt_f32_ubyte1_e32 v66, v223
	v_rcp_iflag_f32_e32 v211, v66
	v_cvt_f32_ubyte3_e32 v227, v224
	v_cvt_f32_ubyte2_e32 v226, v224
	v_pk_mul_f32 v[220:221], v[220:221], v[226:227]
	v_cvt_f32_ubyte2_e32 v66, v223
	v_pk_mul_f32 v[124:125], v[124:125], v[220:221]
	v_rcp_iflag_f32_e32 v220, v66
	v_cvt_f32_ubyte3_e32 v66, v223
	v_cvt_f32_ubyte1_e32 v227, v225
	v_cvt_f32_ubyte0_e32 v226, v225
	v_rcp_iflag_f32_e32 v221, v66
	v_pk_mul_f32 v[210:211], v[210:211], v[226:227]
	s_waitcnt vmcnt(26)
	v_cvt_f32_ubyte0_e32 v66, v204
	v_pk_mul_f32 v[118:119], v[118:119], v[210:211]
	v_rcp_iflag_f32_e32 v210, v66
	v_cvt_f32_ubyte1_e32 v66, v204
	v_rcp_iflag_f32_e32 v211, v66
	v_cvt_f32_ubyte3_e32 v223, v225
	v_cvt_f32_ubyte2_e32 v222, v225
	v_pk_mul_f32 v[220:221], v[220:221], v[222:223]
	v_cvt_f32_ubyte2_e32 v66, v204
	v_pk_mul_f32 v[120:121], v[120:121], v[220:221]
	v_rcp_iflag_f32_e32 v220, v66
	v_cvt_f32_ubyte3_e32 v66, v204
	v_cvt_f32_ubyte1_e32 v225, v202
	v_cvt_f32_ubyte0_e32 v224, v202
	v_rcp_iflag_f32_e32 v221, v66
	v_pk_mul_f32 v[210:211], v[210:211], v[224:225]
	v_cvt_f32_ubyte0_e32 v66, v205
	v_pk_mul_f32 v[114:115], v[114:115], v[210:211]
	v_rcp_iflag_f32_e32 v210, v66
	v_cvt_f32_ubyte1_e32 v66, v205
	v_rcp_iflag_f32_e32 v211, v66
	v_cvt_f32_ubyte3_e32 v223, v202
	v_cvt_f32_ubyte2_e32 v222, v202
	v_cvt_f32_ubyte2_e32 v66, v205
	v_pk_mul_f32 v[220:221], v[220:221], v[222:223]
	v_rcp_iflag_f32_e32 v204, v66
	v_cvt_f32_ubyte3_e32 v66, v205
	v_cvt_f32_ubyte1_e32 v223, v203
	v_cvt_f32_ubyte0_e32 v222, v203
	v_pk_mul_f32 v[116:117], v[116:117], v[220:221]
	v_rcp_iflag_f32_e32 v205, v66
	v_cvt_f32_ubyte3_e32 v221, v203
	v_cvt_f32_ubyte2_e32 v220, v203
	v_pk_mul_f32 v[202:203], v[210:211], v[222:223]
	s_waitcnt vmcnt(25)
	v_cvt_f32_ubyte0_e32 v66, v200
	v_pk_mul_f32 v[110:111], v[110:111], v[202:203]
	v_rcp_iflag_f32_e32 v202, v66
	v_cvt_f32_ubyte1_e32 v66, v200
	v_rcp_iflag_f32_e32 v203, v66
	v_pk_mul_f32 v[204:205], v[204:205], v[220:221]
	v_cvt_f32_ubyte2_e32 v66, v200
	v_pk_mul_f32 v[112:113], v[112:113], v[204:205]
	v_rcp_iflag_f32_e32 v204, v66
	v_cvt_f32_ubyte3_e32 v66, v200
	s_waitcnt vmcnt(24)
; __device__ __forceinline__ float gate_v(unsigned q) { return (float)q; }
;     __device__ __forceinline__ void mid(f32x4 (&acc)[2][2][4][2], const Unit& u, int seg, int wr, int wc, int fr, int fq) const {
;     ...
;         for (int ai = 0; ai < 2; ++ai)
; #pragma unroll
;             for (int m = 0; m < 4; ++m)
; #pragma unroll
;                 for (int bj = 0; bj < 2; ++bj)
; #pragma unroll
;                     for (int e = 0; e < 8; ++e) { const unsigned a = (ga[ai][m][bj][e >> 2] >> (8 * (e & 3))) & 255u, b = (gb[ai][m][bj][e >> 2] >> (8 * (e & 3))) & 255u;
;                         acc[ai][bj][m][e >> 2][e & 3] *= gate_v(a) * __builtin_amdgcn_rcpf(gate_v(b)); }
	v_cvt_f32_ubyte1_e32 v221, v198
	v_cvt_f32_ubyte0_e32 v220, v198
	v_rcp_iflag_f32_e32 v205, v66
	v_pk_mul_f32 v[202:203], v[202:203], v[220:221]
	v_cvt_f32_ubyte0_e32 v66, v201
	v_pk_mul_f32 v[106:107], v[106:107], v[202:203]
	v_rcp_iflag_f32_e32 v202, v66
	v_cvt_f32_ubyte1_e32 v66, v201
	v_rcp_iflag_f32_e32 v203, v66
	v_cvt_f32_ubyte3_e32 v211, v198
	v_cvt_f32_ubyte2_e32 v210, v198
	v_cvt_f32_ubyte2_e32 v66, v201
	v_pk_mul_f32 v[204:205], v[204:205], v[210:211]
	v_rcp_iflag_f32_e32 v200, v66
	v_cvt_f32_ubyte3_e32 v66, v201
	v_cvt_f32_ubyte1_e32 v211, v199
	v_cvt_f32_ubyte0_e32 v210, v199
	v_pk_mul_f32 v[108:109], v[108:109], v[204:205]
	v_rcp_iflag_f32_e32 v201, v66
	v_cvt_f32_ubyte3_e32 v205, v199
	v_cvt_f32_ubyte2_e32 v204, v199
	v_pk_mul_f32 v[198:199], v[202:203], v[210:211]
	s_waitcnt vmcnt(22)
	v_cvt_f32_ubyte0_e32 v66, v196
	v_pk_mul_f32 v[102:103], v[102:103], v[198:199]
	v_rcp_iflag_f32_e32 v198, v66
	v_cvt_f32_ubyte1_e32 v66, v196
	v_rcp_iflag_f32_e32 v199, v66
	v_pk_mul_f32 v[200:201], v[200:201], v[204:205]
	v_cvt_f32_ubyte2_e32 v66, v196
	v_pk_mul_f32 v[104:105], v[104:105], v[200:201]
	v_rcp_iflag_f32_e32 v200, v66
	v_cvt_f32_ubyte3_e32 v66, v196
	v_cvt_f32_ubyte1_e32 v205, v194
	v_cvt_f32_ubyte0_e32 v204, v194
	v_rcp_iflag_f32_e32 v201, v66
	v_pk_mul_f32 v[198:199], v[198:199], v[204:205]
	v_cvt_f32_ubyte0_e32 v66, v197
	v_pk_mul_f32 v[98:99], v[98:99], v[198:199]
	v_rcp_iflag_f32_e32 v198, v66
	v_cvt_f32_ubyte1_e32 v66, v197
	v_rcp_iflag_f32_e32 v199, v66
	v_cvt_f32_ubyte3_e32 v203, v194
	v_cvt_f32_ubyte2_e32 v202, v194
	v_cvt_f32_ubyte2_e32 v66, v197
	v_pk_mul_f32 v[200:201], v[200:201], v[202:203]
	v_rcp_iflag_f32_e32 v196, v66
	v_cvt_f32_ubyte3_e32 v66, v197
	v_cvt_f32_ubyte1_e32 v203, v195
	v_cvt_f32_ubyte0_e32 v202, v195
	v_pk_mul_f32 v[100:101], v[100:101], v[200:201]
	v_rcp_iflag_f32_e32 v197, v66
	v_cvt_f32_ubyte3_e32 v201, v195
	v_cvt_f32_ubyte2_e32 v200, v195
	v_pk_mul_f32 v[194:195], v[198:199], v[202:203]
	s_waitcnt vmcnt(21)
	v_cvt_f32_ubyte0_e32 v66, v192
	v_pk_mul_f32 v[94:95], v[94:95], v[194:195]
	v_rcp_iflag_f32_e32 v194, v66
	v_cvt_f32_ubyte1_e32 v66, v192
	v_rcp_iflag_f32_e32 v195, v66
	v_pk_mul_f32 v[196:197], v[196:197], v[200:201]
	v_cvt_f32_ubyte2_e32 v66, v192
	v_pk_mul_f32 v[96:97], v[96:97], v[196:197]
	v_rcp_iflag_f32_e32 v196, v66
	v_cvt_f32_ubyte3_e32 v66, v192
	s_waitcnt vmcnt(20)
	v_cvt_f32_ubyte1_e32 v201, v190
	v_cvt_f32_ubyte0_e32 v200, v190
	v_rcp_iflag_f32_e32 v197, v66
	v_pk_mul_f32 v[194:195], v[194:195], v[200:201]
	v_cvt_f32_ubyte0_e32 v66, v193
	v_pk_mul_f32 v[90:91], v[90:91], v[194:195]
	v_rcp_iflag_f32_e32 v194, v66
	v_cvt_f32_ubyte1_e32 v66, v193
	v_rcp_iflag_f32_e32 v195, v66
	v_cvt_f32_ubyte3_e32 v199, v190
	v_cvt_f32_ubyte2_e32 v198, v190
	v_cvt_f32_ubyte2_e32 v66, v193
	v_pk_mul_f32 v[196:197], v[196:197], v[198:199]
	v_rcp_iflag_f32_e32 v192, v66
	v_cvt_f32_ubyte3_e32 v66, v193
	v_cvt_f32_ubyte1_e32 v199, v191
	v_cvt_f32_ubyte0_e32 v198, v191
	v_pk_mul_f32 v[92:93], v[92:93], v[196:197]
	v_rcp_iflag_f32_e32 v193, v66
	v_cvt_f32_ubyte3_e32 v197, v191
	v_cvt_f32_ubyte2_e32 v196, v191
	v_pk_mul_f32 v[190:191], v[194:195], v[198:199]
	s_waitcnt vmcnt(18)
	v_cvt_f32_ubyte0_e32 v66, v188
	v_pk_mul_f32 v[86:87], v[86:87], v[190:191]
	v_rcp_iflag_f32_e32 v190, v66
	v_cvt_f32_ubyte1_e32 v66, v188
	v_rcp_iflag_f32_e32 v191, v66
	v_pk_mul_f32 v[192:193], v[192:193], v[196:197]
	v_cvt_f32_ubyte2_e32 v66, v188
	v_pk_mul_f32 v[88:89], v[88:89], v[192:193]
	v_rcp_iflag_f32_e32 v192, v66
	v_cvt_f32_ubyte3_e32 v66, v188
	v_cvt_f32_ubyte1_e32 v197, v186
	v_cvt_f32_ubyte0_e32 v196, v186
	v_rcp_iflag_f32_e32 v193, v66
	v_pk_mul_f32 v[190:191], v[190:191], v[196:197]
	v_cvt_f32_ubyte0_e32 v66, v189
	v_pk_mul_f32 v[82:83], v[82:83], v[190:191]
	v_rcp_iflag_f32_e32 v190, v66
	v_cvt_f32_ubyte1_e32 v66, v189
	v_rcp_iflag_f32_e32 v191, v66
	v_cvt_f32_ubyte3_e32 v195, v186
	v_cvt_f32_ubyte2_e32 v194, v186
	v_cvt_f32_ubyte2_e32 v66, v189
	v_pk_mul_f32 v[192:193], v[192:193], v[194:195]
	v_rcp_iflag_f32_e32 v188, v66
	v_cvt_f32_ubyte3_e32 v66, v189
	v_cvt_f32_ubyte1_e32 v195, v187
	v_cvt_f32_ubyte0_e32 v194, v187
	v_pk_mul_f32 v[84:85], v[84:85], v[192:193]
	v_rcp_iflag_f32_e32 v189, v66
	v_cvt_f32_ubyte3_e32 v193, v187
	v_cvt_f32_ubyte2_e32 v192, v187
	v_pk_mul_f32 v[186:187], v[190:191], v[194:195]
	s_waitcnt vmcnt(17)
	v_cvt_f32_ubyte0_e32 v66, v184
	v_pk_mul_f32 v[78:79], v[78:79], v[186:187]
	v_rcp_iflag_f32_e32 v186, v66
	v_cvt_f32_ubyte1_e32 v66, v184
	v_rcp_iflag_f32_e32 v187, v66
	v_pk_mul_f32 v[188:189], v[188:189], v[192:193]
	v_cvt_f32_ubyte2_e32 v66, v184
	v_pk_mul_f32 v[80:81], v[80:81], v[188:189]
	v_rcp_iflag_f32_e32 v188, v66
	v_cvt_f32_ubyte3_e32 v66, v184
	s_waitcnt vmcnt(16)
	v_cvt_f32_ubyte1_e32 v193, v182
	v_cvt_f32_ubyte0_e32 v192, v182
	v_rcp_iflag_f32_e32 v189, v66
	v_pk_mul_f32 v[186:187], v[186:187], v[192:193]
	v_cvt_f32_ubyte0_e32 v66, v185
	v_pk_mul_f32 v[74:75], v[74:75], v[186:187]
	v_rcp_iflag_f32_e32 v186, v66
	v_cvt_f32_ubyte1_e32 v66, v185
	v_rcp_iflag_f32_e32 v187, v66
	v_cvt_f32_ubyte3_e32 v191, v182
	v_cvt_f32_ubyte2_e32 v190, v182
	v_cvt_f32_ubyte2_e32 v66, v185
	v_pk_mul_f32 v[188:189], v[188:189], v[190:191]
	v_rcp_iflag_f32_e32 v184, v66
	v_cvt_f32_ubyte3_e32 v66, v185
	v_cvt_f32_ubyte1_e32 v191, v183
	v_cvt_f32_ubyte0_e32 v190, v183
	v_pk_mul_f32 v[76:77], v[76:77], v[188:189]
	v_rcp_iflag_f32_e32 v185, v66
	v_cvt_f32_ubyte3_e32 v189, v183
	v_cvt_f32_ubyte2_e32 v188, v183
	v_pk_mul_f32 v[182:183], v[186:187], v[190:191]
	s_waitcnt vmcnt(14)
; __device__ __forceinline__ float gate_v(unsigned q) { return (float)q; }
;     __device__ __forceinline__ void mid(f32x4 (&acc)[2][2][4][2], const Unit& u, int seg, int wr, int wc, int fr, int fq) const {
;     ...
;         for (int ai = 0; ai < 2; ++ai)
; #pragma unroll
;             for (int m = 0; m < 4; ++m)
; #pragma unroll
;                 for (int bj = 0; bj < 2; ++bj)
; #pragma unroll
;                     for (int e = 0; e < 8; ++e) { const unsigned a = (ga[ai][m][bj][e >> 2] >> (8 * (e & 3))) & 255u, b = (gb[ai][m][bj][e >> 2] >> (8 * (e & 3))) & 255u;
;                         acc[ai][bj][m][e >> 2][e & 3] *= gate_v(a) * __builtin_amdgcn_rcpf(gate_v(b)); }
	v_cvt_f32_ubyte0_e32 v66, v180
	v_pk_mul_f32 v[70:71], v[70:71], v[182:183]
	v_rcp_iflag_f32_e32 v182, v66
	v_cvt_f32_ubyte1_e32 v66, v180
	v_rcp_iflag_f32_e32 v183, v66
	v_pk_mul_f32 v[184:185], v[184:185], v[188:189]
	v_cvt_f32_ubyte2_e32 v66, v180
	v_pk_mul_f32 v[72:73], v[72:73], v[184:185]
	v_rcp_iflag_f32_e32 v184, v66
	v_cvt_f32_ubyte3_e32 v66, v180
	v_cvt_f32_ubyte1_e32 v189, v178
	v_cvt_f32_ubyte0_e32 v188, v178
	v_rcp_iflag_f32_e32 v185, v66
	v_pk_mul_f32 v[182:183], v[182:183], v[188:189]
	v_cvt_f32_ubyte0_e32 v66, v181
	v_pk_mul_f32 v[62:63], v[62:63], v[182:183]
	v_rcp_iflag_f32_e32 v182, v66
	v_cvt_f32_ubyte1_e32 v66, v181
	v_rcp_iflag_f32_e32 v183, v66
	v_cvt_f32_ubyte3_e32 v187, v178
	v_cvt_f32_ubyte2_e32 v186, v178
	v_cvt_f32_ubyte2_e32 v66, v181
	v_pk_mul_f32 v[184:185], v[184:185], v[186:187]
	v_rcp_iflag_f32_e32 v180, v66
	v_cvt_f32_ubyte3_e32 v66, v181
	v_cvt_f32_ubyte1_e32 v187, v179
	v_cvt_f32_ubyte0_e32 v186, v179
	v_pk_mul_f32 v[64:65], v[64:65], v[184:185]
	v_rcp_iflag_f32_e32 v181, v66
	v_cvt_f32_ubyte3_e32 v185, v179
	v_cvt_f32_ubyte2_e32 v184, v179
	v_pk_mul_f32 v[178:179], v[182:183], v[186:187]
	s_waitcnt vmcnt(13)
	v_cvt_f32_ubyte0_e32 v66, v176
	v_pk_mul_f32 v[58:59], v[58:59], v[178:179]
	v_rcp_iflag_f32_e32 v178, v66
	v_cvt_f32_ubyte1_e32 v66, v176
	v_rcp_iflag_f32_e32 v179, v66
	v_pk_mul_f32 v[180:181], v[180:181], v[184:185]
	v_cvt_f32_ubyte2_e32 v66, v176
	v_pk_mul_f32 v[60:61], v[60:61], v[180:181]
	v_rcp_iflag_f32_e32 v180, v66
	v_cvt_f32_ubyte3_e32 v66, v176
	s_waitcnt vmcnt(12)
	v_cvt_f32_ubyte1_e32 v185, v174
	v_cvt_f32_ubyte0_e32 v184, v174
	v_rcp_iflag_f32_e32 v181, v66
	v_pk_mul_f32 v[178:179], v[178:179], v[184:185]
	v_cvt_f32_ubyte0_e32 v66, v177
	v_pk_mul_f32 v[54:55], v[54:55], v[178:179]
	v_rcp_iflag_f32_e32 v178, v66
	v_cvt_f32_ubyte1_e32 v66, v177
	v_rcp_iflag_f32_e32 v179, v66
	v_cvt_f32_ubyte3_e32 v183, v174
	v_cvt_f32_ubyte2_e32 v182, v174
	v_cvt_f32_ubyte2_e32 v66, v177
	v_pk_mul_f32 v[180:181], v[180:181], v[182:183]
	v_rcp_iflag_f32_e32 v176, v66
	v_cvt_f32_ubyte3_e32 v66, v177
	v_cvt_f32_ubyte1_e32 v183, v175
	v_cvt_f32_ubyte0_e32 v182, v175
	v_pk_mul_f32 v[56:57], v[56:57], v[180:181]
	v_rcp_iflag_f32_e32 v177, v66
	v_cvt_f32_ubyte3_e32 v181, v175
	v_cvt_f32_ubyte2_e32 v180, v175
	v_pk_mul_f32 v[174:175], v[178:179], v[182:183]
	s_waitcnt vmcnt(10)
	v_cvt_f32_ubyte0_e32 v66, v172
	v_pk_mul_f32 v[50:51], v[50:51], v[174:175]
	v_rcp_iflag_f32_e32 v174, v66
	v_cvt_f32_ubyte1_e32 v66, v172
	v_rcp_iflag_f32_e32 v175, v66
	v_pk_mul_f32 v[176:177], v[176:177], v[180:181]
	v_cvt_f32_ubyte2_e32 v66, v172
	v_pk_mul_f32 v[52:53], v[52:53], v[176:177]
	v_rcp_iflag_f32_e32 v176, v66
	v_cvt_f32_ubyte3_e32 v66, v172
	v_cvt_f32_ubyte1_e32 v181, v170
	v_cvt_f32_ubyte0_e32 v180, v170
	v_rcp_iflag_f32_e32 v177, v66
	v_pk_mul_f32 v[174:175], v[174:175], v[180:181]
	v_cvt_f32_ubyte0_e32 v66, v173
	v_pk_mul_f32 v[46:47], v[46:47], v[174:175]
	v_rcp_iflag_f32_e32 v174, v66
	v_cvt_f32_ubyte1_e32 v66, v173
	v_rcp_iflag_f32_e32 v175, v66
	v_cvt_f32_ubyte3_e32 v179, v170
	v_cvt_f32_ubyte2_e32 v178, v170
	v_cvt_f32_ubyte2_e32 v66, v173
	v_pk_mul_f32 v[176:177], v[176:177], v[178:179]
	v_rcp_iflag_f32_e32 v172, v66
	v_cvt_f32_ubyte3_e32 v66, v173
	v_cvt_f32_ubyte1_e32 v179, v171
	v_cvt_f32_ubyte0_e32 v178, v171
	v_pk_mul_f32 v[48:49], v[48:49], v[176:177]
	v_rcp_iflag_f32_e32 v173, v66
	v_cvt_f32_ubyte3_e32 v177, v171
	v_cvt_f32_ubyte2_e32 v176, v171
	v_pk_mul_f32 v[170:171], v[174:175], v[178:179]
	s_waitcnt vmcnt(9)
	v_cvt_f32_ubyte0_e32 v66, v168
	v_pk_mul_f32 v[42:43], v[42:43], v[170:171]
	v_rcp_iflag_f32_e32 v170, v66
	v_cvt_f32_ubyte1_e32 v66, v168
	v_rcp_iflag_f32_e32 v171, v66
	v_pk_mul_f32 v[172:173], v[172:173], v[176:177]
	v_cvt_f32_ubyte2_e32 v66, v168
	v_pk_mul_f32 v[44:45], v[44:45], v[172:173]
	v_rcp_iflag_f32_e32 v172, v66
	v_cvt_f32_ubyte3_e32 v66, v168
	s_waitcnt vmcnt(8)
	v_cvt_f32_ubyte1_e32 v177, v166
	v_cvt_f32_ubyte0_e32 v176, v166
	v_rcp_iflag_f32_e32 v173, v66
	v_pk_mul_f32 v[170:171], v[170:171], v[176:177]
	v_cvt_f32_ubyte0_e32 v66, v169
	v_pk_mul_f32 v[38:39], v[38:39], v[170:171]
	v_rcp_iflag_f32_e32 v170, v66
	v_cvt_f32_ubyte1_e32 v66, v169
	v_rcp_iflag_f32_e32 v171, v66
	v_cvt_f32_ubyte3_e32 v175, v166
	v_cvt_f32_ubyte2_e32 v174, v166
	v_cvt_f32_ubyte2_e32 v66, v169
	v_pk_mul_f32 v[172:173], v[172:173], v[174:175]
	v_rcp_iflag_f32_e32 v168, v66
	v_cvt_f32_ubyte3_e32 v66, v169
	v_cvt_f32_ubyte1_e32 v175, v167
	v_cvt_f32_ubyte0_e32 v174, v167
	v_pk_mul_f32 v[40:41], v[40:41], v[172:173]
	v_rcp_iflag_f32_e32 v169, v66
	v_cvt_f32_ubyte3_e32 v173, v167
	v_cvt_f32_ubyte2_e32 v172, v167
	v_pk_mul_f32 v[166:167], v[170:171], v[174:175]
	s_waitcnt vmcnt(6)
; __device__ __forceinline__ float gate_v(unsigned q) { return (float)q; }
;     __device__ __forceinline__ void mid(f32x4 (&acc)[2][2][4][2], const Unit& u, int seg, int wr, int wc, int fr, int fq) const {
;     ...
;         for (int ai = 0; ai < 2; ++ai)
; #pragma unroll
;             for (int m = 0; m < 4; ++m)
; #pragma unroll
;                 for (int bj = 0; bj < 2; ++bj)
; #pragma unroll
;                     for (int e = 0; e < 8; ++e) { const unsigned a = (ga[ai][m][bj][e >> 2] >> (8 * (e & 3))) & 255u, b = (gb[ai][m][bj][e >> 2] >> (8 * (e & 3))) & 255u;
;                         acc[ai][bj][m][e >> 2][e & 3] *= gate_v(a) * __builtin_amdgcn_rcpf(gate_v(b)); }
	v_cvt_f32_ubyte0_e32 v66, v164
	v_pk_mul_f32 v[34:35], v[34:35], v[166:167]
	v_rcp_iflag_f32_e32 v166, v66
	v_cvt_f32_ubyte1_e32 v66, v164
	v_rcp_iflag_f32_e32 v167, v66
	v_pk_mul_f32 v[168:169], v[168:169], v[172:173]
	v_cvt_f32_ubyte2_e32 v66, v164
	v_pk_mul_f32 v[36:37], v[36:37], v[168:169]
	v_rcp_iflag_f32_e32 v168, v66
	v_cvt_f32_ubyte3_e32 v66, v164
	v_cvt_f32_ubyte1_e32 v173, v162
	v_cvt_f32_ubyte0_e32 v172, v162
	v_rcp_iflag_f32_e32 v169, v66
	v_pk_mul_f32 v[166:167], v[166:167], v[172:173]
	v_cvt_f32_ubyte0_e32 v66, v165
	v_pk_mul_f32 v[30:31], v[30:31], v[166:167]
	v_rcp_iflag_f32_e32 v166, v66
	v_cvt_f32_ubyte1_e32 v66, v165
	v_rcp_iflag_f32_e32 v167, v66
	v_cvt_f32_ubyte3_e32 v171, v162
	v_cvt_f32_ubyte2_e32 v170, v162
	v_cvt_f32_ubyte2_e32 v66, v165
	v_pk_mul_f32 v[168:169], v[168:169], v[170:171]
	v_rcp_iflag_f32_e32 v164, v66
	v_cvt_f32_ubyte3_e32 v66, v165
	v_cvt_f32_ubyte1_e32 v171, v163
	v_cvt_f32_ubyte0_e32 v170, v163
	v_pk_mul_f32 v[32:33], v[32:33], v[168:169]
	v_rcp_iflag_f32_e32 v165, v66
	v_cvt_f32_ubyte3_e32 v169, v163
	v_cvt_f32_ubyte2_e32 v168, v163
	v_pk_mul_f32 v[162:163], v[166:167], v[170:171]
	s_waitcnt vmcnt(5)
	v_cvt_f32_ubyte0_e32 v66, v160
	v_pk_mul_f32 v[26:27], v[26:27], v[162:163]
	v_rcp_iflag_f32_e32 v162, v66
	v_cvt_f32_ubyte1_e32 v66, v160
	v_rcp_iflag_f32_e32 v163, v66
	v_pk_mul_f32 v[164:165], v[164:165], v[168:169]
	v_cvt_f32_ubyte2_e32 v66, v160
	v_pk_mul_f32 v[28:29], v[28:29], v[164:165]
	v_rcp_iflag_f32_e32 v164, v66
	v_cvt_f32_ubyte3_e32 v66, v160
	s_waitcnt vmcnt(4)
	v_cvt_f32_ubyte1_e32 v169, v158
	v_cvt_f32_ubyte0_e32 v168, v158
	v_rcp_iflag_f32_e32 v165, v66
	v_pk_mul_f32 v[162:163], v[162:163], v[168:169]
	v_cvt_f32_ubyte0_e32 v66, v161
	v_pk_mul_f32 v[22:23], v[22:23], v[162:163]
	v_rcp_iflag_f32_e32 v162, v66
	v_cvt_f32_ubyte1_e32 v66, v161
	v_rcp_iflag_f32_e32 v163, v66
	v_cvt_f32_ubyte3_e32 v167, v158
	v_cvt_f32_ubyte2_e32 v166, v158
	v_cvt_f32_ubyte2_e32 v66, v161
	v_pk_mul_f32 v[164:165], v[164:165], v[166:167]
	v_rcp_iflag_f32_e32 v160, v66
	v_cvt_f32_ubyte3_e32 v66, v161
	v_cvt_f32_ubyte1_e32 v167, v159
	v_cvt_f32_ubyte0_e32 v166, v159
	v_pk_mul_f32 v[24:25], v[24:25], v[164:165]
	v_rcp_iflag_f32_e32 v161, v66
	v_cvt_f32_ubyte3_e32 v165, v159
	v_cvt_f32_ubyte2_e32 v164, v159
	v_pk_mul_f32 v[158:159], v[162:163], v[166:167]
	s_waitcnt vmcnt(2)
	v_cvt_f32_ubyte0_e32 v66, v156
	v_pk_mul_f32 v[18:19], v[18:19], v[158:159]
	v_rcp_iflag_f32_e32 v158, v66
	v_cvt_f32_ubyte1_e32 v66, v156
	v_rcp_iflag_f32_e32 v159, v66
	v_pk_mul_f32 v[160:161], v[160:161], v[164:165]
	v_cvt_f32_ubyte2_e32 v66, v156
	v_pk_mul_f32 v[20:21], v[20:21], v[160:161]
	v_rcp_iflag_f32_e32 v160, v66
	v_cvt_f32_ubyte3_e32 v66, v156
	v_cvt_f32_ubyte1_e32 v165, v154
	v_cvt_f32_ubyte0_e32 v164, v154
	v_rcp_iflag_f32_e32 v161, v66
	v_pk_mul_f32 v[158:159], v[158:159], v[164:165]
	v_cvt_f32_ubyte0_e32 v66, v157
	v_pk_mul_f32 v[14:15], v[14:15], v[158:159]
	v_rcp_iflag_f32_e32 v158, v66
	v_cvt_f32_ubyte1_e32 v66, v157
	v_rcp_iflag_f32_e32 v159, v66
	v_cvt_f32_ubyte3_e32 v163, v154
	v_cvt_f32_ubyte2_e32 v162, v154
	v_cvt_f32_ubyte2_e32 v66, v157
	v_pk_mul_f32 v[160:161], v[160:161], v[162:163]
	v_rcp_iflag_f32_e32 v156, v66
	v_cvt_f32_ubyte3_e32 v66, v157
	v_cvt_f32_ubyte1_e32 v163, v155
	v_cvt_f32_ubyte0_e32 v162, v155
	v_pk_mul_f32 v[16:17], v[16:17], v[160:161]
	v_rcp_iflag_f32_e32 v157, v66
	v_cvt_f32_ubyte3_e32 v161, v155
	v_cvt_f32_ubyte2_e32 v160, v155
	v_pk_mul_f32 v[154:155], v[158:159], v[162:163]
	s_waitcnt vmcnt(1)
	v_cvt_f32_ubyte0_e32 v66, v152
	v_pk_mul_f32 v[10:11], v[10:11], v[154:155]
	v_rcp_iflag_f32_e32 v154, v66
	v_cvt_f32_ubyte1_e32 v66, v152
	v_rcp_iflag_f32_e32 v155, v66
	v_pk_mul_f32 v[156:157], v[156:157], v[160:161]
	v_cvt_f32_ubyte2_e32 v66, v152
	v_pk_mul_f32 v[12:13], v[12:13], v[156:157]
	v_rcp_iflag_f32_e32 v156, v66
	v_cvt_f32_ubyte3_e32 v66, v152
	s_waitcnt vmcnt(0)
	v_cvt_f32_ubyte1_e32 v161, v68
	v_cvt_f32_ubyte0_e32 v160, v68
	v_rcp_iflag_f32_e32 v157, v66
	v_pk_mul_f32 v[154:155], v[154:155], v[160:161]
	v_cvt_f32_ubyte0_e32 v66, v153
	v_pk_mul_f32 v[6:7], v[6:7], v[154:155]
	v_rcp_iflag_f32_e32 v154, v66
	v_cvt_f32_ubyte1_e32 v66, v153
	v_rcp_iflag_f32_e32 v155, v66
	v_cvt_f32_ubyte2_e32 v66, v153
	v_rcp_iflag_f32_e32 v152, v66
	v_cvt_f32_ubyte3_e32 v66, v153
	v_rcp_iflag_f32_e32 v153, v66
	v_cvt_f32_ubyte3_e32 v159, v68
	v_cvt_f32_ubyte2_e32 v158, v68
	v_pk_mul_f32 v[156:157], v[156:157], v[158:159]
	v_cvt_f32_ubyte1_e32 v159, v69
	v_pk_mul_f32 v[8:9], v[8:9], v[156:157]
	v_cvt_f32_ubyte3_e32 v157, v69
	v_cvt_f32_ubyte2_e32 v156, v69
	v_cvt_f32_ubyte0_e32 v158, v69
	v_pk_mul_f32 v[68:69], v[154:155], v[158:159]
	v_pk_mul_f32 v[152:153], v[152:153], v[156:157]
	v_pk_mul_f32 v[2:3], v[2:3], v[68:69]
	v_pk_mul_f32 v[4:5], v[4:5], v[152:153]
	s_branch .LBB0_781

;     __host__ __device__ bool next(int i, Unit& u) const { if (i != 0 || r < 0 || r >= 148) return false; if (r < 116) { u.pm = r % 29; u.pn = 47 + r / 29; } else { u.pm = 32; u.pn = 19 + (r - 116); } u.ko = 0; return true; }
;     __host__ __device__ bool next(int i, Unit& u) const { const int L = i * G + (G - 1 - c); if (L >= nN * S) return false; u.pm = pm; u.pn = L % nN; u.ko = (L / nN) * ksub; return true; }
; #define PG8_STAGE(bufoff, gbase, voff) do { _Pragma("unroll") for (int _i = 0; _i < 2; ++_i) \
;         __builtin_amdgcn_global_load_lds((const unsigned*)((const char*)(gbase) + (voff)[_i]), (PG8_LAS unsigned*)(lds + (bufoff) + ldsw + _i * 8192), 16, 0, 0); } while (0)
; #define PG8_LDA(dst, b, h) do { _Pragma("unroll") for (int m = 0; m < 4; ++m) _Pragma("unroll") for (int k = 0; k < 2; ++k) dst[m][k] = *(const PG8_LAS bf16x8*)(lds + PG8_SA(b, h) + aoff + m * 2048 + k * 1024); } while (0)
; #define PG8_WAIT_V(n) asm volatile("s_waitcnt vmcnt(" #n ")" ::: "memory")
; #define PG8_WAIT_L(n) asm volatile("s_waitcnt lgkmcnt(" #n ")" ::: "memory")
; template <class Epi, class Sched, bool ALIGN_EPI = false, bool SP2 = false>
; __device__ __forceinline__ void gemm_phase(PG8_LAS unsigned char* lds, const Gemm g, const Sched& S, const Epi& E) {
;     ...
;     for (;;) {
;         const bool has_next = S.next(ui + 1, nxt);
;         const char* nA = has_next ? (const char*)g.A + (size_t)nxt.pm * tstep + (size_t)nxt.ko * 2 : cA; const char* nB = has_next ? (const char*)g.Bt + (size_t)nxt.pn * tstep + (size_t)nxt.ko * 2 : cB;
;         for (int t = 0; t < nt; t += 2) {
;             const bool last = (t == nt - 2);
;             const char* a1 = cA + (size_t)(t + 1) * kstep;
;             const char* a2 = last ? nA : cA + (size_t)(t + 2) * kstep; const char* b2 = last ? nB : cB + (size_t)(t + 2) * kstep;
;             const char* a3 = a2 + kstep; const char* b3 = b2 + kstep;
;             if (last && has_next) S.a_ready(nxt);
;             if constexpr (SP2) {
;             PG8_LDB(B0, 0, 0); PG8_LDB(B1, 0, 1); PG8_SCHED; PG8_LDA(At, 0, 0); PG8_STAGE(PG8_SA(1, 1), a1 + hstep, voffA);
;             PG8_WAIT_V(8); PG8_WAIT_L(0); PG8_BAR; PG8_MMA(0, 0, At, B0); PG8_MMA(0, 1, At, B1); PG8_BAR; PG8_SCHED;
;             PG8_LDA(At, 0, 1); PG8_STAGE(PG8_SB(0, 0), b2, voffB); PG8_STAGE(PG8_SB(0, 1), b2 + hstep, voffB); PG8_STAGE(PG8_SA(0, 0), a2, voffA);
.LBB0_802:
	s_add_u32 s22, s20, 0x100
	s_addc_u32 s23, s21, 0
	s_cmp_eq_u32 s43, 4
	s_cselect_b32 s27, s19, s23
	s_cselect_b32 s26, s18, s22
	s_cselect_b32 s25, s17, s15
	s_cselect_b32 s24, s16, s13
	s_add_i32 s44, 0, 0x10000
	s_add_i32 s45, 0, 0x14000
	v_add_u32_e32 v168, s44, v0
	v_add_u32_e32 v184, s45, v0
	ds_read_b128 v[156:159], v168
	ds_read_b128 v[160:163], v168 offset:1024
	ds_read_b128 v[164:167], v168 offset:2048
	ds_read_b128 v[168:171], v168 offset:3072
	ds_read_b128 v[172:175], v184
	ds_read_b128 v[176:179], v184 offset:1024
	ds_read_b128 v[180:183], v184 offset:2048
	ds_read_b128 v[184:187], v184 offset:3072
	v_lshl_add_u64 v[228:229], s[20:21], 0, v[150:151]
	s_add_i32 m0, s30, 0xc000
	ds_read_b128 v[188:191], v155
	ds_read_b128 v[192:195], v155 offset:1024
	ds_read_b128 v[196:199], v155 offset:2048
	ds_read_b128 v[200:203], v155 offset:3072
	ds_read_b128 v[204:207], v155 offset:4096
	ds_read_b128 v[208:211], v155 offset:5120
	ds_read_b128 v[220:223], v155 offset:6144
	ds_read_b128 v[224:227], v155 offset:7168
	global_load_lds_dwordx4 v[228:229], off
	v_lshl_add_u64 v[228:229], s[20:21], 0, v[152:153]
	s_add_i32 m0, s30, 0xe000
	s_nop 0
	global_load_lds_dwordx4 v[228:229], off
	s_waitcnt vmcnt(8)
	s_waitcnt lgkmcnt(0)
	s_barrier
	s_setprio 0
	s_waitcnt lgkmcnt(0)
	v_mfma_f32_16x16x32_bf16 v[128:131], v[156:159], v[188:191], v[128:131]
	v_mfma_f32_16x16x32_bf16 v[124:127], v[164:167], v[188:191], v[124:127]
	v_mfma_f32_16x16x32_bf16 v[120:123], v[156:159], v[196:199], v[120:123]
	v_mfma_f32_16x16x32_bf16 v[116:119], v[164:167], v[196:199], v[116:119]
	v_mfma_f32_16x16x32_bf16 v[112:115], v[156:159], v[204:207], v[112:115]
	v_mfma_f32_16x16x32_bf16 v[108:111], v[164:167], v[204:207], v[108:111]
	v_mfma_f32_16x16x32_bf16 v[100:103], v[156:159], v[220:223], v[100:103]
	v_mfma_f32_16x16x32_bf16 v[92:95], v[164:167], v[220:223], v[92:95]
	v_mfma_f32_16x16x32_bf16 v[128:131], v[160:163], v[192:195], v[128:131]
	v_mfma_f32_16x16x32_bf16 v[124:127], v[168:171], v[192:195], v[124:127]
	v_mfma_f32_16x16x32_bf16 v[120:123], v[160:163], v[200:203], v[120:123]
	v_mfma_f32_16x16x32_bf16 v[116:119], v[168:171], v[200:203], v[116:119]
	v_mfma_f32_16x16x32_bf16 v[112:115], v[160:163], v[208:211], v[112:115]
	v_mfma_f32_16x16x32_bf16 v[108:111], v[168:171], v[208:211], v[108:111]
	v_mfma_f32_16x16x32_bf16 v[100:103], v[160:163], v[224:227], v[100:103]
	v_mfma_f32_16x16x32_bf16 v[92:95], v[168:171], v[224:227], v[92:95]
	s_setprio 0
	s_setprio 0
	v_mfma_f32_16x16x32_bf16 v[104:107], v[172:175], v[188:191], v[104:107]
	v_mfma_f32_16x16x32_bf16 v[96:99], v[180:183], v[188:191], v[96:99]
	v_mfma_f32_16x16x32_bf16 v[88:91], v[172:175], v[196:199], v[88:91]
	v_mfma_f32_16x16x32_bf16 v[84:87], v[180:183], v[196:199], v[84:87]
	v_mfma_f32_16x16x32_bf16 v[80:83], v[172:175], v[204:207], v[80:83]
	v_mfma_f32_16x16x32_bf16 v[76:79], v[180:183], v[204:207], v[76:79]
	v_mfma_f32_16x16x32_bf16 v[72:75], v[172:175], v[220:223], v[72:75]
	v_mfma_f32_16x16x32_bf16 v[68:71], v[180:183], v[220:223], v[68:71]
	v_mfma_f32_16x16x32_bf16 v[104:107], v[176:179], v[192:195], v[104:107]
	v_mfma_f32_16x16x32_bf16 v[96:99], v[184:187], v[192:195], v[96:99]
	v_mfma_f32_16x16x32_bf16 v[88:91], v[176:179], v[200:203], v[88:91]
	v_mfma_f32_16x16x32_bf16 v[84:87], v[184:187], v[200:203], v[84:87]
	v_mfma_f32_16x16x32_bf16 v[80:83], v[176:179], v[208:211], v[80:83]
	v_mfma_f32_16x16x32_bf16 v[76:79], v[184:187], v[208:211], v[76:79]
	v_mfma_f32_16x16x32_bf16 v[72:75], v[176:179], v[224:227], v[72:75]
	v_mfma_f32_16x16x32_bf16 v[68:71], v[184:187], v[224:227], v[68:71]
	s_setprio 1
	s_barrier
	s_add_i32 s20, s44, s1
	v_lshl_add_u64 v[228:229], s[24:25], 0, v[66:67]
	s_mov_b32 m0, s20
	ds_read_b128 v[188:191], v155 offset:16384
	ds_read_b128 v[192:195], v155 offset:17408
	ds_read_b128 v[196:199], v155 offset:18432
	ds_read_b128 v[200:203], v155 offset:19456
	ds_read_b128 v[204:207], v155 offset:20480
	ds_read_b128 v[208:211], v155 offset:21504
	ds_read_b128 v[220:223], v155 offset:22528
	ds_read_b128 v[224:227], v155 offset:23552
	global_load_lds_dwordx4 v[228:229], off
	s_add_i32 m0, s20, 0x2000
	s_add_u32 s20, s24, 0x80000
	v_lshl_add_u64 v[230:231], s[24:25], 0, v[132:133]
	s_addc_u32 s21, s25, 0
	s_add_i32 s44, s45, s1
	global_load_lds_dwordx4 v[230:231], off
	v_lshl_add_u64 v[232:233], s[20:21], 0, v[66:67]
	s_mov_b32 m0, s44
	v_lshl_add_u64 v[234:235], s[26:27], 0, v[132:133]
	global_load_lds_dwordx4 v[232:233], off
	v_lshl_add_u64 v[232:233], s[20:21], 0, v[132:133]
	s_add_i32 m0, s44, 0x2000
	s_nop 0
	global_load_lds_dwordx4 v[232:233], off
	v_lshl_add_u64 v[232:233], s[26:27], 0, v[66:67]
	s_mov_b32 m0, s30
	s_nop 0
	global_load_lds_dwordx4 v[232:233], off
	s_mov_b32 m0, s31
	s_nop 0
	global_load_lds_dwordx4 v[234:235], off
	s_waitcnt vmcnt(8)
	s_waitcnt lgkmcnt(0)
	s_barrier
; #define PG8_STAGE(bufoff, gbase, voff) do { _Pragma("unroll") for (int _i = 0; _i < 2; ++_i) \
;         __builtin_amdgcn_global_load_lds((const unsigned*)((const char*)(gbase) + (voff)[_i]), (PG8_LAS unsigned*)(lds + (bufoff) + ldsw + _i * 8192), 16, 0, 0); } while (0)
; #define PG8_LDA(dst, b, h) do { _Pragma("unroll") for (int m = 0; m < 4; ++m) _Pragma("unroll") for (int k = 0; k < 2; ++k) dst[m][k] = *(const PG8_LAS bf16x8*)(lds + PG8_SA(b, h) + aoff + m * 2048 + k * 1024); } while (0)
; #define PG8_LDB(dst, b, h) do { _Pragma("unroll") for (int n = 0; n < 2; ++n) _Pragma("unroll") for (int k = 0; k < 2; ++k) dst[n][k] = *(const PG8_LAS bf16x8*)(lds + PG8_SB(b, h) + boff + n * 2048 + k * 1024); } while (0)
; #define PG8_MMA(ai, bj, At, Bt) do { __builtin_amdgcn_s_setprio(1); _Pragma("unroll") for (int m = 0; m < 4; ++m) _Pragma("unroll") for (int n = 0; n < 2; ++n) _Pragma("unroll") for (int k = 0; k < 2; ++k) \
;         acc[ai][bj][m][n] = __builtin_amdgcn_mfma_f32_16x16x32_bf16(Bt[n][k], At[m][k], acc[ai][bj][m][n], 0, 0, 0); __builtin_amdgcn_s_setprio(0); } while (0)
; #define PG8_WAIT_V(n) asm volatile("s_waitcnt vmcnt(" #n ")" ::: "memory")
; #define PG8_WAIT_L(n) asm volatile("s_waitcnt lgkmcnt(" #n ")" ::: "memory")
; #define PG8_BAR __builtin_amdgcn_s_barrier()
; #define PG8_SCHED __builtin_amdgcn_sched_barrier(0)
; template <class Epi, class Sched, bool ALIGN_EPI = false, bool SP2 = false>
; __device__ __forceinline__ void gemm_phase(PG8_LAS unsigned char* lds, const Gemm g, const Sched& S, const Epi& E) {
;     ...
;             PG8_WAIT_V(8); PG8_WAIT_L(0); PG8_BAR; PG8_MMA(1, 0, At, B0); PG8_MMA(1, 1, At, B1); PG8_BAR; PG8_SCHED;
;             PG8_LDB(B0, 1, 0); PG8_LDB(B1, 1, 1); PG8_SCHED; PG8_LDA(At, 1, 0); PG8_STAGE(PG8_SA(0, 1), a2 + hstep, voffA);
;             PG8_WAIT_V(8); PG8_WAIT_L(0); PG8_BAR; PG8_MMA(0, 0, At, B0); PG8_MMA(0, 1, At, B1); PG8_BAR; PG8_SCHED;
	s_setprio 0
	s_waitcnt lgkmcnt(0)
	v_mfma_f32_16x16x32_bf16 v[62:65], v[156:159], v[188:191], v[62:65]
	v_mfma_f32_16x16x32_bf16 v[58:61], v[164:167], v[188:191], v[58:61]
	v_mfma_f32_16x16x32_bf16 v[54:57], v[156:159], v[196:199], v[54:57]
	v_mfma_f32_16x16x32_bf16 v[50:53], v[164:167], v[196:199], v[50:53]
	v_mfma_f32_16x16x32_bf16 v[46:49], v[156:159], v[204:207], v[46:49]
	v_mfma_f32_16x16x32_bf16 v[42:45], v[164:167], v[204:207], v[42:45]
	v_mfma_f32_16x16x32_bf16 v[34:37], v[156:159], v[220:223], v[34:37]
	v_mfma_f32_16x16x32_bf16 v[26:29], v[164:167], v[220:223], v[26:29]
	v_mfma_f32_16x16x32_bf16 v[62:65], v[160:163], v[192:195], v[62:65]
	v_mfma_f32_16x16x32_bf16 v[58:61], v[168:171], v[192:195], v[58:61]
	v_mfma_f32_16x16x32_bf16 v[54:57], v[160:163], v[200:203], v[54:57]
	v_mfma_f32_16x16x32_bf16 v[50:53], v[168:171], v[200:203], v[50:53]
	v_mfma_f32_16x16x32_bf16 v[46:49], v[160:163], v[208:211], v[46:49]
	v_mfma_f32_16x16x32_bf16 v[42:45], v[168:171], v[208:211], v[42:45]
	v_mfma_f32_16x16x32_bf16 v[34:37], v[160:163], v[224:227], v[34:37]
	v_mfma_f32_16x16x32_bf16 v[26:29], v[168:171], v[224:227], v[26:29]
	s_setprio 0
	s_setprio 0
	v_mfma_f32_16x16x32_bf16 v[38:41], v[172:175], v[188:191], v[38:41]
	v_mfma_f32_16x16x32_bf16 v[30:33], v[180:183], v[188:191], v[30:33]
	v_mfma_f32_16x16x32_bf16 v[22:25], v[172:175], v[196:199], v[22:25]
	v_mfma_f32_16x16x32_bf16 v[18:21], v[180:183], v[196:199], v[18:21]
	v_mfma_f32_16x16x32_bf16 v[14:17], v[172:175], v[204:207], v[14:17]
	v_mfma_f32_16x16x32_bf16 v[10:13], v[180:183], v[204:207], v[10:13]
	v_mfma_f32_16x16x32_bf16 v[6:9], v[172:175], v[220:223], v[6:9]
	v_mfma_f32_16x16x32_bf16 v[2:5], v[180:183], v[220:223], v[2:5]
	v_mfma_f32_16x16x32_bf16 v[38:41], v[176:179], v[192:195], v[38:41]
	v_mfma_f32_16x16x32_bf16 v[30:33], v[184:187], v[192:195], v[30:33]
	v_mfma_f32_16x16x32_bf16 v[22:25], v[176:179], v[200:203], v[22:25]
	v_mfma_f32_16x16x32_bf16 v[18:21], v[184:187], v[200:203], v[18:21]
	v_mfma_f32_16x16x32_bf16 v[14:17], v[176:179], v[208:211], v[14:17]
	v_mfma_f32_16x16x32_bf16 v[10:13], v[184:187], v[208:211], v[10:13]
	v_mfma_f32_16x16x32_bf16 v[6:9], v[176:179], v[224:227], v[6:9]
	v_mfma_f32_16x16x32_bf16 v[2:5], v[184:187], v[224:227], v[2:5]
	s_setprio 1
	s_barrier
	s_add_i32 s44, 0, 0x18000
	s_add_i32 s45, 0, 0x1c000
	v_add_u32_e32 v168, s44, v0
	v_add_u32_e32 v184, s45, v0
	ds_read_b128 v[156:159], v168
	ds_read_b128 v[160:163], v168 offset:1024
	ds_read_b128 v[164:167], v168 offset:2048
	ds_read_b128 v[168:171], v168 offset:3072
	ds_read_b128 v[172:175], v184
	ds_read_b128 v[176:179], v184 offset:1024
	ds_read_b128 v[180:183], v184 offset:2048
	ds_read_b128 v[184:187], v184 offset:3072
	s_add_u32 s20, s26, 0x80000
	s_addc_u32 s21, s27, 0
	s_mov_b32 m0, s34
	v_lshl_add_u64 v[246:247], s[20:21], 0, v[66:67]
	ds_read_b128 v[188:191], v155 offset:32768
	ds_read_b128 v[192:195], v155 offset:33792
	ds_read_b128 v[196:199], v155 offset:34816
	ds_read_b128 v[200:203], v155 offset:35840
	ds_read_b128 v[204:207], v155 offset:36864
	ds_read_b128 v[208:211], v155 offset:37888
	ds_read_b128 v[220:223], v155 offset:38912
	ds_read_b128 v[224:227], v155 offset:39936
	global_load_lds_dwordx4 v[246:247], off
	v_lshl_add_u64 v[246:247], s[20:21], 0, v[132:133]
	s_mov_b32 m0, s35
	s_nop 0
	global_load_lds_dwordx4 v[246:247], off
	s_waitcnt vmcnt(8)
	s_waitcnt lgkmcnt(0)
	s_barrier
	s_setprio 0
	s_waitcnt lgkmcnt(0)
	v_mfma_f32_16x16x32_bf16 v[128:131], v[156:159], v[188:191], v[128:131]
	v_mfma_f32_16x16x32_bf16 v[124:127], v[164:167], v[188:191], v[124:127]
	v_mfma_f32_16x16x32_bf16 v[120:123], v[156:159], v[196:199], v[120:123]
	v_mfma_f32_16x16x32_bf16 v[116:119], v[164:167], v[196:199], v[116:119]
	v_mfma_f32_16x16x32_bf16 v[112:115], v[156:159], v[204:207], v[112:115]
	v_mfma_f32_16x16x32_bf16 v[108:111], v[164:167], v[204:207], v[108:111]
	v_mfma_f32_16x16x32_bf16 v[100:103], v[156:159], v[220:223], v[100:103]
	v_mfma_f32_16x16x32_bf16 v[92:95], v[164:167], v[220:223], v[92:95]
	v_mfma_f32_16x16x32_bf16 v[128:131], v[160:163], v[192:195], v[128:131]
	v_mfma_f32_16x16x32_bf16 v[124:127], v[168:171], v[192:195], v[124:127]
	v_mfma_f32_16x16x32_bf16 v[120:123], v[160:163], v[200:203], v[120:123]
	v_mfma_f32_16x16x32_bf16 v[116:119], v[168:171], v[200:203], v[116:119]
	v_mfma_f32_16x16x32_bf16 v[112:115], v[160:163], v[208:211], v[112:115]
	v_mfma_f32_16x16x32_bf16 v[108:111], v[168:171], v[208:211], v[108:111]
	v_mfma_f32_16x16x32_bf16 v[100:103], v[160:163], v[224:227], v[100:103]
	v_mfma_f32_16x16x32_bf16 v[92:95], v[168:171], v[224:227], v[92:95]
	s_setprio 0
	s_setprio 0
	v_mfma_f32_16x16x32_bf16 v[104:107], v[172:175], v[188:191], v[104:107]
	v_mfma_f32_16x16x32_bf16 v[96:99], v[180:183], v[188:191], v[96:99]
	v_mfma_f32_16x16x32_bf16 v[88:91], v[172:175], v[196:199], v[88:91]
	v_mfma_f32_16x16x32_bf16 v[84:87], v[180:183], v[196:199], v[84:87]
	v_mfma_f32_16x16x32_bf16 v[80:83], v[172:175], v[204:207], v[80:83]
	v_mfma_f32_16x16x32_bf16 v[76:79], v[180:183], v[204:207], v[76:79]
	v_mfma_f32_16x16x32_bf16 v[72:75], v[172:175], v[220:223], v[72:75]
	v_mfma_f32_16x16x32_bf16 v[68:71], v[180:183], v[220:223], v[68:71]
	v_mfma_f32_16x16x32_bf16 v[104:107], v[176:179], v[192:195], v[104:107]
	v_mfma_f32_16x16x32_bf16 v[96:99], v[184:187], v[192:195], v[96:99]
	v_mfma_f32_16x16x32_bf16 v[88:91], v[176:179], v[200:203], v[88:91]
	v_mfma_f32_16x16x32_bf16 v[84:87], v[184:187], v[200:203], v[84:87]
	v_mfma_f32_16x16x32_bf16 v[80:83], v[176:179], v[208:211], v[80:83]
	v_mfma_f32_16x16x32_bf16 v[76:79], v[184:187], v[208:211], v[76:79]
	v_mfma_f32_16x16x32_bf16 v[72:75], v[176:179], v[224:227], v[72:75]
	v_mfma_f32_16x16x32_bf16 v[68:71], v[184:187], v[224:227], v[68:71]
	s_setprio 1
	s_barrier
; #define PG8_STAGE(bufoff, gbase, voff) do { _Pragma("unroll") for (int _i = 0; _i < 2; ++_i) \
;         __builtin_amdgcn_global_load_lds((const unsigned*)((const char*)(gbase) + (voff)[_i]), (PG8_LAS unsigned*)(lds + (bufoff) + ldsw + _i * 8192), 16, 0, 0); } while (0)
; #define PG8_WAIT_V(n) asm volatile("s_waitcnt vmcnt(" #n ")" ::: "memory")
; #define PG8_WAIT_L(n) asm volatile("s_waitcnt lgkmcnt(" #n ")" ::: "memory")
; template <class Epi, class Sched, bool ALIGN_EPI = false, bool SP2 = false>
; __device__ __forceinline__ void gemm_phase(PG8_LAS unsigned char* lds, const Gemm g, const Sched& S, const Epi& E) {
;     ...
;             PG8_LDA(At, 1, 1); PG8_STAGE(PG8_SB(1, 0), b3, voffB); PG8_STAGE(PG8_SB(1, 1), b3 + hstep, voffB); PG8_STAGE(PG8_SA(1, 0), a3, voffA);
;             PG8_WAIT_V(8); PG8_WAIT_L(0); PG8_BAR; PG8_MMA(1, 0, At, B0); PG8_MMA(1, 1, At, B1); PG8_BAR; PG8_SCHED;
;             } else {
;             PG8_LDB(B0, 0, 0); PG8_SCHED; PG8_LDA(At, 0, 0); PG8_STAGE(PG8_SA(1, 1), a1 + hstep, voffA);
;             PG8_WAIT_L(8); PG8_BAR; PG8_WAIT_L(0); PG8_MMA(0, 0, At, B0); PG8_BAR; PG8_SCHED;
;             PG8_LDB(B1, 0, 1); PG8_STAGE(PG8_SB(0, 0), b2, voffB);
;             PG8_BAR; PG8_WAIT_L(0); PG8_MMA(0, 1, At, B1); PG8_BAR;
;             PG8_LDA(At, 0, 1); PG8_STAGE(PG8_SA(0, 0), a2, voffA);
;             PG8_BAR; PG8_WAIT_L(0); PG8_MMA(1, 0, At, B0); PG8_BAR; PG8_SCHED;
;             PG8_STAGE(PG8_SB(0, 1), b2 + hstep, voffB);
;             PG8_WAIT_V(6); PG8_BAR; PG8_MMA(1, 1, At, B1); PG8_BAR;
;             PG8_LDB(B0, 1, 0); PG8_SCHED; PG8_LDA(At, 1, 0); PG8_STAGE(PG8_SA(0, 1), a2 + hstep, voffA);
;             PG8_WAIT_L(8); PG8_BAR; PG8_WAIT_L(0); PG8_MMA(0, 0, At, B0); PG8_BAR; PG8_SCHED;
;             PG8_LDB(B1, 1, 1); PG8_STAGE(PG8_SB(1, 0), b3, voffB);
;             PG8_BAR; PG8_WAIT_L(0); PG8_MMA(0, 1, At, B1); PG8_BAR;
;             PG8_LDA(At, 1, 1); PG8_STAGE(PG8_SA(1, 0), a3, voffA);
;             PG8_BAR; PG8_WAIT_L(0); PG8_MMA(1, 0, At, B0); PG8_BAR; PG8_SCHED;
;             PG8_STAGE(PG8_SB(1, 1), b3 + hstep, voffB);
;             PG8_WAIT_V(6); PG8_BAR; PG8_MMA(1, 1, At, B1); PG8_BAR;
;             }
;             if constexpr (Epi::HAS_MID) { if ((((t + 2) & 7) == 0) && ((t + 2) < nt)) E.mid(acc, cur, ((t + 2) >> 3) - 1, wr, wc, fr, fq); }
;         }
;         if constexpr (ALIGN_EPI) { if (wr == 0) PG8_BAR; }
	s_add_i32 s20, s44, s1
	v_lshl_add_u64 v[228:229], v[228:229], 0, s[88:89]
	s_mov_b32 m0, s20
	ds_read_b128 v[188:191], v155 offset:49152
	ds_read_b128 v[192:195], v155 offset:50176
	ds_read_b128 v[196:199], v155 offset:51200
	ds_read_b128 v[200:203], v155 offset:52224
	ds_read_b128 v[204:207], v155 offset:53248
	ds_read_b128 v[208:211], v155 offset:54272
	ds_read_b128 v[220:223], v155 offset:55296
	ds_read_b128 v[224:227], v155 offset:56320
	global_load_lds_dwordx4 v[228:229], off
	s_add_i32 m0, s20, 0x2000
	s_add_u32 s20, s24, 0x80080
	v_lshl_add_u64 v[228:229], v[230:231], 0, s[88:89]
	s_addc_u32 s21, s25, 0
	s_add_i32 s24, s45, s1
	global_load_lds_dwordx4 v[228:229], off
	v_lshl_add_u64 v[228:229], s[20:21], 0, v[66:67]
	s_mov_b32 m0, s24
	s_nop 0
	global_load_lds_dwordx4 v[228:229], off
	v_lshl_add_u64 v[228:229], s[20:21], 0, v[132:133]
	s_add_i32 m0, s24, 0x2000
	s_nop 0
	global_load_lds_dwordx4 v[228:229], off
	v_lshl_add_u64 v[228:229], v[232:233], 0, s[88:89]
	s_mov_b32 m0, s40
	s_nop 0
	global_load_lds_dwordx4 v[228:229], off
	v_lshl_add_u64 v[228:229], v[234:235], 0, s[88:89]
	s_mov_b32 m0, s41
	s_nop 0
	global_load_lds_dwordx4 v[228:229], off
	s_waitcnt vmcnt(8)
	s_waitcnt lgkmcnt(0)
	s_barrier
	s_setprio 0
	s_waitcnt lgkmcnt(0)
	v_mfma_f32_16x16x32_bf16 v[62:65], v[156:159], v[188:191], v[62:65]
	v_mfma_f32_16x16x32_bf16 v[58:61], v[164:167], v[188:191], v[58:61]
	v_mfma_f32_16x16x32_bf16 v[54:57], v[156:159], v[196:199], v[54:57]
	v_mfma_f32_16x16x32_bf16 v[50:53], v[164:167], v[196:199], v[50:53]
	v_mfma_f32_16x16x32_bf16 v[46:49], v[156:159], v[204:207], v[46:49]
	v_mfma_f32_16x16x32_bf16 v[42:45], v[164:167], v[204:207], v[42:45]
	v_mfma_f32_16x16x32_bf16 v[34:37], v[156:159], v[220:223], v[34:37]
	v_mfma_f32_16x16x32_bf16 v[26:29], v[164:167], v[220:223], v[26:29]
	v_mfma_f32_16x16x32_bf16 v[62:65], v[160:163], v[192:195], v[62:65]
	v_mfma_f32_16x16x32_bf16 v[58:61], v[168:171], v[192:195], v[58:61]
	v_mfma_f32_16x16x32_bf16 v[54:57], v[160:163], v[200:203], v[54:57]
	v_mfma_f32_16x16x32_bf16 v[50:53], v[168:171], v[200:203], v[50:53]
	v_mfma_f32_16x16x32_bf16 v[46:49], v[160:163], v[208:211], v[46:49]
	v_mfma_f32_16x16x32_bf16 v[42:45], v[168:171], v[208:211], v[42:45]
	v_mfma_f32_16x16x32_bf16 v[34:37], v[160:163], v[224:227], v[34:37]
	v_mfma_f32_16x16x32_bf16 v[26:29], v[168:171], v[224:227], v[26:29]
	s_setprio 0
	s_setprio 0
	v_mfma_f32_16x16x32_bf16 v[38:41], v[172:175], v[188:191], v[38:41]
	v_mfma_f32_16x16x32_bf16 v[30:33], v[180:183], v[188:191], v[30:33]
	v_mfma_f32_16x16x32_bf16 v[22:25], v[172:175], v[196:199], v[22:25]
	v_mfma_f32_16x16x32_bf16 v[18:21], v[180:183], v[196:199], v[18:21]
	v_mfma_f32_16x16x32_bf16 v[14:17], v[172:175], v[204:207], v[14:17]
	v_mfma_f32_16x16x32_bf16 v[10:13], v[180:183], v[204:207], v[10:13]
	v_mfma_f32_16x16x32_bf16 v[6:9], v[172:175], v[220:223], v[6:9]
	v_mfma_f32_16x16x32_bf16 v[2:5], v[180:183], v[220:223], v[2:5]
	v_mfma_f32_16x16x32_bf16 v[38:41], v[176:179], v[192:195], v[38:41]
	v_mfma_f32_16x16x32_bf16 v[30:33], v[184:187], v[192:195], v[30:33]
	v_mfma_f32_16x16x32_bf16 v[22:25], v[176:179], v[200:203], v[22:25]
	v_mfma_f32_16x16x32_bf16 v[18:21], v[184:187], v[200:203], v[18:21]
	v_mfma_f32_16x16x32_bf16 v[14:17], v[176:179], v[208:211], v[14:17]
	v_mfma_f32_16x16x32_bf16 v[10:13], v[184:187], v[208:211], v[10:13]
	v_mfma_f32_16x16x32_bf16 v[6:9], v[176:179], v[224:227], v[6:9]
	v_mfma_f32_16x16x32_bf16 v[2:5], v[184:187], v[224:227], v[2:5]
	s_setprio 1
	s_barrier
	s_add_i32 s43, s43, 2
	s_add_u32 s13, s13, 0x100
	s_addc_u32 s15, s15, 0
	s_cmp_gt_u32 s43, 5
	s_mov_b64 s[20:21], s[22:23]
	s_cbranch_scc0 .LBB0_802
	s_and_b64 vcc, exec, s[8:9]
	s_cbranch_vccz .LBB0_805
	s_barrier

;     __host__ __device__ bool next(int i, Unit& u) const { if (i != 0 || r < 0 || r >= 148) return false; if (r < 116) { u.pm = r % 29; u.pn = 47 + r / 29; } else { u.pm = 32; u.pn = 19 + (r - 116); } u.ko = 0; return true; }
;     __host__ __device__ bool next(int i, Unit& u) const { const int L = i * G + (G - 1 - c); if (L >= nN * S) return false; u.pm = pm; u.pn = L % nN; u.ko = (L / nN) * ksub; return true; }
; #define PG8_STAGE(bufoff, gbase, voff) do { _Pragma("unroll") for (int _i = 0; _i < 2; ++_i) \
;         __builtin_amdgcn_global_load_lds((const unsigned*)((const char*)(gbase) + (voff)[_i]), (PG8_LAS unsigned*)(lds + (bufoff) + ldsw + _i * 8192), 16, 0, 0); } while (0)
; #define PG8_LDA(dst, b, h) do { _Pragma("unroll") for (int m = 0; m < 4; ++m) _Pragma("unroll") for (int k = 0; k < 2; ++k) dst[m][k] = *(const PG8_LAS bf16x8*)(lds + PG8_SA(b, h) + aoff + m * 2048 + k * 1024); } while (0)
; #define PG8_WAIT_V(n) asm volatile("s_waitcnt vmcnt(" #n ")" ::: "memory")
; #define PG8_WAIT_L(n) asm volatile("s_waitcnt lgkmcnt(" #n ")" ::: "memory")
; template <class Epi, class Sched, bool ALIGN_EPI = false, bool SP2 = false>
; __device__ __forceinline__ void gemm_phase(PG8_LAS unsigned char* lds, const Gemm g, const Sched& S, const Epi& E) {
;     ...
;     for (;;) {
;         const bool has_next = S.next(ui + 1, nxt);
;         const char* nA = has_next ? (const char*)g.A + (size_t)nxt.pm * tstep + (size_t)nxt.ko * 2 : cA; const char* nB = has_next ? (const char*)g.Bt + (size_t)nxt.pn * tstep + (size_t)nxt.ko * 2 : cB;
;         for (int t = 0; t < nt; t += 2) {
;             const bool last = (t == nt - 2);
;             const char* a1 = cA + (size_t)(t + 1) * kstep;
;             const char* a2 = last ? nA : cA + (size_t)(t + 2) * kstep; const char* b2 = last ? nB : cB + (size_t)(t + 2) * kstep;
;             const char* a3 = a2 + kstep; const char* b3 = b2 + kstep;
;             if (last && has_next) S.a_ready(nxt);
;             if constexpr (SP2) {
;             PG8_LDB(B0, 0, 0); PG8_LDB(B1, 0, 1); PG8_SCHED; PG8_LDA(At, 0, 0); PG8_STAGE(PG8_SA(1, 1), a1 + hstep, voffA);
;             PG8_WAIT_V(8); PG8_WAIT_L(0); PG8_BAR; PG8_MMA(0, 0, At, B0); PG8_MMA(0, 1, At, B1); PG8_BAR; PG8_SCHED;
;             PG8_LDA(At, 0, 1); PG8_STAGE(PG8_SB(0, 0), b2, voffB); PG8_STAGE(PG8_SB(0, 1), b2 + hstep, voffB); PG8_STAGE(PG8_SA(0, 0), a2, voffA);
.LBB0_881:
	s_add_u32 s30, s28, 0x100
	s_addc_u32 s31, s29, 0
	s_add_i32 s59, 0, 0x10000
	s_cmp_eq_u32 s57, 28
	s_cselect_b32 s37, s2, s31
	s_cselect_b32 s36, s3, s30
	s_cselect_b32 s35, s21, s56
	s_cselect_b32 s34, s23, s55
	s_add_i32 s60, 0, 0x14000
	v_add_u32_e32 v144, s59, v156
	v_add_u32_e32 v154, s60, v156
	ds_read_b128 v[132:135], v144
	ds_read_b128 v[136:139], v144 offset:1024
	ds_read_b128 v[140:143], v144 offset:2048
	ds_read_b128 v[144:147], v144 offset:3072
	ds_read_b128 v[160:163], v154
	ds_read_b128 v[164:167], v154 offset:1024
	ds_read_b128 v[168:171], v154 offset:2048
	ds_read_b128 v[172:175], v154 offset:3072
	v_lshl_add_u64 v[154:155], s[28:29], 0, v[150:151]
	s_add_i32 m0, s39, 0xc000
	ds_read_b128 v[176:179], v158
	ds_read_b128 v[180:183], v158 offset:1024
	ds_read_b128 v[184:187], v158 offset:2048
	ds_read_b128 v[188:191], v158 offset:3072
	ds_read_b128 v[192:195], v158 offset:4096
	ds_read_b128 v[196:199], v158 offset:5120
	ds_read_b128 v[200:203], v158 offset:6144
	ds_read_b128 v[204:207], v158 offset:7168
	global_load_lds_dwordx4 v[154:155], off
	v_lshl_add_u64 v[154:155], s[28:29], 0, v[152:153]
	s_add_i32 m0, s39, 0xe000
	s_nop 0
	global_load_lds_dwordx4 v[154:155], off
	s_waitcnt vmcnt(8)
	s_waitcnt lgkmcnt(0)
	s_barrier
	s_setprio 0
	s_waitcnt lgkmcnt(0)
	v_mfma_f32_16x16x32_bf16 v[128:131], v[132:135], v[176:179], v[128:131]
	v_mfma_f32_16x16x32_bf16 v[124:127], v[140:143], v[176:179], v[124:127]
	v_mfma_f32_16x16x32_bf16 v[120:123], v[132:135], v[184:187], v[120:123]
	v_mfma_f32_16x16x32_bf16 v[112:115], v[140:143], v[184:187], v[112:115]
	v_mfma_f32_16x16x32_bf16 v[104:107], v[132:135], v[192:195], v[104:107]
	v_mfma_f32_16x16x32_bf16 v[96:99], v[140:143], v[192:195], v[96:99]
	v_mfma_f32_16x16x32_bf16 v[88:91], v[132:135], v[200:203], v[88:91]
	v_mfma_f32_16x16x32_bf16 v[76:79], v[140:143], v[200:203], v[76:79]
	v_mfma_f32_16x16x32_bf16 v[128:131], v[136:139], v[180:183], v[128:131]
	v_mfma_f32_16x16x32_bf16 v[124:127], v[144:147], v[180:183], v[124:127]
	v_mfma_f32_16x16x32_bf16 v[120:123], v[136:139], v[188:191], v[120:123]
	v_mfma_f32_16x16x32_bf16 v[112:115], v[144:147], v[188:191], v[112:115]
	v_mfma_f32_16x16x32_bf16 v[104:107], v[136:139], v[196:199], v[104:107]
	v_mfma_f32_16x16x32_bf16 v[96:99], v[144:147], v[196:199], v[96:99]
	v_mfma_f32_16x16x32_bf16 v[88:91], v[136:139], v[204:207], v[88:91]
	v_mfma_f32_16x16x32_bf16 v[76:79], v[144:147], v[204:207], v[76:79]
	s_setprio 0
	s_setprio 0
	v_mfma_f32_16x16x32_bf16 v[116:119], v[160:163], v[176:179], v[116:119]
	v_mfma_f32_16x16x32_bf16 v[108:111], v[168:171], v[176:179], v[108:111]
	v_mfma_f32_16x16x32_bf16 v[100:103], v[160:163], v[184:187], v[100:103]
	v_mfma_f32_16x16x32_bf16 v[92:95], v[168:171], v[184:187], v[92:95]
	v_mfma_f32_16x16x32_bf16 v[84:87], v[160:163], v[192:195], v[84:87]
	v_mfma_f32_16x16x32_bf16 v[80:83], v[168:171], v[192:195], v[80:83]
	v_mfma_f32_16x16x32_bf16 v[72:75], v[160:163], v[200:203], v[72:75]
	v_mfma_f32_16x16x32_bf16 v[68:71], v[168:171], v[200:203], v[68:71]
	v_mfma_f32_16x16x32_bf16 v[116:119], v[164:167], v[180:183], v[116:119]
	v_mfma_f32_16x16x32_bf16 v[108:111], v[172:175], v[180:183], v[108:111]
	v_mfma_f32_16x16x32_bf16 v[100:103], v[164:167], v[188:191], v[100:103]
	v_mfma_f32_16x16x32_bf16 v[92:95], v[172:175], v[188:191], v[92:95]
	v_mfma_f32_16x16x32_bf16 v[84:87], v[164:167], v[196:199], v[84:87]
	v_mfma_f32_16x16x32_bf16 v[80:83], v[172:175], v[196:199], v[80:83]
	v_mfma_f32_16x16x32_bf16 v[72:75], v[164:167], v[204:207], v[72:75]
	v_mfma_f32_16x16x32_bf16 v[68:71], v[172:175], v[204:207], v[68:71]
	s_setprio 1
	s_barrier
	s_add_i32 s28, s59, s38
	v_lshl_add_u64 v[154:155], s[34:35], 0, v[66:67]
	s_mov_b32 m0, s28
	ds_read_b128 v[176:179], v158 offset:16384
	ds_read_b128 v[180:183], v158 offset:17408
	ds_read_b128 v[184:187], v158 offset:18432
	ds_read_b128 v[188:191], v158 offset:19456
	ds_read_b128 v[192:195], v158 offset:20480
	ds_read_b128 v[196:199], v158 offset:21504
	ds_read_b128 v[200:203], v158 offset:22528
	ds_read_b128 v[204:207], v158 offset:23552
	global_load_lds_dwordx4 v[154:155], off
	s_add_i32 m0, s28, 0x2000
	s_add_u32 s28, s34, 0x80000
	v_lshl_add_u64 v[208:209], s[34:35], 0, v[148:149]
	s_addc_u32 s29, s35, 0
	s_add_i32 s59, s60, s38
	global_load_lds_dwordx4 v[208:209], off
	v_lshl_add_u64 v[210:211], s[28:29], 0, v[66:67]
	s_mov_b32 m0, s59
	v_lshl_add_u64 v[220:221], s[36:37], 0, v[148:149]
	global_load_lds_dwordx4 v[210:211], off
	v_lshl_add_u64 v[210:211], s[28:29], 0, v[148:149]
	s_add_i32 m0, s59, 0x2000
	s_nop 0
	global_load_lds_dwordx4 v[210:211], off
	v_lshl_add_u64 v[210:211], s[36:37], 0, v[66:67]
	s_mov_b32 m0, s39
	s_nop 0
	global_load_lds_dwordx4 v[210:211], off
	s_mov_b32 m0, s40
	s_nop 0
	global_load_lds_dwordx4 v[220:221], off
	s_waitcnt vmcnt(8)
	s_waitcnt lgkmcnt(0)
	s_barrier
; #define PG8_STAGE(bufoff, gbase, voff) do { _Pragma("unroll") for (int _i = 0; _i < 2; ++_i) \
;         __builtin_amdgcn_global_load_lds((const unsigned*)((const char*)(gbase) + (voff)[_i]), (PG8_LAS unsigned*)(lds + (bufoff) + ldsw + _i * 8192), 16, 0, 0); } while (0)
; #define PG8_LDA(dst, b, h) do { _Pragma("unroll") for (int m = 0; m < 4; ++m) _Pragma("unroll") for (int k = 0; k < 2; ++k) dst[m][k] = *(const PG8_LAS bf16x8*)(lds + PG8_SA(b, h) + aoff + m * 2048 + k * 1024); } while (0)
; #define PG8_LDB(dst, b, h) do { _Pragma("unroll") for (int n = 0; n < 2; ++n) _Pragma("unroll") for (int k = 0; k < 2; ++k) dst[n][k] = *(const PG8_LAS bf16x8*)(lds + PG8_SB(b, h) + boff + n * 2048 + k * 1024); } while (0)
; #define PG8_MMA(ai, bj, At, Bt) do { __builtin_amdgcn_s_setprio(1); _Pragma("unroll") for (int m = 0; m < 4; ++m) _Pragma("unroll") for (int n = 0; n < 2; ++n) _Pragma("unroll") for (int k = 0; k < 2; ++k) \
;         acc[ai][bj][m][n] = __builtin_amdgcn_mfma_f32_16x16x32_bf16(Bt[n][k], At[m][k], acc[ai][bj][m][n], 0, 0, 0); __builtin_amdgcn_s_setprio(0); } while (0)
; #define PG8_WAIT_V(n) asm volatile("s_waitcnt vmcnt(" #n ")" ::: "memory")
; #define PG8_WAIT_L(n) asm volatile("s_waitcnt lgkmcnt(" #n ")" ::: "memory")
; #define PG8_BAR __builtin_amdgcn_s_barrier()
; #define PG8_SCHED __builtin_amdgcn_sched_barrier(0)
; template <class Epi, class Sched, bool ALIGN_EPI = false, bool SP2 = false>
; __device__ __forceinline__ void gemm_phase(PG8_LAS unsigned char* lds, const Gemm g, const Sched& S, const Epi& E) {
;     ...
;             PG8_WAIT_V(8); PG8_WAIT_L(0); PG8_BAR; PG8_MMA(1, 0, At, B0); PG8_MMA(1, 1, At, B1); PG8_BAR; PG8_SCHED;
;             PG8_LDB(B0, 1, 0); PG8_LDB(B1, 1, 1); PG8_SCHED; PG8_LDA(At, 1, 0); PG8_STAGE(PG8_SA(0, 1), a2 + hstep, voffA);
;             PG8_WAIT_V(8); PG8_WAIT_L(0); PG8_BAR; PG8_MMA(0, 0, At, B0); PG8_MMA(0, 1, At, B1); PG8_BAR; PG8_SCHED;
	s_setprio 0
	s_waitcnt lgkmcnt(0)
	v_mfma_f32_16x16x32_bf16 v[62:65], v[132:135], v[176:179], v[62:65]
	v_mfma_f32_16x16x32_bf16 v[58:61], v[140:143], v[176:179], v[58:61]
	v_mfma_f32_16x16x32_bf16 v[54:57], v[132:135], v[184:187], v[54:57]
	v_mfma_f32_16x16x32_bf16 v[46:49], v[140:143], v[184:187], v[46:49]
	v_mfma_f32_16x16x32_bf16 v[38:41], v[132:135], v[192:195], v[38:41]
	v_mfma_f32_16x16x32_bf16 v[30:33], v[140:143], v[192:195], v[30:33]
	v_mfma_f32_16x16x32_bf16 v[22:25], v[132:135], v[200:203], v[22:25]
	v_mfma_f32_16x16x32_bf16 v[10:13], v[140:143], v[200:203], v[10:13]
	v_mfma_f32_16x16x32_bf16 v[62:65], v[136:139], v[180:183], v[62:65]
	v_mfma_f32_16x16x32_bf16 v[58:61], v[144:147], v[180:183], v[58:61]
	v_mfma_f32_16x16x32_bf16 v[54:57], v[136:139], v[188:191], v[54:57]
	v_mfma_f32_16x16x32_bf16 v[46:49], v[144:147], v[188:191], v[46:49]
	v_mfma_f32_16x16x32_bf16 v[38:41], v[136:139], v[196:199], v[38:41]
	v_mfma_f32_16x16x32_bf16 v[30:33], v[144:147], v[196:199], v[30:33]
	v_mfma_f32_16x16x32_bf16 v[22:25], v[136:139], v[204:207], v[22:25]
	v_mfma_f32_16x16x32_bf16 v[10:13], v[144:147], v[204:207], v[10:13]
	s_setprio 0
	s_setprio 0
	v_mfma_f32_16x16x32_bf16 v[50:53], v[160:163], v[176:179], v[50:53]
	v_mfma_f32_16x16x32_bf16 v[42:45], v[168:171], v[176:179], v[42:45]
	v_mfma_f32_16x16x32_bf16 v[34:37], v[160:163], v[184:187], v[34:37]
	v_mfma_f32_16x16x32_bf16 v[26:29], v[168:171], v[184:187], v[26:29]
	v_mfma_f32_16x16x32_bf16 v[18:21], v[160:163], v[192:195], v[18:21]
	v_mfma_f32_16x16x32_bf16 v[14:17], v[168:171], v[192:195], v[14:17]
	v_mfma_f32_16x16x32_bf16 v[6:9], v[160:163], v[200:203], v[6:9]
	v_mfma_f32_16x16x32_bf16 v[2:5], v[168:171], v[200:203], v[2:5]
	v_mfma_f32_16x16x32_bf16 v[50:53], v[164:167], v[180:183], v[50:53]
	v_mfma_f32_16x16x32_bf16 v[42:45], v[172:175], v[180:183], v[42:45]
	v_mfma_f32_16x16x32_bf16 v[34:37], v[164:167], v[188:191], v[34:37]
	v_mfma_f32_16x16x32_bf16 v[26:29], v[172:175], v[188:191], v[26:29]
	v_mfma_f32_16x16x32_bf16 v[18:21], v[164:167], v[196:199], v[18:21]
	v_mfma_f32_16x16x32_bf16 v[14:17], v[172:175], v[196:199], v[14:17]
	v_mfma_f32_16x16x32_bf16 v[6:9], v[164:167], v[204:207], v[6:9]
	v_mfma_f32_16x16x32_bf16 v[2:5], v[172:175], v[204:207], v[2:5]
	s_setprio 1
	s_barrier
	s_add_i32 s59, 0, 0x18000
	s_add_i32 s60, 0, 0x1c000
	v_add_u32_e32 v144, s59, v156
	v_add_u32_e32 v159, s60, v156
	ds_read_b128 v[132:135], v144
	ds_read_b128 v[136:139], v144 offset:1024
	ds_read_b128 v[140:143], v144 offset:2048
	ds_read_b128 v[144:147], v144 offset:3072
	ds_read_b128 v[160:163], v159
	ds_read_b128 v[164:167], v159 offset:1024
	ds_read_b128 v[168:171], v159 offset:2048
	ds_read_b128 v[172:175], v159 offset:3072
	s_add_u32 s28, s36, 0x80000
	s_addc_u32 s29, s37, 0
	s_mov_b32 m0, s41
	v_lshl_add_u64 v[222:223], s[28:29], 0, v[66:67]
	ds_read_b128 v[176:179], v158 offset:32768
	ds_read_b128 v[180:183], v158 offset:33792
	ds_read_b128 v[184:187], v158 offset:34816
	ds_read_b128 v[188:191], v158 offset:35840
	ds_read_b128 v[192:195], v158 offset:36864
	ds_read_b128 v[196:199], v158 offset:37888
	ds_read_b128 v[200:203], v158 offset:38912
	ds_read_b128 v[204:207], v158 offset:39936
	global_load_lds_dwordx4 v[222:223], off
	v_lshl_add_u64 v[222:223], s[28:29], 0, v[148:149]
	s_mov_b32 m0, s44
	s_nop 0
	global_load_lds_dwordx4 v[222:223], off
	s_waitcnt vmcnt(8)
	s_waitcnt lgkmcnt(0)
	s_barrier
	s_setprio 0
	s_waitcnt lgkmcnt(0)
	v_mfma_f32_16x16x32_bf16 v[128:131], v[132:135], v[176:179], v[128:131]
	v_mfma_f32_16x16x32_bf16 v[124:127], v[140:143], v[176:179], v[124:127]
	v_mfma_f32_16x16x32_bf16 v[120:123], v[132:135], v[184:187], v[120:123]
	v_mfma_f32_16x16x32_bf16 v[112:115], v[140:143], v[184:187], v[112:115]
	v_mfma_f32_16x16x32_bf16 v[104:107], v[132:135], v[192:195], v[104:107]
	v_mfma_f32_16x16x32_bf16 v[96:99], v[140:143], v[192:195], v[96:99]
	v_mfma_f32_16x16x32_bf16 v[88:91], v[132:135], v[200:203], v[88:91]
	v_mfma_f32_16x16x32_bf16 v[76:79], v[140:143], v[200:203], v[76:79]
	v_mfma_f32_16x16x32_bf16 v[128:131], v[136:139], v[180:183], v[128:131]
	v_mfma_f32_16x16x32_bf16 v[124:127], v[144:147], v[180:183], v[124:127]
	v_mfma_f32_16x16x32_bf16 v[120:123], v[136:139], v[188:191], v[120:123]
	v_mfma_f32_16x16x32_bf16 v[112:115], v[144:147], v[188:191], v[112:115]
	v_mfma_f32_16x16x32_bf16 v[104:107], v[136:139], v[196:199], v[104:107]
	v_mfma_f32_16x16x32_bf16 v[96:99], v[144:147], v[196:199], v[96:99]
	v_mfma_f32_16x16x32_bf16 v[88:91], v[136:139], v[204:207], v[88:91]
	v_mfma_f32_16x16x32_bf16 v[76:79], v[144:147], v[204:207], v[76:79]
	s_setprio 0
	s_setprio 0
	v_mfma_f32_16x16x32_bf16 v[116:119], v[160:163], v[176:179], v[116:119]
	v_mfma_f32_16x16x32_bf16 v[108:111], v[168:171], v[176:179], v[108:111]
	v_mfma_f32_16x16x32_bf16 v[100:103], v[160:163], v[184:187], v[100:103]
	v_mfma_f32_16x16x32_bf16 v[92:95], v[168:171], v[184:187], v[92:95]
	v_mfma_f32_16x16x32_bf16 v[84:87], v[160:163], v[192:195], v[84:87]
	v_mfma_f32_16x16x32_bf16 v[80:83], v[168:171], v[192:195], v[80:83]
	v_mfma_f32_16x16x32_bf16 v[72:75], v[160:163], v[200:203], v[72:75]
	v_mfma_f32_16x16x32_bf16 v[68:71], v[168:171], v[200:203], v[68:71]
	v_mfma_f32_16x16x32_bf16 v[116:119], v[164:167], v[180:183], v[116:119]
	v_mfma_f32_16x16x32_bf16 v[108:111], v[172:175], v[180:183], v[108:111]
	v_mfma_f32_16x16x32_bf16 v[100:103], v[164:167], v[188:191], v[100:103]
	v_mfma_f32_16x16x32_bf16 v[92:95], v[172:175], v[188:191], v[92:95]
	v_mfma_f32_16x16x32_bf16 v[84:87], v[164:167], v[196:199], v[84:87]
	v_mfma_f32_16x16x32_bf16 v[80:83], v[172:175], v[196:199], v[80:83]
	v_mfma_f32_16x16x32_bf16 v[72:75], v[164:167], v[204:207], v[72:75]
	v_mfma_f32_16x16x32_bf16 v[68:71], v[172:175], v[204:207], v[68:71]
	s_setprio 1
	s_barrier
; #define PG8_STAGE(bufoff, gbase, voff) do { _Pragma("unroll") for (int _i = 0; _i < 2; ++_i) \
;         __builtin_amdgcn_global_load_lds((const unsigned*)((const char*)(gbase) + (voff)[_i]), (PG8_LAS unsigned*)(lds + (bufoff) + ldsw + _i * 8192), 16, 0, 0); } while (0)
; #define PG8_WAIT_V(n) asm volatile("s_waitcnt vmcnt(" #n ")" ::: "memory")
; #define PG8_WAIT_L(n) asm volatile("s_waitcnt lgkmcnt(" #n ")" ::: "memory")
; template <class Epi, class Sched, bool ALIGN_EPI = false, bool SP2 = false>
; __device__ __forceinline__ void gemm_phase(PG8_LAS unsigned char* lds, const Gemm g, const Sched& S, const Epi& E) {
;     ...
;             PG8_LDA(At, 1, 1); PG8_STAGE(PG8_SB(1, 0), b3, voffB); PG8_STAGE(PG8_SB(1, 1), b3 + hstep, voffB); PG8_STAGE(PG8_SA(1, 0), a3, voffA);
;             PG8_WAIT_V(8); PG8_WAIT_L(0); PG8_BAR; PG8_MMA(1, 0, At, B0); PG8_MMA(1, 1, At, B1); PG8_BAR; PG8_SCHED;
;             } else {
;             PG8_LDB(B0, 0, 0); PG8_SCHED; PG8_LDA(At, 0, 0); PG8_STAGE(PG8_SA(1, 1), a1 + hstep, voffA);
;             PG8_WAIT_L(8); PG8_BAR; PG8_WAIT_L(0); PG8_MMA(0, 0, At, B0); PG8_BAR; PG8_SCHED;
;             PG8_LDB(B1, 0, 1); PG8_STAGE(PG8_SB(0, 0), b2, voffB);
;             PG8_BAR; PG8_WAIT_L(0); PG8_MMA(0, 1, At, B1); PG8_BAR;
;             PG8_LDA(At, 0, 1); PG8_STAGE(PG8_SA(0, 0), a2, voffA);
;             PG8_BAR; PG8_WAIT_L(0); PG8_MMA(1, 0, At, B0); PG8_BAR; PG8_SCHED;
;             PG8_STAGE(PG8_SB(0, 1), b2 + hstep, voffB);
;             PG8_WAIT_V(6); PG8_BAR; PG8_MMA(1, 1, At, B1); PG8_BAR;
;             PG8_LDB(B0, 1, 0); PG8_SCHED; PG8_LDA(At, 1, 0); PG8_STAGE(PG8_SA(0, 1), a2 + hstep, voffA);
;             PG8_WAIT_L(8); PG8_BAR; PG8_WAIT_L(0); PG8_MMA(0, 0, At, B0); PG8_BAR; PG8_SCHED;
;             PG8_LDB(B1, 1, 1); PG8_STAGE(PG8_SB(1, 0), b3, voffB);
;             PG8_BAR; PG8_WAIT_L(0); PG8_MMA(0, 1, At, B1); PG8_BAR;
;             PG8_LDA(At, 1, 1); PG8_STAGE(PG8_SA(1, 0), a3, voffA);
;             PG8_BAR; PG8_WAIT_L(0); PG8_MMA(1, 0, At, B0); PG8_BAR; PG8_SCHED;
;             PG8_STAGE(PG8_SB(1, 1), b3 + hstep, voffB);
;             PG8_WAIT_V(6); PG8_BAR; PG8_MMA(1, 1, At, B1); PG8_BAR;
;             }
;             if constexpr (Epi::HAS_MID) { if ((((t + 2) & 7) == 0) && ((t + 2) < nt)) E.mid(acc, cur, ((t + 2) >> 3) - 1, wr, wc, fr, fq); }
;         }
;         if constexpr (ALIGN_EPI) { if (wr == 0) PG8_BAR; }
	s_add_i32 s28, s59, s38
	v_lshl_add_u64 v[154:155], v[154:155], 0, s[88:89]
	s_mov_b32 m0, s28
	ds_read_b128 v[176:179], v158 offset:49152
	ds_read_b128 v[180:183], v158 offset:50176
	ds_read_b128 v[184:187], v158 offset:51200
	ds_read_b128 v[188:191], v158 offset:52224
	ds_read_b128 v[192:195], v158 offset:53248
	ds_read_b128 v[196:199], v158 offset:54272
	ds_read_b128 v[200:203], v158 offset:55296
	ds_read_b128 v[204:207], v158 offset:56320
	global_load_lds_dwordx4 v[154:155], off
	s_add_i32 m0, s28, 0x2000
	s_add_u32 s28, s34, 0x80080
	v_lshl_add_u64 v[154:155], v[208:209], 0, s[88:89]
	s_addc_u32 s29, s35, 0
	s_add_i32 s34, s60, s38
	global_load_lds_dwordx4 v[154:155], off
	v_lshl_add_u64 v[154:155], s[28:29], 0, v[66:67]
	s_mov_b32 m0, s34
	s_nop 0
	global_load_lds_dwordx4 v[154:155], off
	v_lshl_add_u64 v[154:155], s[28:29], 0, v[148:149]
	s_add_i32 m0, s34, 0x2000
	s_nop 0
	global_load_lds_dwordx4 v[154:155], off
	v_lshl_add_u64 v[154:155], v[210:211], 0, s[88:89]
	s_mov_b32 m0, s47
	s_nop 0
	global_load_lds_dwordx4 v[154:155], off
	v_lshl_add_u64 v[154:155], v[220:221], 0, s[88:89]
	s_mov_b32 m0, s50
	s_nop 0
	global_load_lds_dwordx4 v[154:155], off
	s_waitcnt vmcnt(8)
	s_waitcnt lgkmcnt(0)
	s_barrier
	s_setprio 0
	s_waitcnt lgkmcnt(0)
	v_mfma_f32_16x16x32_bf16 v[62:65], v[132:135], v[176:179], v[62:65]
	v_mfma_f32_16x16x32_bf16 v[58:61], v[140:143], v[176:179], v[58:61]
	v_mfma_f32_16x16x32_bf16 v[54:57], v[132:135], v[184:187], v[54:57]
	v_mfma_f32_16x16x32_bf16 v[46:49], v[140:143], v[184:187], v[46:49]
	v_mfma_f32_16x16x32_bf16 v[38:41], v[132:135], v[192:195], v[38:41]
	v_mfma_f32_16x16x32_bf16 v[30:33], v[140:143], v[192:195], v[30:33]
	v_mfma_f32_16x16x32_bf16 v[22:25], v[132:135], v[200:203], v[22:25]
	v_mfma_f32_16x16x32_bf16 v[10:13], v[140:143], v[200:203], v[10:13]
	v_mfma_f32_16x16x32_bf16 v[62:65], v[136:139], v[180:183], v[62:65]
	v_mfma_f32_16x16x32_bf16 v[58:61], v[144:147], v[180:183], v[58:61]
	v_mfma_f32_16x16x32_bf16 v[54:57], v[136:139], v[188:191], v[54:57]
	v_mfma_f32_16x16x32_bf16 v[46:49], v[144:147], v[188:191], v[46:49]
	v_mfma_f32_16x16x32_bf16 v[38:41], v[136:139], v[196:199], v[38:41]
	v_mfma_f32_16x16x32_bf16 v[30:33], v[144:147], v[196:199], v[30:33]
	v_mfma_f32_16x16x32_bf16 v[22:25], v[136:139], v[204:207], v[22:25]
	v_mfma_f32_16x16x32_bf16 v[10:13], v[144:147], v[204:207], v[10:13]
	s_setprio 0
	s_setprio 0
	v_mfma_f32_16x16x32_bf16 v[50:53], v[160:163], v[176:179], v[50:53]
	v_mfma_f32_16x16x32_bf16 v[42:45], v[168:171], v[176:179], v[42:45]
	v_mfma_f32_16x16x32_bf16 v[34:37], v[160:163], v[184:187], v[34:37]
	v_mfma_f32_16x16x32_bf16 v[26:29], v[168:171], v[184:187], v[26:29]
	v_mfma_f32_16x16x32_bf16 v[18:21], v[160:163], v[192:195], v[18:21]
	v_mfma_f32_16x16x32_bf16 v[14:17], v[168:171], v[192:195], v[14:17]
	v_mfma_f32_16x16x32_bf16 v[6:9], v[160:163], v[200:203], v[6:9]
	v_mfma_f32_16x16x32_bf16 v[2:5], v[168:171], v[200:203], v[2:5]
	v_mfma_f32_16x16x32_bf16 v[50:53], v[164:167], v[180:183], v[50:53]
	v_mfma_f32_16x16x32_bf16 v[42:45], v[172:175], v[180:183], v[42:45]
	v_mfma_f32_16x16x32_bf16 v[34:37], v[164:167], v[188:191], v[34:37]
	v_mfma_f32_16x16x32_bf16 v[26:29], v[172:175], v[188:191], v[26:29]
	v_mfma_f32_16x16x32_bf16 v[18:21], v[164:167], v[196:199], v[18:21]
	v_mfma_f32_16x16x32_bf16 v[14:17], v[172:175], v[196:199], v[14:17]
	v_mfma_f32_16x16x32_bf16 v[6:9], v[164:167], v[204:207], v[6:9]
	v_mfma_f32_16x16x32_bf16 v[2:5], v[172:175], v[204:207], v[2:5]
	s_setprio 1
	s_barrier
	s_add_i32 s57, s57, 2
	s_add_u32 s55, s55, 0x100
	s_addc_u32 s56, s56, 0
	s_cmp_gt_u32 s57, 29
	s_mov_b64 s[28:29], s[30:31]
	s_cbranch_scc0 .LBB0_881
	s_and_b64 vcc, exec, s[12:13]
	s_cbranch_vccz .LBB0_884
	s_barrier

;     __host__ __device__ bool next(int i, Unit& u) const { if (i != 0 || r < 0 || r >= 148) return false; if (r < 116) { u.pm = r % 29; u.pn = 47 + r / 29; } else { u.pm = 32; u.pn = 19 + (r - 116); } u.ko = 0; return true; }
;     __host__ __device__ bool next(int i, Unit& u) const { const int L = i * G + (G - 1 - c); if (L >= nN * S) return false; u.pm = pm; u.pn = L % nN; u.ko = (L / nN) * ksub; return true; }
; #define PG8_STAGE(bufoff, gbase, voff) do { _Pragma("unroll") for (int _i = 0; _i < 2; ++_i) \
;         __builtin_amdgcn_global_load_lds((const unsigned*)((const char*)(gbase) + (voff)[_i]), (PG8_LAS unsigned*)(lds + (bufoff) + ldsw + _i * 8192), 16, 0, 0); } while (0)
; #define PG8_LDA(dst, b, h) do { _Pragma("unroll") for (int m = 0; m < 4; ++m) _Pragma("unroll") for (int k = 0; k < 2; ++k) dst[m][k] = *(const PG8_LAS bf16x8*)(lds + PG8_SA(b, h) + aoff + m * 2048 + k * 1024); } while (0)
; #define PG8_WAIT_V(n) asm volatile("s_waitcnt vmcnt(" #n ")" ::: "memory")
; #define PG8_WAIT_L(n) asm volatile("s_waitcnt lgkmcnt(" #n ")" ::: "memory")
; template <class Epi, class Sched, bool ALIGN_EPI = false, bool SP2 = false>
; __device__ __forceinline__ void gemm_phase(PG8_LAS unsigned char* lds, const Gemm g, const Sched& S, const Epi& E) {
;     ...
;     for (;;) {
;         const bool has_next = S.next(ui + 1, nxt);
;         const char* nA = has_next ? (const char*)g.A + (size_t)nxt.pm * tstep + (size_t)nxt.ko * 2 : cA; const char* nB = has_next ? (const char*)g.Bt + (size_t)nxt.pn * tstep + (size_t)nxt.ko * 2 : cB;
;         for (int t = 0; t < nt; t += 2) {
;             const bool last = (t == nt - 2);
;             const char* a1 = cA + (size_t)(t + 1) * kstep;
;             const char* a2 = last ? nA : cA + (size_t)(t + 2) * kstep; const char* b2 = last ? nB : cB + (size_t)(t + 2) * kstep;
;             const char* a3 = a2 + kstep; const char* b3 = b2 + kstep;
;             if (last && has_next) S.a_ready(nxt);
;             if constexpr (SP2) {
;             PG8_LDB(B0, 0, 0); PG8_LDB(B1, 0, 1); PG8_SCHED; PG8_LDA(At, 0, 0); PG8_STAGE(PG8_SA(1, 1), a1 + hstep, voffA);
;             PG8_WAIT_V(8); PG8_WAIT_L(0); PG8_BAR; PG8_MMA(0, 0, At, B0); PG8_MMA(0, 1, At, B1); PG8_BAR; PG8_SCHED;
;             PG8_LDA(At, 0, 1); PG8_STAGE(PG8_SB(0, 0), b2, voffB); PG8_STAGE(PG8_SB(0, 1), b2 + hstep, voffB); PG8_STAGE(PG8_SA(0, 0), a2, voffA);
.LBB0_905:
	s_add_u32 s38, s22, s36
	s_addc_u32 s39, s23, s37
	s_add_u32 s38, s38, 0x100
	s_addc_u32 s39, s39, 0
	s_add_u32 s63, s3, s36
	s_addc_u32 s64, s59, s37
	s_add_i32 s65, 0, 0x10000
	s_cmpk_eq_i32 s36, 0xf00
	s_cselect_b32 s41, s29, s39
	s_cselect_b32 s40, s60, s38
	s_cselect_b32 s39, s27, s64
	s_cselect_b32 s38, s61, s63
	s_add_i32 s63, 0, 0x14000
	v_add_u32_e32 v156, s65, v142
	v_add_u32_e32 v172, s63, v142
	ds_read_b128 v[144:147], v156
	ds_read_b128 v[148:151], v156 offset:1024
	ds_read_b128 v[152:155], v156 offset:2048
	ds_read_b128 v[156:159], v156 offset:3072
	ds_read_b128 v[160:163], v172
	ds_read_b128 v[164:167], v172 offset:1024
	ds_read_b128 v[168:171], v172 offset:2048
	ds_read_b128 v[172:175], v172 offset:3072
	v_lshl_add_u64 v[188:189], v[134:135], 0, s[36:37]
	s_add_i32 m0, s51, 0xc000
	ds_read_b128 v[176:179], v143
	ds_read_b128 v[180:183], v143 offset:1024
	ds_read_b128 v[184:187], v143 offset:2048
	ds_read_b128 v[192:195], v143 offset:3072
	ds_read_b128 v[196:199], v143 offset:4096
	ds_read_b128 v[200:203], v143 offset:5120
	ds_read_b128 v[204:207], v143 offset:6144
	ds_read_b128 v[208:211], v143 offset:7168
	global_load_lds_dwordx4 v[188:189], off
	v_lshl_add_u64 v[188:189], v[140:141], 0, s[36:37]
	s_add_i32 m0, s51, 0xe000
	s_nop 0
	global_load_lds_dwordx4 v[188:189], off
	s_waitcnt vmcnt(8)
	s_waitcnt lgkmcnt(0)
	s_barrier
	s_setprio 0
	s_waitcnt lgkmcnt(0)
	v_mfma_f32_16x16x32_bf16 v[68:71], v[144:147], v[176:179], v[68:71]
	v_mfma_f32_16x16x32_bf16 v[72:75], v[152:155], v[176:179], v[72:75]
	v_mfma_f32_16x16x32_bf16 v[92:95], v[144:147], v[184:187], v[92:95]
	v_mfma_f32_16x16x32_bf16 v[80:83], v[152:155], v[184:187], v[80:83]
	v_mfma_f32_16x16x32_bf16 v[128:131], v[144:147], v[196:199], v[128:131]
	v_mfma_f32_16x16x32_bf16 v[112:115], v[152:155], v[196:199], v[112:115]
	v_mfma_f32_16x16x32_bf16 v[136:139], v[144:147], v[204:207], v[136:139]
	v_mfma_f32_16x16x32_bf16 v[120:123], v[152:155], v[204:207], v[120:123]
	v_mfma_f32_16x16x32_bf16 v[68:71], v[148:151], v[180:183], v[68:71]
	v_mfma_f32_16x16x32_bf16 v[72:75], v[156:159], v[180:183], v[72:75]
	v_mfma_f32_16x16x32_bf16 v[92:95], v[148:151], v[192:195], v[92:95]
	v_mfma_f32_16x16x32_bf16 v[80:83], v[156:159], v[192:195], v[80:83]
	v_mfma_f32_16x16x32_bf16 v[128:131], v[148:151], v[200:203], v[128:131]
	v_mfma_f32_16x16x32_bf16 v[112:115], v[156:159], v[200:203], v[112:115]
	v_mfma_f32_16x16x32_bf16 v[136:139], v[148:151], v[208:211], v[136:139]
	v_mfma_f32_16x16x32_bf16 v[120:123], v[156:159], v[208:211], v[120:123]
	s_setprio 0
	s_setprio 0
	v_mfma_f32_16x16x32_bf16 v[58:61], v[160:163], v[176:179], v[58:61]
	v_mfma_f32_16x16x32_bf16 v[46:49], v[168:171], v[176:179], v[46:49]
	v_mfma_f32_16x16x32_bf16 v[76:79], v[160:163], v[184:187], v[76:79]
	v_mfma_f32_16x16x32_bf16 v[50:53], v[168:171], v[184:187], v[50:53]
	v_mfma_f32_16x16x32_bf16 v[124:127], v[160:163], v[196:199], v[124:127]
	v_mfma_f32_16x16x32_bf16 v[116:119], v[168:171], v[196:199], v[116:119]
	v_mfma_f32_16x16x32_bf16 v[108:111], v[160:163], v[204:207], v[108:111]
	v_mfma_f32_16x16x32_bf16 v[104:107], v[168:171], v[204:207], v[104:107]
	v_mfma_f32_16x16x32_bf16 v[58:61], v[164:167], v[180:183], v[58:61]
	v_mfma_f32_16x16x32_bf16 v[46:49], v[172:175], v[180:183], v[46:49]
	v_mfma_f32_16x16x32_bf16 v[76:79], v[164:167], v[192:195], v[76:79]
	v_mfma_f32_16x16x32_bf16 v[50:53], v[172:175], v[192:195], v[50:53]
	v_mfma_f32_16x16x32_bf16 v[124:127], v[164:167], v[200:203], v[124:127]
	v_mfma_f32_16x16x32_bf16 v[116:119], v[172:175], v[200:203], v[116:119]
	v_mfma_f32_16x16x32_bf16 v[108:111], v[164:167], v[208:211], v[108:111]
	v_mfma_f32_16x16x32_bf16 v[104:107], v[172:175], v[208:211], v[104:107]
	s_setprio 1
	s_barrier
	s_add_i32 s64, s65, s50
	v_lshl_add_u64 v[188:189], s[38:39], 0, v[66:67]
	s_mov_b32 m0, s64
	ds_read_b128 v[176:179], v143 offset:16384
	ds_read_b128 v[180:183], v143 offset:17408
	ds_read_b128 v[184:187], v143 offset:18432
	ds_read_b128 v[192:195], v143 offset:19456
	ds_read_b128 v[196:199], v143 offset:20480
	ds_read_b128 v[200:203], v143 offset:21504
	ds_read_b128 v[204:207], v143 offset:22528
	ds_read_b128 v[208:211], v143 offset:23552
	global_load_lds_dwordx4 v[188:189], off
	s_add_i32 m0, s64, 0x2000
	s_add_u32 s64, s38, 0x80000
	v_lshl_add_u64 v[220:221], s[38:39], 0, v[84:85]
	s_addc_u32 s65, s39, 0
	s_add_i32 s63, s63, s50
	global_load_lds_dwordx4 v[220:221], off
	v_lshl_add_u64 v[222:223], s[64:65], 0, v[66:67]
	s_mov_b32 m0, s63
	v_lshl_add_u64 v[224:225], s[40:41], 0, v[84:85]
	global_load_lds_dwordx4 v[222:223], off
	v_lshl_add_u64 v[222:223], s[64:65], 0, v[84:85]
	s_add_i32 m0, s63, 0x2000
	s_nop 0
	global_load_lds_dwordx4 v[222:223], off
	v_lshl_add_u64 v[222:223], s[40:41], 0, v[66:67]
	s_mov_b32 m0, s51
	s_nop 0
	global_load_lds_dwordx4 v[222:223], off
	s_mov_b32 m0, s52
	s_nop 0
	global_load_lds_dwordx4 v[224:225], off
	s_waitcnt vmcnt(8)
	s_waitcnt lgkmcnt(0)
	s_barrier
; #define PG8_STAGE(bufoff, gbase, voff) do { _Pragma("unroll") for (int _i = 0; _i < 2; ++_i) \
;         __builtin_amdgcn_global_load_lds((const unsigned*)((const char*)(gbase) + (voff)[_i]), (PG8_LAS unsigned*)(lds + (bufoff) + ldsw + _i * 8192), 16, 0, 0); } while (0)
; #define PG8_LDA(dst, b, h) do { _Pragma("unroll") for (int m = 0; m < 4; ++m) _Pragma("unroll") for (int k = 0; k < 2; ++k) dst[m][k] = *(const PG8_LAS bf16x8*)(lds + PG8_SA(b, h) + aoff + m * 2048 + k * 1024); } while (0)
; #define PG8_LDB(dst, b, h) do { _Pragma("unroll") for (int n = 0; n < 2; ++n) _Pragma("unroll") for (int k = 0; k < 2; ++k) dst[n][k] = *(const PG8_LAS bf16x8*)(lds + PG8_SB(b, h) + boff + n * 2048 + k * 1024); } while (0)
; #define PG8_MMA(ai, bj, At, Bt) do { __builtin_amdgcn_s_setprio(1); _Pragma("unroll") for (int m = 0; m < 4; ++m) _Pragma("unroll") for (int n = 0; n < 2; ++n) _Pragma("unroll") for (int k = 0; k < 2; ++k) \
;         acc[ai][bj][m][n] = __builtin_amdgcn_mfma_f32_16x16x32_bf16(Bt[n][k], At[m][k], acc[ai][bj][m][n], 0, 0, 0); __builtin_amdgcn_s_setprio(0); } while (0)
; #define PG8_WAIT_V(n) asm volatile("s_waitcnt vmcnt(" #n ")" ::: "memory")
; #define PG8_WAIT_L(n) asm volatile("s_waitcnt lgkmcnt(" #n ")" ::: "memory")
; #define PG8_BAR __builtin_amdgcn_s_barrier()
; #define PG8_SCHED __builtin_amdgcn_sched_barrier(0)
; template <class Epi, class Sched, bool ALIGN_EPI = false, bool SP2 = false>
; __device__ __forceinline__ void gemm_phase(PG8_LAS unsigned char* lds, const Gemm g, const Sched& S, const Epi& E) {
;     ...
;             PG8_WAIT_V(8); PG8_WAIT_L(0); PG8_BAR; PG8_MMA(1, 0, At, B0); PG8_MMA(1, 1, At, B1); PG8_BAR; PG8_SCHED;
;             PG8_LDB(B0, 1, 0); PG8_LDB(B1, 1, 1); PG8_SCHED; PG8_LDA(At, 1, 0); PG8_STAGE(PG8_SA(0, 1), a2 + hstep, voffA);
;             PG8_WAIT_V(8); PG8_WAIT_L(0); PG8_BAR; PG8_MMA(0, 0, At, B0); PG8_MMA(0, 1, At, B1); PG8_BAR; PG8_SCHED;
	s_setprio 0
	s_waitcnt lgkmcnt(0)
	v_mfma_f32_16x16x32_bf16 v[100:103], v[144:147], v[176:179], v[100:103]
	v_mfma_f32_16x16x32_bf16 v[96:99], v[152:155], v[176:179], v[96:99]
	v_mfma_f32_16x16x32_bf16 v[88:91], v[144:147], v[184:187], v[88:91]
	v_mfma_f32_16x16x32_bf16 v[42:45], v[152:155], v[184:187], v[42:45]
	v_mfma_f32_16x16x32_bf16 v[38:41], v[144:147], v[196:199], v[38:41]
	v_mfma_f32_16x16x32_bf16 v[26:29], v[152:155], v[196:199], v[26:29]
	v_mfma_f32_16x16x32_bf16 v[22:25], v[144:147], v[204:207], v[22:25]
	v_mfma_f32_16x16x32_bf16 v[14:17], v[152:155], v[204:207], v[14:17]
	v_mfma_f32_16x16x32_bf16 v[100:103], v[148:151], v[180:183], v[100:103]
	v_mfma_f32_16x16x32_bf16 v[96:99], v[156:159], v[180:183], v[96:99]
	v_mfma_f32_16x16x32_bf16 v[88:91], v[148:151], v[192:195], v[88:91]
	v_mfma_f32_16x16x32_bf16 v[42:45], v[156:159], v[192:195], v[42:45]
	v_mfma_f32_16x16x32_bf16 v[38:41], v[148:151], v[200:203], v[38:41]
	v_mfma_f32_16x16x32_bf16 v[26:29], v[156:159], v[200:203], v[26:29]
	v_mfma_f32_16x16x32_bf16 v[22:25], v[148:151], v[208:211], v[22:25]
	v_mfma_f32_16x16x32_bf16 v[14:17], v[156:159], v[208:211], v[14:17]
	s_setprio 0
	s_setprio 0
	v_mfma_f32_16x16x32_bf16 v[62:65], v[160:163], v[176:179], v[62:65]
	v_mfma_f32_16x16x32_bf16 v[54:57], v[168:171], v[176:179], v[54:57]
	v_mfma_f32_16x16x32_bf16 v[34:37], v[160:163], v[184:187], v[34:37]
	v_mfma_f32_16x16x32_bf16 v[30:33], v[168:171], v[184:187], v[30:33]
	v_mfma_f32_16x16x32_bf16 v[18:21], v[160:163], v[196:199], v[18:21]
	v_mfma_f32_16x16x32_bf16 v[10:13], v[168:171], v[196:199], v[10:13]
	v_mfma_f32_16x16x32_bf16 v[6:9], v[160:163], v[204:207], v[6:9]
	v_mfma_f32_16x16x32_bf16 v[2:5], v[168:171], v[204:207], v[2:5]
	v_mfma_f32_16x16x32_bf16 v[62:65], v[164:167], v[180:183], v[62:65]
	v_mfma_f32_16x16x32_bf16 v[54:57], v[172:175], v[180:183], v[54:57]
	v_mfma_f32_16x16x32_bf16 v[34:37], v[164:167], v[192:195], v[34:37]
	v_mfma_f32_16x16x32_bf16 v[30:33], v[172:175], v[192:195], v[30:33]
	v_mfma_f32_16x16x32_bf16 v[18:21], v[164:167], v[200:203], v[18:21]
	v_mfma_f32_16x16x32_bf16 v[10:13], v[172:175], v[200:203], v[10:13]
	v_mfma_f32_16x16x32_bf16 v[6:9], v[164:167], v[208:211], v[6:9]
	v_mfma_f32_16x16x32_bf16 v[2:5], v[172:175], v[208:211], v[2:5]
	s_setprio 1
	s_barrier
	s_add_i32 s63, 0, 0x18000
	s_add_i32 s64, 0, 0x1c000
	v_add_u32_e32 v156, s63, v142
	v_add_u32_e32 v172, s64, v142
	ds_read_b128 v[144:147], v156
	ds_read_b128 v[148:151], v156 offset:1024
	ds_read_b128 v[152:155], v156 offset:2048
	ds_read_b128 v[156:159], v156 offset:3072
	ds_read_b128 v[160:163], v172
	ds_read_b128 v[164:167], v172 offset:1024
	ds_read_b128 v[168:171], v172 offset:2048
	ds_read_b128 v[172:175], v172 offset:3072
	s_add_u32 s40, s40, 0x80000
	s_addc_u32 s41, s41, 0
	s_mov_b32 m0, s1
	v_lshl_add_u64 v[226:227], s[40:41], 0, v[66:67]
	ds_read_b128 v[176:179], v143 offset:32768
	ds_read_b128 v[180:183], v143 offset:33792
	ds_read_b128 v[184:187], v143 offset:34816
	ds_read_b128 v[192:195], v143 offset:35840
	ds_read_b128 v[196:199], v143 offset:36864
	ds_read_b128 v[200:203], v143 offset:37888
	ds_read_b128 v[204:207], v143 offset:38912
	ds_read_b128 v[208:211], v143 offset:39936
	global_load_lds_dwordx4 v[226:227], off
	v_lshl_add_u64 v[226:227], s[40:41], 0, v[84:85]
	s_mov_b32 m0, s54
	s_nop 0
	global_load_lds_dwordx4 v[226:227], off
	s_waitcnt vmcnt(8)
	s_waitcnt lgkmcnt(0)
	s_barrier
	s_setprio 0
	s_waitcnt lgkmcnt(0)
	v_mfma_f32_16x16x32_bf16 v[68:71], v[144:147], v[176:179], v[68:71]
	v_mfma_f32_16x16x32_bf16 v[72:75], v[152:155], v[176:179], v[72:75]
	v_mfma_f32_16x16x32_bf16 v[92:95], v[144:147], v[184:187], v[92:95]
	v_mfma_f32_16x16x32_bf16 v[80:83], v[152:155], v[184:187], v[80:83]
	v_mfma_f32_16x16x32_bf16 v[128:131], v[144:147], v[196:199], v[128:131]
	v_mfma_f32_16x16x32_bf16 v[112:115], v[152:155], v[196:199], v[112:115]
	v_mfma_f32_16x16x32_bf16 v[136:139], v[144:147], v[204:207], v[136:139]
	v_mfma_f32_16x16x32_bf16 v[120:123], v[152:155], v[204:207], v[120:123]
	v_mfma_f32_16x16x32_bf16 v[68:71], v[148:151], v[180:183], v[68:71]
	v_mfma_f32_16x16x32_bf16 v[72:75], v[156:159], v[180:183], v[72:75]
	v_mfma_f32_16x16x32_bf16 v[92:95], v[148:151], v[192:195], v[92:95]
	v_mfma_f32_16x16x32_bf16 v[80:83], v[156:159], v[192:195], v[80:83]
	v_mfma_f32_16x16x32_bf16 v[128:131], v[148:151], v[200:203], v[128:131]
	v_mfma_f32_16x16x32_bf16 v[112:115], v[156:159], v[200:203], v[112:115]
	v_mfma_f32_16x16x32_bf16 v[136:139], v[148:151], v[208:211], v[136:139]
	v_mfma_f32_16x16x32_bf16 v[120:123], v[156:159], v[208:211], v[120:123]
	s_setprio 0
	s_setprio 0
	v_mfma_f32_16x16x32_bf16 v[58:61], v[160:163], v[176:179], v[58:61]
	v_mfma_f32_16x16x32_bf16 v[46:49], v[168:171], v[176:179], v[46:49]
	v_mfma_f32_16x16x32_bf16 v[76:79], v[160:163], v[184:187], v[76:79]
	v_mfma_f32_16x16x32_bf16 v[50:53], v[168:171], v[184:187], v[50:53]
	v_mfma_f32_16x16x32_bf16 v[124:127], v[160:163], v[196:199], v[124:127]
	v_mfma_f32_16x16x32_bf16 v[116:119], v[168:171], v[196:199], v[116:119]
	v_mfma_f32_16x16x32_bf16 v[108:111], v[160:163], v[204:207], v[108:111]
	v_mfma_f32_16x16x32_bf16 v[104:107], v[168:171], v[204:207], v[104:107]
	v_mfma_f32_16x16x32_bf16 v[58:61], v[164:167], v[180:183], v[58:61]
	v_mfma_f32_16x16x32_bf16 v[46:49], v[172:175], v[180:183], v[46:49]
	v_mfma_f32_16x16x32_bf16 v[76:79], v[164:167], v[192:195], v[76:79]
	v_mfma_f32_16x16x32_bf16 v[50:53], v[172:175], v[192:195], v[50:53]
	v_mfma_f32_16x16x32_bf16 v[124:127], v[164:167], v[200:203], v[124:127]
	v_mfma_f32_16x16x32_bf16 v[116:119], v[172:175], v[200:203], v[116:119]
	v_mfma_f32_16x16x32_bf16 v[108:111], v[164:167], v[208:211], v[108:111]
	v_mfma_f32_16x16x32_bf16 v[104:107], v[172:175], v[208:211], v[104:107]
	s_setprio 1
	s_barrier
; #define PG8_STAGE(bufoff, gbase, voff) do { _Pragma("unroll") for (int _i = 0; _i < 2; ++_i) \
;         __builtin_amdgcn_global_load_lds((const unsigned*)((const char*)(gbase) + (voff)[_i]), (PG8_LAS unsigned*)(lds + (bufoff) + ldsw + _i * 8192), 16, 0, 0); } while (0)
; #define PG8_LDA(dst, b, h) do { _Pragma("unroll") for (int m = 0; m < 4; ++m) _Pragma("unroll") for (int k = 0; k < 2; ++k) dst[m][k] = *(const PG8_LAS bf16x8*)(lds + PG8_SA(b, h) + aoff + m * 2048 + k * 1024); } while (0)
; #define PG8_MMA(ai, bj, At, Bt) do { __builtin_amdgcn_s_setprio(1); _Pragma("unroll") for (int m = 0; m < 4; ++m) _Pragma("unroll") for (int n = 0; n < 2; ++n) _Pragma("unroll") for (int k = 0; k < 2; ++k) \
;         acc[ai][bj][m][n] = __builtin_amdgcn_mfma_f32_16x16x32_bf16(Bt[n][k], At[m][k], acc[ai][bj][m][n], 0, 0, 0); __builtin_amdgcn_s_setprio(0); } while (0)
; #define PG8_WAIT_V(n) asm volatile("s_waitcnt vmcnt(" #n ")" ::: "memory")
; #define PG8_WAIT_L(n) asm volatile("s_waitcnt lgkmcnt(" #n ")" ::: "memory")
; #define PG8_BAR __builtin_amdgcn_s_barrier()
; #define PG8_SCHED __builtin_amdgcn_sched_barrier(0)
; template <class Epi, class Sched, bool ALIGN_EPI = false, bool SP2 = false>
; __device__ __forceinline__ void gemm_phase(PG8_LAS unsigned char* lds, const Gemm g, const Sched& S, const Epi& E) {
;     ...
;             PG8_LDA(At, 1, 1); PG8_STAGE(PG8_SB(1, 0), b3, voffB); PG8_STAGE(PG8_SB(1, 1), b3 + hstep, voffB); PG8_STAGE(PG8_SA(1, 0), a3, voffA);
;             PG8_WAIT_V(8); PG8_WAIT_L(0); PG8_BAR; PG8_MMA(1, 0, At, B0); PG8_MMA(1, 1, At, B1); PG8_BAR; PG8_SCHED;
;     ...
;         if (!has_next) break;
; #pragma unroll
;         for (int a = 0; a < 2; ++a)
; #pragma unroll
;             for (int b = 0; b < 2; ++b)
; #pragma unroll
;                 for (int m = 0; m < 4; ++m)
; #pragma unroll
;                     for (int n = 0; n < 2; ++n) acc[a][b][m][n] = (f32x4){0.f, 0.f, 0.f, 0.f};
;         cur = nxt; cA = nA; cB = nB; ++ui;
	s_add_i32 s40, s63, s50
	v_lshl_add_u64 v[188:189], v[188:189], 0, s[88:89]
	s_mov_b32 m0, s40
	ds_read_b128 v[176:179], v143 offset:49152
	ds_read_b128 v[180:183], v143 offset:50176
	ds_read_b128 v[184:187], v143 offset:51200
	ds_read_b128 v[192:195], v143 offset:52224
	ds_read_b128 v[196:199], v143 offset:53248
	ds_read_b128 v[200:203], v143 offset:54272
	ds_read_b128 v[204:207], v143 offset:55296
	ds_read_b128 v[208:211], v143 offset:56320
	global_load_lds_dwordx4 v[188:189], off
	s_add_i32 m0, s40, 0x2000
	s_add_u32 s38, s38, 0x80080
	v_lshl_add_u64 v[188:189], v[220:221], 0, s[88:89]
	s_addc_u32 s39, s39, 0
	s_add_i32 s40, s64, s50
	global_load_lds_dwordx4 v[188:189], off
	v_lshl_add_u64 v[188:189], s[38:39], 0, v[66:67]
	s_mov_b32 m0, s40
	s_nop 0
	global_load_lds_dwordx4 v[188:189], off
	v_lshl_add_u64 v[188:189], s[38:39], 0, v[84:85]
	s_add_i32 m0, s40, 0x2000
	s_nop 0
	global_load_lds_dwordx4 v[188:189], off
	v_lshl_add_u64 v[188:189], v[222:223], 0, s[88:89]
	s_mov_b32 m0, s55
	s_nop 0
	global_load_lds_dwordx4 v[188:189], off
	v_lshl_add_u64 v[188:189], v[224:225], 0, s[88:89]
	s_mov_b32 m0, s56
	s_nop 0
	global_load_lds_dwordx4 v[188:189], off
	s_waitcnt vmcnt(8)
	s_waitcnt lgkmcnt(0)
	s_barrier
	s_setprio 0
	s_waitcnt lgkmcnt(0)
	v_mfma_f32_16x16x32_bf16 v[100:103], v[144:147], v[176:179], v[100:103]
	v_mfma_f32_16x16x32_bf16 v[96:99], v[152:155], v[176:179], v[96:99]
	v_mfma_f32_16x16x32_bf16 v[88:91], v[144:147], v[184:187], v[88:91]
	v_mfma_f32_16x16x32_bf16 v[42:45], v[152:155], v[184:187], v[42:45]
	v_mfma_f32_16x16x32_bf16 v[38:41], v[144:147], v[196:199], v[38:41]
	v_mfma_f32_16x16x32_bf16 v[26:29], v[152:155], v[196:199], v[26:29]
	v_mfma_f32_16x16x32_bf16 v[22:25], v[144:147], v[204:207], v[22:25]
	v_mfma_f32_16x16x32_bf16 v[14:17], v[152:155], v[204:207], v[14:17]
	v_mfma_f32_16x16x32_bf16 v[100:103], v[148:151], v[180:183], v[100:103]
	v_mfma_f32_16x16x32_bf16 v[96:99], v[156:159], v[180:183], v[96:99]
	v_mfma_f32_16x16x32_bf16 v[88:91], v[148:151], v[192:195], v[88:91]
	v_mfma_f32_16x16x32_bf16 v[42:45], v[156:159], v[192:195], v[42:45]
	v_mfma_f32_16x16x32_bf16 v[38:41], v[148:151], v[200:203], v[38:41]
	v_mfma_f32_16x16x32_bf16 v[26:29], v[156:159], v[200:203], v[26:29]
	v_mfma_f32_16x16x32_bf16 v[22:25], v[148:151], v[208:211], v[22:25]
	v_mfma_f32_16x16x32_bf16 v[14:17], v[156:159], v[208:211], v[14:17]
	s_setprio 0
	s_setprio 0
	v_mfma_f32_16x16x32_bf16 v[62:65], v[160:163], v[176:179], v[62:65]
	v_mfma_f32_16x16x32_bf16 v[54:57], v[168:171], v[176:179], v[54:57]
	v_mfma_f32_16x16x32_bf16 v[34:37], v[160:163], v[184:187], v[34:37]
	v_mfma_f32_16x16x32_bf16 v[30:33], v[168:171], v[184:187], v[30:33]
	v_mfma_f32_16x16x32_bf16 v[18:21], v[160:163], v[196:199], v[18:21]
	v_mfma_f32_16x16x32_bf16 v[10:13], v[168:171], v[196:199], v[10:13]
	v_mfma_f32_16x16x32_bf16 v[6:9], v[160:163], v[204:207], v[6:9]
	v_mfma_f32_16x16x32_bf16 v[2:5], v[168:171], v[204:207], v[2:5]
	v_mfma_f32_16x16x32_bf16 v[62:65], v[164:167], v[180:183], v[62:65]
	v_mfma_f32_16x16x32_bf16 v[54:57], v[172:175], v[180:183], v[54:57]
	v_mfma_f32_16x16x32_bf16 v[34:37], v[164:167], v[192:195], v[34:37]
	v_mfma_f32_16x16x32_bf16 v[30:33], v[172:175], v[192:195], v[30:33]
	v_mfma_f32_16x16x32_bf16 v[18:21], v[164:167], v[200:203], v[18:21]
	v_mfma_f32_16x16x32_bf16 v[10:13], v[172:175], v[200:203], v[10:13]
	v_mfma_f32_16x16x32_bf16 v[6:9], v[164:167], v[208:211], v[6:9]
	v_mfma_f32_16x16x32_bf16 v[2:5], v[172:175], v[208:211], v[2:5]
	s_setprio 1
	s_barrier
	s_add_i32 s62, s62, 2
	s_add_u32 s36, s36, 0x100
	s_addc_u32 s37, s37, 0
	s_cmp_gt_u32 s62, 29
	s_cbranch_scc0 .LBB0_905
	s_add_u32 s36, s3, 0xffffff00
	s_addc_u32 s37, s59, -1
	s_andn2_b64 vcc, exec, s[10:11]
	s_cbranch_vccnz .LBB0_896
	v_mov_b32_e32 v2, 0
	s_mov_b32 s12, s26
	s_mov_b32 s46, s28
	s_mov_b64 s[22:23], s[34:35]
	s_mov_b32 s57, s2
	v_mov_b32_e32 v3, v2
	v_mov_b32_e32 v4, v2
	v_mov_b32_e32 v5, v2
	v_mov_b32_e32 v6, v2
	v_mov_b32_e32 v7, v2
	v_mov_b32_e32 v8, v2
	v_mov_b32_e32 v9, v2
	v_mov_b32_e32 v10, v2
	v_mov_b32_e32 v11, v2
	v_mov_b32_e32 v12, v2
	v_mov_b32_e32 v13, v2
	v_mov_b32_e32 v18, v2
	v_mov_b32_e32 v19, v2
	v_mov_b32_e32 v20, v2
	v_mov_b32_e32 v21, v2
	v_mov_b32_e32 v30, v2
	v_mov_b32_e32 v31, v2
	v_mov_b32_e32 v32, v2
	v_mov_b32_e32 v33, v2
	v_mov_b32_e32 v34, v2
	v_mov_b32_e32 v35, v2
	v_mov_b32_e32 v36, v2
	v_mov_b32_e32 v37, v2
	v_mov_b32_e32 v54, v2
	v_mov_b32_e32 v55, v2
	v_mov_b32_e32 v56, v2
	v_mov_b32_e32 v57, v2
	v_mov_b32_e32 v62, v2
	v_mov_b32_e32 v63, v2
	v_mov_b32_e32 v64, v2
	v_mov_b32_e32 v65, v2
	v_mov_b32_e32 v14, v2
	v_mov_b32_e32 v15, v2
	v_mov_b32_e32 v16, v2
	v_mov_b32_e32 v17, v2
	v_mov_b32_e32 v22, v2
	v_mov_b32_e32 v23, v2
	v_mov_b32_e32 v24, v2
	v_mov_b32_e32 v25, v2
	v_mov_b32_e32 v26, v2
	v_mov_b32_e32 v27, v2
	v_mov_b32_e32 v28, v2
	v_mov_b32_e32 v29, v2
	v_mov_b32_e32 v38, v2
	v_mov_b32_e32 v39, v2
	v_mov_b32_e32 v40, v2
	v_mov_b32_e32 v41, v2
	v_mov_b32_e32 v42, v2
	v_mov_b32_e32 v43, v2
	v_mov_b32_e32 v44, v2
	v_mov_b32_e32 v45, v2
	v_mov_b32_e32 v88, v2
	v_mov_b32_e32 v89, v2
	v_mov_b32_e32 v90, v2
	v_mov_b32_e32 v91, v2
	v_mov_b32_e32 v96, v2
	v_mov_b32_e32 v97, v2
	v_mov_b32_e32 v98, v2
	v_mov_b32_e32 v99, v2
	v_mov_b32_e32 v100, v2
	v_mov_b32_e32 v101, v2
	v_mov_b32_e32 v102, v2
	v_mov_b32_e32 v103, v2
	v_mov_b32_e32 v104, v2
	v_mov_b32_e32 v105, v2
	v_mov_b32_e32 v106, v2
	v_mov_b32_e32 v107, v2
	v_mov_b32_e32 v108, v2
	v_mov_b32_e32 v109, v2
	v_mov_b32_e32 v110, v2
	v_mov_b32_e32 v111, v2
	v_mov_b32_e32 v116, v2
	v_mov_b32_e32 v117, v2
	v_mov_b32_e32 v118, v2
	v_mov_b32_e32 v119, v2
	v_mov_b32_e32 v124, v2
	v_mov_b32_e32 v125, v2
	v_mov_b32_e32 v126, v2
	v_mov_b32_e32 v127, v2
	v_mov_b32_e32 v50, v2
	v_mov_b32_e32 v51, v2
	v_mov_b32_e32 v52, v2
	v_mov_b32_e32 v53, v2
	v_mov_b32_e32 v76, v2
	v_mov_b32_e32 v77, v2
	v_mov_b32_e32 v78, v2
	v_mov_b32_e32 v79, v2
	v_mov_b32_e32 v46, v2
	v_mov_b32_e32 v47, v2
	v_mov_b32_e32 v48, v2
	v_mov_b32_e32 v49, v2
	v_mov_b32_e32 v58, v2
	v_mov_b32_e32 v59, v2
	v_mov_b32_e32 v60, v2
	v_mov_b32_e32 v61, v2
	v_mov_b32_e32 v120, v2
	v_mov_b32_e32 v121, v2
	v_mov_b32_e32 v122, v2
	v_mov_b32_e32 v123, v2
	v_mov_b32_e32 v136, v2
	v_mov_b32_e32 v137, v2
	v_mov_b32_e32 v138, v2
	v_mov_b32_e32 v139, v2
	v_mov_b32_e32 v112, v2
	v_mov_b32_e32 v113, v2
	v_mov_b32_e32 v114, v2
	v_mov_b32_e32 v115, v2
	v_mov_b32_e32 v128, v2
	v_mov_b32_e32 v129, v2
	v_mov_b32_e32 v130, v2
	v_mov_b32_e32 v131, v2
	v_mov_b32_e32 v80, v2
	v_mov_b32_e32 v81, v2
	v_mov_b32_e32 v82, v2
	v_mov_b32_e32 v83, v2
	v_mov_b32_e32 v92, v2
	v_mov_b32_e32 v93, v2
	v_mov_b32_e32 v94, v2
	v_mov_b32_e32 v95, v2
	v_mov_b32_e32 v72, v2
	v_mov_b32_e32 v73, v2
	v_mov_b32_e32 v74, v2
	v_mov_b32_e32 v75, v2
	v_mov_b32_e32 v68, v2
	v_mov_b32_e32 v69, v2
	v_mov_b32_e32 v70, v2
	v_mov_b32_e32 v71, v2
	s_mov_b64 s[64:65], s[72:73]
	s_andn2_b64 vcc, exec, s[8:9]
	s_mov_b32 s72, s67
	s_cbranch_vccnz .LBB0_897

; #define PG8_STAGE(bufoff, gbase, voff) do { _Pragma("unroll") for (int _i = 0; _i < 2; ++_i) \
;         __builtin_amdgcn_global_load_lds((const unsigned*)((const char*)(gbase) + (voff)[_i]), (PG8_LAS unsigned*)(lds + (bufoff) + ldsw + _i * 8192), 16, 0, 0); } while (0)
; #define PG8_LDA(dst, b, h) do { _Pragma("unroll") for (int m = 0; m < 4; ++m) _Pragma("unroll") for (int k = 0; k < 2; ++k) dst[m][k] = *(const PG8_LAS bf16x8*)(lds + PG8_SA(b, h) + aoff + m * 2048 + k * 1024); } while (0)
; #define PG8_LDB(dst, b, h) do { _Pragma("unroll") for (int n = 0; n < 2; ++n) _Pragma("unroll") for (int k = 0; k < 2; ++k) dst[n][k] = *(const PG8_LAS bf16x8*)(lds + PG8_SB(b, h) + boff + n * 2048 + k * 1024); } while (0)
; #define PG8_MMA(ai, bj, At, Bt) do { __builtin_amdgcn_s_setprio(1); _Pragma("unroll") for (int m = 0; m < 4; ++m) _Pragma("unroll") for (int n = 0; n < 2; ++n) _Pragma("unroll") for (int k = 0; k < 2; ++k) \
;         acc[ai][bj][m][n] = __builtin_amdgcn_mfma_f32_16x16x32_bf16(Bt[n][k], At[m][k], acc[ai][bj][m][n], 0, 0, 0); __builtin_amdgcn_s_setprio(0); } while (0)
; #define PG8_BAR __builtin_amdgcn_s_barrier()
; template <class Epi, class Sched, bool ALIGN_EPI = false, bool SP2 = false>
; __device__ __forceinline__ void gemm_phase(PG8_LAS unsigned char* lds, const Gemm g, const Sched& S, const Epi& E) {
;     ...
;         const char* nA = has_next ? (const char*)g.A + (size_t)nxt.pm * tstep + (size_t)nxt.ko * 2 : cA; const char* nB = has_next ? (const char*)g.Bt + (size_t)nxt.pn * tstep + (size_t)nxt.ko * 2 : cB;
;         for (int t = 0; t < nt; t += 2) {
;             const bool last = (t == nt - 2);
;             const char* a1 = cA + (size_t)(t + 1) * kstep;
;             const char* a2 = last ? nA : cA + (size_t)(t + 2) * kstep; const char* b2 = last ? nB : cB + (size_t)(t + 2) * kstep;
;             const char* a3 = a2 + kstep; const char* b3 = b2 + kstep;
;             if (last && has_next) S.a_ready(nxt);
;             if constexpr (SP2) {
;             PG8_LDB(B0, 0, 0); PG8_LDB(B1, 0, 1); PG8_SCHED; PG8_LDA(At, 0, 0); PG8_STAGE(PG8_SA(1, 1), a1 + hstep, voffA);
;             PG8_WAIT_V(8); PG8_WAIT_L(0); PG8_BAR; PG8_MMA(0, 0, At, B0); PG8_MMA(0, 1, At, B1); PG8_BAR; PG8_SCHED;
;             PG8_LDA(At, 0, 1); PG8_STAGE(PG8_SB(0, 0), b2, voffB); PG8_STAGE(PG8_SB(0, 1), b2 + hstep, voffB); PG8_STAGE(PG8_SA(0, 0), a2, voffA);
.LBB0_979:
	s_xor_b64 s[40:41], s[38:39], -1
	s_add_u32 s27, s12, s2
	s_addc_u32 s29, s13, 0
	s_add_u32 s3, s27, 0x100
	s_addc_u32 s44, s29, 0
	s_and_b64 s[42:43], s[38:39], exec
	s_cselect_b32 s43, s44, s35
	s_cselect_b32 s42, s3, s34
	s_add_u32 s2, s20, s2
	s_addc_u32 s3, s21, 0
	s_add_u32 s44, s2, 0x100
	s_addc_u32 s45, s3, 0
	s_and_b64 s[2:3], s[38:39], exec
	s_cselect_b32 s39, s45, s31
	s_cselect_b32 s38, s44, s30
	s_add_i32 s44, 0, 0x10000
	s_add_i32 s45, 0, 0x14000
	v_add_u32_e32 v164, s44, v0
	v_add_u32_e32 v180, s45, v0
	ds_read_b128 v[152:155], v164
	ds_read_b128 v[156:159], v164 offset:1024
	ds_read_b128 v[160:163], v164 offset:2048
	ds_read_b128 v[164:167], v164 offset:3072
	ds_read_b128 v[168:171], v180
	ds_read_b128 v[172:175], v180 offset:1024
	ds_read_b128 v[176:179], v180 offset:2048
	ds_read_b128 v[180:183], v180 offset:3072
	s_add_u32 s2, s27, 0x80080
	s_addc_u32 s3, s29, 0
	v_lshl_add_u64 v[224:225], s[2:3], 0, v[66:67]
	s_add_i32 m0, s52, 0xc000
	ds_read_b128 v[184:187], v151
	ds_read_b128 v[188:191], v151 offset:1024
	ds_read_b128 v[192:195], v151 offset:2048
	ds_read_b128 v[196:199], v151 offset:3072
	ds_read_b128 v[200:203], v151 offset:4096
	ds_read_b128 v[204:207], v151 offset:5120
	ds_read_b128 v[208:211], v151 offset:6144
	ds_read_b128 v[220:223], v151 offset:7168
	global_load_lds_dwordx4 v[224:225], off
	v_lshl_add_u64 v[224:225], s[2:3], 0, v[132:133]
	s_add_i32 m0, s52, 0xe000
	s_nop 0
	global_load_lds_dwordx4 v[224:225], off
	s_waitcnt vmcnt(8)
	s_waitcnt lgkmcnt(0)
	s_barrier
	s_setprio 0
	s_waitcnt lgkmcnt(0)
	v_mfma_f32_16x16x32_bf16 v[128:131], v[152:155], v[184:187], v[128:131]
	v_mfma_f32_16x16x32_bf16 v[124:127], v[160:163], v[184:187], v[124:127]
	v_mfma_f32_16x16x32_bf16 v[120:123], v[152:155], v[192:195], v[120:123]
	v_mfma_f32_16x16x32_bf16 v[116:119], v[160:163], v[192:195], v[116:119]
	v_mfma_f32_16x16x32_bf16 v[112:115], v[152:155], v[200:203], v[112:115]
	v_mfma_f32_16x16x32_bf16 v[108:111], v[160:163], v[200:203], v[108:111]
	v_mfma_f32_16x16x32_bf16 v[100:103], v[152:155], v[208:211], v[100:103]
	v_mfma_f32_16x16x32_bf16 v[92:95], v[160:163], v[208:211], v[92:95]
	v_mfma_f32_16x16x32_bf16 v[128:131], v[156:159], v[188:191], v[128:131]
	v_mfma_f32_16x16x32_bf16 v[124:127], v[164:167], v[188:191], v[124:127]
	v_mfma_f32_16x16x32_bf16 v[120:123], v[156:159], v[196:199], v[120:123]
	v_mfma_f32_16x16x32_bf16 v[116:119], v[164:167], v[196:199], v[116:119]
	v_mfma_f32_16x16x32_bf16 v[112:115], v[156:159], v[204:207], v[112:115]
	v_mfma_f32_16x16x32_bf16 v[108:111], v[164:167], v[204:207], v[108:111]
	v_mfma_f32_16x16x32_bf16 v[100:103], v[156:159], v[220:223], v[100:103]
	v_mfma_f32_16x16x32_bf16 v[92:95], v[164:167], v[220:223], v[92:95]
	s_setprio 0
	s_setprio 0
	v_mfma_f32_16x16x32_bf16 v[104:107], v[168:171], v[184:187], v[104:107]
	v_mfma_f32_16x16x32_bf16 v[96:99], v[176:179], v[184:187], v[96:99]
	v_mfma_f32_16x16x32_bf16 v[88:91], v[168:171], v[192:195], v[88:91]
	v_mfma_f32_16x16x32_bf16 v[84:87], v[176:179], v[192:195], v[84:87]
	v_mfma_f32_16x16x32_bf16 v[80:83], v[168:171], v[200:203], v[80:83]
	v_mfma_f32_16x16x32_bf16 v[76:79], v[176:179], v[200:203], v[76:79]
	v_mfma_f32_16x16x32_bf16 v[72:75], v[168:171], v[208:211], v[72:75]
	v_mfma_f32_16x16x32_bf16 v[68:71], v[176:179], v[208:211], v[68:71]
	v_mfma_f32_16x16x32_bf16 v[104:107], v[172:175], v[188:191], v[104:107]
	v_mfma_f32_16x16x32_bf16 v[96:99], v[180:183], v[188:191], v[96:99]
	v_mfma_f32_16x16x32_bf16 v[88:91], v[172:175], v[196:199], v[88:91]
	v_mfma_f32_16x16x32_bf16 v[84:87], v[180:183], v[196:199], v[84:87]
	v_mfma_f32_16x16x32_bf16 v[80:83], v[172:175], v[204:207], v[80:83]
	v_mfma_f32_16x16x32_bf16 v[76:79], v[180:183], v[204:207], v[76:79]
	v_mfma_f32_16x16x32_bf16 v[72:75], v[172:175], v[220:223], v[72:75]
	v_mfma_f32_16x16x32_bf16 v[68:71], v[180:183], v[220:223], v[68:71]
	s_setprio 1
	s_barrier
	s_add_i32 s2, s44, s51
	v_lshl_add_u64 v[224:225], s[38:39], 0, v[66:67]
	s_mov_b32 m0, s2
	ds_read_b128 v[184:187], v151 offset:16384
	ds_read_b128 v[188:191], v151 offset:17408
	ds_read_b128 v[192:195], v151 offset:18432
	ds_read_b128 v[196:199], v151 offset:19456
	ds_read_b128 v[200:203], v151 offset:20480
	ds_read_b128 v[204:207], v151 offset:21504
	ds_read_b128 v[208:211], v151 offset:22528
	ds_read_b128 v[220:223], v151 offset:23552
	global_load_lds_dwordx4 v[224:225], off
	s_add_i32 m0, s2, 0x2000
	s_add_u32 s2, s38, 0x80000
	v_lshl_add_u64 v[226:227], s[38:39], 0, v[132:133]
	s_addc_u32 s3, s39, 0
	s_add_i32 s27, s45, s51
	global_load_lds_dwordx4 v[226:227], off
	v_lshl_add_u64 v[228:229], s[2:3], 0, v[66:67]
	s_mov_b32 m0, s27
	v_lshl_add_u64 v[230:231], s[42:43], 0, v[132:133]
	global_load_lds_dwordx4 v[228:229], off
	v_lshl_add_u64 v[228:229], s[2:3], 0, v[132:133]
	s_add_i32 m0, s27, 0x2000
	s_nop 0
	global_load_lds_dwordx4 v[228:229], off
	v_lshl_add_u64 v[228:229], s[42:43], 0, v[66:67]
	s_mov_b32 m0, s52
	s_nop 0
	global_load_lds_dwordx4 v[228:229], off
	s_mov_b32 m0, s53
	s_nop 0
	global_load_lds_dwordx4 v[230:231], off
	s_waitcnt vmcnt(8)
	s_waitcnt lgkmcnt(0)
	s_barrier
; #define PG8_STAGE(bufoff, gbase, voff) do { _Pragma("unroll") for (int _i = 0; _i < 2; ++_i) \
;         __builtin_amdgcn_global_load_lds((const unsigned*)((const char*)(gbase) + (voff)[_i]), (PG8_LAS unsigned*)(lds + (bufoff) + ldsw + _i * 8192), 16, 0, 0); } while (0)
; #define PG8_LDA(dst, b, h) do { _Pragma("unroll") for (int m = 0; m < 4; ++m) _Pragma("unroll") for (int k = 0; k < 2; ++k) dst[m][k] = *(const PG8_LAS bf16x8*)(lds + PG8_SA(b, h) + aoff + m * 2048 + k * 1024); } while (0)
; #define PG8_LDB(dst, b, h) do { _Pragma("unroll") for (int n = 0; n < 2; ++n) _Pragma("unroll") for (int k = 0; k < 2; ++k) dst[n][k] = *(const PG8_LAS bf16x8*)(lds + PG8_SB(b, h) + boff + n * 2048 + k * 1024); } while (0)
; #define PG8_MMA(ai, bj, At, Bt) do { __builtin_amdgcn_s_setprio(1); _Pragma("unroll") for (int m = 0; m < 4; ++m) _Pragma("unroll") for (int n = 0; n < 2; ++n) _Pragma("unroll") for (int k = 0; k < 2; ++k) \
;         acc[ai][bj][m][n] = __builtin_amdgcn_mfma_f32_16x16x32_bf16(Bt[n][k], At[m][k], acc[ai][bj][m][n], 0, 0, 0); __builtin_amdgcn_s_setprio(0); } while (0)
; #define PG8_WAIT_V(n) asm volatile("s_waitcnt vmcnt(" #n ")" ::: "memory")
; #define PG8_WAIT_L(n) asm volatile("s_waitcnt lgkmcnt(" #n ")" ::: "memory")
; #define PG8_BAR __builtin_amdgcn_s_barrier()
; #define PG8_SCHED __builtin_amdgcn_sched_barrier(0)
; template <class Epi, class Sched, bool ALIGN_EPI = false, bool SP2 = false>
; __device__ __forceinline__ void gemm_phase(PG8_LAS unsigned char* lds, const Gemm g, const Sched& S, const Epi& E) {
;     ...
;             PG8_WAIT_V(8); PG8_WAIT_L(0); PG8_BAR; PG8_MMA(1, 0, At, B0); PG8_MMA(1, 1, At, B1); PG8_BAR; PG8_SCHED;
;             PG8_LDB(B0, 1, 0); PG8_LDB(B1, 1, 1); PG8_SCHED; PG8_LDA(At, 1, 0); PG8_STAGE(PG8_SA(0, 1), a2 + hstep, voffA);
;             PG8_WAIT_V(8); PG8_WAIT_L(0); PG8_BAR; PG8_MMA(0, 0, At, B0); PG8_MMA(0, 1, At, B1); PG8_BAR; PG8_SCHED;
	s_setprio 0
	s_waitcnt lgkmcnt(0)
	v_mfma_f32_16x16x32_bf16 v[62:65], v[152:155], v[184:187], v[62:65]
	v_mfma_f32_16x16x32_bf16 v[58:61], v[160:163], v[184:187], v[58:61]
	v_mfma_f32_16x16x32_bf16 v[54:57], v[152:155], v[192:195], v[54:57]
	v_mfma_f32_16x16x32_bf16 v[50:53], v[160:163], v[192:195], v[50:53]
	v_mfma_f32_16x16x32_bf16 v[46:49], v[152:155], v[200:203], v[46:49]
	v_mfma_f32_16x16x32_bf16 v[42:45], v[160:163], v[200:203], v[42:45]
	v_mfma_f32_16x16x32_bf16 v[34:37], v[152:155], v[208:211], v[34:37]
	v_mfma_f32_16x16x32_bf16 v[26:29], v[160:163], v[208:211], v[26:29]
	v_mfma_f32_16x16x32_bf16 v[62:65], v[156:159], v[188:191], v[62:65]
	v_mfma_f32_16x16x32_bf16 v[58:61], v[164:167], v[188:191], v[58:61]
	v_mfma_f32_16x16x32_bf16 v[54:57], v[156:159], v[196:199], v[54:57]
	v_mfma_f32_16x16x32_bf16 v[50:53], v[164:167], v[196:199], v[50:53]
	v_mfma_f32_16x16x32_bf16 v[46:49], v[156:159], v[204:207], v[46:49]
	v_mfma_f32_16x16x32_bf16 v[42:45], v[164:167], v[204:207], v[42:45]
	v_mfma_f32_16x16x32_bf16 v[34:37], v[156:159], v[220:223], v[34:37]
	v_mfma_f32_16x16x32_bf16 v[26:29], v[164:167], v[220:223], v[26:29]
	s_setprio 0
	s_setprio 0
	v_mfma_f32_16x16x32_bf16 v[38:41], v[168:171], v[184:187], v[38:41]
	v_mfma_f32_16x16x32_bf16 v[30:33], v[176:179], v[184:187], v[30:33]
	v_mfma_f32_16x16x32_bf16 v[22:25], v[168:171], v[192:195], v[22:25]
	v_mfma_f32_16x16x32_bf16 v[18:21], v[176:179], v[192:195], v[18:21]
	v_mfma_f32_16x16x32_bf16 v[14:17], v[168:171], v[200:203], v[14:17]
	v_mfma_f32_16x16x32_bf16 v[10:13], v[176:179], v[200:203], v[10:13]
	v_mfma_f32_16x16x32_bf16 v[6:9], v[168:171], v[208:211], v[6:9]
	v_mfma_f32_16x16x32_bf16 v[2:5], v[176:179], v[208:211], v[2:5]
	v_mfma_f32_16x16x32_bf16 v[38:41], v[172:175], v[188:191], v[38:41]
	v_mfma_f32_16x16x32_bf16 v[30:33], v[180:183], v[188:191], v[30:33]
	v_mfma_f32_16x16x32_bf16 v[22:25], v[172:175], v[196:199], v[22:25]
	v_mfma_f32_16x16x32_bf16 v[18:21], v[180:183], v[196:199], v[18:21]
	v_mfma_f32_16x16x32_bf16 v[14:17], v[172:175], v[204:207], v[14:17]
	v_mfma_f32_16x16x32_bf16 v[10:13], v[180:183], v[204:207], v[10:13]
	v_mfma_f32_16x16x32_bf16 v[6:9], v[172:175], v[220:223], v[6:9]
	v_mfma_f32_16x16x32_bf16 v[2:5], v[180:183], v[220:223], v[2:5]
	s_setprio 1
	s_barrier
	s_add_i32 s27, 0, 0x18000
	s_add_i32 s29, 0, 0x1c000
	v_add_u32_e32 v164, s27, v0
	v_add_u32_e32 v180, s29, v0
	ds_read_b128 v[152:155], v164
	ds_read_b128 v[156:159], v164 offset:1024
	ds_read_b128 v[160:163], v164 offset:2048
	ds_read_b128 v[164:167], v164 offset:3072
	ds_read_b128 v[168:171], v180
	ds_read_b128 v[172:175], v180 offset:1024
	ds_read_b128 v[176:179], v180 offset:2048
	ds_read_b128 v[180:183], v180 offset:3072
	s_add_u32 s2, s42, 0x80000
	s_addc_u32 s3, s43, 0
	s_mov_b32 m0, s54
	v_lshl_add_u64 v[232:233], s[2:3], 0, v[66:67]
	ds_read_b128 v[184:187], v151 offset:32768
	ds_read_b128 v[188:191], v151 offset:33792
	ds_read_b128 v[192:195], v151 offset:34816
	ds_read_b128 v[196:199], v151 offset:35840
	ds_read_b128 v[200:203], v151 offset:36864
	ds_read_b128 v[204:207], v151 offset:37888
	ds_read_b128 v[208:211], v151 offset:38912
	ds_read_b128 v[220:223], v151 offset:39936
	global_load_lds_dwordx4 v[232:233], off
	v_lshl_add_u64 v[232:233], s[2:3], 0, v[132:133]
	s_mov_b32 m0, s55
	s_nop 0
	global_load_lds_dwordx4 v[232:233], off
	s_waitcnt vmcnt(8)
	s_waitcnt lgkmcnt(0)
	s_barrier
	s_setprio 0
	s_waitcnt lgkmcnt(0)
	v_mfma_f32_16x16x32_bf16 v[128:131], v[152:155], v[184:187], v[128:131]
	v_mfma_f32_16x16x32_bf16 v[124:127], v[160:163], v[184:187], v[124:127]
	v_mfma_f32_16x16x32_bf16 v[120:123], v[152:155], v[192:195], v[120:123]
	v_mfma_f32_16x16x32_bf16 v[116:119], v[160:163], v[192:195], v[116:119]
	v_mfma_f32_16x16x32_bf16 v[112:115], v[152:155], v[200:203], v[112:115]
	v_mfma_f32_16x16x32_bf16 v[108:111], v[160:163], v[200:203], v[108:111]
	v_mfma_f32_16x16x32_bf16 v[100:103], v[152:155], v[208:211], v[100:103]
	v_mfma_f32_16x16x32_bf16 v[92:95], v[160:163], v[208:211], v[92:95]
	v_mfma_f32_16x16x32_bf16 v[128:131], v[156:159], v[188:191], v[128:131]
	v_mfma_f32_16x16x32_bf16 v[124:127], v[164:167], v[188:191], v[124:127]
	v_mfma_f32_16x16x32_bf16 v[120:123], v[156:159], v[196:199], v[120:123]
	v_mfma_f32_16x16x32_bf16 v[116:119], v[164:167], v[196:199], v[116:119]
	v_mfma_f32_16x16x32_bf16 v[112:115], v[156:159], v[204:207], v[112:115]
	v_mfma_f32_16x16x32_bf16 v[108:111], v[164:167], v[204:207], v[108:111]
	v_mfma_f32_16x16x32_bf16 v[100:103], v[156:159], v[220:223], v[100:103]
	v_mfma_f32_16x16x32_bf16 v[92:95], v[164:167], v[220:223], v[92:95]
	s_setprio 0
	s_setprio 0
	v_mfma_f32_16x16x32_bf16 v[104:107], v[168:171], v[184:187], v[104:107]
	v_mfma_f32_16x16x32_bf16 v[96:99], v[176:179], v[184:187], v[96:99]
	v_mfma_f32_16x16x32_bf16 v[88:91], v[168:171], v[192:195], v[88:91]
	v_mfma_f32_16x16x32_bf16 v[84:87], v[176:179], v[192:195], v[84:87]
	v_mfma_f32_16x16x32_bf16 v[80:83], v[168:171], v[200:203], v[80:83]
	v_mfma_f32_16x16x32_bf16 v[76:79], v[176:179], v[200:203], v[76:79]
	v_mfma_f32_16x16x32_bf16 v[72:75], v[168:171], v[208:211], v[72:75]
	v_mfma_f32_16x16x32_bf16 v[68:71], v[176:179], v[208:211], v[68:71]
	v_mfma_f32_16x16x32_bf16 v[104:107], v[172:175], v[188:191], v[104:107]
	v_mfma_f32_16x16x32_bf16 v[96:99], v[180:183], v[188:191], v[96:99]
	v_mfma_f32_16x16x32_bf16 v[88:91], v[172:175], v[196:199], v[88:91]
	v_mfma_f32_16x16x32_bf16 v[84:87], v[180:183], v[196:199], v[84:87]
	v_mfma_f32_16x16x32_bf16 v[80:83], v[172:175], v[204:207], v[80:83]
	v_mfma_f32_16x16x32_bf16 v[76:79], v[180:183], v[204:207], v[76:79]
	v_mfma_f32_16x16x32_bf16 v[72:75], v[172:175], v[220:223], v[72:75]
	v_mfma_f32_16x16x32_bf16 v[68:71], v[180:183], v[220:223], v[68:71]
	s_setprio 1
	s_barrier
; #define PG8_STAGE(bufoff, gbase, voff) do { _Pragma("unroll") for (int _i = 0; _i < 2; ++_i) \
;         __builtin_amdgcn_global_load_lds((const unsigned*)((const char*)(gbase) + (voff)[_i]), (PG8_LAS unsigned*)(lds + (bufoff) + ldsw + _i * 8192), 16, 0, 0); } while (0)
; #define PG8_LDA(dst, b, h) do { _Pragma("unroll") for (int m = 0; m < 4; ++m) _Pragma("unroll") for (int k = 0; k < 2; ++k) dst[m][k] = *(const PG8_LAS bf16x8*)(lds + PG8_SA(b, h) + aoff + m * 2048 + k * 1024); } while (0)
; #define PG8_MMA(ai, bj, At, Bt) do { __builtin_amdgcn_s_setprio(1); _Pragma("unroll") for (int m = 0; m < 4; ++m) _Pragma("unroll") for (int n = 0; n < 2; ++n) _Pragma("unroll") for (int k = 0; k < 2; ++k) \
;         acc[ai][bj][m][n] = __builtin_amdgcn_mfma_f32_16x16x32_bf16(Bt[n][k], At[m][k], acc[ai][bj][m][n], 0, 0, 0); __builtin_amdgcn_s_setprio(0); } while (0)
; #define PG8_WAIT_V(n) asm volatile("s_waitcnt vmcnt(" #n ")" ::: "memory")
; #define PG8_WAIT_L(n) asm volatile("s_waitcnt lgkmcnt(" #n ")" ::: "memory")
; #define PG8_BAR __builtin_amdgcn_s_barrier()
; #define PG8_SCHED __builtin_amdgcn_sched_barrier(0)
; template <class Epi, class Sched, bool ALIGN_EPI = false, bool SP2 = false>
; __device__ __forceinline__ void gemm_phase(PG8_LAS unsigned char* lds, const Gemm g, const Sched& S, const Epi& E) {
;     ...
;             PG8_LDA(At, 1, 1); PG8_STAGE(PG8_SB(1, 0), b3, voffB); PG8_STAGE(PG8_SB(1, 1), b3 + hstep, voffB); PG8_STAGE(PG8_SA(1, 0), a3, voffA);
;             PG8_WAIT_V(8); PG8_WAIT_L(0); PG8_BAR; PG8_MMA(1, 0, At, B0); PG8_MMA(1, 1, At, B1); PG8_BAR; PG8_SCHED;
	s_add_i32 s2, s27, s51
	v_lshl_add_u64 v[224:225], v[224:225], 0, s[88:89]
	s_mov_b32 m0, s2
	ds_read_b128 v[184:187], v151 offset:49152
	ds_read_b128 v[188:191], v151 offset:50176
	ds_read_b128 v[192:195], v151 offset:51200
	ds_read_b128 v[196:199], v151 offset:52224
	ds_read_b128 v[200:203], v151 offset:53248
	ds_read_b128 v[204:207], v151 offset:54272
	ds_read_b128 v[208:211], v151 offset:55296
	ds_read_b128 v[220:223], v151 offset:56320
	global_load_lds_dwordx4 v[224:225], off
	s_add_i32 m0, s2, 0x2000
	s_add_u32 s2, s38, 0x80080
	v_lshl_add_u64 v[224:225], v[226:227], 0, s[88:89]
	s_addc_u32 s3, s39, 0
	s_add_i32 s27, s29, s51
	global_load_lds_dwordx4 v[224:225], off
	v_lshl_add_u64 v[224:225], s[2:3], 0, v[66:67]
	s_mov_b32 m0, s27
	s_nop 0
	global_load_lds_dwordx4 v[224:225], off
	v_lshl_add_u64 v[224:225], s[2:3], 0, v[132:133]
	s_add_i32 m0, s27, 0x2000
	s_nop 0
	global_load_lds_dwordx4 v[224:225], off
	v_lshl_add_u64 v[224:225], v[228:229], 0, s[88:89]
	s_mov_b32 m0, s59
	s_nop 0
	global_load_lds_dwordx4 v[224:225], off
	v_lshl_add_u64 v[224:225], v[230:231], 0, s[88:89]
	s_mov_b32 m0, s60
	s_nop 0
	global_load_lds_dwordx4 v[224:225], off
	s_waitcnt vmcnt(8)
	s_waitcnt lgkmcnt(0)
	s_barrier
	s_setprio 0
	s_waitcnt lgkmcnt(0)
	v_mfma_f32_16x16x32_bf16 v[62:65], v[152:155], v[184:187], v[62:65]
	v_mfma_f32_16x16x32_bf16 v[58:61], v[160:163], v[184:187], v[58:61]
	v_mfma_f32_16x16x32_bf16 v[54:57], v[152:155], v[192:195], v[54:57]
	v_mfma_f32_16x16x32_bf16 v[50:53], v[160:163], v[192:195], v[50:53]
	v_mfma_f32_16x16x32_bf16 v[46:49], v[152:155], v[200:203], v[46:49]
	v_mfma_f32_16x16x32_bf16 v[42:45], v[160:163], v[200:203], v[42:45]
	v_mfma_f32_16x16x32_bf16 v[34:37], v[152:155], v[208:211], v[34:37]
	v_mfma_f32_16x16x32_bf16 v[26:29], v[160:163], v[208:211], v[26:29]
	v_mfma_f32_16x16x32_bf16 v[62:65], v[156:159], v[188:191], v[62:65]
	v_mfma_f32_16x16x32_bf16 v[58:61], v[164:167], v[188:191], v[58:61]
	v_mfma_f32_16x16x32_bf16 v[54:57], v[156:159], v[196:199], v[54:57]
	v_mfma_f32_16x16x32_bf16 v[50:53], v[164:167], v[196:199], v[50:53]
	v_mfma_f32_16x16x32_bf16 v[46:49], v[156:159], v[204:207], v[46:49]
	v_mfma_f32_16x16x32_bf16 v[42:45], v[164:167], v[204:207], v[42:45]
	v_mfma_f32_16x16x32_bf16 v[34:37], v[156:159], v[220:223], v[34:37]
	v_mfma_f32_16x16x32_bf16 v[26:29], v[164:167], v[220:223], v[26:29]
	s_setprio 0
	s_setprio 0
	v_mfma_f32_16x16x32_bf16 v[38:41], v[168:171], v[184:187], v[38:41]
	v_mfma_f32_16x16x32_bf16 v[30:33], v[176:179], v[184:187], v[30:33]
	v_mfma_f32_16x16x32_bf16 v[22:25], v[168:171], v[192:195], v[22:25]
	v_mfma_f32_16x16x32_bf16 v[18:21], v[176:179], v[192:195], v[18:21]
	v_mfma_f32_16x16x32_bf16 v[14:17], v[168:171], v[200:203], v[14:17]
	v_mfma_f32_16x16x32_bf16 v[10:13], v[176:179], v[200:203], v[10:13]
	v_mfma_f32_16x16x32_bf16 v[6:9], v[168:171], v[208:211], v[6:9]
	v_mfma_f32_16x16x32_bf16 v[2:5], v[176:179], v[208:211], v[2:5]
	v_mfma_f32_16x16x32_bf16 v[38:41], v[172:175], v[188:191], v[38:41]
	v_mfma_f32_16x16x32_bf16 v[30:33], v[180:183], v[188:191], v[30:33]
	v_mfma_f32_16x16x32_bf16 v[22:25], v[172:175], v[196:199], v[22:25]
	v_mfma_f32_16x16x32_bf16 v[18:21], v[180:183], v[196:199], v[18:21]
	v_mfma_f32_16x16x32_bf16 v[14:17], v[172:175], v[204:207], v[14:17]
	v_mfma_f32_16x16x32_bf16 v[10:13], v[180:183], v[204:207], v[10:13]
	v_mfma_f32_16x16x32_bf16 v[6:9], v[172:175], v[220:223], v[6:9]
	v_mfma_f32_16x16x32_bf16 v[2:5], v[180:183], v[220:223], v[2:5]
	s_setprio 1
	s_barrier
	s_movk_i32 s2, 0x100
	s_mov_b64 s[38:39], 0
	s_and_b64 vcc, exec, s[40:41]
	s_cbranch_vccnz .LBB0_991

; #define PG8_STAGE(bufoff, gbase, voff) do { _Pragma("unroll") for (int _i = 0; _i < 2; ++_i) \
;         __builtin_amdgcn_global_load_lds((const unsigned*)((const char*)(gbase) + (voff)[_i]), (PG8_LAS unsigned*)(lds + (bufoff) + ldsw + _i * 8192), 16, 0, 0); } while (0)
; #define PG8_LDA(dst, b, h) do { _Pragma("unroll") for (int m = 0; m < 4; ++m) _Pragma("unroll") for (int k = 0; k < 2; ++k) dst[m][k] = *(const PG8_LAS bf16x8*)(lds + PG8_SA(b, h) + aoff + m * 2048 + k * 1024); } while (0)
; #define PG8_LDB(dst, b, h) do { _Pragma("unroll") for (int n = 0; n < 2; ++n) _Pragma("unroll") for (int k = 0; k < 2; ++k) dst[n][k] = *(const PG8_LAS bf16x8*)(lds + PG8_SB(b, h) + boff + n * 2048 + k * 1024); } while (0)
; #define PG8_MMA(ai, bj, At, Bt) do { __builtin_amdgcn_s_setprio(1); _Pragma("unroll") for (int m = 0; m < 4; ++m) _Pragma("unroll") for (int n = 0; n < 2; ++n) _Pragma("unroll") for (int k = 0; k < 2; ++k) \
;         acc[ai][bj][m][n] = __builtin_amdgcn_mfma_f32_16x16x32_bf16(Bt[n][k], At[m][k], acc[ai][bj][m][n], 0, 0, 0); __builtin_amdgcn_s_setprio(0); } while (0)
; #define PG8_BAR __builtin_amdgcn_s_barrier()
; template <class Epi, class Sched, bool ALIGN_EPI = false, bool SP2 = false>
; __device__ __forceinline__ void gemm_phase(PG8_LAS unsigned char* lds, const Gemm g, const Sched& S, const Epi& E) {
;     ...
;         const char* nA = has_next ? (const char*)g.A + (size_t)nxt.pm * tstep + (size_t)nxt.ko * 2 : cA; const char* nB = has_next ? (const char*)g.Bt + (size_t)nxt.pn * tstep + (size_t)nxt.ko * 2 : cB;
;         for (int t = 0; t < nt; t += 2) {
;             const bool last = (t == nt - 2);
;             const char* a1 = cA + (size_t)(t + 1) * kstep;
;             const char* a2 = last ? nA : cA + (size_t)(t + 2) * kstep; const char* b2 = last ? nB : cB + (size_t)(t + 2) * kstep;
;             const char* a3 = a2 + kstep; const char* b3 = b2 + kstep;
;             if (last && has_next) S.a_ready(nxt);
;             if constexpr (SP2) {
;             PG8_LDB(B0, 0, 0); PG8_LDB(B1, 0, 1); PG8_SCHED; PG8_LDA(At, 0, 0); PG8_STAGE(PG8_SA(1, 1), a1 + hstep, voffA);
;             PG8_WAIT_V(8); PG8_WAIT_L(0); PG8_BAR; PG8_MMA(0, 0, At, B0); PG8_MMA(0, 1, At, B1); PG8_BAR; PG8_SCHED;
;             PG8_LDA(At, 0, 1); PG8_STAGE(PG8_SB(0, 0), b2, voffB); PG8_STAGE(PG8_SB(0, 1), b2 + hstep, voffB); PG8_STAGE(PG8_SA(0, 0), a2, voffA);
.LBB0_1205:
	s_lshl_b32 s52, s31, 7
	s_add_u32 s53, s42, s52
	s_addc_u32 s54, s43, 0
	s_add_u32 s55, s53, 0x100
	s_addc_u32 s56, s54, 0
	s_and_b64 s[50:51], s[48:49], exec
	s_cselect_b32 s51, s56, s1
	s_cselect_b32 s50, s55, s2
	s_add_u32 s52, s44, s52
	s_addc_u32 s55, s45, 0
	s_add_u32 s52, s52, 0x100
	s_addc_u32 s55, s55, 0
	s_and_b64 s[48:49], s[48:49], exec
	s_cselect_b32 s49, s55, s3
	s_cselect_b32 s48, s52, s29
	s_add_i32 s55, 0, 0x10000
	v_add_u32_e32 v138, s55, v140
	s_add_i32 s56, 0, 0x14000
	ds_read_b128 v[144:147], v138
	ds_read_b128 v[148:151], v138 offset:1024
	ds_read_b128 v[152:155], v138 offset:2048
	ds_read_b128 v[156:159], v138 offset:3072
	v_add_u32_e32 v138, s56, v140
	ds_read_b128 v[160:163], v138
	ds_read_b128 v[164:167], v138 offset:1024
	ds_read_b128 v[168:171], v138 offset:2048
	ds_read_b128 v[172:175], v138 offset:3072
	s_add_u32 s52, s53, 0x80080
	s_addc_u32 s53, s54, 0
	v_lshl_add_u64 v[138:139], s[52:53], 0, v[132:133]
	s_add_i32 m0, s41, 0xc000
	ds_read_b128 v[176:179], v142
	ds_read_b128 v[180:183], v142 offset:1024
	ds_read_b128 v[184:187], v142 offset:2048
	ds_read_b128 v[188:191], v142 offset:3072
	ds_read_b128 v[192:195], v142 offset:4096
	ds_read_b128 v[196:199], v142 offset:5120
	ds_read_b128 v[200:203], v142 offset:6144
	ds_read_b128 v[204:207], v142 offset:7168
	global_load_lds_dwordx4 v[138:139], off
	v_lshl_add_u64 v[138:139], s[52:53], 0, v[134:135]
	s_add_i32 m0, s41, 0xe000
	s_nop 0
	global_load_lds_dwordx4 v[138:139], off
	s_waitcnt vmcnt(8)
	s_waitcnt lgkmcnt(0)
	s_barrier
	s_setprio 0
	s_waitcnt lgkmcnt(0)
	v_mfma_f32_16x16x32_bf16 v[128:131], v[144:147], v[176:179], v[128:131]
	v_mfma_f32_16x16x32_bf16 v[124:127], v[152:155], v[176:179], v[124:127]
	v_mfma_f32_16x16x32_bf16 v[112:115], v[144:147], v[184:187], v[112:115]
	v_mfma_f32_16x16x32_bf16 v[108:111], v[152:155], v[184:187], v[108:111]
	v_mfma_f32_16x16x32_bf16 v[96:99], v[144:147], v[192:195], v[96:99]
	v_mfma_f32_16x16x32_bf16 v[92:95], v[152:155], v[192:195], v[92:95]
	v_mfma_f32_16x16x32_bf16 v[80:83], v[144:147], v[200:203], v[80:83]
	v_mfma_f32_16x16x32_bf16 v[76:79], v[152:155], v[200:203], v[76:79]
	v_mfma_f32_16x16x32_bf16 v[128:131], v[148:151], v[180:183], v[128:131]
	v_mfma_f32_16x16x32_bf16 v[124:127], v[156:159], v[180:183], v[124:127]
	v_mfma_f32_16x16x32_bf16 v[112:115], v[148:151], v[188:191], v[112:115]
	v_mfma_f32_16x16x32_bf16 v[108:111], v[156:159], v[188:191], v[108:111]
	v_mfma_f32_16x16x32_bf16 v[96:99], v[148:151], v[196:199], v[96:99]
	v_mfma_f32_16x16x32_bf16 v[92:95], v[156:159], v[196:199], v[92:95]
	v_mfma_f32_16x16x32_bf16 v[80:83], v[148:151], v[204:207], v[80:83]
	v_mfma_f32_16x16x32_bf16 v[76:79], v[156:159], v[204:207], v[76:79]
	s_setprio 0
	s_setprio 0
	v_mfma_f32_16x16x32_bf16 v[120:123], v[160:163], v[176:179], v[120:123]
	v_mfma_f32_16x16x32_bf16 v[116:119], v[168:171], v[176:179], v[116:119]
	v_mfma_f32_16x16x32_bf16 v[104:107], v[160:163], v[184:187], v[104:107]
	v_mfma_f32_16x16x32_bf16 v[100:103], v[168:171], v[184:187], v[100:103]
	v_mfma_f32_16x16x32_bf16 v[88:91], v[160:163], v[192:195], v[88:91]
	v_mfma_f32_16x16x32_bf16 v[84:87], v[168:171], v[192:195], v[84:87]
	v_mfma_f32_16x16x32_bf16 v[72:75], v[160:163], v[200:203], v[72:75]
	v_mfma_f32_16x16x32_bf16 v[68:71], v[168:171], v[200:203], v[68:71]
	v_mfma_f32_16x16x32_bf16 v[120:123], v[164:167], v[180:183], v[120:123]
	v_mfma_f32_16x16x32_bf16 v[116:119], v[172:175], v[180:183], v[116:119]
	v_mfma_f32_16x16x32_bf16 v[104:107], v[164:167], v[188:191], v[104:107]
	v_mfma_f32_16x16x32_bf16 v[100:103], v[172:175], v[188:191], v[100:103]
	v_mfma_f32_16x16x32_bf16 v[88:91], v[164:167], v[196:199], v[88:91]
	v_mfma_f32_16x16x32_bf16 v[84:87], v[172:175], v[196:199], v[84:87]
	v_mfma_f32_16x16x32_bf16 v[72:75], v[164:167], v[204:207], v[72:75]
	v_mfma_f32_16x16x32_bf16 v[68:71], v[172:175], v[204:207], v[68:71]
	s_setprio 1
	s_barrier
	s_add_i32 s52, s55, s39
	v_lshl_add_u64 v[138:139], s[48:49], 0, v[66:67]
	s_mov_b32 m0, s52
	ds_read_b128 v[176:179], v142 offset:16384
	ds_read_b128 v[180:183], v142 offset:17408
	ds_read_b128 v[184:187], v142 offset:18432
	ds_read_b128 v[188:191], v142 offset:19456
	ds_read_b128 v[192:195], v142 offset:20480
	ds_read_b128 v[196:199], v142 offset:21504
	ds_read_b128 v[200:203], v142 offset:22528
	ds_read_b128 v[204:207], v142 offset:23552
	global_load_lds_dwordx4 v[138:139], off
	s_add_i32 m0, s52, 0x2000
	s_add_u32 s52, s48, 0x80000
	v_lshl_add_u64 v[208:209], s[48:49], 0, v[136:137]
	s_addc_u32 s53, s49, 0
	s_add_i32 s54, s56, s39
	global_load_lds_dwordx4 v[208:209], off
	v_lshl_add_u64 v[210:211], s[52:53], 0, v[66:67]
	s_mov_b32 m0, s54
	v_lshl_add_u64 v[220:221], s[50:51], 0, v[134:135]
	global_load_lds_dwordx4 v[210:211], off
	v_lshl_add_u64 v[210:211], s[52:53], 0, v[136:137]
	s_add_i32 m0, s54, 0x2000
	s_nop 0
	global_load_lds_dwordx4 v[210:211], off
	v_lshl_add_u64 v[210:211], s[50:51], 0, v[132:133]
	s_mov_b32 m0, s41
	s_nop 0
	global_load_lds_dwordx4 v[210:211], off
	s_mov_b32 m0, s68
	s_nop 0
	global_load_lds_dwordx4 v[220:221], off
	s_waitcnt vmcnt(8)
	s_waitcnt lgkmcnt(0)
	s_barrier
; #define PG8_STAGE(bufoff, gbase, voff) do { _Pragma("unroll") for (int _i = 0; _i < 2; ++_i) \
;         __builtin_amdgcn_global_load_lds((const unsigned*)((const char*)(gbase) + (voff)[_i]), (PG8_LAS unsigned*)(lds + (bufoff) + ldsw + _i * 8192), 16, 0, 0); } while (0)
; #define PG8_LDA(dst, b, h) do { _Pragma("unroll") for (int m = 0; m < 4; ++m) _Pragma("unroll") for (int k = 0; k < 2; ++k) dst[m][k] = *(const PG8_LAS bf16x8*)(lds + PG8_SA(b, h) + aoff + m * 2048 + k * 1024); } while (0)
; #define PG8_LDB(dst, b, h) do { _Pragma("unroll") for (int n = 0; n < 2; ++n) _Pragma("unroll") for (int k = 0; k < 2; ++k) dst[n][k] = *(const PG8_LAS bf16x8*)(lds + PG8_SB(b, h) + boff + n * 2048 + k * 1024); } while (0)
; #define PG8_MMA(ai, bj, At, Bt) do { __builtin_amdgcn_s_setprio(1); _Pragma("unroll") for (int m = 0; m < 4; ++m) _Pragma("unroll") for (int n = 0; n < 2; ++n) _Pragma("unroll") for (int k = 0; k < 2; ++k) \
;         acc[ai][bj][m][n] = __builtin_amdgcn_mfma_f32_16x16x32_bf16(Bt[n][k], At[m][k], acc[ai][bj][m][n], 0, 0, 0); __builtin_amdgcn_s_setprio(0); } while (0)
; #define PG8_WAIT_V(n) asm volatile("s_waitcnt vmcnt(" #n ")" ::: "memory")
; #define PG8_WAIT_L(n) asm volatile("s_waitcnt lgkmcnt(" #n ")" ::: "memory")
; #define PG8_BAR __builtin_amdgcn_s_barrier()
; #define PG8_SCHED __builtin_amdgcn_sched_barrier(0)
; template <class Epi, class Sched, bool ALIGN_EPI = false, bool SP2 = false>
; __device__ __forceinline__ void gemm_phase(PG8_LAS unsigned char* lds, const Gemm g, const Sched& S, const Epi& E) {
;     ...
;             PG8_WAIT_V(8); PG8_WAIT_L(0); PG8_BAR; PG8_MMA(1, 0, At, B0); PG8_MMA(1, 1, At, B1); PG8_BAR; PG8_SCHED;
;             PG8_LDB(B0, 1, 0); PG8_LDB(B1, 1, 1); PG8_SCHED; PG8_LDA(At, 1, 0); PG8_STAGE(PG8_SA(0, 1), a2 + hstep, voffA);
;             PG8_WAIT_V(8); PG8_WAIT_L(0); PG8_BAR; PG8_MMA(0, 0, At, B0); PG8_MMA(0, 1, At, B1); PG8_BAR; PG8_SCHED;
	s_setprio 0
	s_waitcnt lgkmcnt(0)
	v_mfma_f32_16x16x32_bf16 v[62:65], v[144:147], v[176:179], v[62:65]
	v_mfma_f32_16x16x32_bf16 v[58:61], v[152:155], v[176:179], v[58:61]
	v_mfma_f32_16x16x32_bf16 v[46:49], v[144:147], v[184:187], v[46:49]
	v_mfma_f32_16x16x32_bf16 v[42:45], v[152:155], v[184:187], v[42:45]
	v_mfma_f32_16x16x32_bf16 v[30:33], v[144:147], v[192:195], v[30:33]
	v_mfma_f32_16x16x32_bf16 v[26:29], v[152:155], v[192:195], v[26:29]
	v_mfma_f32_16x16x32_bf16 v[14:17], v[144:147], v[200:203], v[14:17]
	v_mfma_f32_16x16x32_bf16 v[10:13], v[152:155], v[200:203], v[10:13]
	v_mfma_f32_16x16x32_bf16 v[62:65], v[148:151], v[180:183], v[62:65]
	v_mfma_f32_16x16x32_bf16 v[58:61], v[156:159], v[180:183], v[58:61]
	v_mfma_f32_16x16x32_bf16 v[46:49], v[148:151], v[188:191], v[46:49]
	v_mfma_f32_16x16x32_bf16 v[42:45], v[156:159], v[188:191], v[42:45]
	v_mfma_f32_16x16x32_bf16 v[30:33], v[148:151], v[196:199], v[30:33]
	v_mfma_f32_16x16x32_bf16 v[26:29], v[156:159], v[196:199], v[26:29]
	v_mfma_f32_16x16x32_bf16 v[14:17], v[148:151], v[204:207], v[14:17]
	v_mfma_f32_16x16x32_bf16 v[10:13], v[156:159], v[204:207], v[10:13]
	s_setprio 0
	s_setprio 0
	v_mfma_f32_16x16x32_bf16 v[54:57], v[160:163], v[176:179], v[54:57]
	v_mfma_f32_16x16x32_bf16 v[50:53], v[168:171], v[176:179], v[50:53]
	v_mfma_f32_16x16x32_bf16 v[38:41], v[160:163], v[184:187], v[38:41]
	v_mfma_f32_16x16x32_bf16 v[34:37], v[168:171], v[184:187], v[34:37]
	v_mfma_f32_16x16x32_bf16 v[22:25], v[160:163], v[192:195], v[22:25]
	v_mfma_f32_16x16x32_bf16 v[18:21], v[168:171], v[192:195], v[18:21]
	v_mfma_f32_16x16x32_bf16 v[6:9], v[160:163], v[200:203], v[6:9]
	v_mfma_f32_16x16x32_bf16 v[2:5], v[168:171], v[200:203], v[2:5]
	v_mfma_f32_16x16x32_bf16 v[54:57], v[164:167], v[180:183], v[54:57]
	v_mfma_f32_16x16x32_bf16 v[50:53], v[172:175], v[180:183], v[50:53]
	v_mfma_f32_16x16x32_bf16 v[38:41], v[164:167], v[188:191], v[38:41]
	v_mfma_f32_16x16x32_bf16 v[34:37], v[172:175], v[188:191], v[34:37]
	v_mfma_f32_16x16x32_bf16 v[22:25], v[164:167], v[196:199], v[22:25]
	v_mfma_f32_16x16x32_bf16 v[18:21], v[172:175], v[196:199], v[18:21]
	v_mfma_f32_16x16x32_bf16 v[6:9], v[164:167], v[204:207], v[6:9]
	v_mfma_f32_16x16x32_bf16 v[2:5], v[172:175], v[204:207], v[2:5]
	s_setprio 1
	s_barrier
	s_add_i32 s52, 0, 0x18000
	v_add_u32_e32 v143, s52, v140
	s_add_i32 s53, 0, 0x1c000
	ds_read_b128 v[144:147], v143
	ds_read_b128 v[148:151], v143 offset:1024
	ds_read_b128 v[152:155], v143 offset:2048
	ds_read_b128 v[156:159], v143 offset:3072
	v_add_u32_e32 v143, s53, v140
	ds_read_b128 v[160:163], v143
	ds_read_b128 v[164:167], v143 offset:1024
	ds_read_b128 v[168:171], v143 offset:2048
	ds_read_b128 v[172:175], v143 offset:3072
	s_add_u32 s50, s50, 0x80000
	s_addc_u32 s51, s51, 0
	s_mov_b32 m0, s69
	v_lshl_add_u64 v[222:223], s[50:51], 0, v[132:133]
	ds_read_b128 v[176:179], v142 offset:32768
	ds_read_b128 v[180:183], v142 offset:33792
	ds_read_b128 v[184:187], v142 offset:34816
	ds_read_b128 v[188:191], v142 offset:35840
	ds_read_b128 v[192:195], v142 offset:36864
	ds_read_b128 v[196:199], v142 offset:37888
	ds_read_b128 v[200:203], v142 offset:38912
	ds_read_b128 v[204:207], v142 offset:39936
	global_load_lds_dwordx4 v[222:223], off
	v_lshl_add_u64 v[222:223], s[50:51], 0, v[134:135]
	s_mov_b32 m0, s70
	s_nop 0
	global_load_lds_dwordx4 v[222:223], off
	s_waitcnt vmcnt(8)
	s_waitcnt lgkmcnt(0)
	s_barrier
	s_setprio 0
	s_waitcnt lgkmcnt(0)
	v_mfma_f32_16x16x32_bf16 v[128:131], v[144:147], v[176:179], v[128:131]
	v_mfma_f32_16x16x32_bf16 v[124:127], v[152:155], v[176:179], v[124:127]
	v_mfma_f32_16x16x32_bf16 v[112:115], v[144:147], v[184:187], v[112:115]
	v_mfma_f32_16x16x32_bf16 v[108:111], v[152:155], v[184:187], v[108:111]
	v_mfma_f32_16x16x32_bf16 v[96:99], v[144:147], v[192:195], v[96:99]
	v_mfma_f32_16x16x32_bf16 v[92:95], v[152:155], v[192:195], v[92:95]
	v_mfma_f32_16x16x32_bf16 v[80:83], v[144:147], v[200:203], v[80:83]
	v_mfma_f32_16x16x32_bf16 v[76:79], v[152:155], v[200:203], v[76:79]
	v_mfma_f32_16x16x32_bf16 v[128:131], v[148:151], v[180:183], v[128:131]
	v_mfma_f32_16x16x32_bf16 v[124:127], v[156:159], v[180:183], v[124:127]
	v_mfma_f32_16x16x32_bf16 v[112:115], v[148:151], v[188:191], v[112:115]
	v_mfma_f32_16x16x32_bf16 v[108:111], v[156:159], v[188:191], v[108:111]
	v_mfma_f32_16x16x32_bf16 v[96:99], v[148:151], v[196:199], v[96:99]
	v_mfma_f32_16x16x32_bf16 v[92:95], v[156:159], v[196:199], v[92:95]
	v_mfma_f32_16x16x32_bf16 v[80:83], v[148:151], v[204:207], v[80:83]
	v_mfma_f32_16x16x32_bf16 v[76:79], v[156:159], v[204:207], v[76:79]
	s_setprio 0
	s_setprio 0
	v_mfma_f32_16x16x32_bf16 v[120:123], v[160:163], v[176:179], v[120:123]
	v_mfma_f32_16x16x32_bf16 v[116:119], v[168:171], v[176:179], v[116:119]
	v_mfma_f32_16x16x32_bf16 v[104:107], v[160:163], v[184:187], v[104:107]
	v_mfma_f32_16x16x32_bf16 v[100:103], v[168:171], v[184:187], v[100:103]
	v_mfma_f32_16x16x32_bf16 v[88:91], v[160:163], v[192:195], v[88:91]
	v_mfma_f32_16x16x32_bf16 v[84:87], v[168:171], v[192:195], v[84:87]
	v_mfma_f32_16x16x32_bf16 v[72:75], v[160:163], v[200:203], v[72:75]
	v_mfma_f32_16x16x32_bf16 v[68:71], v[168:171], v[200:203], v[68:71]
	v_mfma_f32_16x16x32_bf16 v[120:123], v[164:167], v[180:183], v[120:123]
	v_mfma_f32_16x16x32_bf16 v[116:119], v[172:175], v[180:183], v[116:119]
	v_mfma_f32_16x16x32_bf16 v[104:107], v[164:167], v[188:191], v[104:107]
	v_mfma_f32_16x16x32_bf16 v[100:103], v[172:175], v[188:191], v[100:103]
	v_mfma_f32_16x16x32_bf16 v[88:91], v[164:167], v[196:199], v[88:91]
	v_mfma_f32_16x16x32_bf16 v[84:87], v[172:175], v[196:199], v[84:87]
	v_mfma_f32_16x16x32_bf16 v[72:75], v[164:167], v[204:207], v[72:75]
	v_mfma_f32_16x16x32_bf16 v[68:71], v[172:175], v[204:207], v[68:71]
	s_setprio 1
	s_barrier
; #define PG8_STAGE(bufoff, gbase, voff) do { _Pragma("unroll") for (int _i = 0; _i < 2; ++_i) \
;         __builtin_amdgcn_global_load_lds((const unsigned*)((const char*)(gbase) + (voff)[_i]), (PG8_LAS unsigned*)(lds + (bufoff) + ldsw + _i * 8192), 16, 0, 0); } while (0)
; #define PG8_LDA(dst, b, h) do { _Pragma("unroll") for (int m = 0; m < 4; ++m) _Pragma("unroll") for (int k = 0; k < 2; ++k) dst[m][k] = *(const PG8_LAS bf16x8*)(lds + PG8_SA(b, h) + aoff + m * 2048 + k * 1024); } while (0)
; #define PG8_MMA(ai, bj, At, Bt) do { __builtin_amdgcn_s_setprio(1); _Pragma("unroll") for (int m = 0; m < 4; ++m) _Pragma("unroll") for (int n = 0; n < 2; ++n) _Pragma("unroll") for (int k = 0; k < 2; ++k) \
;         acc[ai][bj][m][n] = __builtin_amdgcn_mfma_f32_16x16x32_bf16(Bt[n][k], At[m][k], acc[ai][bj][m][n], 0, 0, 0); __builtin_amdgcn_s_setprio(0); } while (0)
; #define PG8_WAIT_V(n) asm volatile("s_waitcnt vmcnt(" #n ")" ::: "memory")
; #define PG8_WAIT_L(n) asm volatile("s_waitcnt lgkmcnt(" #n ")" ::: "memory")
; #define PG8_BAR __builtin_amdgcn_s_barrier()
; #define PG8_SCHED __builtin_amdgcn_sched_barrier(0)
; template <class Epi, class Sched, bool ALIGN_EPI = false, bool SP2 = false>
; __device__ __forceinline__ void gemm_phase(PG8_LAS unsigned char* lds, const Gemm g, const Sched& S, const Epi& E) {
;     ...
;             PG8_LDA(At, 1, 1); PG8_STAGE(PG8_SB(1, 0), b3, voffB); PG8_STAGE(PG8_SB(1, 1), b3 + hstep, voffB); PG8_STAGE(PG8_SA(1, 0), a3, voffA);
;             PG8_WAIT_V(8); PG8_WAIT_L(0); PG8_BAR; PG8_MMA(1, 0, At, B0); PG8_MMA(1, 1, At, B1); PG8_BAR; PG8_SCHED;
	s_add_i32 s50, s52, s39
	v_lshl_add_u64 v[138:139], v[138:139], 0, s[88:89]
	s_mov_b32 m0, s50
	ds_read_b128 v[176:179], v142 offset:49152
	ds_read_b128 v[180:183], v142 offset:50176
	ds_read_b128 v[184:187], v142 offset:51200
	ds_read_b128 v[188:191], v142 offset:52224
	ds_read_b128 v[192:195], v142 offset:53248
	ds_read_b128 v[196:199], v142 offset:54272
	ds_read_b128 v[200:203], v142 offset:55296
	ds_read_b128 v[204:207], v142 offset:56320
	global_load_lds_dwordx4 v[138:139], off
	s_add_i32 m0, s50, 0x2000
	s_add_u32 s48, s48, 0x80080
	v_lshl_add_u64 v[138:139], v[208:209], 0, s[88:89]
	s_addc_u32 s49, s49, 0
	s_add_i32 s50, s53, s39
	global_load_lds_dwordx4 v[138:139], off
	v_lshl_add_u64 v[138:139], s[48:49], 0, v[66:67]
	s_mov_b32 m0, s50
	s_nop 0
	global_load_lds_dwordx4 v[138:139], off
	v_lshl_add_u64 v[138:139], s[48:49], 0, v[136:137]
	s_add_i32 m0, s50, 0x2000
	s_nop 0
	global_load_lds_dwordx4 v[138:139], off
	v_lshl_add_u64 v[138:139], v[210:211], 0, s[88:89]
	s_mov_b32 m0, s71
	s_nop 0
	global_load_lds_dwordx4 v[138:139], off
	v_lshl_add_u64 v[138:139], v[220:221], 0, s[88:89]
	s_mov_b32 m0, s72
	s_nop 0
	global_load_lds_dwordx4 v[138:139], off
	s_waitcnt vmcnt(8)
	s_waitcnt lgkmcnt(0)
	s_barrier
	s_setprio 0
	s_waitcnt lgkmcnt(0)
	v_mfma_f32_16x16x32_bf16 v[62:65], v[144:147], v[176:179], v[62:65]
	v_mfma_f32_16x16x32_bf16 v[58:61], v[152:155], v[176:179], v[58:61]
	v_mfma_f32_16x16x32_bf16 v[46:49], v[144:147], v[184:187], v[46:49]
	v_mfma_f32_16x16x32_bf16 v[42:45], v[152:155], v[184:187], v[42:45]
	v_mfma_f32_16x16x32_bf16 v[30:33], v[144:147], v[192:195], v[30:33]
	v_mfma_f32_16x16x32_bf16 v[26:29], v[152:155], v[192:195], v[26:29]
	v_mfma_f32_16x16x32_bf16 v[14:17], v[144:147], v[200:203], v[14:17]
	v_mfma_f32_16x16x32_bf16 v[10:13], v[152:155], v[200:203], v[10:13]
	v_mfma_f32_16x16x32_bf16 v[62:65], v[148:151], v[180:183], v[62:65]
	v_mfma_f32_16x16x32_bf16 v[58:61], v[156:159], v[180:183], v[58:61]
	v_mfma_f32_16x16x32_bf16 v[46:49], v[148:151], v[188:191], v[46:49]
	v_mfma_f32_16x16x32_bf16 v[42:45], v[156:159], v[188:191], v[42:45]
	v_mfma_f32_16x16x32_bf16 v[30:33], v[148:151], v[196:199], v[30:33]
	v_mfma_f32_16x16x32_bf16 v[26:29], v[156:159], v[196:199], v[26:29]
	v_mfma_f32_16x16x32_bf16 v[14:17], v[148:151], v[204:207], v[14:17]
	v_mfma_f32_16x16x32_bf16 v[10:13], v[156:159], v[204:207], v[10:13]
	s_setprio 0
	s_setprio 0
	v_mfma_f32_16x16x32_bf16 v[54:57], v[160:163], v[176:179], v[54:57]
	v_mfma_f32_16x16x32_bf16 v[50:53], v[168:171], v[176:179], v[50:53]
	v_mfma_f32_16x16x32_bf16 v[38:41], v[160:163], v[184:187], v[38:41]
	v_mfma_f32_16x16x32_bf16 v[34:37], v[168:171], v[184:187], v[34:37]
	v_mfma_f32_16x16x32_bf16 v[22:25], v[160:163], v[192:195], v[22:25]
	v_mfma_f32_16x16x32_bf16 v[18:21], v[168:171], v[192:195], v[18:21]
	v_mfma_f32_16x16x32_bf16 v[6:9], v[160:163], v[200:203], v[6:9]
	v_mfma_f32_16x16x32_bf16 v[2:5], v[168:171], v[200:203], v[2:5]
	v_mfma_f32_16x16x32_bf16 v[54:57], v[164:167], v[180:183], v[54:57]
	v_mfma_f32_16x16x32_bf16 v[50:53], v[172:175], v[180:183], v[50:53]
	v_mfma_f32_16x16x32_bf16 v[38:41], v[164:167], v[188:191], v[38:41]
	v_mfma_f32_16x16x32_bf16 v[34:37], v[172:175], v[188:191], v[34:37]
	v_mfma_f32_16x16x32_bf16 v[22:25], v[164:167], v[196:199], v[22:25]
	v_mfma_f32_16x16x32_bf16 v[18:21], v[172:175], v[196:199], v[18:21]
	v_mfma_f32_16x16x32_bf16 v[6:9], v[164:167], v[204:207], v[6:9]
	v_mfma_f32_16x16x32_bf16 v[2:5], v[172:175], v[204:207], v[2:5]
	s_setprio 1
	s_barrier
	s_add_i32 s48, s31, 2
	s_cmp_gt_u32 s31, 29
	s_mov_b32 s31, s48
	s_cbranch_scc1 .LBB0_1217

; #define PG8_STAGE(bufoff, gbase, voff) do { _Pragma("unroll") for (int _i = 0; _i < 2; ++_i) \
;         __builtin_amdgcn_global_load_lds((const unsigned*)((const char*)(gbase) + (voff)[_i]), (PG8_LAS unsigned*)(lds + (bufoff) + ldsw + _i * 8192), 16, 0, 0); } while (0)
; #define PG8_LDA(dst, b, h) do { _Pragma("unroll") for (int m = 0; m < 4; ++m) _Pragma("unroll") for (int k = 0; k < 2; ++k) dst[m][k] = *(const PG8_LAS bf16x8*)(lds + PG8_SA(b, h) + aoff + m * 2048 + k * 1024); } while (0)
; #define PG8_LDB(dst, b, h) do { _Pragma("unroll") for (int n = 0; n < 2; ++n) _Pragma("unroll") for (int k = 0; k < 2; ++k) dst[n][k] = *(const PG8_LAS bf16x8*)(lds + PG8_SB(b, h) + boff + n * 2048 + k * 1024); } while (0)
; #define PG8_MMA(ai, bj, At, Bt) do { __builtin_amdgcn_s_setprio(1); _Pragma("unroll") for (int m = 0; m < 4; ++m) _Pragma("unroll") for (int n = 0; n < 2; ++n) _Pragma("unroll") for (int k = 0; k < 2; ++k) \
;         acc[ai][bj][m][n] = __builtin_amdgcn_mfma_f32_16x16x32_bf16(Bt[n][k], At[m][k], acc[ai][bj][m][n], 0, 0, 0); __builtin_amdgcn_s_setprio(0); } while (0)
; #define PG8_BAR __builtin_amdgcn_s_barrier()
; template <class Epi, class Sched, bool ALIGN_EPI = false, bool SP2 = false>
; __device__ __forceinline__ void gemm_phase(PG8_LAS unsigned char* lds, const Gemm g, const Sched& S, const Epi& E) {
;     ...
;         const char* nA = has_next ? (const char*)g.A + (size_t)nxt.pm * tstep + (size_t)nxt.ko * 2 : cA; const char* nB = has_next ? (const char*)g.Bt + (size_t)nxt.pn * tstep + (size_t)nxt.ko * 2 : cB;
;         for (int t = 0; t < nt; t += 2) {
;             const bool last = (t == nt - 2);
;             const char* a1 = cA + (size_t)(t + 1) * kstep;
;             const char* a2 = last ? nA : cA + (size_t)(t + 2) * kstep; const char* b2 = last ? nB : cB + (size_t)(t + 2) * kstep;
;             const char* a3 = a2 + kstep; const char* b3 = b2 + kstep;
;             if (last && has_next) S.a_ready(nxt);
;             if constexpr (SP2) {
;             PG8_LDB(B0, 0, 0); PG8_LDB(B1, 0, 1); PG8_SCHED; PG8_LDA(At, 0, 0); PG8_STAGE(PG8_SA(1, 1), a1 + hstep, voffA);
;             PG8_WAIT_V(8); PG8_WAIT_L(0); PG8_BAR; PG8_MMA(0, 0, At, B0); PG8_MMA(0, 1, At, B1); PG8_BAR; PG8_SCHED;
;             PG8_LDA(At, 0, 1); PG8_STAGE(PG8_SB(0, 0), b2, voffB); PG8_STAGE(PG8_SB(0, 1), b2 + hstep, voffB); PG8_STAGE(PG8_SA(0, 0), a2, voffA);
.LBB0_1294:
	s_add_u32 s26, s24, 0x100
	s_addc_u32 s27, s25, 0
	s_add_i32 s54, 0, 0x10000
	s_cmpk_eq_i32 s53, 0x54
	s_cselect_b32 s31, s13, s27
	s_cselect_b32 s30, s12, s26
	s_cselect_b32 s29, s23, s3
	s_cselect_b32 s28, s22, s2
	s_add_i32 s55, 0, 0x14000
	v_add_u32_e32 v144, s54, v156
	v_add_u32_e32 v154, s55, v156
	ds_read_b128 v[132:135], v144
	ds_read_b128 v[136:139], v144 offset:1024
	ds_read_b128 v[140:143], v144 offset:2048
	ds_read_b128 v[144:147], v144 offset:3072
	ds_read_b128 v[160:163], v154
	ds_read_b128 v[164:167], v154 offset:1024
	ds_read_b128 v[168:171], v154 offset:2048
	ds_read_b128 v[172:175], v154 offset:3072
	v_lshl_add_u64 v[154:155], s[24:25], 0, v[150:151]
	s_add_i32 m0, s39, 0xc000
	ds_read_b128 v[176:179], v158
	ds_read_b128 v[180:183], v158 offset:1024
	ds_read_b128 v[184:187], v158 offset:2048
	ds_read_b128 v[188:191], v158 offset:3072
	ds_read_b128 v[192:195], v158 offset:4096
	ds_read_b128 v[196:199], v158 offset:5120
	ds_read_b128 v[200:203], v158 offset:6144
	ds_read_b128 v[204:207], v158 offset:7168
	global_load_lds_dwordx4 v[154:155], off
	v_lshl_add_u64 v[154:155], s[24:25], 0, v[152:153]
	s_add_i32 m0, s39, 0xe000
	s_nop 0
	global_load_lds_dwordx4 v[154:155], off
	s_waitcnt vmcnt(8)
	s_waitcnt lgkmcnt(0)
	s_barrier
	s_setprio 0
	s_waitcnt lgkmcnt(0)
	v_mfma_f32_16x16x32_bf16 v[128:131], v[132:135], v[176:179], v[128:131]
	v_mfma_f32_16x16x32_bf16 v[124:127], v[140:143], v[176:179], v[124:127]
	v_mfma_f32_16x16x32_bf16 v[120:123], v[132:135], v[184:187], v[120:123]
	v_mfma_f32_16x16x32_bf16 v[112:115], v[140:143], v[184:187], v[112:115]
	v_mfma_f32_16x16x32_bf16 v[104:107], v[132:135], v[192:195], v[104:107]
	v_mfma_f32_16x16x32_bf16 v[96:99], v[140:143], v[192:195], v[96:99]
	v_mfma_f32_16x16x32_bf16 v[88:91], v[132:135], v[200:203], v[88:91]
	v_mfma_f32_16x16x32_bf16 v[76:79], v[140:143], v[200:203], v[76:79]
	v_mfma_f32_16x16x32_bf16 v[128:131], v[136:139], v[180:183], v[128:131]
	v_mfma_f32_16x16x32_bf16 v[124:127], v[144:147], v[180:183], v[124:127]
	v_mfma_f32_16x16x32_bf16 v[120:123], v[136:139], v[188:191], v[120:123]
	v_mfma_f32_16x16x32_bf16 v[112:115], v[144:147], v[188:191], v[112:115]
	v_mfma_f32_16x16x32_bf16 v[104:107], v[136:139], v[196:199], v[104:107]
	v_mfma_f32_16x16x32_bf16 v[96:99], v[144:147], v[196:199], v[96:99]
	v_mfma_f32_16x16x32_bf16 v[88:91], v[136:139], v[204:207], v[88:91]
	v_mfma_f32_16x16x32_bf16 v[76:79], v[144:147], v[204:207], v[76:79]
	s_setprio 0
	s_setprio 0
	v_mfma_f32_16x16x32_bf16 v[116:119], v[160:163], v[176:179], v[116:119]
	v_mfma_f32_16x16x32_bf16 v[108:111], v[168:171], v[176:179], v[108:111]
	v_mfma_f32_16x16x32_bf16 v[100:103], v[160:163], v[184:187], v[100:103]
	v_mfma_f32_16x16x32_bf16 v[92:95], v[168:171], v[184:187], v[92:95]
	v_mfma_f32_16x16x32_bf16 v[84:87], v[160:163], v[192:195], v[84:87]
	v_mfma_f32_16x16x32_bf16 v[80:83], v[168:171], v[192:195], v[80:83]
	v_mfma_f32_16x16x32_bf16 v[72:75], v[160:163], v[200:203], v[72:75]
	v_mfma_f32_16x16x32_bf16 v[68:71], v[168:171], v[200:203], v[68:71]
	v_mfma_f32_16x16x32_bf16 v[116:119], v[164:167], v[180:183], v[116:119]
	v_mfma_f32_16x16x32_bf16 v[108:111], v[172:175], v[180:183], v[108:111]
	v_mfma_f32_16x16x32_bf16 v[100:103], v[164:167], v[188:191], v[100:103]
	v_mfma_f32_16x16x32_bf16 v[92:95], v[172:175], v[188:191], v[92:95]
	v_mfma_f32_16x16x32_bf16 v[84:87], v[164:167], v[196:199], v[84:87]
	v_mfma_f32_16x16x32_bf16 v[80:83], v[172:175], v[196:199], v[80:83]
	v_mfma_f32_16x16x32_bf16 v[72:75], v[164:167], v[204:207], v[72:75]
	v_mfma_f32_16x16x32_bf16 v[68:71], v[172:175], v[204:207], v[68:71]
	s_setprio 1
	s_barrier
	s_add_i32 s24, s54, s38
	v_lshl_add_u64 v[154:155], s[28:29], 0, v[66:67]
	s_mov_b32 m0, s24
	ds_read_b128 v[176:179], v158 offset:16384
	ds_read_b128 v[180:183], v158 offset:17408
	ds_read_b128 v[184:187], v158 offset:18432
	ds_read_b128 v[188:191], v158 offset:19456
	ds_read_b128 v[192:195], v158 offset:20480
	ds_read_b128 v[196:199], v158 offset:21504
	ds_read_b128 v[200:203], v158 offset:22528
	ds_read_b128 v[204:207], v158 offset:23552
	global_load_lds_dwordx4 v[154:155], off
	s_add_i32 m0, s24, 0x2000
	s_add_u32 s24, s28, 0x160000
	v_lshl_add_u64 v[208:209], s[28:29], 0, v[148:149]
	s_addc_u32 s25, s29, 0
	s_add_i32 s54, s55, s38
	global_load_lds_dwordx4 v[208:209], off
	v_lshl_add_u64 v[210:211], s[24:25], 0, v[66:67]
	s_mov_b32 m0, s54
	v_lshl_add_u64 v[220:221], s[30:31], 0, v[148:149]
	global_load_lds_dwordx4 v[210:211], off
	v_lshl_add_u64 v[210:211], s[24:25], 0, v[148:149]
	s_add_i32 m0, s54, 0x2000
	s_nop 0
	global_load_lds_dwordx4 v[210:211], off
	v_lshl_add_u64 v[210:211], s[30:31], 0, v[66:67]
	s_mov_b32 m0, s39
	s_nop 0
	global_load_lds_dwordx4 v[210:211], off
	s_mov_b32 m0, s40
	s_nop 0
	global_load_lds_dwordx4 v[220:221], off
	s_waitcnt vmcnt(8)
	s_waitcnt lgkmcnt(0)
	s_barrier
; #define PG8_STAGE(bufoff, gbase, voff) do { _Pragma("unroll") for (int _i = 0; _i < 2; ++_i) \
;         __builtin_amdgcn_global_load_lds((const unsigned*)((const char*)(gbase) + (voff)[_i]), (PG8_LAS unsigned*)(lds + (bufoff) + ldsw + _i * 8192), 16, 0, 0); } while (0)
; #define PG8_LDA(dst, b, h) do { _Pragma("unroll") for (int m = 0; m < 4; ++m) _Pragma("unroll") for (int k = 0; k < 2; ++k) dst[m][k] = *(const PG8_LAS bf16x8*)(lds + PG8_SA(b, h) + aoff + m * 2048 + k * 1024); } while (0)
; #define PG8_LDB(dst, b, h) do { _Pragma("unroll") for (int n = 0; n < 2; ++n) _Pragma("unroll") for (int k = 0; k < 2; ++k) dst[n][k] = *(const PG8_LAS bf16x8*)(lds + PG8_SB(b, h) + boff + n * 2048 + k * 1024); } while (0)
; #define PG8_MMA(ai, bj, At, Bt) do { __builtin_amdgcn_s_setprio(1); _Pragma("unroll") for (int m = 0; m < 4; ++m) _Pragma("unroll") for (int n = 0; n < 2; ++n) _Pragma("unroll") for (int k = 0; k < 2; ++k) \
;         acc[ai][bj][m][n] = __builtin_amdgcn_mfma_f32_16x16x32_bf16(Bt[n][k], At[m][k], acc[ai][bj][m][n], 0, 0, 0); __builtin_amdgcn_s_setprio(0); } while (0)
; #define PG8_WAIT_V(n) asm volatile("s_waitcnt vmcnt(" #n ")" ::: "memory")
; #define PG8_WAIT_L(n) asm volatile("s_waitcnt lgkmcnt(" #n ")" ::: "memory")
; #define PG8_BAR __builtin_amdgcn_s_barrier()
; #define PG8_SCHED __builtin_amdgcn_sched_barrier(0)
; template <class Epi, class Sched, bool ALIGN_EPI = false, bool SP2 = false>
; __device__ __forceinline__ void gemm_phase(PG8_LAS unsigned char* lds, const Gemm g, const Sched& S, const Epi& E) {
;     ...
;             PG8_WAIT_V(8); PG8_WAIT_L(0); PG8_BAR; PG8_MMA(1, 0, At, B0); PG8_MMA(1, 1, At, B1); PG8_BAR; PG8_SCHED;
;             PG8_LDB(B0, 1, 0); PG8_LDB(B1, 1, 1); PG8_SCHED; PG8_LDA(At, 1, 0); PG8_STAGE(PG8_SA(0, 1), a2 + hstep, voffA);
;             PG8_WAIT_V(8); PG8_WAIT_L(0); PG8_BAR; PG8_MMA(0, 0, At, B0); PG8_MMA(0, 1, At, B1); PG8_BAR; PG8_SCHED;
	s_setprio 0
	s_waitcnt lgkmcnt(0)
	v_mfma_f32_16x16x32_bf16 v[62:65], v[132:135], v[176:179], v[62:65]
	v_mfma_f32_16x16x32_bf16 v[58:61], v[140:143], v[176:179], v[58:61]
	v_mfma_f32_16x16x32_bf16 v[54:57], v[132:135], v[184:187], v[54:57]
	v_mfma_f32_16x16x32_bf16 v[46:49], v[140:143], v[184:187], v[46:49]
	v_mfma_f32_16x16x32_bf16 v[38:41], v[132:135], v[192:195], v[38:41]
	v_mfma_f32_16x16x32_bf16 v[30:33], v[140:143], v[192:195], v[30:33]
	v_mfma_f32_16x16x32_bf16 v[22:25], v[132:135], v[200:203], v[22:25]
	v_mfma_f32_16x16x32_bf16 v[10:13], v[140:143], v[200:203], v[10:13]
	v_mfma_f32_16x16x32_bf16 v[62:65], v[136:139], v[180:183], v[62:65]
	v_mfma_f32_16x16x32_bf16 v[58:61], v[144:147], v[180:183], v[58:61]
	v_mfma_f32_16x16x32_bf16 v[54:57], v[136:139], v[188:191], v[54:57]
	v_mfma_f32_16x16x32_bf16 v[46:49], v[144:147], v[188:191], v[46:49]
	v_mfma_f32_16x16x32_bf16 v[38:41], v[136:139], v[196:199], v[38:41]
	v_mfma_f32_16x16x32_bf16 v[30:33], v[144:147], v[196:199], v[30:33]
	v_mfma_f32_16x16x32_bf16 v[22:25], v[136:139], v[204:207], v[22:25]
	v_mfma_f32_16x16x32_bf16 v[10:13], v[144:147], v[204:207], v[10:13]
	s_setprio 0
	s_setprio 0
	v_mfma_f32_16x16x32_bf16 v[50:53], v[160:163], v[176:179], v[50:53]
	v_mfma_f32_16x16x32_bf16 v[42:45], v[168:171], v[176:179], v[42:45]
	v_mfma_f32_16x16x32_bf16 v[34:37], v[160:163], v[184:187], v[34:37]
	v_mfma_f32_16x16x32_bf16 v[26:29], v[168:171], v[184:187], v[26:29]
	v_mfma_f32_16x16x32_bf16 v[18:21], v[160:163], v[192:195], v[18:21]
	v_mfma_f32_16x16x32_bf16 v[14:17], v[168:171], v[192:195], v[14:17]
	v_mfma_f32_16x16x32_bf16 v[6:9], v[160:163], v[200:203], v[6:9]
	v_mfma_f32_16x16x32_bf16 v[2:5], v[168:171], v[200:203], v[2:5]
	v_mfma_f32_16x16x32_bf16 v[50:53], v[164:167], v[180:183], v[50:53]
	v_mfma_f32_16x16x32_bf16 v[42:45], v[172:175], v[180:183], v[42:45]
	v_mfma_f32_16x16x32_bf16 v[34:37], v[164:167], v[188:191], v[34:37]
	v_mfma_f32_16x16x32_bf16 v[26:29], v[172:175], v[188:191], v[26:29]
	v_mfma_f32_16x16x32_bf16 v[18:21], v[164:167], v[196:199], v[18:21]
	v_mfma_f32_16x16x32_bf16 v[14:17], v[172:175], v[196:199], v[14:17]
	v_mfma_f32_16x16x32_bf16 v[6:9], v[164:167], v[204:207], v[6:9]
	v_mfma_f32_16x16x32_bf16 v[2:5], v[172:175], v[204:207], v[2:5]
	s_setprio 1
	s_barrier
	s_add_i32 s54, 0, 0x18000
	s_add_i32 s55, 0, 0x1c000
	v_add_u32_e32 v144, s54, v156
	v_add_u32_e32 v159, s55, v156
	ds_read_b128 v[132:135], v144
	ds_read_b128 v[136:139], v144 offset:1024
	ds_read_b128 v[140:143], v144 offset:2048
	ds_read_b128 v[144:147], v144 offset:3072
	ds_read_b128 v[160:163], v159
	ds_read_b128 v[164:167], v159 offset:1024
	ds_read_b128 v[168:171], v159 offset:2048
	ds_read_b128 v[172:175], v159 offset:3072
	s_add_u32 s24, s30, 0x160000
	s_addc_u32 s25, s31, 0
	s_mov_b32 m0, s41
	v_lshl_add_u64 v[222:223], s[24:25], 0, v[66:67]
	ds_read_b128 v[176:179], v158 offset:32768
	ds_read_b128 v[180:183], v158 offset:33792
	ds_read_b128 v[184:187], v158 offset:34816
	ds_read_b128 v[188:191], v158 offset:35840
	ds_read_b128 v[192:195], v158 offset:36864
	ds_read_b128 v[196:199], v158 offset:37888
	ds_read_b128 v[200:203], v158 offset:38912
	ds_read_b128 v[204:207], v158 offset:39936
	global_load_lds_dwordx4 v[222:223], off
	v_lshl_add_u64 v[222:223], s[24:25], 0, v[148:149]
	s_mov_b32 m0, s42
	s_nop 0
	global_load_lds_dwordx4 v[222:223], off
	s_waitcnt vmcnt(8)
	s_waitcnt lgkmcnt(0)
	s_barrier
	s_setprio 0
	s_waitcnt lgkmcnt(0)
	v_mfma_f32_16x16x32_bf16 v[128:131], v[132:135], v[176:179], v[128:131]
	v_mfma_f32_16x16x32_bf16 v[124:127], v[140:143], v[176:179], v[124:127]
	v_mfma_f32_16x16x32_bf16 v[120:123], v[132:135], v[184:187], v[120:123]
	v_mfma_f32_16x16x32_bf16 v[112:115], v[140:143], v[184:187], v[112:115]
	v_mfma_f32_16x16x32_bf16 v[104:107], v[132:135], v[192:195], v[104:107]
	v_mfma_f32_16x16x32_bf16 v[96:99], v[140:143], v[192:195], v[96:99]
	v_mfma_f32_16x16x32_bf16 v[88:91], v[132:135], v[200:203], v[88:91]
	v_mfma_f32_16x16x32_bf16 v[76:79], v[140:143], v[200:203], v[76:79]
	v_mfma_f32_16x16x32_bf16 v[128:131], v[136:139], v[180:183], v[128:131]
	v_mfma_f32_16x16x32_bf16 v[124:127], v[144:147], v[180:183], v[124:127]
	v_mfma_f32_16x16x32_bf16 v[120:123], v[136:139], v[188:191], v[120:123]
	v_mfma_f32_16x16x32_bf16 v[112:115], v[144:147], v[188:191], v[112:115]
	v_mfma_f32_16x16x32_bf16 v[104:107], v[136:139], v[196:199], v[104:107]
	v_mfma_f32_16x16x32_bf16 v[96:99], v[144:147], v[196:199], v[96:99]
	v_mfma_f32_16x16x32_bf16 v[88:91], v[136:139], v[204:207], v[88:91]
	v_mfma_f32_16x16x32_bf16 v[76:79], v[144:147], v[204:207], v[76:79]
	s_setprio 0
	s_setprio 0
	v_mfma_f32_16x16x32_bf16 v[116:119], v[160:163], v[176:179], v[116:119]
	v_mfma_f32_16x16x32_bf16 v[108:111], v[168:171], v[176:179], v[108:111]
	v_mfma_f32_16x16x32_bf16 v[100:103], v[160:163], v[184:187], v[100:103]
	v_mfma_f32_16x16x32_bf16 v[92:95], v[168:171], v[184:187], v[92:95]
	v_mfma_f32_16x16x32_bf16 v[84:87], v[160:163], v[192:195], v[84:87]
	v_mfma_f32_16x16x32_bf16 v[80:83], v[168:171], v[192:195], v[80:83]
	v_mfma_f32_16x16x32_bf16 v[72:75], v[160:163], v[200:203], v[72:75]
	v_mfma_f32_16x16x32_bf16 v[68:71], v[168:171], v[200:203], v[68:71]
	v_mfma_f32_16x16x32_bf16 v[116:119], v[164:167], v[180:183], v[116:119]
	v_mfma_f32_16x16x32_bf16 v[108:111], v[172:175], v[180:183], v[108:111]
	v_mfma_f32_16x16x32_bf16 v[100:103], v[164:167], v[188:191], v[100:103]
	v_mfma_f32_16x16x32_bf16 v[92:95], v[172:175], v[188:191], v[92:95]
	v_mfma_f32_16x16x32_bf16 v[84:87], v[164:167], v[196:199], v[84:87]
	v_mfma_f32_16x16x32_bf16 v[80:83], v[172:175], v[196:199], v[80:83]
	v_mfma_f32_16x16x32_bf16 v[72:75], v[164:167], v[204:207], v[72:75]
	v_mfma_f32_16x16x32_bf16 v[68:71], v[172:175], v[204:207], v[68:71]
	s_setprio 1
	s_barrier
; #define PG8_STAGE(bufoff, gbase, voff) do { _Pragma("unroll") for (int _i = 0; _i < 2; ++_i) \
;         __builtin_amdgcn_global_load_lds((const unsigned*)((const char*)(gbase) + (voff)[_i]), (PG8_LAS unsigned*)(lds + (bufoff) + ldsw + _i * 8192), 16, 0, 0); } while (0)
; #define PG8_LDA(dst, b, h) do { _Pragma("unroll") for (int m = 0; m < 4; ++m) _Pragma("unroll") for (int k = 0; k < 2; ++k) dst[m][k] = *(const PG8_LAS bf16x8*)(lds + PG8_SA(b, h) + aoff + m * 2048 + k * 1024); } while (0)
; #define PG8_MMA(ai, bj, At, Bt) do { __builtin_amdgcn_s_setprio(1); _Pragma("unroll") for (int m = 0; m < 4; ++m) _Pragma("unroll") for (int n = 0; n < 2; ++n) _Pragma("unroll") for (int k = 0; k < 2; ++k) \
;         acc[ai][bj][m][n] = __builtin_amdgcn_mfma_f32_16x16x32_bf16(Bt[n][k], At[m][k], acc[ai][bj][m][n], 0, 0, 0); __builtin_amdgcn_s_setprio(0); } while (0)
; #define PG8_WAIT_V(n) asm volatile("s_waitcnt vmcnt(" #n ")" ::: "memory")
; #define PG8_WAIT_L(n) asm volatile("s_waitcnt lgkmcnt(" #n ")" ::: "memory")
; #define PG8_BAR __builtin_amdgcn_s_barrier()
; #define PG8_SCHED __builtin_amdgcn_sched_barrier(0)
; template <class Epi, class Sched, bool ALIGN_EPI = false, bool SP2 = false>
; __device__ __forceinline__ void gemm_phase(PG8_LAS unsigned char* lds, const Gemm g, const Sched& S, const Epi& E) {
;     ...
;             PG8_LDA(At, 1, 1); PG8_STAGE(PG8_SB(1, 0), b3, voffB); PG8_STAGE(PG8_SB(1, 1), b3 + hstep, voffB); PG8_STAGE(PG8_SA(1, 0), a3, voffA);
;             PG8_WAIT_V(8); PG8_WAIT_L(0); PG8_BAR; PG8_MMA(1, 0, At, B0); PG8_MMA(1, 1, At, B1); PG8_BAR; PG8_SCHED;
;     ...
;         if constexpr (ALIGN_EPI) { if (wr == 0) PG8_BAR; }
	s_add_i32 s24, s54, s38
	v_lshl_add_u64 v[154:155], v[154:155], 0, s[88:89]
	s_mov_b32 m0, s24
	ds_read_b128 v[176:179], v158 offset:49152
	ds_read_b128 v[180:183], v158 offset:50176
	ds_read_b128 v[184:187], v158 offset:51200
	ds_read_b128 v[188:191], v158 offset:52224
	ds_read_b128 v[192:195], v158 offset:53248
	ds_read_b128 v[196:199], v158 offset:54272
	ds_read_b128 v[200:203], v158 offset:55296
	ds_read_b128 v[204:207], v158 offset:56320
	global_load_lds_dwordx4 v[154:155], off
	s_add_i32 m0, s24, 0x2000
	s_add_u32 s24, s28, 0x160080
	v_lshl_add_u64 v[154:155], v[208:209], 0, s[88:89]
	s_addc_u32 s25, s29, 0
	s_add_i32 s28, s55, s38
	global_load_lds_dwordx4 v[154:155], off
	v_lshl_add_u64 v[154:155], s[24:25], 0, v[66:67]
	s_mov_b32 m0, s28
	s_nop 0
	global_load_lds_dwordx4 v[154:155], off
	v_lshl_add_u64 v[154:155], s[24:25], 0, v[148:149]
	s_add_i32 m0, s28, 0x2000
	s_nop 0
	global_load_lds_dwordx4 v[154:155], off
	v_lshl_add_u64 v[154:155], v[210:211], 0, s[88:89]
	s_mov_b32 m0, s45
	s_nop 0
	global_load_lds_dwordx4 v[154:155], off
	v_lshl_add_u64 v[154:155], v[220:221], 0, s[88:89]
	s_mov_b32 m0, s46
	s_nop 0
	global_load_lds_dwordx4 v[154:155], off
	s_waitcnt vmcnt(8)
	s_waitcnt lgkmcnt(0)
	s_barrier
	s_setprio 0
	s_waitcnt lgkmcnt(0)
	v_mfma_f32_16x16x32_bf16 v[62:65], v[132:135], v[176:179], v[62:65]
	v_mfma_f32_16x16x32_bf16 v[58:61], v[140:143], v[176:179], v[58:61]
	v_mfma_f32_16x16x32_bf16 v[54:57], v[132:135], v[184:187], v[54:57]
	v_mfma_f32_16x16x32_bf16 v[46:49], v[140:143], v[184:187], v[46:49]
	v_mfma_f32_16x16x32_bf16 v[38:41], v[132:135], v[192:195], v[38:41]
	v_mfma_f32_16x16x32_bf16 v[30:33], v[140:143], v[192:195], v[30:33]
	v_mfma_f32_16x16x32_bf16 v[22:25], v[132:135], v[200:203], v[22:25]
	v_mfma_f32_16x16x32_bf16 v[10:13], v[140:143], v[200:203], v[10:13]
	v_mfma_f32_16x16x32_bf16 v[62:65], v[136:139], v[180:183], v[62:65]
	v_mfma_f32_16x16x32_bf16 v[58:61], v[144:147], v[180:183], v[58:61]
	v_mfma_f32_16x16x32_bf16 v[54:57], v[136:139], v[188:191], v[54:57]
	v_mfma_f32_16x16x32_bf16 v[46:49], v[144:147], v[188:191], v[46:49]
	v_mfma_f32_16x16x32_bf16 v[38:41], v[136:139], v[196:199], v[38:41]
	v_mfma_f32_16x16x32_bf16 v[30:33], v[144:147], v[196:199], v[30:33]
	v_mfma_f32_16x16x32_bf16 v[22:25], v[136:139], v[204:207], v[22:25]
	v_mfma_f32_16x16x32_bf16 v[10:13], v[144:147], v[204:207], v[10:13]
	s_setprio 0
	s_setprio 0
	v_mfma_f32_16x16x32_bf16 v[50:53], v[160:163], v[176:179], v[50:53]
	v_mfma_f32_16x16x32_bf16 v[42:45], v[168:171], v[176:179], v[42:45]
	v_mfma_f32_16x16x32_bf16 v[34:37], v[160:163], v[184:187], v[34:37]
	v_mfma_f32_16x16x32_bf16 v[26:29], v[168:171], v[184:187], v[26:29]
	v_mfma_f32_16x16x32_bf16 v[18:21], v[160:163], v[192:195], v[18:21]
	v_mfma_f32_16x16x32_bf16 v[14:17], v[168:171], v[192:195], v[14:17]
	v_mfma_f32_16x16x32_bf16 v[6:9], v[160:163], v[200:203], v[6:9]
	v_mfma_f32_16x16x32_bf16 v[2:5], v[168:171], v[200:203], v[2:5]
	v_mfma_f32_16x16x32_bf16 v[50:53], v[164:167], v[180:183], v[50:53]
	v_mfma_f32_16x16x32_bf16 v[42:45], v[172:175], v[180:183], v[42:45]
	v_mfma_f32_16x16x32_bf16 v[34:37], v[164:167], v[188:191], v[34:37]
	v_mfma_f32_16x16x32_bf16 v[26:29], v[172:175], v[188:191], v[26:29]
	v_mfma_f32_16x16x32_bf16 v[18:21], v[164:167], v[196:199], v[18:21]
	v_mfma_f32_16x16x32_bf16 v[14:17], v[172:175], v[196:199], v[14:17]
	v_mfma_f32_16x16x32_bf16 v[6:9], v[164:167], v[204:207], v[6:9]
	v_mfma_f32_16x16x32_bf16 v[2:5], v[172:175], v[204:207], v[2:5]
	s_setprio 1
	s_barrier
	s_add_i32 s53, s53, 2
	s_add_u32 s2, s2, 0x100
	s_addc_u32 s3, s3, 0
	s_cmpk_gt_u32 s53, 0x55
	s_mov_b64 s[24:25], s[26:27]
	s_cbranch_scc0 .LBB0_1294
	s_and_b64 vcc, exec, s[20:21]
	s_cbranch_vccz .LBB0_1297
	s_barrier

; #define PG8_STAGE(bufoff, gbase, voff) do { _Pragma("unroll") for (int _i = 0; _i < 2; ++_i) \
;         __builtin_amdgcn_global_load_lds((const unsigned*)((const char*)(gbase) + (voff)[_i]), (PG8_LAS unsigned*)(lds + (bufoff) + ldsw + _i * 8192), 16, 0, 0); } while (0)
; #define PG8_LDA(dst, b, h) do { _Pragma("unroll") for (int m = 0; m < 4; ++m) _Pragma("unroll") for (int k = 0; k < 2; ++k) dst[m][k] = *(const PG8_LAS bf16x8*)(lds + PG8_SA(b, h) + aoff + m * 2048 + k * 1024); } while (0)
; #define PG8_LDB(dst, b, h) do { _Pragma("unroll") for (int n = 0; n < 2; ++n) _Pragma("unroll") for (int k = 0; k < 2; ++k) dst[n][k] = *(const PG8_LAS bf16x8*)(lds + PG8_SB(b, h) + boff + n * 2048 + k * 1024); } while (0)
; #define PG8_MMA(ai, bj, At, Bt) do { __builtin_amdgcn_s_setprio(1); _Pragma("unroll") for (int m = 0; m < 4; ++m) _Pragma("unroll") for (int n = 0; n < 2; ++n) _Pragma("unroll") for (int k = 0; k < 2; ++k) \
;         acc[ai][bj][m][n] = __builtin_amdgcn_mfma_f32_16x16x32_bf16(Bt[n][k], At[m][k], acc[ai][bj][m][n], 0, 0, 0); __builtin_amdgcn_s_setprio(0); } while (0)
; #define PG8_BAR __builtin_amdgcn_s_barrier()
; template <class Epi, class Sched, bool ALIGN_EPI = false, bool SP2 = false>
; __device__ __forceinline__ void gemm_phase(PG8_LAS unsigned char* lds, const Gemm g, const Sched& S, const Epi& E) {
;     ...
;         const char* nA = has_next ? (const char*)g.A + (size_t)nxt.pm * tstep + (size_t)nxt.ko * 2 : cA; const char* nB = has_next ? (const char*)g.Bt + (size_t)nxt.pn * tstep + (size_t)nxt.ko * 2 : cB;
;         for (int t = 0; t < nt; t += 2) {
;             const bool last = (t == nt - 2);
;             const char* a1 = cA + (size_t)(t + 1) * kstep;
;             const char* a2 = last ? nA : cA + (size_t)(t + 2) * kstep; const char* b2 = last ? nB : cB + (size_t)(t + 2) * kstep;
;             const char* a3 = a2 + kstep; const char* b3 = b2 + kstep;
;             if (last && has_next) S.a_ready(nxt);
;             if constexpr (SP2) {
;             PG8_LDB(B0, 0, 0); PG8_LDB(B1, 0, 1); PG8_SCHED; PG8_LDA(At, 0, 0); PG8_STAGE(PG8_SA(1, 1), a1 + hstep, voffA);
;             PG8_WAIT_V(8); PG8_WAIT_L(0); PG8_BAR; PG8_MMA(0, 0, At, B0); PG8_MMA(0, 1, At, B1); PG8_BAR; PG8_SCHED;
;             PG8_LDA(At, 0, 1); PG8_STAGE(PG8_SB(0, 0), b2, voffB); PG8_STAGE(PG8_SB(0, 1), b2 + hstep, voffB); PG8_STAGE(PG8_SA(0, 0), a2, voffA);
.LBB0_1324:
	s_add_u32 s28, s22, s26
	s_addc_u32 s29, s23, s27
	s_add_u32 s28, s28, 0x100
	s_addc_u32 s29, s29, 0
	s_add_u32 s54, s3, s26
	s_addc_u32 s55, s52, s27
	s_add_i32 s56, 0, 0x10000
	s_cmpk_eq_i32 s26, 0x2b00
	s_cselect_b32 s31, s25, s29
	s_cselect_b32 s30, s24, s28
	s_cselect_b32 s29, s13, s55
	s_cselect_b32 s28, s12, s54
	s_add_i32 s57, 0, 0x14000
	v_add_u32_e32 v156, s56, v142
	v_add_u32_e32 v172, s57, v142
	ds_read_b128 v[144:147], v156
	ds_read_b128 v[148:151], v156 offset:1024
	ds_read_b128 v[152:155], v156 offset:2048
	ds_read_b128 v[156:159], v156 offset:3072
	ds_read_b128 v[160:163], v172
	ds_read_b128 v[164:167], v172 offset:1024
	ds_read_b128 v[168:171], v172 offset:2048
	ds_read_b128 v[172:175], v172 offset:3072
	v_lshl_add_u64 v[208:209], v[138:139], 0, s[26:27]
	s_add_i32 m0, s43, 0xc000
	ds_read_b128 v[176:179], v143
	ds_read_b128 v[180:183], v143 offset:1024
	ds_read_b128 v[184:187], v143 offset:2048
	ds_read_b128 v[188:191], v143 offset:3072
	ds_read_b128 v[192:195], v143 offset:4096
	ds_read_b128 v[196:199], v143 offset:5120
	ds_read_b128 v[200:203], v143 offset:6144
	ds_read_b128 v[204:207], v143 offset:7168
	global_load_lds_dwordx4 v[208:209], off
	v_lshl_add_u64 v[208:209], v[140:141], 0, s[26:27]
	s_add_i32 m0, s43, 0xe000
	s_nop 0
	global_load_lds_dwordx4 v[208:209], off
	s_waitcnt vmcnt(8)
	s_waitcnt lgkmcnt(0)
	s_barrier
	s_setprio 0
	s_waitcnt lgkmcnt(0)
	v_mfma_f32_16x16x32_bf16 v[128:131], v[144:147], v[176:179], v[128:131]
	v_mfma_f32_16x16x32_bf16 v[124:127], v[152:155], v[176:179], v[124:127]
	v_mfma_f32_16x16x32_bf16 v[112:115], v[144:147], v[184:187], v[112:115]
	v_mfma_f32_16x16x32_bf16 v[104:107], v[152:155], v[184:187], v[104:107]
	v_mfma_f32_16x16x32_bf16 v[96:99], v[144:147], v[192:195], v[96:99]
	v_mfma_f32_16x16x32_bf16 v[88:91], v[152:155], v[192:195], v[88:91]
	v_mfma_f32_16x16x32_bf16 v[80:83], v[144:147], v[200:203], v[80:83]
	v_mfma_f32_16x16x32_bf16 v[72:75], v[152:155], v[200:203], v[72:75]
	v_mfma_f32_16x16x32_bf16 v[128:131], v[148:151], v[180:183], v[128:131]
	v_mfma_f32_16x16x32_bf16 v[124:127], v[156:159], v[180:183], v[124:127]
	v_mfma_f32_16x16x32_bf16 v[112:115], v[148:151], v[188:191], v[112:115]
	v_mfma_f32_16x16x32_bf16 v[104:107], v[156:159], v[188:191], v[104:107]
	v_mfma_f32_16x16x32_bf16 v[96:99], v[148:151], v[196:199], v[96:99]
	v_mfma_f32_16x16x32_bf16 v[88:91], v[156:159], v[196:199], v[88:91]
	v_mfma_f32_16x16x32_bf16 v[80:83], v[148:151], v[204:207], v[80:83]
	v_mfma_f32_16x16x32_bf16 v[72:75], v[156:159], v[204:207], v[72:75]
	s_setprio 0
	s_setprio 0
	v_mfma_f32_16x16x32_bf16 v[116:119], v[160:163], v[176:179], v[116:119]
	v_mfma_f32_16x16x32_bf16 v[108:111], v[168:171], v[176:179], v[108:111]
	v_mfma_f32_16x16x32_bf16 v[100:103], v[160:163], v[184:187], v[100:103]
	v_mfma_f32_16x16x32_bf16 v[92:95], v[168:171], v[184:187], v[92:95]
	v_mfma_f32_16x16x32_bf16 v[84:87], v[160:163], v[192:195], v[84:87]
	v_mfma_f32_16x16x32_bf16 v[76:79], v[168:171], v[192:195], v[76:79]
	v_mfma_f32_16x16x32_bf16 v[68:71], v[160:163], v[200:203], v[68:71]
	v_mfma_f32_16x16x32_bf16 v[62:65], v[168:171], v[200:203], v[62:65]
	v_mfma_f32_16x16x32_bf16 v[116:119], v[164:167], v[180:183], v[116:119]
	v_mfma_f32_16x16x32_bf16 v[108:111], v[172:175], v[180:183], v[108:111]
	v_mfma_f32_16x16x32_bf16 v[100:103], v[164:167], v[188:191], v[100:103]
	v_mfma_f32_16x16x32_bf16 v[92:95], v[172:175], v[188:191], v[92:95]
	v_mfma_f32_16x16x32_bf16 v[84:87], v[164:167], v[196:199], v[84:87]
	v_mfma_f32_16x16x32_bf16 v[76:79], v[172:175], v[196:199], v[76:79]
	v_mfma_f32_16x16x32_bf16 v[68:71], v[164:167], v[204:207], v[68:71]
	v_mfma_f32_16x16x32_bf16 v[62:65], v[172:175], v[204:207], v[62:65]
	s_setprio 1
	s_barrier
	s_add_i32 s54, s56, s42
	v_lshl_add_u64 v[208:209], s[28:29], 0, v[66:67]
	s_mov_b32 m0, s54
	ds_read_b128 v[176:179], v143 offset:16384
	ds_read_b128 v[180:183], v143 offset:17408
	ds_read_b128 v[184:187], v143 offset:18432
	ds_read_b128 v[188:191], v143 offset:19456
	ds_read_b128 v[192:195], v143 offset:20480
	ds_read_b128 v[196:199], v143 offset:21504
	ds_read_b128 v[200:203], v143 offset:22528
	ds_read_b128 v[204:207], v143 offset:23552
	global_load_lds_dwordx4 v[208:209], off
	s_add_i32 m0, s54, 0x2000
	s_add_u32 s54, s28, 0x160000
	v_lshl_add_u64 v[210:211], s[28:29], 0, v[132:133]
	s_addc_u32 s55, s29, 0
	s_add_i32 s56, s57, s42
	global_load_lds_dwordx4 v[210:211], off
	v_lshl_add_u64 v[220:221], s[54:55], 0, v[66:67]
	s_mov_b32 m0, s56
	v_lshl_add_u64 v[222:223], s[30:31], 0, v[132:133]
	global_load_lds_dwordx4 v[220:221], off
	v_lshl_add_u64 v[220:221], s[54:55], 0, v[132:133]
	s_add_i32 m0, s56, 0x2000
	s_nop 0
	global_load_lds_dwordx4 v[220:221], off
	v_lshl_add_u64 v[220:221], s[30:31], 0, v[66:67]
	s_mov_b32 m0, s43
	s_nop 0
	global_load_lds_dwordx4 v[220:221], off
	s_mov_b32 m0, s44
	s_nop 0
	global_load_lds_dwordx4 v[222:223], off
	s_waitcnt vmcnt(8)
	s_waitcnt lgkmcnt(0)
	s_barrier
; #define PG8_STAGE(bufoff, gbase, voff) do { _Pragma("unroll") for (int _i = 0; _i < 2; ++_i) \
;         __builtin_amdgcn_global_load_lds((const unsigned*)((const char*)(gbase) + (voff)[_i]), (PG8_LAS unsigned*)(lds + (bufoff) + ldsw + _i * 8192), 16, 0, 0); } while (0)
; #define PG8_LDA(dst, b, h) do { _Pragma("unroll") for (int m = 0; m < 4; ++m) _Pragma("unroll") for (int k = 0; k < 2; ++k) dst[m][k] = *(const PG8_LAS bf16x8*)(lds + PG8_SA(b, h) + aoff + m * 2048 + k * 1024); } while (0)
; #define PG8_LDB(dst, b, h) do { _Pragma("unroll") for (int n = 0; n < 2; ++n) _Pragma("unroll") for (int k = 0; k < 2; ++k) dst[n][k] = *(const PG8_LAS bf16x8*)(lds + PG8_SB(b, h) + boff + n * 2048 + k * 1024); } while (0)
; #define PG8_MMA(ai, bj, At, Bt) do { __builtin_amdgcn_s_setprio(1); _Pragma("unroll") for (int m = 0; m < 4; ++m) _Pragma("unroll") for (int n = 0; n < 2; ++n) _Pragma("unroll") for (int k = 0; k < 2; ++k) \
;         acc[ai][bj][m][n] = __builtin_amdgcn_mfma_f32_16x16x32_bf16(Bt[n][k], At[m][k], acc[ai][bj][m][n], 0, 0, 0); __builtin_amdgcn_s_setprio(0); } while (0)
; #define PG8_WAIT_V(n) asm volatile("s_waitcnt vmcnt(" #n ")" ::: "memory")
; #define PG8_WAIT_L(n) asm volatile("s_waitcnt lgkmcnt(" #n ")" ::: "memory")
; #define PG8_BAR __builtin_amdgcn_s_barrier()
; #define PG8_SCHED __builtin_amdgcn_sched_barrier(0)
; template <class Epi, class Sched, bool ALIGN_EPI = false, bool SP2 = false>
; __device__ __forceinline__ void gemm_phase(PG8_LAS unsigned char* lds, const Gemm g, const Sched& S, const Epi& E) {
;     ...
;             PG8_WAIT_V(8); PG8_WAIT_L(0); PG8_BAR; PG8_MMA(1, 0, At, B0); PG8_MMA(1, 1, At, B1); PG8_BAR; PG8_SCHED;
;             PG8_LDB(B0, 1, 0); PG8_LDB(B1, 1, 1); PG8_SCHED; PG8_LDA(At, 1, 0); PG8_STAGE(PG8_SA(0, 1), a2 + hstep, voffA);
;             PG8_WAIT_V(8); PG8_WAIT_L(0); PG8_BAR; PG8_MMA(0, 0, At, B0); PG8_MMA(0, 1, At, B1); PG8_BAR; PG8_SCHED;
	s_setprio 0
	s_waitcnt lgkmcnt(0)
	v_mfma_f32_16x16x32_bf16 v[58:61], v[144:147], v[176:179], v[58:61]
	v_mfma_f32_16x16x32_bf16 v[54:57], v[152:155], v[176:179], v[54:57]
	v_mfma_f32_16x16x32_bf16 v[46:49], v[144:147], v[184:187], v[46:49]
	v_mfma_f32_16x16x32_bf16 v[38:41], v[152:155], v[184:187], v[38:41]
	v_mfma_f32_16x16x32_bf16 v[30:33], v[144:147], v[192:195], v[30:33]
	v_mfma_f32_16x16x32_bf16 v[22:25], v[152:155], v[192:195], v[22:25]
	v_mfma_f32_16x16x32_bf16 v[120:123], v[144:147], v[200:203], v[120:123]
	v_mfma_f32_16x16x32_bf16 v[10:13], v[152:155], v[200:203], v[10:13]
	v_mfma_f32_16x16x32_bf16 v[58:61], v[148:151], v[180:183], v[58:61]
	v_mfma_f32_16x16x32_bf16 v[54:57], v[156:159], v[180:183], v[54:57]
	v_mfma_f32_16x16x32_bf16 v[46:49], v[148:151], v[188:191], v[46:49]
	v_mfma_f32_16x16x32_bf16 v[38:41], v[156:159], v[188:191], v[38:41]
	v_mfma_f32_16x16x32_bf16 v[30:33], v[148:151], v[196:199], v[30:33]
	v_mfma_f32_16x16x32_bf16 v[22:25], v[156:159], v[196:199], v[22:25]
	v_mfma_f32_16x16x32_bf16 v[120:123], v[148:151], v[204:207], v[120:123]
	v_mfma_f32_16x16x32_bf16 v[10:13], v[156:159], v[204:207], v[10:13]
	s_setprio 0
	s_setprio 0
	v_mfma_f32_16x16x32_bf16 v[50:53], v[160:163], v[176:179], v[50:53]
	v_mfma_f32_16x16x32_bf16 v[42:45], v[168:171], v[176:179], v[42:45]
	v_mfma_f32_16x16x32_bf16 v[34:37], v[160:163], v[184:187], v[34:37]
	v_mfma_f32_16x16x32_bf16 v[26:29], v[168:171], v[184:187], v[26:29]
	v_mfma_f32_16x16x32_bf16 v[18:21], v[160:163], v[192:195], v[18:21]
	v_mfma_f32_16x16x32_bf16 v[14:17], v[168:171], v[192:195], v[14:17]
	v_mfma_f32_16x16x32_bf16 v[6:9], v[160:163], v[200:203], v[6:9]
	v_mfma_f32_16x16x32_bf16 v[2:5], v[168:171], v[200:203], v[2:5]
	v_mfma_f32_16x16x32_bf16 v[50:53], v[164:167], v[180:183], v[50:53]
	v_mfma_f32_16x16x32_bf16 v[42:45], v[172:175], v[180:183], v[42:45]
	v_mfma_f32_16x16x32_bf16 v[34:37], v[164:167], v[188:191], v[34:37]
	v_mfma_f32_16x16x32_bf16 v[26:29], v[172:175], v[188:191], v[26:29]
	v_mfma_f32_16x16x32_bf16 v[18:21], v[164:167], v[196:199], v[18:21]
	v_mfma_f32_16x16x32_bf16 v[14:17], v[172:175], v[196:199], v[14:17]
	v_mfma_f32_16x16x32_bf16 v[6:9], v[164:167], v[204:207], v[6:9]
	v_mfma_f32_16x16x32_bf16 v[2:5], v[172:175], v[204:207], v[2:5]
	s_setprio 1
	s_barrier
	s_add_i32 s54, 0, 0x18000
	s_add_i32 s55, 0, 0x1c000
	v_add_u32_e32 v156, s54, v142
	v_add_u32_e32 v172, s55, v142
	ds_read_b128 v[144:147], v156
	ds_read_b128 v[148:151], v156 offset:1024
	ds_read_b128 v[152:155], v156 offset:2048
	ds_read_b128 v[156:159], v156 offset:3072
	ds_read_b128 v[160:163], v172
	ds_read_b128 v[164:167], v172 offset:1024
	ds_read_b128 v[168:171], v172 offset:2048
	ds_read_b128 v[172:175], v172 offset:3072
	s_add_u32 s30, s30, 0x160000
	s_addc_u32 s31, s31, 0
	s_mov_b32 m0, s45
	v_lshl_add_u64 v[224:225], s[30:31], 0, v[66:67]
	ds_read_b128 v[176:179], v143 offset:32768
	ds_read_b128 v[180:183], v143 offset:33792
	ds_read_b128 v[184:187], v143 offset:34816
	ds_read_b128 v[188:191], v143 offset:35840
	ds_read_b128 v[192:195], v143 offset:36864
	ds_read_b128 v[196:199], v143 offset:37888
	ds_read_b128 v[200:203], v143 offset:38912
	ds_read_b128 v[204:207], v143 offset:39936
	global_load_lds_dwordx4 v[224:225], off
	v_lshl_add_u64 v[224:225], s[30:31], 0, v[132:133]
	s_mov_b32 m0, s1
	s_nop 0
	global_load_lds_dwordx4 v[224:225], off
	s_waitcnt vmcnt(8)
	s_waitcnt lgkmcnt(0)
	s_barrier
	s_setprio 0
	s_waitcnt lgkmcnt(0)
	v_mfma_f32_16x16x32_bf16 v[128:131], v[144:147], v[176:179], v[128:131]
	v_mfma_f32_16x16x32_bf16 v[124:127], v[152:155], v[176:179], v[124:127]
	v_mfma_f32_16x16x32_bf16 v[112:115], v[144:147], v[184:187], v[112:115]
	v_mfma_f32_16x16x32_bf16 v[104:107], v[152:155], v[184:187], v[104:107]
	v_mfma_f32_16x16x32_bf16 v[96:99], v[144:147], v[192:195], v[96:99]
	v_mfma_f32_16x16x32_bf16 v[88:91], v[152:155], v[192:195], v[88:91]
	v_mfma_f32_16x16x32_bf16 v[80:83], v[144:147], v[200:203], v[80:83]
	v_mfma_f32_16x16x32_bf16 v[72:75], v[152:155], v[200:203], v[72:75]
	v_mfma_f32_16x16x32_bf16 v[128:131], v[148:151], v[180:183], v[128:131]
	v_mfma_f32_16x16x32_bf16 v[124:127], v[156:159], v[180:183], v[124:127]
	v_mfma_f32_16x16x32_bf16 v[112:115], v[148:151], v[188:191], v[112:115]
	v_mfma_f32_16x16x32_bf16 v[104:107], v[156:159], v[188:191], v[104:107]
	v_mfma_f32_16x16x32_bf16 v[96:99], v[148:151], v[196:199], v[96:99]
	v_mfma_f32_16x16x32_bf16 v[88:91], v[156:159], v[196:199], v[88:91]
	v_mfma_f32_16x16x32_bf16 v[80:83], v[148:151], v[204:207], v[80:83]
	v_mfma_f32_16x16x32_bf16 v[72:75], v[156:159], v[204:207], v[72:75]
	s_setprio 0
	s_setprio 0
	v_mfma_f32_16x16x32_bf16 v[116:119], v[160:163], v[176:179], v[116:119]
	v_mfma_f32_16x16x32_bf16 v[108:111], v[168:171], v[176:179], v[108:111]
	v_mfma_f32_16x16x32_bf16 v[100:103], v[160:163], v[184:187], v[100:103]
	v_mfma_f32_16x16x32_bf16 v[92:95], v[168:171], v[184:187], v[92:95]
	v_mfma_f32_16x16x32_bf16 v[84:87], v[160:163], v[192:195], v[84:87]
	v_mfma_f32_16x16x32_bf16 v[76:79], v[168:171], v[192:195], v[76:79]
	v_mfma_f32_16x16x32_bf16 v[68:71], v[160:163], v[200:203], v[68:71]
	v_mfma_f32_16x16x32_bf16 v[62:65], v[168:171], v[200:203], v[62:65]
	v_mfma_f32_16x16x32_bf16 v[116:119], v[164:167], v[180:183], v[116:119]
	v_mfma_f32_16x16x32_bf16 v[108:111], v[172:175], v[180:183], v[108:111]
	v_mfma_f32_16x16x32_bf16 v[100:103], v[164:167], v[188:191], v[100:103]
	v_mfma_f32_16x16x32_bf16 v[92:95], v[172:175], v[188:191], v[92:95]
	v_mfma_f32_16x16x32_bf16 v[84:87], v[164:167], v[196:199], v[84:87]
	v_mfma_f32_16x16x32_bf16 v[76:79], v[172:175], v[196:199], v[76:79]
	v_mfma_f32_16x16x32_bf16 v[68:71], v[164:167], v[204:207], v[68:71]
	v_mfma_f32_16x16x32_bf16 v[62:65], v[172:175], v[204:207], v[62:65]
	s_setprio 1
	s_barrier
; #define PG8_STAGE(bufoff, gbase, voff) do { _Pragma("unroll") for (int _i = 0; _i < 2; ++_i) \
;         __builtin_amdgcn_global_load_lds((const unsigned*)((const char*)(gbase) + (voff)[_i]), (PG8_LAS unsigned*)(lds + (bufoff) + ldsw + _i * 8192), 16, 0, 0); } while (0)
; #define PG8_LDA(dst, b, h) do { _Pragma("unroll") for (int m = 0; m < 4; ++m) _Pragma("unroll") for (int k = 0; k < 2; ++k) dst[m][k] = *(const PG8_LAS bf16x8*)(lds + PG8_SA(b, h) + aoff + m * 2048 + k * 1024); } while (0)
; #define PG8_MMA(ai, bj, At, Bt) do { __builtin_amdgcn_s_setprio(1); _Pragma("unroll") for (int m = 0; m < 4; ++m) _Pragma("unroll") for (int n = 0; n < 2; ++n) _Pragma("unroll") for (int k = 0; k < 2; ++k) \
;         acc[ai][bj][m][n] = __builtin_amdgcn_mfma_f32_16x16x32_bf16(Bt[n][k], At[m][k], acc[ai][bj][m][n], 0, 0, 0); __builtin_amdgcn_s_setprio(0); } while (0)
; #define PG8_WAIT_V(n) asm volatile("s_waitcnt vmcnt(" #n ")" ::: "memory")
; #define PG8_WAIT_L(n) asm volatile("s_waitcnt lgkmcnt(" #n ")" ::: "memory")
; #define PG8_BAR __builtin_amdgcn_s_barrier()
; #define PG8_SCHED __builtin_amdgcn_sched_barrier(0)
; template <class Epi, class Sched, bool ALIGN_EPI = false, bool SP2 = false>
; __device__ __forceinline__ void gemm_phase(PG8_LAS unsigned char* lds, const Gemm g, const Sched& S, const Epi& E) {
;     ...
;             PG8_LDA(At, 1, 1); PG8_STAGE(PG8_SB(1, 0), b3, voffB); PG8_STAGE(PG8_SB(1, 1), b3 + hstep, voffB); PG8_STAGE(PG8_SA(1, 0), a3, voffA);
;             PG8_WAIT_V(8); PG8_WAIT_L(0); PG8_BAR; PG8_MMA(1, 0, At, B0); PG8_MMA(1, 1, At, B1); PG8_BAR; PG8_SCHED;
;     ...
;         if (!has_next) break;
; #pragma unroll
;         for (int a = 0; a < 2; ++a)
; #pragma unroll
;             for (int b = 0; b < 2; ++b)
; #pragma unroll
;                 for (int m = 0; m < 4; ++m)
; #pragma unroll
;                     for (int n = 0; n < 2; ++n) acc[a][b][m][n] = (f32x4){0.f, 0.f, 0.f, 0.f};
;         cur = nxt; cA = nA; cB = nB; ++ui;
	s_add_i32 s30, s54, s42
	v_lshl_add_u64 v[208:209], v[208:209], 0, s[88:89]
	s_mov_b32 m0, s30
	ds_read_b128 v[176:179], v143 offset:49152
	ds_read_b128 v[180:183], v143 offset:50176
	ds_read_b128 v[184:187], v143 offset:51200
	ds_read_b128 v[188:191], v143 offset:52224
	ds_read_b128 v[192:195], v143 offset:53248
	ds_read_b128 v[196:199], v143 offset:54272
	ds_read_b128 v[200:203], v143 offset:55296
	ds_read_b128 v[204:207], v143 offset:56320
	global_load_lds_dwordx4 v[208:209], off
	s_add_i32 m0, s30, 0x2000
	s_add_u32 s28, s28, 0x160080
	v_lshl_add_u64 v[208:209], v[210:211], 0, s[88:89]
	s_addc_u32 s29, s29, 0
	s_add_i32 s30, s55, s42
	global_load_lds_dwordx4 v[208:209], off
	v_lshl_add_u64 v[208:209], s[28:29], 0, v[66:67]
	s_mov_b32 m0, s30
	s_nop 0
	global_load_lds_dwordx4 v[208:209], off
	v_lshl_add_u64 v[208:209], s[28:29], 0, v[132:133]
	s_add_i32 m0, s30, 0x2000
	s_nop 0
	global_load_lds_dwordx4 v[208:209], off
	v_lshl_add_u64 v[208:209], v[220:221], 0, s[88:89]
	s_mov_b32 m0, s47
	s_nop 0
	global_load_lds_dwordx4 v[208:209], off
	v_lshl_add_u64 v[208:209], v[222:223], 0, s[88:89]
	s_mov_b32 m0, s48
	s_nop 0
	global_load_lds_dwordx4 v[208:209], off
	s_waitcnt vmcnt(8)
	s_waitcnt lgkmcnt(0)
	s_barrier
	s_setprio 0
	s_waitcnt lgkmcnt(0)
	v_mfma_f32_16x16x32_bf16 v[58:61], v[144:147], v[176:179], v[58:61]
	v_mfma_f32_16x16x32_bf16 v[54:57], v[152:155], v[176:179], v[54:57]
	v_mfma_f32_16x16x32_bf16 v[46:49], v[144:147], v[184:187], v[46:49]
	v_mfma_f32_16x16x32_bf16 v[38:41], v[152:155], v[184:187], v[38:41]
	v_mfma_f32_16x16x32_bf16 v[30:33], v[144:147], v[192:195], v[30:33]
	v_mfma_f32_16x16x32_bf16 v[22:25], v[152:155], v[192:195], v[22:25]
	v_mfma_f32_16x16x32_bf16 v[120:123], v[144:147], v[200:203], v[120:123]
	v_mfma_f32_16x16x32_bf16 v[10:13], v[152:155], v[200:203], v[10:13]
	v_mfma_f32_16x16x32_bf16 v[58:61], v[148:151], v[180:183], v[58:61]
	v_mfma_f32_16x16x32_bf16 v[54:57], v[156:159], v[180:183], v[54:57]
	v_mfma_f32_16x16x32_bf16 v[46:49], v[148:151], v[188:191], v[46:49]
	v_mfma_f32_16x16x32_bf16 v[38:41], v[156:159], v[188:191], v[38:41]
	v_mfma_f32_16x16x32_bf16 v[30:33], v[148:151], v[196:199], v[30:33]
	v_mfma_f32_16x16x32_bf16 v[22:25], v[156:159], v[196:199], v[22:25]
	v_mfma_f32_16x16x32_bf16 v[120:123], v[148:151], v[204:207], v[120:123]
	v_mfma_f32_16x16x32_bf16 v[10:13], v[156:159], v[204:207], v[10:13]
	s_setprio 0
	s_setprio 0
	v_mfma_f32_16x16x32_bf16 v[50:53], v[160:163], v[176:179], v[50:53]
	v_mfma_f32_16x16x32_bf16 v[42:45], v[168:171], v[176:179], v[42:45]
	v_mfma_f32_16x16x32_bf16 v[34:37], v[160:163], v[184:187], v[34:37]
	v_mfma_f32_16x16x32_bf16 v[26:29], v[168:171], v[184:187], v[26:29]
	v_mfma_f32_16x16x32_bf16 v[18:21], v[160:163], v[192:195], v[18:21]
	v_mfma_f32_16x16x32_bf16 v[14:17], v[168:171], v[192:195], v[14:17]
	v_mfma_f32_16x16x32_bf16 v[6:9], v[160:163], v[200:203], v[6:9]
	v_mfma_f32_16x16x32_bf16 v[2:5], v[168:171], v[200:203], v[2:5]
	v_mfma_f32_16x16x32_bf16 v[50:53], v[164:167], v[180:183], v[50:53]
	v_mfma_f32_16x16x32_bf16 v[42:45], v[172:175], v[180:183], v[42:45]
	v_mfma_f32_16x16x32_bf16 v[34:37], v[164:167], v[188:191], v[34:37]
	v_mfma_f32_16x16x32_bf16 v[26:29], v[172:175], v[188:191], v[26:29]
	v_mfma_f32_16x16x32_bf16 v[18:21], v[164:167], v[196:199], v[18:21]
	v_mfma_f32_16x16x32_bf16 v[14:17], v[172:175], v[196:199], v[14:17]
	v_mfma_f32_16x16x32_bf16 v[6:9], v[164:167], v[204:207], v[6:9]
	v_mfma_f32_16x16x32_bf16 v[2:5], v[172:175], v[204:207], v[2:5]
	s_setprio 1
	s_barrier
	s_add_i32 s53, s53, 2
	s_add_u32 s26, s26, 0x100
	s_addc_u32 s27, s27, 0
	s_cmpk_gt_u32 s53, 0x55
	s_cbranch_scc0 .LBB0_1324
	s_add_u32 s26, s3, 0xffffff00
	s_addc_u32 s27, s52, -1
	s_and_b64 vcc, exec, s[10:11]
	s_cbranch_vccnz .LBB0_1311
	v_mov_b32_e32 v2, 0
	s_mov_b32 s20, s50
	s_mov_b32 s40, s51
	s_mov_b64 s[22:23], s[24:25]
	s_mov_b32 s49, s2
	v_mov_b32_e32 v3, v2
	v_mov_b32_e32 v4, v2
	v_mov_b32_e32 v5, v2
	v_mov_b32_e32 v6, v2
	v_mov_b32_e32 v7, v2
	v_mov_b32_e32 v8, v2
	v_mov_b32_e32 v9, v2
	v_mov_b32_e32 v14, v2
	v_mov_b32_e32 v15, v2
	v_mov_b32_e32 v16, v2
	v_mov_b32_e32 v17, v2
	v_mov_b32_e32 v18, v2
	v_mov_b32_e32 v19, v2
	v_mov_b32_e32 v20, v2
	v_mov_b32_e32 v21, v2
	v_mov_b32_e32 v26, v2
	v_mov_b32_e32 v27, v2
	v_mov_b32_e32 v28, v2
	v_mov_b32_e32 v29, v2
	v_mov_b32_e32 v34, v2
	v_mov_b32_e32 v35, v2
	v_mov_b32_e32 v36, v2
	v_mov_b32_e32 v37, v2
	v_mov_b32_e32 v42, v2
	v_mov_b32_e32 v43, v2
	v_mov_b32_e32 v44, v2
	v_mov_b32_e32 v45, v2
	v_mov_b32_e32 v50, v2
	v_mov_b32_e32 v51, v2
	v_mov_b32_e32 v52, v2
	v_mov_b32_e32 v53, v2
	v_mov_b32_e32 v10, v2
	v_mov_b32_e32 v11, v2
	v_mov_b32_e32 v12, v2
	v_mov_b32_e32 v13, v2
	v_mov_b32_e32 v120, v2
	v_mov_b32_e32 v121, v2
	v_mov_b32_e32 v122, v2
	v_mov_b32_e32 v123, v2
	v_mov_b32_e32 v22, v2
	v_mov_b32_e32 v23, v2
	v_mov_b32_e32 v24, v2
	v_mov_b32_e32 v25, v2
	v_mov_b32_e32 v30, v2
	v_mov_b32_e32 v31, v2
	v_mov_b32_e32 v32, v2
	v_mov_b32_e32 v33, v2
	v_mov_b32_e32 v38, v2
	v_mov_b32_e32 v39, v2
	v_mov_b32_e32 v40, v2
	v_mov_b32_e32 v41, v2
	v_mov_b32_e32 v46, v2
	v_mov_b32_e32 v47, v2
	v_mov_b32_e32 v48, v2
	v_mov_b32_e32 v49, v2
	v_mov_b32_e32 v54, v2
	v_mov_b32_e32 v55, v2
	v_mov_b32_e32 v56, v2
	v_mov_b32_e32 v57, v2
	v_mov_b32_e32 v58, v2
	v_mov_b32_e32 v59, v2
	v_mov_b32_e32 v60, v2
	v_mov_b32_e32 v61, v2
	v_mov_b32_e32 v62, v2
	v_mov_b32_e32 v63, v2
	v_mov_b32_e32 v64, v2
	v_mov_b32_e32 v65, v2
	v_mov_b32_e32 v68, v2
	v_mov_b32_e32 v69, v2
	v_mov_b32_e32 v70, v2
	v_mov_b32_e32 v71, v2
	v_mov_b32_e32 v76, v2
	v_mov_b32_e32 v77, v2
	v_mov_b32_e32 v78, v2
	v_mov_b32_e32 v79, v2
	v_mov_b32_e32 v84, v2
	v_mov_b32_e32 v85, v2
	v_mov_b32_e32 v86, v2
	v_mov_b32_e32 v87, v2
	v_mov_b32_e32 v92, v2
	v_mov_b32_e32 v93, v2
	v_mov_b32_e32 v94, v2
	v_mov_b32_e32 v95, v2
	v_mov_b32_e32 v100, v2
	v_mov_b32_e32 v101, v2
	v_mov_b32_e32 v102, v2
	v_mov_b32_e32 v103, v2
	v_mov_b32_e32 v108, v2
	v_mov_b32_e32 v109, v2
	v_mov_b32_e32 v110, v2
	v_mov_b32_e32 v111, v2
	v_mov_b32_e32 v116, v2
	v_mov_b32_e32 v117, v2
	v_mov_b32_e32 v118, v2
	v_mov_b32_e32 v119, v2
	v_mov_b32_e32 v72, v2
	v_mov_b32_e32 v73, v2
	v_mov_b32_e32 v74, v2
	v_mov_b32_e32 v75, v2
	v_mov_b32_e32 v80, v2
	v_mov_b32_e32 v81, v2
	v_mov_b32_e32 v82, v2
	v_mov_b32_e32 v83, v2
	v_mov_b32_e32 v88, v2
	v_mov_b32_e32 v89, v2
	v_mov_b32_e32 v90, v2
	v_mov_b32_e32 v91, v2
	v_mov_b32_e32 v96, v2
	v_mov_b32_e32 v97, v2
	v_mov_b32_e32 v98, v2
	v_mov_b32_e32 v99, v2
	v_mov_b32_e32 v104, v2
	v_mov_b32_e32 v105, v2
	v_mov_b32_e32 v106, v2
	v_mov_b32_e32 v107, v2
	v_mov_b32_e32 v112, v2
	v_mov_b32_e32 v113, v2
	v_mov_b32_e32 v114, v2
	v_mov_b32_e32 v115, v2
	v_mov_b32_e32 v124, v2
	v_mov_b32_e32 v125, v2
	v_mov_b32_e32 v126, v2
	v_mov_b32_e32 v127, v2
	v_mov_b32_e32 v128, v2
	v_mov_b32_e32 v129, v2
	v_mov_b32_e32 v130, v2
	v_mov_b32_e32 v131, v2
	s_andn2_b64 vcc, exec, s[6:7]
	s_cbranch_vccnz .LBB0_1312

; #define PG8_STAGE(bufoff, gbase, voff) do { _Pragma("unroll") for (int _i = 0; _i < 2; ++_i) \
;         __builtin_amdgcn_global_load_lds((const unsigned*)((const char*)(gbase) + (voff)[_i]), (PG8_LAS unsigned*)(lds + (bufoff) + ldsw + _i * 8192), 16, 0, 0); } while (0)
; #define PG8_LDA(dst, b, h) do { _Pragma("unroll") for (int m = 0; m < 4; ++m) _Pragma("unroll") for (int k = 0; k < 2; ++k) dst[m][k] = *(const PG8_LAS bf16x8*)(lds + PG8_SA(b, h) + aoff + m * 2048 + k * 1024); } while (0)
; #define PG8_LDB(dst, b, h) do { _Pragma("unroll") for (int n = 0; n < 2; ++n) _Pragma("unroll") for (int k = 0; k < 2; ++k) dst[n][k] = *(const PG8_LAS bf16x8*)(lds + PG8_SB(b, h) + boff + n * 2048 + k * 1024); } while (0)
; #define PG8_MMA(ai, bj, At, Bt) do { __builtin_amdgcn_s_setprio(1); _Pragma("unroll") for (int m = 0; m < 4; ++m) _Pragma("unroll") for (int n = 0; n < 2; ++n) _Pragma("unroll") for (int k = 0; k < 2; ++k) \
;         acc[ai][bj][m][n] = __builtin_amdgcn_mfma_f32_16x16x32_bf16(Bt[n][k], At[m][k], acc[ai][bj][m][n], 0, 0, 0); __builtin_amdgcn_s_setprio(0); } while (0)
; #define PG8_BAR __builtin_amdgcn_s_barrier()
; template <class Epi, class Sched, bool ALIGN_EPI = false, bool SP2 = false>
; __device__ __forceinline__ void gemm_phase(PG8_LAS unsigned char* lds, const Gemm g, const Sched& S, const Epi& E) {
;     ...
;         const char* nA = has_next ? (const char*)g.A + (size_t)nxt.pm * tstep + (size_t)nxt.ko * 2 : cA; const char* nB = has_next ? (const char*)g.Bt + (size_t)nxt.pn * tstep + (size_t)nxt.ko * 2 : cB;
;         for (int t = 0; t < nt; t += 2) {
;             const bool last = (t == nt - 2);
;             const char* a1 = cA + (size_t)(t + 1) * kstep;
;             const char* a2 = last ? nA : cA + (size_t)(t + 2) * kstep; const char* b2 = last ? nB : cB + (size_t)(t + 2) * kstep;
;             const char* a3 = a2 + kstep; const char* b3 = b2 + kstep;
;             if (last && has_next) S.a_ready(nxt);
;             if constexpr (SP2) {
;             PG8_LDB(B0, 0, 0); PG8_LDB(B1, 0, 1); PG8_SCHED; PG8_LDA(At, 0, 0); PG8_STAGE(PG8_SA(1, 1), a1 + hstep, voffA);
;             PG8_WAIT_V(8); PG8_WAIT_L(0); PG8_BAR; PG8_MMA(0, 0, At, B0); PG8_MMA(0, 1, At, B1); PG8_BAR; PG8_SCHED;
;             PG8_LDA(At, 0, 1); PG8_STAGE(PG8_SB(0, 0), b2, voffB); PG8_STAGE(PG8_SB(0, 1), b2 + hstep, voffB); PG8_STAGE(PG8_SA(0, 0), a2, voffA);
.LBB0_1583:
	s_add_u32 s20, s18, 0x100
	s_addc_u32 s21, s19, 0
	s_cmp_eq_u32 s43, 4
	s_cselect_b32 s25, s17, s21
	s_cselect_b32 s24, s16, s20
	s_cselect_b32 s23, s15, s42
	s_cselect_b32 s22, s14, s13
	s_add_i32 s44, 0, 0x10000
	s_add_i32 s45, 0, 0x14000
	v_add_u32_e32 v168, s44, v0
	v_add_u32_e32 v184, s45, v0
	ds_read_b128 v[156:159], v168
	ds_read_b128 v[160:163], v168 offset:1024
	ds_read_b128 v[164:167], v168 offset:2048
	ds_read_b128 v[168:171], v168 offset:3072
	ds_read_b128 v[172:175], v184
	ds_read_b128 v[176:179], v184 offset:1024
	ds_read_b128 v[180:183], v184 offset:2048
	ds_read_b128 v[184:187], v184 offset:3072
	v_lshl_add_u64 v[228:229], s[18:19], 0, v[150:151]
	s_add_i32 m0, s28, 0xc000
	ds_read_b128 v[188:191], v155
	ds_read_b128 v[192:195], v155 offset:1024
	ds_read_b128 v[196:199], v155 offset:2048
	ds_read_b128 v[200:203], v155 offset:3072
	ds_read_b128 v[204:207], v155 offset:4096
	ds_read_b128 v[208:211], v155 offset:5120
	ds_read_b128 v[220:223], v155 offset:6144
	ds_read_b128 v[224:227], v155 offset:7168
	global_load_lds_dwordx4 v[228:229], off
	v_lshl_add_u64 v[228:229], s[18:19], 0, v[152:153]
	s_add_i32 m0, s28, 0xe000
	s_nop 0
	global_load_lds_dwordx4 v[228:229], off
	s_waitcnt vmcnt(8)
	s_waitcnt lgkmcnt(0)
	s_barrier
	s_setprio 0
	s_waitcnt lgkmcnt(0)
	v_mfma_f32_16x16x32_bf16 v[128:131], v[156:159], v[188:191], v[128:131]
	v_mfma_f32_16x16x32_bf16 v[124:127], v[164:167], v[188:191], v[124:127]
	v_mfma_f32_16x16x32_bf16 v[120:123], v[156:159], v[196:199], v[120:123]
	v_mfma_f32_16x16x32_bf16 v[116:119], v[164:167], v[196:199], v[116:119]
	v_mfma_f32_16x16x32_bf16 v[112:115], v[156:159], v[204:207], v[112:115]
	v_mfma_f32_16x16x32_bf16 v[108:111], v[164:167], v[204:207], v[108:111]
	v_mfma_f32_16x16x32_bf16 v[100:103], v[156:159], v[220:223], v[100:103]
	v_mfma_f32_16x16x32_bf16 v[92:95], v[164:167], v[220:223], v[92:95]
	v_mfma_f32_16x16x32_bf16 v[128:131], v[160:163], v[192:195], v[128:131]
	v_mfma_f32_16x16x32_bf16 v[124:127], v[168:171], v[192:195], v[124:127]
	v_mfma_f32_16x16x32_bf16 v[120:123], v[160:163], v[200:203], v[120:123]
	v_mfma_f32_16x16x32_bf16 v[116:119], v[168:171], v[200:203], v[116:119]
	v_mfma_f32_16x16x32_bf16 v[112:115], v[160:163], v[208:211], v[112:115]
	v_mfma_f32_16x16x32_bf16 v[108:111], v[168:171], v[208:211], v[108:111]
	v_mfma_f32_16x16x32_bf16 v[100:103], v[160:163], v[224:227], v[100:103]
	v_mfma_f32_16x16x32_bf16 v[92:95], v[168:171], v[224:227], v[92:95]
	s_setprio 0
	s_setprio 0
	v_mfma_f32_16x16x32_bf16 v[104:107], v[172:175], v[188:191], v[104:107]
	v_mfma_f32_16x16x32_bf16 v[96:99], v[180:183], v[188:191], v[96:99]
	v_mfma_f32_16x16x32_bf16 v[88:91], v[172:175], v[196:199], v[88:91]
	v_mfma_f32_16x16x32_bf16 v[84:87], v[180:183], v[196:199], v[84:87]
	v_mfma_f32_16x16x32_bf16 v[80:83], v[172:175], v[204:207], v[80:83]
	v_mfma_f32_16x16x32_bf16 v[76:79], v[180:183], v[204:207], v[76:79]
	v_mfma_f32_16x16x32_bf16 v[72:75], v[172:175], v[220:223], v[72:75]
	v_mfma_f32_16x16x32_bf16 v[68:71], v[180:183], v[220:223], v[68:71]
	v_mfma_f32_16x16x32_bf16 v[104:107], v[176:179], v[192:195], v[104:107]
	v_mfma_f32_16x16x32_bf16 v[96:99], v[184:187], v[192:195], v[96:99]
	v_mfma_f32_16x16x32_bf16 v[88:91], v[176:179], v[200:203], v[88:91]
	v_mfma_f32_16x16x32_bf16 v[84:87], v[184:187], v[200:203], v[84:87]
	v_mfma_f32_16x16x32_bf16 v[80:83], v[176:179], v[208:211], v[80:83]
	v_mfma_f32_16x16x32_bf16 v[76:79], v[184:187], v[208:211], v[76:79]
	v_mfma_f32_16x16x32_bf16 v[72:75], v[176:179], v[224:227], v[72:75]
	v_mfma_f32_16x16x32_bf16 v[68:71], v[184:187], v[224:227], v[68:71]
	s_setprio 1
	s_barrier
	s_add_i32 s18, s44, s1
	v_lshl_add_u64 v[228:229], s[22:23], 0, v[66:67]
	s_mov_b32 m0, s18
	ds_read_b128 v[188:191], v155 offset:16384
	ds_read_b128 v[192:195], v155 offset:17408
	ds_read_b128 v[196:199], v155 offset:18432
	ds_read_b128 v[200:203], v155 offset:19456
	ds_read_b128 v[204:207], v155 offset:20480
	ds_read_b128 v[208:211], v155 offset:21504
	ds_read_b128 v[220:223], v155 offset:22528
	ds_read_b128 v[224:227], v155 offset:23552
	global_load_lds_dwordx4 v[228:229], off
	s_add_i32 m0, s18, 0x2000
	s_add_u32 s18, s22, 0x160000
	v_lshl_add_u64 v[230:231], s[22:23], 0, v[132:133]
	s_addc_u32 s19, s23, 0
	s_add_i32 s44, s45, s1
	global_load_lds_dwordx4 v[230:231], off
	v_lshl_add_u64 v[232:233], s[18:19], 0, v[66:67]
	s_mov_b32 m0, s44
	v_lshl_add_u64 v[234:235], s[24:25], 0, v[132:133]
	global_load_lds_dwordx4 v[232:233], off
	v_lshl_add_u64 v[232:233], s[18:19], 0, v[132:133]
	s_add_i32 m0, s44, 0x2000
	s_nop 0
	global_load_lds_dwordx4 v[232:233], off
	v_lshl_add_u64 v[232:233], s[24:25], 0, v[66:67]
	s_mov_b32 m0, s28
	s_nop 0
	global_load_lds_dwordx4 v[232:233], off
	s_mov_b32 m0, s29
	s_nop 0
	global_load_lds_dwordx4 v[234:235], off
	s_waitcnt vmcnt(8)
	s_waitcnt lgkmcnt(0)
	s_barrier
; #define PG8_STAGE(bufoff, gbase, voff) do { _Pragma("unroll") for (int _i = 0; _i < 2; ++_i) \
;         __builtin_amdgcn_global_load_lds((const unsigned*)((const char*)(gbase) + (voff)[_i]), (PG8_LAS unsigned*)(lds + (bufoff) + ldsw + _i * 8192), 16, 0, 0); } while (0)
; #define PG8_LDA(dst, b, h) do { _Pragma("unroll") for (int m = 0; m < 4; ++m) _Pragma("unroll") for (int k = 0; k < 2; ++k) dst[m][k] = *(const PG8_LAS bf16x8*)(lds + PG8_SA(b, h) + aoff + m * 2048 + k * 1024); } while (0)
; #define PG8_LDB(dst, b, h) do { _Pragma("unroll") for (int n = 0; n < 2; ++n) _Pragma("unroll") for (int k = 0; k < 2; ++k) dst[n][k] = *(const PG8_LAS bf16x8*)(lds + PG8_SB(b, h) + boff + n * 2048 + k * 1024); } while (0)
; #define PG8_MMA(ai, bj, At, Bt) do { __builtin_amdgcn_s_setprio(1); _Pragma("unroll") for (int m = 0; m < 4; ++m) _Pragma("unroll") for (int n = 0; n < 2; ++n) _Pragma("unroll") for (int k = 0; k < 2; ++k) \
;         acc[ai][bj][m][n] = __builtin_amdgcn_mfma_f32_16x16x32_bf16(Bt[n][k], At[m][k], acc[ai][bj][m][n], 0, 0, 0); __builtin_amdgcn_s_setprio(0); } while (0)
; #define PG8_WAIT_V(n) asm volatile("s_waitcnt vmcnt(" #n ")" ::: "memory")
; #define PG8_WAIT_L(n) asm volatile("s_waitcnt lgkmcnt(" #n ")" ::: "memory")
; #define PG8_BAR __builtin_amdgcn_s_barrier()
; #define PG8_SCHED __builtin_amdgcn_sched_barrier(0)
; template <class Epi, class Sched, bool ALIGN_EPI = false, bool SP2 = false>
; __device__ __forceinline__ void gemm_phase(PG8_LAS unsigned char* lds, const Gemm g, const Sched& S, const Epi& E) {
;     ...
;             PG8_WAIT_V(8); PG8_WAIT_L(0); PG8_BAR; PG8_MMA(1, 0, At, B0); PG8_MMA(1, 1, At, B1); PG8_BAR; PG8_SCHED;
;             PG8_LDB(B0, 1, 0); PG8_LDB(B1, 1, 1); PG8_SCHED; PG8_LDA(At, 1, 0); PG8_STAGE(PG8_SA(0, 1), a2 + hstep, voffA);
;             PG8_WAIT_V(8); PG8_WAIT_L(0); PG8_BAR; PG8_MMA(0, 0, At, B0); PG8_MMA(0, 1, At, B1); PG8_BAR; PG8_SCHED;
	s_setprio 0
	s_waitcnt lgkmcnt(0)
	v_mfma_f32_16x16x32_bf16 v[62:65], v[156:159], v[188:191], v[62:65]
	v_mfma_f32_16x16x32_bf16 v[58:61], v[164:167], v[188:191], v[58:61]
	v_mfma_f32_16x16x32_bf16 v[54:57], v[156:159], v[196:199], v[54:57]
	v_mfma_f32_16x16x32_bf16 v[50:53], v[164:167], v[196:199], v[50:53]
	v_mfma_f32_16x16x32_bf16 v[46:49], v[156:159], v[204:207], v[46:49]
	v_mfma_f32_16x16x32_bf16 v[42:45], v[164:167], v[204:207], v[42:45]
	v_mfma_f32_16x16x32_bf16 v[34:37], v[156:159], v[220:223], v[34:37]
	v_mfma_f32_16x16x32_bf16 v[26:29], v[164:167], v[220:223], v[26:29]
	v_mfma_f32_16x16x32_bf16 v[62:65], v[160:163], v[192:195], v[62:65]
	v_mfma_f32_16x16x32_bf16 v[58:61], v[168:171], v[192:195], v[58:61]
	v_mfma_f32_16x16x32_bf16 v[54:57], v[160:163], v[200:203], v[54:57]
	v_mfma_f32_16x16x32_bf16 v[50:53], v[168:171], v[200:203], v[50:53]
	v_mfma_f32_16x16x32_bf16 v[46:49], v[160:163], v[208:211], v[46:49]
	v_mfma_f32_16x16x32_bf16 v[42:45], v[168:171], v[208:211], v[42:45]
	v_mfma_f32_16x16x32_bf16 v[34:37], v[160:163], v[224:227], v[34:37]
	v_mfma_f32_16x16x32_bf16 v[26:29], v[168:171], v[224:227], v[26:29]
	s_setprio 0
	s_setprio 0
	v_mfma_f32_16x16x32_bf16 v[38:41], v[172:175], v[188:191], v[38:41]
	v_mfma_f32_16x16x32_bf16 v[30:33], v[180:183], v[188:191], v[30:33]
	v_mfma_f32_16x16x32_bf16 v[22:25], v[172:175], v[196:199], v[22:25]
	v_mfma_f32_16x16x32_bf16 v[18:21], v[180:183], v[196:199], v[18:21]
	v_mfma_f32_16x16x32_bf16 v[14:17], v[172:175], v[204:207], v[14:17]
	v_mfma_f32_16x16x32_bf16 v[10:13], v[180:183], v[204:207], v[10:13]
	v_mfma_f32_16x16x32_bf16 v[6:9], v[172:175], v[220:223], v[6:9]
	v_mfma_f32_16x16x32_bf16 v[2:5], v[180:183], v[220:223], v[2:5]
	v_mfma_f32_16x16x32_bf16 v[38:41], v[176:179], v[192:195], v[38:41]
	v_mfma_f32_16x16x32_bf16 v[30:33], v[184:187], v[192:195], v[30:33]
	v_mfma_f32_16x16x32_bf16 v[22:25], v[176:179], v[200:203], v[22:25]
	v_mfma_f32_16x16x32_bf16 v[18:21], v[184:187], v[200:203], v[18:21]
	v_mfma_f32_16x16x32_bf16 v[14:17], v[176:179], v[208:211], v[14:17]
	v_mfma_f32_16x16x32_bf16 v[10:13], v[184:187], v[208:211], v[10:13]
	v_mfma_f32_16x16x32_bf16 v[6:9], v[176:179], v[224:227], v[6:9]
	v_mfma_f32_16x16x32_bf16 v[2:5], v[184:187], v[224:227], v[2:5]
	s_setprio 1
	s_barrier
	s_add_i32 s44, 0, 0x18000
	s_add_i32 s45, 0, 0x1c000
	v_add_u32_e32 v168, s44, v0
	v_add_u32_e32 v184, s45, v0
	ds_read_b128 v[156:159], v168
	ds_read_b128 v[160:163], v168 offset:1024
	ds_read_b128 v[164:167], v168 offset:2048
	ds_read_b128 v[168:171], v168 offset:3072
	ds_read_b128 v[172:175], v184
	ds_read_b128 v[176:179], v184 offset:1024
	ds_read_b128 v[180:183], v184 offset:2048
	ds_read_b128 v[184:187], v184 offset:3072
	s_add_u32 s18, s24, 0x160000
	s_addc_u32 s19, s25, 0
	s_mov_b32 m0, s30
	v_lshl_add_u64 v[246:247], s[18:19], 0, v[66:67]
	ds_read_b128 v[188:191], v155 offset:32768
	ds_read_b128 v[192:195], v155 offset:33792
	ds_read_b128 v[196:199], v155 offset:34816
	ds_read_b128 v[200:203], v155 offset:35840
	ds_read_b128 v[204:207], v155 offset:36864
	ds_read_b128 v[208:211], v155 offset:37888
	ds_read_b128 v[220:223], v155 offset:38912
	ds_read_b128 v[224:227], v155 offset:39936
	global_load_lds_dwordx4 v[246:247], off
	v_lshl_add_u64 v[246:247], s[18:19], 0, v[132:133]
	s_mov_b32 m0, s31
	s_nop 0
	global_load_lds_dwordx4 v[246:247], off
	s_waitcnt vmcnt(8)
	s_waitcnt lgkmcnt(0)
	s_barrier
	s_setprio 0
	s_waitcnt lgkmcnt(0)
	v_mfma_f32_16x16x32_bf16 v[128:131], v[156:159], v[188:191], v[128:131]
	v_mfma_f32_16x16x32_bf16 v[124:127], v[164:167], v[188:191], v[124:127]
	v_mfma_f32_16x16x32_bf16 v[120:123], v[156:159], v[196:199], v[120:123]
	v_mfma_f32_16x16x32_bf16 v[116:119], v[164:167], v[196:199], v[116:119]
	v_mfma_f32_16x16x32_bf16 v[112:115], v[156:159], v[204:207], v[112:115]
	v_mfma_f32_16x16x32_bf16 v[108:111], v[164:167], v[204:207], v[108:111]
	v_mfma_f32_16x16x32_bf16 v[100:103], v[156:159], v[220:223], v[100:103]
	v_mfma_f32_16x16x32_bf16 v[92:95], v[164:167], v[220:223], v[92:95]
	v_mfma_f32_16x16x32_bf16 v[128:131], v[160:163], v[192:195], v[128:131]
	v_mfma_f32_16x16x32_bf16 v[124:127], v[168:171], v[192:195], v[124:127]
	v_mfma_f32_16x16x32_bf16 v[120:123], v[160:163], v[200:203], v[120:123]
	v_mfma_f32_16x16x32_bf16 v[116:119], v[168:171], v[200:203], v[116:119]
	v_mfma_f32_16x16x32_bf16 v[112:115], v[160:163], v[208:211], v[112:115]
	v_mfma_f32_16x16x32_bf16 v[108:111], v[168:171], v[208:211], v[108:111]
	v_mfma_f32_16x16x32_bf16 v[100:103], v[160:163], v[224:227], v[100:103]
	v_mfma_f32_16x16x32_bf16 v[92:95], v[168:171], v[224:227], v[92:95]
	s_setprio 0
	s_setprio 0
	v_mfma_f32_16x16x32_bf16 v[104:107], v[172:175], v[188:191], v[104:107]
	v_mfma_f32_16x16x32_bf16 v[96:99], v[180:183], v[188:191], v[96:99]
	v_mfma_f32_16x16x32_bf16 v[88:91], v[172:175], v[196:199], v[88:91]
	v_mfma_f32_16x16x32_bf16 v[84:87], v[180:183], v[196:199], v[84:87]
	v_mfma_f32_16x16x32_bf16 v[80:83], v[172:175], v[204:207], v[80:83]
	v_mfma_f32_16x16x32_bf16 v[76:79], v[180:183], v[204:207], v[76:79]
	v_mfma_f32_16x16x32_bf16 v[72:75], v[172:175], v[220:223], v[72:75]
	v_mfma_f32_16x16x32_bf16 v[68:71], v[180:183], v[220:223], v[68:71]
	v_mfma_f32_16x16x32_bf16 v[104:107], v[176:179], v[192:195], v[104:107]
	v_mfma_f32_16x16x32_bf16 v[96:99], v[184:187], v[192:195], v[96:99]
	v_mfma_f32_16x16x32_bf16 v[88:91], v[176:179], v[200:203], v[88:91]
	v_mfma_f32_16x16x32_bf16 v[84:87], v[184:187], v[200:203], v[84:87]
	v_mfma_f32_16x16x32_bf16 v[80:83], v[176:179], v[208:211], v[80:83]
	v_mfma_f32_16x16x32_bf16 v[76:79], v[184:187], v[208:211], v[76:79]
	v_mfma_f32_16x16x32_bf16 v[72:75], v[176:179], v[224:227], v[72:75]
	v_mfma_f32_16x16x32_bf16 v[68:71], v[184:187], v[224:227], v[68:71]
	s_setprio 1
	s_barrier
; #define PG8_STAGE(bufoff, gbase, voff) do { _Pragma("unroll") for (int _i = 0; _i < 2; ++_i) \
;         __builtin_amdgcn_global_load_lds((const unsigned*)((const char*)(gbase) + (voff)[_i]), (PG8_LAS unsigned*)(lds + (bufoff) + ldsw + _i * 8192), 16, 0, 0); } while (0)
; #define PG8_LDA(dst, b, h) do { _Pragma("unroll") for (int m = 0; m < 4; ++m) _Pragma("unroll") for (int k = 0; k < 2; ++k) dst[m][k] = *(const PG8_LAS bf16x8*)(lds + PG8_SA(b, h) + aoff + m * 2048 + k * 1024); } while (0)
; #define PG8_MMA(ai, bj, At, Bt) do { __builtin_amdgcn_s_setprio(1); _Pragma("unroll") for (int m = 0; m < 4; ++m) _Pragma("unroll") for (int n = 0; n < 2; ++n) _Pragma("unroll") for (int k = 0; k < 2; ++k) \
;         acc[ai][bj][m][n] = __builtin_amdgcn_mfma_f32_16x16x32_bf16(Bt[n][k], At[m][k], acc[ai][bj][m][n], 0, 0, 0); __builtin_amdgcn_s_setprio(0); } while (0)
; #define PG8_WAIT_V(n) asm volatile("s_waitcnt vmcnt(" #n ")" ::: "memory")
; #define PG8_WAIT_L(n) asm volatile("s_waitcnt lgkmcnt(" #n ")" ::: "memory")
; #define PG8_BAR __builtin_amdgcn_s_barrier()
; #define PG8_SCHED __builtin_amdgcn_sched_barrier(0)
; template <class Epi, class Sched, bool ALIGN_EPI = false, bool SP2 = false>
; __device__ __forceinline__ void gemm_phase(PG8_LAS unsigned char* lds, const Gemm g, const Sched& S, const Epi& E) {
;     ...
;             PG8_LDA(At, 1, 1); PG8_STAGE(PG8_SB(1, 0), b3, voffB); PG8_STAGE(PG8_SB(1, 1), b3 + hstep, voffB); PG8_STAGE(PG8_SA(1, 0), a3, voffA);
;             PG8_WAIT_V(8); PG8_WAIT_L(0); PG8_BAR; PG8_MMA(1, 0, At, B0); PG8_MMA(1, 1, At, B1); PG8_BAR; PG8_SCHED;
;     ...
;         if constexpr (ALIGN_EPI) { if (wr == 0) PG8_BAR; }
	s_add_i32 s18, s44, s1
	v_lshl_add_u64 v[228:229], v[228:229], 0, s[88:89]
	s_mov_b32 m0, s18
	ds_read_b128 v[188:191], v155 offset:49152
	ds_read_b128 v[192:195], v155 offset:50176
	ds_read_b128 v[196:199], v155 offset:51200
	ds_read_b128 v[200:203], v155 offset:52224
	ds_read_b128 v[204:207], v155 offset:53248
	ds_read_b128 v[208:211], v155 offset:54272
	ds_read_b128 v[220:223], v155 offset:55296
	ds_read_b128 v[224:227], v155 offset:56320
	global_load_lds_dwordx4 v[228:229], off
	s_add_i32 m0, s18, 0x2000
	s_add_u32 s18, s22, 0x160080
	v_lshl_add_u64 v[228:229], v[230:231], 0, s[88:89]
	s_addc_u32 s19, s23, 0
	s_add_i32 s22, s45, s1
	global_load_lds_dwordx4 v[228:229], off
	v_lshl_add_u64 v[228:229], s[18:19], 0, v[66:67]
	s_mov_b32 m0, s22
	s_nop 0
	global_load_lds_dwordx4 v[228:229], off
	v_lshl_add_u64 v[228:229], s[18:19], 0, v[132:133]
	s_add_i32 m0, s22, 0x2000
	s_nop 0
	global_load_lds_dwordx4 v[228:229], off
	v_lshl_add_u64 v[228:229], v[232:233], 0, s[88:89]
	s_mov_b32 m0, s38
	s_nop 0
	global_load_lds_dwordx4 v[228:229], off
	v_lshl_add_u64 v[228:229], v[234:235], 0, s[88:89]
	s_mov_b32 m0, s39
	s_nop 0
	global_load_lds_dwordx4 v[228:229], off
	s_waitcnt vmcnt(8)
	s_waitcnt lgkmcnt(0)
	s_barrier
	s_setprio 0
	s_waitcnt lgkmcnt(0)
	v_mfma_f32_16x16x32_bf16 v[62:65], v[156:159], v[188:191], v[62:65]
	v_mfma_f32_16x16x32_bf16 v[58:61], v[164:167], v[188:191], v[58:61]
	v_mfma_f32_16x16x32_bf16 v[54:57], v[156:159], v[196:199], v[54:57]
	v_mfma_f32_16x16x32_bf16 v[50:53], v[164:167], v[196:199], v[50:53]
	v_mfma_f32_16x16x32_bf16 v[46:49], v[156:159], v[204:207], v[46:49]
	v_mfma_f32_16x16x32_bf16 v[42:45], v[164:167], v[204:207], v[42:45]
	v_mfma_f32_16x16x32_bf16 v[34:37], v[156:159], v[220:223], v[34:37]
	v_mfma_f32_16x16x32_bf16 v[26:29], v[164:167], v[220:223], v[26:29]
	v_mfma_f32_16x16x32_bf16 v[62:65], v[160:163], v[192:195], v[62:65]
	v_mfma_f32_16x16x32_bf16 v[58:61], v[168:171], v[192:195], v[58:61]
	v_mfma_f32_16x16x32_bf16 v[54:57], v[160:163], v[200:203], v[54:57]
	v_mfma_f32_16x16x32_bf16 v[50:53], v[168:171], v[200:203], v[50:53]
	v_mfma_f32_16x16x32_bf16 v[46:49], v[160:163], v[208:211], v[46:49]
	v_mfma_f32_16x16x32_bf16 v[42:45], v[168:171], v[208:211], v[42:45]
	v_mfma_f32_16x16x32_bf16 v[34:37], v[160:163], v[224:227], v[34:37]
	v_mfma_f32_16x16x32_bf16 v[26:29], v[168:171], v[224:227], v[26:29]
	s_setprio 0
	s_setprio 0
	v_mfma_f32_16x16x32_bf16 v[38:41], v[172:175], v[188:191], v[38:41]
	v_mfma_f32_16x16x32_bf16 v[30:33], v[180:183], v[188:191], v[30:33]
	v_mfma_f32_16x16x32_bf16 v[22:25], v[172:175], v[196:199], v[22:25]
	v_mfma_f32_16x16x32_bf16 v[18:21], v[180:183], v[196:199], v[18:21]
	v_mfma_f32_16x16x32_bf16 v[14:17], v[172:175], v[204:207], v[14:17]
	v_mfma_f32_16x16x32_bf16 v[10:13], v[180:183], v[204:207], v[10:13]
	v_mfma_f32_16x16x32_bf16 v[6:9], v[172:175], v[220:223], v[6:9]
	v_mfma_f32_16x16x32_bf16 v[2:5], v[180:183], v[220:223], v[2:5]
	v_mfma_f32_16x16x32_bf16 v[38:41], v[176:179], v[192:195], v[38:41]
	v_mfma_f32_16x16x32_bf16 v[30:33], v[184:187], v[192:195], v[30:33]
	v_mfma_f32_16x16x32_bf16 v[22:25], v[176:179], v[200:203], v[22:25]
	v_mfma_f32_16x16x32_bf16 v[18:21], v[184:187], v[200:203], v[18:21]
	v_mfma_f32_16x16x32_bf16 v[14:17], v[176:179], v[208:211], v[14:17]
	v_mfma_f32_16x16x32_bf16 v[10:13], v[184:187], v[208:211], v[10:13]
	v_mfma_f32_16x16x32_bf16 v[6:9], v[176:179], v[224:227], v[6:9]
	v_mfma_f32_16x16x32_bf16 v[2:5], v[184:187], v[224:227], v[2:5]
	s_setprio 1
	s_barrier
	s_add_i32 s43, s43, 2
	s_add_u32 s13, s13, 0x100
	s_addc_u32 s42, s42, 0
	s_cmp_gt_u32 s43, 5
	s_mov_b64 s[18:19], s[20:21]
	s_cbranch_scc0 .LBB0_1583
	s_and_b64 vcc, exec, s[10:11]
	s_cbranch_vccz .LBB0_1586
	s_barrier
